# c11 = c10 + snake MFMA order in K-loops (every consecutive MFMA shares one source operand)
# speedup vs baseline: 1.0089x; 1.0072x over previous
.LBB0_343:
	s_ashr_i32 s11, s10, 31
	s_lshl_b64 s[12:13], s[10:11], 20
	s_add_u32 s12, s26, s12
	s_addc_u32 s13, s27, s13
	s_and_b64 s[14:15], s[2:3], exec
	s_cselect_b32 s11, s13, s21
	s_cselect_b32 s75, s12, s20
	s_ashr_i32 s9, s8, 31
	s_lshl_b64 s[14:15], s[8:9], 20
	s_add_u32 s14, s28, s14
	s_addc_u32 s15, s29, s15
	s_and_b64 s[22:23], s[2:3], exec
	s_cselect_b32 s9, s15, s19
	s_cselect_b32 s76, s14, s18
	s_add_u32 s77, s18, 0x100
	s_addc_u32 s78, s19, 0
	s_add_u32 s18, s20, 0x80080
	s_addc_u32 s19, s21, 0
	s_add_u32 s79, s20, 0x100
	s_addc_u32 s80, s21, 0
	s_mov_b32 s81, -2
	ds_read_b128 v[148:151], v143
	ds_read_b128 v[152:155], v143 offset:1024
	ds_read_b128 v[156:159], v143 offset:2048
	ds_read_b128 v[160:163], v143 offset:3072
	ds_read_b128 v[164:167], v144
	ds_read_b128 v[168:171], v144 offset:1024
	ds_read_b128 v[172:175], v144 offset:2048
	ds_read_b128 v[176:179], v144 offset:3072
	s_cmp_eq_u32 s81, 28
	s_cselect_b32 s21, s9, s78
	s_cselect_b32 s20, s76, s77
	s_cselect_b32 s23, s11, s80
	s_cselect_b32 s22, s75, s79
	ds_read_b128 v[180:183], v145
	ds_read_b128 v[184:187], v145 offset:1024
	ds_read_b128 v[188:191], v145 offset:2048
	ds_read_b128 v[192:195], v145 offset:3072
	ds_read_b128 v[196:199], v145 offset:4096
	ds_read_b128 v[200:203], v145 offset:5120
	ds_read_b128 v[204:207], v145 offset:6144
	ds_read_b128 v[208:211], v145 offset:7168
	s_add_u32 s82, s18, 0xfff80000
	s_addc_u32 s83, s19, -1
	s_mov_b32 s86, m0
	s_mov_b32 m0, s64
	s_nop 0
	global_load_lds_dwordx4 v138, s[82:83]
	s_mov_b32 m0, s86
	s_nop 0
	s_mov_b32 s86, m0
	s_mov_b32 m0, s67
	s_nop 0
	global_load_lds_dwordx4 v140, s[82:83]
	s_mov_b32 m0, s86
	s_mov_b32 s82, m0
	s_mov_b32 m0, s65
	s_nop 0
	global_load_lds_dwordx4 v138, s[18:19]
	s_mov_b32 m0, s82
	s_nop 0
	s_mov_b32 s82, m0
	s_mov_b32 m0, s73
	s_nop 0
	global_load_lds_dwordx4 v140, s[18:19]
	s_mov_b32 m0, s82
	s_waitcnt vmcnt(8)
	s_waitcnt lgkmcnt(0)
	s_barrier
	s_setprio 1
	s_waitcnt lgkmcnt(7)
	v_mfma_f32_16x16x32_bf16 v[126:129], v[148:151], v[180:183], 0
	v_mfma_f32_16x16x32_bf16 v[122:125], v[156:159], v[180:183], 0
	s_waitcnt lgkmcnt(5)
	v_mfma_f32_16x16x32_bf16 v[106:109], v[156:159], v[188:191], 0
	v_mfma_f32_16x16x32_bf16 v[110:113], v[148:151], v[188:191], 0
	s_waitcnt lgkmcnt(3)
	v_mfma_f32_16x16x32_bf16 v[94:97], v[148:151], v[196:199], 0
	v_mfma_f32_16x16x32_bf16 v[90:93], v[156:159], v[196:199], 0
	s_waitcnt lgkmcnt(1)
	v_mfma_f32_16x16x32_bf16 v[74:77], v[156:159], v[204:207], 0
	v_mfma_f32_16x16x32_bf16 v[78:81], v[148:151], v[204:207], 0
	v_mfma_f32_16x16x32_bf16 v[126:129], v[152:155], v[184:187], v[126:129]
	v_mfma_f32_16x16x32_bf16 v[122:125], v[160:163], v[184:187], v[122:125]
	v_mfma_f32_16x16x32_bf16 v[106:109], v[160:163], v[192:195], v[106:109]
	v_mfma_f32_16x16x32_bf16 v[110:113], v[152:155], v[192:195], v[110:113]
	v_mfma_f32_16x16x32_bf16 v[94:97], v[152:155], v[200:203], v[94:97]
	v_mfma_f32_16x16x32_bf16 v[90:93], v[160:163], v[200:203], v[90:93]
	s_waitcnt lgkmcnt(0)
	v_mfma_f32_16x16x32_bf16 v[74:77], v[160:163], v[208:211], v[74:77]
	v_mfma_f32_16x16x32_bf16 v[78:81], v[152:155], v[208:211], v[78:81]
	s_setprio 0
	s_setprio 1
	v_mfma_f32_16x16x32_bf16 v[118:121], v[164:167], v[180:183], 0
	v_mfma_f32_16x16x32_bf16 v[114:117], v[172:175], v[180:183], 0
	v_mfma_f32_16x16x32_bf16 v[98:101], v[172:175], v[188:191], 0
	v_mfma_f32_16x16x32_bf16 v[102:105], v[164:167], v[188:191], 0
	v_mfma_f32_16x16x32_bf16 v[86:89], v[164:167], v[196:199], 0
	v_mfma_f32_16x16x32_bf16 v[82:85], v[172:175], v[196:199], 0
	v_mfma_f32_16x16x32_bf16 v[66:69], v[172:175], v[204:207], 0
	v_mfma_f32_16x16x32_bf16 v[70:73], v[164:167], v[204:207], 0
	v_mfma_f32_16x16x32_bf16 v[118:121], v[168:171], v[184:187], v[118:121]
	v_mfma_f32_16x16x32_bf16 v[114:117], v[176:179], v[184:187], v[114:117]
	v_mfma_f32_16x16x32_bf16 v[98:101], v[176:179], v[192:195], v[98:101]
	v_mfma_f32_16x16x32_bf16 v[102:105], v[168:171], v[192:195], v[102:105]
	v_mfma_f32_16x16x32_bf16 v[86:89], v[168:171], v[200:203], v[86:89]
	v_mfma_f32_16x16x32_bf16 v[82:85], v[176:179], v[200:203], v[82:85]
	s_setprio 2
	s_barrier
	v_mfma_f32_16x16x32_bf16 v[66:69], v[176:179], v[208:211], v[66:69]
	v_mfma_f32_16x16x32_bf16 v[70:73], v[168:171], v[208:211], v[70:73]
	s_setprio 0
	ds_read_b128 v[180:183], v145 offset:16384
	ds_read_b128 v[184:187], v145 offset:17408
	ds_read_b128 v[188:191], v145 offset:18432
	ds_read_b128 v[192:195], v145 offset:19456
	ds_read_b128 v[196:199], v145 offset:20480
	ds_read_b128 v[200:203], v145 offset:21504
	ds_read_b128 v[204:207], v145 offset:22528
	ds_read_b128 v[208:211], v145 offset:23552
	s_mov_b32 s82, m0
	s_mov_b32 m0, s35
	s_nop 0
	global_load_lds_dwordx4 v139, s[20:21]
	s_mov_b32 m0, s82
	s_nop 0
	s_mov_b32 s82, m0
	s_mov_b32 m0, s36
	s_nop 0
	global_load_lds_dwordx4 v141, s[20:21]
	s_mov_b32 m0, s82
	s_add_u32 s82, s20, 0x80000
	s_addc_u32 s83, s21, 0
	s_mov_b32 s86, m0
	s_mov_b32 m0, s37
	s_nop 0
	global_load_lds_dwordx4 v139, s[82:83]
	s_mov_b32 m0, s86
	s_nop 0
	s_mov_b32 s86, m0
	s_mov_b32 m0, s42
	s_nop 0
	global_load_lds_dwordx4 v141, s[82:83]
	s_mov_b32 m0, s86
	s_waitcnt vmcnt(4)
	s_waitcnt lgkmcnt(0)
	s_barrier
	s_setprio 1
	s_waitcnt lgkmcnt(7)
	v_mfma_f32_16x16x32_bf16 v[62:65], v[148:151], v[180:183], 0
	v_mfma_f32_16x16x32_bf16 v[58:61], v[156:159], v[180:183], 0
	s_waitcnt lgkmcnt(5)
	v_mfma_f32_16x16x32_bf16 v[42:45], v[156:159], v[188:191], 0
	v_mfma_f32_16x16x32_bf16 v[46:49], v[148:151], v[188:191], 0
	s_waitcnt lgkmcnt(3)
	v_mfma_f32_16x16x32_bf16 v[30:33], v[148:151], v[196:199], 0
	v_mfma_f32_16x16x32_bf16 v[26:29], v[156:159], v[196:199], 0
	s_waitcnt lgkmcnt(1)
	v_mfma_f32_16x16x32_bf16 v[10:13], v[156:159], v[204:207], 0
	v_mfma_f32_16x16x32_bf16 v[14:17], v[148:151], v[204:207], 0
	v_mfma_f32_16x16x32_bf16 v[62:65], v[152:155], v[184:187], v[62:65]
	v_mfma_f32_16x16x32_bf16 v[58:61], v[160:163], v[184:187], v[58:61]
	v_mfma_f32_16x16x32_bf16 v[42:45], v[160:163], v[192:195], v[42:45]
	v_mfma_f32_16x16x32_bf16 v[46:49], v[152:155], v[192:195], v[46:49]
	v_mfma_f32_16x16x32_bf16 v[30:33], v[152:155], v[200:203], v[30:33]
	v_mfma_f32_16x16x32_bf16 v[26:29], v[160:163], v[200:203], v[26:29]
	s_waitcnt lgkmcnt(0)
	v_mfma_f32_16x16x32_bf16 v[10:13], v[160:163], v[208:211], v[10:13]
	v_mfma_f32_16x16x32_bf16 v[14:17], v[152:155], v[208:211], v[14:17]
	s_setprio 0
	s_setprio 1
	v_mfma_f32_16x16x32_bf16 v[54:57], v[164:167], v[180:183], 0
	v_mfma_f32_16x16x32_bf16 v[50:53], v[172:175], v[180:183], 0
	v_mfma_f32_16x16x32_bf16 v[34:37], v[172:175], v[188:191], 0
	v_mfma_f32_16x16x32_bf16 v[38:41], v[164:167], v[188:191], 0
	v_mfma_f32_16x16x32_bf16 v[22:25], v[164:167], v[196:199], 0
	v_mfma_f32_16x16x32_bf16 v[18:21], v[172:175], v[196:199], 0
	v_mfma_f32_16x16x32_bf16 v[2:5], v[172:175], v[204:207], 0
	v_mfma_f32_16x16x32_bf16 v[6:9], v[164:167], v[204:207], 0
	v_mfma_f32_16x16x32_bf16 v[54:57], v[168:171], v[184:187], v[54:57]
	v_mfma_f32_16x16x32_bf16 v[50:53], v[176:179], v[184:187], v[50:53]
	v_mfma_f32_16x16x32_bf16 v[34:37], v[176:179], v[192:195], v[34:37]
	v_mfma_f32_16x16x32_bf16 v[38:41], v[168:171], v[192:195], v[38:41]
	v_mfma_f32_16x16x32_bf16 v[22:25], v[168:171], v[200:203], v[22:25]
	v_mfma_f32_16x16x32_bf16 v[18:21], v[176:179], v[200:203], v[18:21]
	s_setprio 2
	s_barrier
	v_mfma_f32_16x16x32_bf16 v[2:5], v[176:179], v[208:211], v[2:5]
	v_mfma_f32_16x16x32_bf16 v[6:9], v[168:171], v[208:211], v[6:9]
	s_setprio 0
	ds_read_b128 v[148:151], v146
	ds_read_b128 v[152:155], v146 offset:1024
	ds_read_b128 v[156:159], v146 offset:2048
	ds_read_b128 v[160:163], v146 offset:3072
	ds_read_b128 v[164:167], v147
	ds_read_b128 v[168:171], v147 offset:1024
	ds_read_b128 v[172:175], v147 offset:2048
	ds_read_b128 v[176:179], v147 offset:3072
	ds_read_b128 v[180:183], v145 offset:32768
	ds_read_b128 v[184:187], v145 offset:33792
	ds_read_b128 v[188:191], v145 offset:34816
	ds_read_b128 v[192:195], v145 offset:35840
	ds_read_b128 v[196:199], v145 offset:36864
	ds_read_b128 v[200:203], v145 offset:37888
	ds_read_b128 v[204:207], v145 offset:38912
	ds_read_b128 v[208:211], v145 offset:39936
	s_mov_b32 s82, m0
	s_mov_b32 m0, s31
	s_nop 0
	global_load_lds_dwordx4 v138, s[22:23]
	s_mov_b32 m0, s82
	s_nop 0
	s_mov_b32 s82, m0
	s_mov_b32 m0, s43
	s_nop 0
	global_load_lds_dwordx4 v140, s[22:23]
	s_mov_b32 m0, s82
	s_add_u32 s22, s22, 0x80000
	s_addc_u32 s23, s23, 0
	s_mov_b32 s82, m0
	s_mov_b32 m0, s46
	s_nop 0
	global_load_lds_dwordx4 v138, s[22:23]
	s_mov_b32 m0, s82
	s_nop 0
	s_mov_b32 s82, m0
	s_mov_b32 m0, s47
	s_nop 0
	global_load_lds_dwordx4 v140, s[22:23]
	s_mov_b32 m0, s82
	s_waitcnt vmcnt(8)
	s_waitcnt lgkmcnt(0)
	s_barrier
	s_setprio 1
	s_waitcnt lgkmcnt(7)
	v_mfma_f32_16x16x32_bf16 v[126:129], v[148:151], v[180:183], v[126:129]
	v_mfma_f32_16x16x32_bf16 v[122:125], v[156:159], v[180:183], v[122:125]
	s_waitcnt lgkmcnt(5)
	v_mfma_f32_16x16x32_bf16 v[106:109], v[156:159], v[188:191], v[106:109]
	v_mfma_f32_16x16x32_bf16 v[110:113], v[148:151], v[188:191], v[110:113]
	s_waitcnt lgkmcnt(3)
	v_mfma_f32_16x16x32_bf16 v[94:97], v[148:151], v[196:199], v[94:97]
	v_mfma_f32_16x16x32_bf16 v[90:93], v[156:159], v[196:199], v[90:93]
	s_waitcnt lgkmcnt(1)
	v_mfma_f32_16x16x32_bf16 v[74:77], v[156:159], v[204:207], v[74:77]
	v_mfma_f32_16x16x32_bf16 v[78:81], v[148:151], v[204:207], v[78:81]
	v_mfma_f32_16x16x32_bf16 v[126:129], v[152:155], v[184:187], v[126:129]
	v_mfma_f32_16x16x32_bf16 v[122:125], v[160:163], v[184:187], v[122:125]
	v_mfma_f32_16x16x32_bf16 v[106:109], v[160:163], v[192:195], v[106:109]
	v_mfma_f32_16x16x32_bf16 v[110:113], v[152:155], v[192:195], v[110:113]
	v_mfma_f32_16x16x32_bf16 v[94:97], v[152:155], v[200:203], v[94:97]
	v_mfma_f32_16x16x32_bf16 v[90:93], v[160:163], v[200:203], v[90:93]
	s_waitcnt lgkmcnt(0)
	v_mfma_f32_16x16x32_bf16 v[74:77], v[160:163], v[208:211], v[74:77]
	v_mfma_f32_16x16x32_bf16 v[78:81], v[152:155], v[208:211], v[78:81]
	s_setprio 0
	s_setprio 1
	v_mfma_f32_16x16x32_bf16 v[118:121], v[164:167], v[180:183], v[118:121]
	v_mfma_f32_16x16x32_bf16 v[114:117], v[172:175], v[180:183], v[114:117]
	v_mfma_f32_16x16x32_bf16 v[98:101], v[172:175], v[188:191], v[98:101]
	v_mfma_f32_16x16x32_bf16 v[102:105], v[164:167], v[188:191], v[102:105]
	v_mfma_f32_16x16x32_bf16 v[86:89], v[164:167], v[196:199], v[86:89]
	v_mfma_f32_16x16x32_bf16 v[82:85], v[172:175], v[196:199], v[82:85]
	v_mfma_f32_16x16x32_bf16 v[66:69], v[172:175], v[204:207], v[66:69]
	v_mfma_f32_16x16x32_bf16 v[70:73], v[164:167], v[204:207], v[70:73]
	v_mfma_f32_16x16x32_bf16 v[118:121], v[168:171], v[184:187], v[118:121]
	v_mfma_f32_16x16x32_bf16 v[114:117], v[176:179], v[184:187], v[114:117]
	v_mfma_f32_16x16x32_bf16 v[98:101], v[176:179], v[192:195], v[98:101]
	v_mfma_f32_16x16x32_bf16 v[102:105], v[168:171], v[192:195], v[102:105]
	v_mfma_f32_16x16x32_bf16 v[86:89], v[168:171], v[200:203], v[86:89]
	v_mfma_f32_16x16x32_bf16 v[82:85], v[176:179], v[200:203], v[82:85]
	s_setprio 2
	s_barrier
	v_mfma_f32_16x16x32_bf16 v[66:69], v[176:179], v[208:211], v[66:69]
	v_mfma_f32_16x16x32_bf16 v[70:73], v[168:171], v[208:211], v[70:73]
	s_setprio 0
	ds_read_b128 v[180:183], v145 offset:49152
	ds_read_b128 v[184:187], v145 offset:50176
	ds_read_b128 v[188:191], v145 offset:51200
	ds_read_b128 v[192:195], v145 offset:52224
	ds_read_b128 v[196:199], v145 offset:53248
	ds_read_b128 v[200:203], v145 offset:54272
	ds_read_b128 v[204:207], v145 offset:55296
	ds_read_b128 v[208:211], v145 offset:56320
	s_add_u32 s22, s20, 0x80
	s_addc_u32 s23, s21, 0
	s_mov_b32 s82, m0
	s_mov_b32 m0, s48
	s_nop 0
	global_load_lds_dwordx4 v139, s[22:23]
	s_mov_b32 m0, s82
	s_add_u32 s20, s20, 0x80080
	s_mov_b32 s82, m0
	s_mov_b32 m0, s49
	s_nop 0
	global_load_lds_dwordx4 v141, s[22:23]
	s_mov_b32 m0, s82
	s_addc_u32 s21, s21, 0
	s_mov_b32 s22, m0
	s_mov_b32 m0, s56
	s_nop 0
	global_load_lds_dwordx4 v139, s[20:21]
	s_mov_b32 m0, s22
	s_nop 0
	s_mov_b32 s22, m0
	s_mov_b32 m0, s57
	s_nop 0
	global_load_lds_dwordx4 v141, s[20:21]
	s_mov_b32 m0, s22
	s_waitcnt vmcnt(4)
	s_waitcnt lgkmcnt(0)
	s_barrier
	s_setprio 1
	s_waitcnt lgkmcnt(7)
	v_mfma_f32_16x16x32_bf16 v[62:65], v[148:151], v[180:183], v[62:65]
	v_mfma_f32_16x16x32_bf16 v[58:61], v[156:159], v[180:183], v[58:61]
	s_waitcnt lgkmcnt(5)
	v_mfma_f32_16x16x32_bf16 v[42:45], v[156:159], v[188:191], v[42:45]
	v_mfma_f32_16x16x32_bf16 v[46:49], v[148:151], v[188:191], v[46:49]
	s_waitcnt lgkmcnt(3)
	v_mfma_f32_16x16x32_bf16 v[30:33], v[148:151], v[196:199], v[30:33]
	v_mfma_f32_16x16x32_bf16 v[26:29], v[156:159], v[196:199], v[26:29]
	s_waitcnt lgkmcnt(1)
	v_mfma_f32_16x16x32_bf16 v[10:13], v[156:159], v[204:207], v[10:13]
	v_mfma_f32_16x16x32_bf16 v[14:17], v[148:151], v[204:207], v[14:17]
	v_mfma_f32_16x16x32_bf16 v[62:65], v[152:155], v[184:187], v[62:65]
	v_mfma_f32_16x16x32_bf16 v[58:61], v[160:163], v[184:187], v[58:61]
	v_mfma_f32_16x16x32_bf16 v[42:45], v[160:163], v[192:195], v[42:45]
	v_mfma_f32_16x16x32_bf16 v[46:49], v[152:155], v[192:195], v[46:49]
	v_mfma_f32_16x16x32_bf16 v[30:33], v[152:155], v[200:203], v[30:33]
	v_mfma_f32_16x16x32_bf16 v[26:29], v[160:163], v[200:203], v[26:29]
	s_waitcnt lgkmcnt(0)
	v_mfma_f32_16x16x32_bf16 v[10:13], v[160:163], v[208:211], v[10:13]
	v_mfma_f32_16x16x32_bf16 v[14:17], v[152:155], v[208:211], v[14:17]
	s_setprio 0
	s_setprio 1
	v_mfma_f32_16x16x32_bf16 v[54:57], v[164:167], v[180:183], v[54:57]
	v_mfma_f32_16x16x32_bf16 v[50:53], v[172:175], v[180:183], v[50:53]
	v_mfma_f32_16x16x32_bf16 v[34:37], v[172:175], v[188:191], v[34:37]
	v_mfma_f32_16x16x32_bf16 v[38:41], v[164:167], v[188:191], v[38:41]
	v_mfma_f32_16x16x32_bf16 v[22:25], v[164:167], v[196:199], v[22:25]
	v_mfma_f32_16x16x32_bf16 v[18:21], v[172:175], v[196:199], v[18:21]
	v_mfma_f32_16x16x32_bf16 v[2:5], v[172:175], v[204:207], v[2:5]
	v_mfma_f32_16x16x32_bf16 v[6:9], v[164:167], v[204:207], v[6:9]
	v_mfma_f32_16x16x32_bf16 v[54:57], v[168:171], v[184:187], v[54:57]
	v_mfma_f32_16x16x32_bf16 v[50:53], v[176:179], v[184:187], v[50:53]
	v_mfma_f32_16x16x32_bf16 v[34:37], v[176:179], v[192:195], v[34:37]
	v_mfma_f32_16x16x32_bf16 v[38:41], v[168:171], v[192:195], v[38:41]
	v_mfma_f32_16x16x32_bf16 v[22:25], v[168:171], v[200:203], v[22:25]
	v_mfma_f32_16x16x32_bf16 v[18:21], v[176:179], v[200:203], v[18:21]
	s_setprio 2
	s_barrier
	v_mfma_f32_16x16x32_bf16 v[2:5], v[176:179], v[208:211], v[2:5]
	v_mfma_f32_16x16x32_bf16 v[6:9], v[168:171], v[208:211], v[6:9]
	s_setprio 0
	s_add_i32 s81, s81, 2
	s_add_u32 s77, s77, 0x100
	s_addc_u32 s78, s78, 0
	s_add_u32 s18, s18, 0x100
	s_addc_u32 s19, s19, 0
	s_add_u32 s79, s79, 0x100
	s_addc_u32 s80, s80, 0
	s_cmp_gt_u32 s81, 29
	.p2align 6
.LBB0_344:
	ds_read_b128 v[148:151], v143
	ds_read_b128 v[152:155], v143 offset:1024
	ds_read_b128 v[156:159], v143 offset:2048
	ds_read_b128 v[160:163], v143 offset:3072
	ds_read_b128 v[164:167], v144
	ds_read_b128 v[168:171], v144 offset:1024
	ds_read_b128 v[172:175], v144 offset:2048
	ds_read_b128 v[176:179], v144 offset:3072
	s_cmp_eq_u32 s81, 28
	s_cselect_b32 s21, s9, s78
	s_cselect_b32 s20, s76, s77
	s_cselect_b32 s23, s11, s80
	s_cselect_b32 s22, s75, s79
	ds_read_b128 v[180:183], v145
	ds_read_b128 v[184:187], v145 offset:1024
	ds_read_b128 v[188:191], v145 offset:2048
	ds_read_b128 v[192:195], v145 offset:3072
	ds_read_b128 v[196:199], v145 offset:4096
	ds_read_b128 v[200:203], v145 offset:5120
	ds_read_b128 v[204:207], v145 offset:6144
	ds_read_b128 v[208:211], v145 offset:7168
	s_add_u32 s82, s18, 0xfff80000
	s_addc_u32 s83, s19, -1
	s_mov_b32 s86, m0
	s_mov_b32 m0, s64
	s_nop 0
	global_load_lds_dwordx4 v138, s[82:83]
	s_mov_b32 m0, s86
	s_nop 0
	s_mov_b32 s86, m0
	s_mov_b32 m0, s67
	s_nop 0
	global_load_lds_dwordx4 v140, s[82:83]
	s_mov_b32 m0, s86
	s_mov_b32 s82, m0
	s_mov_b32 m0, s65
	s_nop 0
	global_load_lds_dwordx4 v138, s[18:19]
	s_mov_b32 m0, s82
	s_nop 0
	s_mov_b32 s82, m0
	s_mov_b32 m0, s73
	s_nop 0
	global_load_lds_dwordx4 v140, s[18:19]
	s_mov_b32 m0, s82
	s_waitcnt vmcnt(8)
	s_waitcnt lgkmcnt(0)
	s_barrier
	s_setprio 1
	s_waitcnt lgkmcnt(7)
	v_mfma_f32_16x16x32_bf16 v[126:129], v[148:151], v[180:183], v[126:129]
	v_mfma_f32_16x16x32_bf16 v[122:125], v[156:159], v[180:183], v[122:125]
	s_waitcnt lgkmcnt(5)
	v_mfma_f32_16x16x32_bf16 v[106:109], v[156:159], v[188:191], v[106:109]
	v_mfma_f32_16x16x32_bf16 v[110:113], v[148:151], v[188:191], v[110:113]
	s_waitcnt lgkmcnt(3)
	v_mfma_f32_16x16x32_bf16 v[94:97], v[148:151], v[196:199], v[94:97]
	v_mfma_f32_16x16x32_bf16 v[90:93], v[156:159], v[196:199], v[90:93]
	s_waitcnt lgkmcnt(1)
	v_mfma_f32_16x16x32_bf16 v[74:77], v[156:159], v[204:207], v[74:77]
	v_mfma_f32_16x16x32_bf16 v[78:81], v[148:151], v[204:207], v[78:81]
	v_mfma_f32_16x16x32_bf16 v[126:129], v[152:155], v[184:187], v[126:129]
	v_mfma_f32_16x16x32_bf16 v[122:125], v[160:163], v[184:187], v[122:125]
	v_mfma_f32_16x16x32_bf16 v[106:109], v[160:163], v[192:195], v[106:109]
	v_mfma_f32_16x16x32_bf16 v[110:113], v[152:155], v[192:195], v[110:113]
	v_mfma_f32_16x16x32_bf16 v[94:97], v[152:155], v[200:203], v[94:97]
	v_mfma_f32_16x16x32_bf16 v[90:93], v[160:163], v[200:203], v[90:93]
	s_waitcnt lgkmcnt(0)
	v_mfma_f32_16x16x32_bf16 v[74:77], v[160:163], v[208:211], v[74:77]
	v_mfma_f32_16x16x32_bf16 v[78:81], v[152:155], v[208:211], v[78:81]
	s_setprio 0
	s_setprio 1
	v_mfma_f32_16x16x32_bf16 v[118:121], v[164:167], v[180:183], v[118:121]
	v_mfma_f32_16x16x32_bf16 v[114:117], v[172:175], v[180:183], v[114:117]
	v_mfma_f32_16x16x32_bf16 v[98:101], v[172:175], v[188:191], v[98:101]
	v_mfma_f32_16x16x32_bf16 v[102:105], v[164:167], v[188:191], v[102:105]
	v_mfma_f32_16x16x32_bf16 v[86:89], v[164:167], v[196:199], v[86:89]
	v_mfma_f32_16x16x32_bf16 v[82:85], v[172:175], v[196:199], v[82:85]
	v_mfma_f32_16x16x32_bf16 v[66:69], v[172:175], v[204:207], v[66:69]
	v_mfma_f32_16x16x32_bf16 v[70:73], v[164:167], v[204:207], v[70:73]
	v_mfma_f32_16x16x32_bf16 v[118:121], v[168:171], v[184:187], v[118:121]
	v_mfma_f32_16x16x32_bf16 v[114:117], v[176:179], v[184:187], v[114:117]
	v_mfma_f32_16x16x32_bf16 v[98:101], v[176:179], v[192:195], v[98:101]
	v_mfma_f32_16x16x32_bf16 v[102:105], v[168:171], v[192:195], v[102:105]
	v_mfma_f32_16x16x32_bf16 v[86:89], v[168:171], v[200:203], v[86:89]
	v_mfma_f32_16x16x32_bf16 v[82:85], v[176:179], v[200:203], v[82:85]
	s_setprio 2
	s_barrier
	v_mfma_f32_16x16x32_bf16 v[66:69], v[176:179], v[208:211], v[66:69]
	v_mfma_f32_16x16x32_bf16 v[70:73], v[168:171], v[208:211], v[70:73]
	s_setprio 0
	ds_read_b128 v[180:183], v145 offset:16384
	ds_read_b128 v[184:187], v145 offset:17408
	ds_read_b128 v[188:191], v145 offset:18432
	ds_read_b128 v[192:195], v145 offset:19456
	ds_read_b128 v[196:199], v145 offset:20480
	ds_read_b128 v[200:203], v145 offset:21504
	ds_read_b128 v[204:207], v145 offset:22528
	ds_read_b128 v[208:211], v145 offset:23552
	s_mov_b32 s82, m0
	s_mov_b32 m0, s35
	s_nop 0
	global_load_lds_dwordx4 v139, s[20:21]
	s_mov_b32 m0, s82
	s_nop 0
	s_mov_b32 s82, m0
	s_mov_b32 m0, s36
	s_nop 0
	global_load_lds_dwordx4 v141, s[20:21]
	s_mov_b32 m0, s82
	s_add_u32 s82, s20, 0x80000
	s_addc_u32 s83, s21, 0
	s_mov_b32 s86, m0
	s_mov_b32 m0, s37
	s_nop 0
	global_load_lds_dwordx4 v139, s[82:83]
	s_mov_b32 m0, s86
	s_nop 0
	s_mov_b32 s86, m0
	s_mov_b32 m0, s42
	s_nop 0
	global_load_lds_dwordx4 v141, s[82:83]
	s_mov_b32 m0, s86
	s_waitcnt vmcnt(4)
	s_waitcnt lgkmcnt(0)
	s_barrier
	s_setprio 1
	s_waitcnt lgkmcnt(7)
	v_mfma_f32_16x16x32_bf16 v[62:65], v[148:151], v[180:183], v[62:65]
	v_mfma_f32_16x16x32_bf16 v[58:61], v[156:159], v[180:183], v[58:61]
	s_waitcnt lgkmcnt(5)
	v_mfma_f32_16x16x32_bf16 v[42:45], v[156:159], v[188:191], v[42:45]
	v_mfma_f32_16x16x32_bf16 v[46:49], v[148:151], v[188:191], v[46:49]
	s_waitcnt lgkmcnt(3)
	v_mfma_f32_16x16x32_bf16 v[30:33], v[148:151], v[196:199], v[30:33]
	v_mfma_f32_16x16x32_bf16 v[26:29], v[156:159], v[196:199], v[26:29]
	s_waitcnt lgkmcnt(1)
	v_mfma_f32_16x16x32_bf16 v[10:13], v[156:159], v[204:207], v[10:13]
	v_mfma_f32_16x16x32_bf16 v[14:17], v[148:151], v[204:207], v[14:17]
	v_mfma_f32_16x16x32_bf16 v[62:65], v[152:155], v[184:187], v[62:65]
	v_mfma_f32_16x16x32_bf16 v[58:61], v[160:163], v[184:187], v[58:61]
	v_mfma_f32_16x16x32_bf16 v[42:45], v[160:163], v[192:195], v[42:45]
	v_mfma_f32_16x16x32_bf16 v[46:49], v[152:155], v[192:195], v[46:49]
	v_mfma_f32_16x16x32_bf16 v[30:33], v[152:155], v[200:203], v[30:33]
	v_mfma_f32_16x16x32_bf16 v[26:29], v[160:163], v[200:203], v[26:29]
	s_waitcnt lgkmcnt(0)
	v_mfma_f32_16x16x32_bf16 v[10:13], v[160:163], v[208:211], v[10:13]
	v_mfma_f32_16x16x32_bf16 v[14:17], v[152:155], v[208:211], v[14:17]
	s_setprio 0
	s_setprio 1
	v_mfma_f32_16x16x32_bf16 v[54:57], v[164:167], v[180:183], v[54:57]
	v_mfma_f32_16x16x32_bf16 v[50:53], v[172:175], v[180:183], v[50:53]
	v_mfma_f32_16x16x32_bf16 v[34:37], v[172:175], v[188:191], v[34:37]
	v_mfma_f32_16x16x32_bf16 v[38:41], v[164:167], v[188:191], v[38:41]
	v_mfma_f32_16x16x32_bf16 v[22:25], v[164:167], v[196:199], v[22:25]
	v_mfma_f32_16x16x32_bf16 v[18:21], v[172:175], v[196:199], v[18:21]
	v_mfma_f32_16x16x32_bf16 v[2:5], v[172:175], v[204:207], v[2:5]
	v_mfma_f32_16x16x32_bf16 v[6:9], v[164:167], v[204:207], v[6:9]
	v_mfma_f32_16x16x32_bf16 v[54:57], v[168:171], v[184:187], v[54:57]
	v_mfma_f32_16x16x32_bf16 v[50:53], v[176:179], v[184:187], v[50:53]
	v_mfma_f32_16x16x32_bf16 v[34:37], v[176:179], v[192:195], v[34:37]
	v_mfma_f32_16x16x32_bf16 v[38:41], v[168:171], v[192:195], v[38:41]
	v_mfma_f32_16x16x32_bf16 v[22:25], v[168:171], v[200:203], v[22:25]
	v_mfma_f32_16x16x32_bf16 v[18:21], v[176:179], v[200:203], v[18:21]
	s_setprio 2
	s_barrier
	v_mfma_f32_16x16x32_bf16 v[2:5], v[176:179], v[208:211], v[2:5]
	v_mfma_f32_16x16x32_bf16 v[6:9], v[168:171], v[208:211], v[6:9]
	s_setprio 0
	ds_read_b128 v[148:151], v146
	ds_read_b128 v[152:155], v146 offset:1024
	ds_read_b128 v[156:159], v146 offset:2048
	ds_read_b128 v[160:163], v146 offset:3072
	ds_read_b128 v[164:167], v147
	ds_read_b128 v[168:171], v147 offset:1024
	ds_read_b128 v[172:175], v147 offset:2048
	ds_read_b128 v[176:179], v147 offset:3072
	ds_read_b128 v[180:183], v145 offset:32768
	ds_read_b128 v[184:187], v145 offset:33792
	ds_read_b128 v[188:191], v145 offset:34816
	ds_read_b128 v[192:195], v145 offset:35840
	ds_read_b128 v[196:199], v145 offset:36864
	ds_read_b128 v[200:203], v145 offset:37888
	ds_read_b128 v[204:207], v145 offset:38912
	ds_read_b128 v[208:211], v145 offset:39936
	s_mov_b32 s82, m0
	s_mov_b32 m0, s31
	s_nop 0
	global_load_lds_dwordx4 v138, s[22:23]
	s_mov_b32 m0, s82
	s_nop 0
	s_mov_b32 s82, m0
	s_mov_b32 m0, s43
	s_nop 0
	global_load_lds_dwordx4 v140, s[22:23]
	s_mov_b32 m0, s82
	s_add_u32 s22, s22, 0x80000
	s_addc_u32 s23, s23, 0
	s_mov_b32 s82, m0
	s_mov_b32 m0, s46
	s_nop 0
	global_load_lds_dwordx4 v138, s[22:23]
	s_mov_b32 m0, s82
	s_nop 0
	s_mov_b32 s82, m0
	s_mov_b32 m0, s47
	s_nop 0
	global_load_lds_dwordx4 v140, s[22:23]
	s_mov_b32 m0, s82
	s_waitcnt vmcnt(8)
	s_waitcnt lgkmcnt(0)
	s_barrier
	s_setprio 1
	s_waitcnt lgkmcnt(7)
	v_mfma_f32_16x16x32_bf16 v[126:129], v[148:151], v[180:183], v[126:129]
	v_mfma_f32_16x16x32_bf16 v[122:125], v[156:159], v[180:183], v[122:125]
	s_waitcnt lgkmcnt(5)
	v_mfma_f32_16x16x32_bf16 v[106:109], v[156:159], v[188:191], v[106:109]
	v_mfma_f32_16x16x32_bf16 v[110:113], v[148:151], v[188:191], v[110:113]
	s_waitcnt lgkmcnt(3)
	v_mfma_f32_16x16x32_bf16 v[94:97], v[148:151], v[196:199], v[94:97]
	v_mfma_f32_16x16x32_bf16 v[90:93], v[156:159], v[196:199], v[90:93]
	s_waitcnt lgkmcnt(1)
	v_mfma_f32_16x16x32_bf16 v[74:77], v[156:159], v[204:207], v[74:77]
	v_mfma_f32_16x16x32_bf16 v[78:81], v[148:151], v[204:207], v[78:81]
	v_mfma_f32_16x16x32_bf16 v[126:129], v[152:155], v[184:187], v[126:129]
	v_mfma_f32_16x16x32_bf16 v[122:125], v[160:163], v[184:187], v[122:125]
	v_mfma_f32_16x16x32_bf16 v[106:109], v[160:163], v[192:195], v[106:109]
	v_mfma_f32_16x16x32_bf16 v[110:113], v[152:155], v[192:195], v[110:113]
	v_mfma_f32_16x16x32_bf16 v[94:97], v[152:155], v[200:203], v[94:97]
	v_mfma_f32_16x16x32_bf16 v[90:93], v[160:163], v[200:203], v[90:93]
	s_waitcnt lgkmcnt(0)
	v_mfma_f32_16x16x32_bf16 v[74:77], v[160:163], v[208:211], v[74:77]
	v_mfma_f32_16x16x32_bf16 v[78:81], v[152:155], v[208:211], v[78:81]
	s_setprio 0
	s_setprio 1
	v_mfma_f32_16x16x32_bf16 v[118:121], v[164:167], v[180:183], v[118:121]
	v_mfma_f32_16x16x32_bf16 v[114:117], v[172:175], v[180:183], v[114:117]
	v_mfma_f32_16x16x32_bf16 v[98:101], v[172:175], v[188:191], v[98:101]
	v_mfma_f32_16x16x32_bf16 v[102:105], v[164:167], v[188:191], v[102:105]
	v_mfma_f32_16x16x32_bf16 v[86:89], v[164:167], v[196:199], v[86:89]
	v_mfma_f32_16x16x32_bf16 v[82:85], v[172:175], v[196:199], v[82:85]
	v_mfma_f32_16x16x32_bf16 v[66:69], v[172:175], v[204:207], v[66:69]
	v_mfma_f32_16x16x32_bf16 v[70:73], v[164:167], v[204:207], v[70:73]
	v_mfma_f32_16x16x32_bf16 v[118:121], v[168:171], v[184:187], v[118:121]
	v_mfma_f32_16x16x32_bf16 v[114:117], v[176:179], v[184:187], v[114:117]
	v_mfma_f32_16x16x32_bf16 v[98:101], v[176:179], v[192:195], v[98:101]
	v_mfma_f32_16x16x32_bf16 v[102:105], v[168:171], v[192:195], v[102:105]
	v_mfma_f32_16x16x32_bf16 v[86:89], v[168:171], v[200:203], v[86:89]
	v_mfma_f32_16x16x32_bf16 v[82:85], v[176:179], v[200:203], v[82:85]
	s_setprio 2
	s_barrier
	v_mfma_f32_16x16x32_bf16 v[66:69], v[176:179], v[208:211], v[66:69]
	v_mfma_f32_16x16x32_bf16 v[70:73], v[168:171], v[208:211], v[70:73]
	s_setprio 0
	ds_read_b128 v[180:183], v145 offset:49152
	ds_read_b128 v[184:187], v145 offset:50176
	ds_read_b128 v[188:191], v145 offset:51200
	ds_read_b128 v[192:195], v145 offset:52224
	ds_read_b128 v[196:199], v145 offset:53248
	ds_read_b128 v[200:203], v145 offset:54272
	ds_read_b128 v[204:207], v145 offset:55296
	ds_read_b128 v[208:211], v145 offset:56320
	s_add_u32 s22, s20, 0x80
	s_addc_u32 s23, s21, 0
	s_mov_b32 s82, m0
	s_mov_b32 m0, s48
	s_nop 0
	global_load_lds_dwordx4 v139, s[22:23]
	s_mov_b32 m0, s82
	s_add_u32 s20, s20, 0x80080
	s_mov_b32 s82, m0
	s_mov_b32 m0, s49
	s_nop 0
	global_load_lds_dwordx4 v141, s[22:23]
	s_mov_b32 m0, s82
	s_addc_u32 s21, s21, 0
	s_mov_b32 s22, m0
	s_mov_b32 m0, s56
	s_nop 0
	global_load_lds_dwordx4 v139, s[20:21]
	s_mov_b32 m0, s22
	s_nop 0
	s_mov_b32 s22, m0
	s_mov_b32 m0, s57
	s_nop 0
	global_load_lds_dwordx4 v141, s[20:21]
	s_mov_b32 m0, s22
	s_waitcnt vmcnt(4)
	s_waitcnt lgkmcnt(0)
	s_barrier
	s_setprio 1
	s_waitcnt lgkmcnt(7)
	v_mfma_f32_16x16x32_bf16 v[62:65], v[148:151], v[180:183], v[62:65]
	v_mfma_f32_16x16x32_bf16 v[58:61], v[156:159], v[180:183], v[58:61]
	s_waitcnt lgkmcnt(5)
	v_mfma_f32_16x16x32_bf16 v[42:45], v[156:159], v[188:191], v[42:45]
	v_mfma_f32_16x16x32_bf16 v[46:49], v[148:151], v[188:191], v[46:49]
	s_waitcnt lgkmcnt(3)
	v_mfma_f32_16x16x32_bf16 v[30:33], v[148:151], v[196:199], v[30:33]
	v_mfma_f32_16x16x32_bf16 v[26:29], v[156:159], v[196:199], v[26:29]
	s_waitcnt lgkmcnt(1)
	v_mfma_f32_16x16x32_bf16 v[10:13], v[156:159], v[204:207], v[10:13]
	v_mfma_f32_16x16x32_bf16 v[14:17], v[148:151], v[204:207], v[14:17]
	v_mfma_f32_16x16x32_bf16 v[62:65], v[152:155], v[184:187], v[62:65]
	v_mfma_f32_16x16x32_bf16 v[58:61], v[160:163], v[184:187], v[58:61]
	v_mfma_f32_16x16x32_bf16 v[42:45], v[160:163], v[192:195], v[42:45]
	v_mfma_f32_16x16x32_bf16 v[46:49], v[152:155], v[192:195], v[46:49]
	v_mfma_f32_16x16x32_bf16 v[30:33], v[152:155], v[200:203], v[30:33]
	v_mfma_f32_16x16x32_bf16 v[26:29], v[160:163], v[200:203], v[26:29]
	s_waitcnt lgkmcnt(0)
	v_mfma_f32_16x16x32_bf16 v[10:13], v[160:163], v[208:211], v[10:13]
	v_mfma_f32_16x16x32_bf16 v[14:17], v[152:155], v[208:211], v[14:17]
	s_setprio 0
	s_setprio 1
	v_mfma_f32_16x16x32_bf16 v[54:57], v[164:167], v[180:183], v[54:57]
	v_mfma_f32_16x16x32_bf16 v[50:53], v[172:175], v[180:183], v[50:53]
	v_mfma_f32_16x16x32_bf16 v[34:37], v[172:175], v[188:191], v[34:37]
	v_mfma_f32_16x16x32_bf16 v[38:41], v[164:167], v[188:191], v[38:41]
	v_mfma_f32_16x16x32_bf16 v[22:25], v[164:167], v[196:199], v[22:25]
	v_mfma_f32_16x16x32_bf16 v[18:21], v[172:175], v[196:199], v[18:21]
	v_mfma_f32_16x16x32_bf16 v[2:5], v[172:175], v[204:207], v[2:5]
	v_mfma_f32_16x16x32_bf16 v[6:9], v[164:167], v[204:207], v[6:9]
	v_mfma_f32_16x16x32_bf16 v[54:57], v[168:171], v[184:187], v[54:57]
	v_mfma_f32_16x16x32_bf16 v[50:53], v[176:179], v[184:187], v[50:53]
	v_mfma_f32_16x16x32_bf16 v[34:37], v[176:179], v[192:195], v[34:37]
	v_mfma_f32_16x16x32_bf16 v[38:41], v[168:171], v[192:195], v[38:41]
	v_mfma_f32_16x16x32_bf16 v[22:25], v[168:171], v[200:203], v[22:25]
	v_mfma_f32_16x16x32_bf16 v[18:21], v[176:179], v[200:203], v[18:21]
	s_setprio 2
	s_barrier
	v_mfma_f32_16x16x32_bf16 v[2:5], v[176:179], v[208:211], v[2:5]
	v_mfma_f32_16x16x32_bf16 v[6:9], v[168:171], v[208:211], v[6:9]
	s_setprio 0
	s_add_i32 s81, s81, 2
	s_add_u32 s77, s77, 0x100
	s_addc_u32 s78, s78, 0
	s_add_u32 s18, s18, 0x100
	s_addc_u32 s19, s19, 0
	s_add_u32 s79, s79, 0x100
	s_addc_u32 s80, s80, 0
	s_cmp_gt_u32 s81, 29
	s_cbranch_scc0 .LBB0_344
	s_and_b64 vcc, exec, s[6:7]
	s_cbranch_vccz .LBB0_347
	s_barrier

.LBB0_472:
	s_ashr_i32 s13, s12, 31
	s_lshl_b64 s[14:15], s[12:13], 15
	s_add_u32 s14, s28, s14
	s_addc_u32 s15, s29, s15
	s_and_b64 s[16:17], s[2:3], exec
	s_cselect_b32 s13, s15, s23
	s_cselect_b32 s76, s14, s22
	s_ashr_i32 s11, s10, 31
	s_lshl_b64 s[16:17], s[10:11], 15
	s_add_u32 s16, s30, s16
	s_addc_u32 s17, s31, s17
	s_and_b64 s[24:25], s[2:3], exec
	s_cselect_b32 s11, s17, s21
	s_cselect_b32 s77, s16, s20
	s_add_u32 s78, s20, 0x80000
	s_addc_u32 s79, s21, 0
	s_add_u32 s20, s22, 0x204000
	s_addc_u32 s21, s23, 0
	s_add_u32 s80, s22, 0x400000
	s_addc_u32 s81, s23, 0
	s_mov_b32 s82, -2
	s_waitcnt vmcnt(25)
	s_waitcnt vmcnt(24)
	s_waitcnt vmcnt(23)
	s_waitcnt vmcnt(22)
	s_waitcnt vmcnt(21)
	s_waitcnt vmcnt(20)
	s_waitcnt vmcnt(15)
	s_waitcnt vmcnt(14)
	s_waitcnt vmcnt(13)
	s_waitcnt vmcnt(12)
	s_waitcnt vmcnt(7)
	s_waitcnt vmcnt(6)
	s_waitcnt vmcnt(5)
	s_waitcnt vmcnt(4)
	s_waitcnt vmcnt(3)
	s_waitcnt vmcnt(2)
	s_waitcnt vmcnt(1)
	s_waitcnt vmcnt(0)
	ds_read_b128 v[134:137], v161
	ds_read_b128 v[138:141], v161 offset:1024
	ds_read_b128 v[142:145], v161 offset:2048
	ds_read_b128 v[146:149], v161 offset:3072
	ds_read_b128 v[150:153], v162
	ds_read_b128 v[166:169], v162 offset:1024
	ds_read_b128 v[170:173], v162 offset:2048
	ds_read_b128 v[174:177], v162 offset:3072
	s_cmpk_eq_i32 s82, 0x52
	s_cselect_b32 s23, s11, s79
	s_cselect_b32 s22, s77, s78
	s_cselect_b32 s25, s13, s81
	s_cselect_b32 s24, s76, s80
	ds_read_b128 v[178:181], v163
	ds_read_b128 v[182:185], v163 offset:1024
	ds_read_b128 v[186:189], v163 offset:2048
	ds_read_b128 v[190:193], v163 offset:3072
	ds_read_b128 v[194:197], v163 offset:4096
	ds_read_b128 v[198:201], v163 offset:5120
	ds_read_b128 v[202:205], v163 offset:6144
	ds_read_b128 v[206:209], v163 offset:7168
	s_add_u32 s86, s20, 0xffffc000
	s_addc_u32 s87, s21, -1
	s_mov_b32 s83, m0
	s_mov_b32 m0, s65
	s_nop 0
	global_load_lds_dwordx4 v1, s[86:87]
	s_mov_b32 m0, s83
	s_nop 0
	s_mov_b32 s83, m0
	s_mov_b32 m0, s67
	s_nop 0
	global_load_lds_dwordx4 v157, s[86:87]
	s_mov_b32 m0, s83
	s_nop 0
	s_mov_b32 s83, m0
	s_mov_b32 m0, s66
	s_nop 0
	global_load_lds_dwordx4 v1, s[20:21]
	s_mov_b32 m0, s83
	s_nop 0
	s_mov_b32 s83, m0
	s_mov_b32 m0, s73
	s_nop 0
	global_load_lds_dwordx4 v157, s[20:21]
	s_mov_b32 m0, s83
	s_waitcnt vmcnt(8)
	s_waitcnt lgkmcnt(0)
	s_barrier
	s_setprio 1
	s_waitcnt lgkmcnt(7)
	v_mfma_f32_16x16x32_bf16 v[126:129], v[134:137], v[178:181], 0
	v_mfma_f32_16x16x32_bf16 v[122:125], v[142:145], v[178:181], 0
	s_waitcnt lgkmcnt(5)
	v_mfma_f32_16x16x32_bf16 v[114:117], v[142:145], v[186:189], 0
	v_mfma_f32_16x16x32_bf16 v[118:121], v[134:137], v[186:189], 0
	s_waitcnt lgkmcnt(3)
	v_mfma_f32_16x16x32_bf16 v[102:105], v[134:137], v[194:197], 0
	v_mfma_f32_16x16x32_bf16 v[94:97], v[142:145], v[194:197], 0
	s_waitcnt lgkmcnt(1)
	v_mfma_f32_16x16x32_bf16 v[78:81], v[142:145], v[202:205], 0
	v_mfma_f32_16x16x32_bf16 v[86:89], v[134:137], v[202:205], 0
	v_mfma_f32_16x16x32_bf16 v[126:129], v[138:141], v[182:185], v[126:129]
	v_mfma_f32_16x16x32_bf16 v[122:125], v[146:149], v[182:185], v[122:125]
	v_mfma_f32_16x16x32_bf16 v[114:117], v[146:149], v[190:193], v[114:117]
	v_mfma_f32_16x16x32_bf16 v[118:121], v[138:141], v[190:193], v[118:121]
	v_mfma_f32_16x16x32_bf16 v[102:105], v[138:141], v[198:201], v[102:105]
	v_mfma_f32_16x16x32_bf16 v[94:97], v[146:149], v[198:201], v[94:97]
	s_waitcnt lgkmcnt(0)
	v_mfma_f32_16x16x32_bf16 v[78:81], v[146:149], v[206:209], v[78:81]
	v_mfma_f32_16x16x32_bf16 v[86:89], v[138:141], v[206:209], v[86:89]
	s_setprio 0
	s_setprio 1
	v_mfma_f32_16x16x32_bf16 v[110:113], v[150:153], v[178:181], 0
	v_mfma_f32_16x16x32_bf16 v[106:109], v[170:173], v[178:181], 0
	v_mfma_f32_16x16x32_bf16 v[90:93], v[170:173], v[186:189], 0
	v_mfma_f32_16x16x32_bf16 v[98:101], v[150:153], v[186:189], 0
	v_mfma_f32_16x16x32_bf16 v[82:85], v[150:153], v[194:197], 0
	v_mfma_f32_16x16x32_bf16 v[74:77], v[170:173], v[194:197], 0
	v_mfma_f32_16x16x32_bf16 v[66:69], v[170:173], v[202:205], 0
	v_mfma_f32_16x16x32_bf16 v[70:73], v[150:153], v[202:205], 0
	v_mfma_f32_16x16x32_bf16 v[110:113], v[166:169], v[182:185], v[110:113]
	v_mfma_f32_16x16x32_bf16 v[106:109], v[174:177], v[182:185], v[106:109]
	v_mfma_f32_16x16x32_bf16 v[90:93], v[174:177], v[190:193], v[90:93]
	v_mfma_f32_16x16x32_bf16 v[98:101], v[166:169], v[190:193], v[98:101]
	v_mfma_f32_16x16x32_bf16 v[82:85], v[166:169], v[198:201], v[82:85]
	v_mfma_f32_16x16x32_bf16 v[74:77], v[174:177], v[198:201], v[74:77]
	s_setprio 2
	s_barrier
	v_mfma_f32_16x16x32_bf16 v[66:69], v[174:177], v[206:209], v[66:69]
	v_mfma_f32_16x16x32_bf16 v[70:73], v[166:169], v[206:209], v[70:73]
	s_setprio 0
	ds_read_b128 v[178:181], v163 offset:16384
	ds_read_b128 v[182:185], v163 offset:17408
	ds_read_b128 v[186:189], v163 offset:18432
	ds_read_b128 v[190:193], v163 offset:19456
	ds_read_b128 v[194:197], v163 offset:20480
	ds_read_b128 v[198:201], v163 offset:21504
	ds_read_b128 v[202:205], v163 offset:22528
	ds_read_b128 v[206:209], v163 offset:23552
	s_mov_b32 s83, m0
	s_mov_b32 m0, s19
	s_nop 0
	global_load_lds_dwordx4 v156, s[22:23]
	s_mov_b32 m0, s83
	s_add_u32 s86, s22, 0x4000
	s_mov_b32 s83, m0
	s_mov_b32 m0, s35
	s_nop 0
	global_load_lds_dwordx4 v158, s[22:23]
	s_mov_b32 m0, s83
	s_addc_u32 s87, s23, 0
	s_mov_b32 s83, m0
	s_mov_b32 m0, s36
	s_nop 0
	global_load_lds_dwordx4 v156, s[86:87]
	s_mov_b32 m0, s83
	s_nop 0
	s_mov_b32 s83, m0
	s_mov_b32 m0, s37
	s_nop 0
	global_load_lds_dwordx4 v158, s[86:87]
	s_mov_b32 m0, s83
	s_waitcnt vmcnt(4)
	s_waitcnt lgkmcnt(0)
	s_barrier
	s_setprio 1
	s_waitcnt lgkmcnt(7)
	v_mfma_f32_16x16x32_bf16 v[62:65], v[134:137], v[178:181], 0
	v_mfma_f32_16x16x32_bf16 v[58:61], v[142:145], v[178:181], 0
	s_waitcnt lgkmcnt(5)
	v_mfma_f32_16x16x32_bf16 v[46:49], v[142:145], v[186:189], 0
	v_mfma_f32_16x16x32_bf16 v[54:57], v[134:137], v[186:189], 0
	s_waitcnt lgkmcnt(3)
	v_mfma_f32_16x16x32_bf16 v[38:41], v[134:137], v[194:197], 0
	v_mfma_f32_16x16x32_bf16 v[30:33], v[142:145], v[194:197], 0
	s_waitcnt lgkmcnt(1)
	v_mfma_f32_16x16x32_bf16 v[14:17], v[142:145], v[202:205], 0
	v_mfma_f32_16x16x32_bf16 v[22:25], v[134:137], v[202:205], 0
	v_mfma_f32_16x16x32_bf16 v[62:65], v[138:141], v[182:185], v[62:65]
	v_mfma_f32_16x16x32_bf16 v[58:61], v[146:149], v[182:185], v[58:61]
	v_mfma_f32_16x16x32_bf16 v[46:49], v[146:149], v[190:193], v[46:49]
	v_mfma_f32_16x16x32_bf16 v[54:57], v[138:141], v[190:193], v[54:57]
	v_mfma_f32_16x16x32_bf16 v[38:41], v[138:141], v[198:201], v[38:41]
	v_mfma_f32_16x16x32_bf16 v[30:33], v[146:149], v[198:201], v[30:33]
	s_waitcnt lgkmcnt(0)
	v_mfma_f32_16x16x32_bf16 v[14:17], v[146:149], v[206:209], v[14:17]
	v_mfma_f32_16x16x32_bf16 v[22:25], v[138:141], v[206:209], v[22:25]
	s_setprio 0
	s_setprio 1
	v_mfma_f32_16x16x32_bf16 v[50:53], v[150:153], v[178:181], 0
	v_mfma_f32_16x16x32_bf16 v[42:45], v[170:173], v[178:181], 0
	v_mfma_f32_16x16x32_bf16 v[26:29], v[170:173], v[186:189], 0
	v_mfma_f32_16x16x32_bf16 v[34:37], v[150:153], v[186:189], 0
	v_mfma_f32_16x16x32_bf16 v[18:21], v[150:153], v[194:197], 0
	v_mfma_f32_16x16x32_bf16 v[10:13], v[170:173], v[194:197], 0
	v_mfma_f32_16x16x32_bf16 v[2:5], v[170:173], v[202:205], 0
	v_mfma_f32_16x16x32_bf16 v[6:9], v[150:153], v[202:205], 0
	v_mfma_f32_16x16x32_bf16 v[50:53], v[166:169], v[182:185], v[50:53]
	v_mfma_f32_16x16x32_bf16 v[42:45], v[174:177], v[182:185], v[42:45]
	v_mfma_f32_16x16x32_bf16 v[26:29], v[174:177], v[190:193], v[26:29]
	v_mfma_f32_16x16x32_bf16 v[34:37], v[166:169], v[190:193], v[34:37]
	v_mfma_f32_16x16x32_bf16 v[18:21], v[166:169], v[198:201], v[18:21]
	v_mfma_f32_16x16x32_bf16 v[10:13], v[174:177], v[198:201], v[10:13]
	s_setprio 2
	s_barrier
	v_mfma_f32_16x16x32_bf16 v[2:5], v[174:177], v[206:209], v[2:5]
	v_mfma_f32_16x16x32_bf16 v[6:9], v[166:169], v[206:209], v[6:9]
	s_setprio 0
	ds_read_b128 v[134:137], v164
	ds_read_b128 v[138:141], v164 offset:1024
	ds_read_b128 v[142:145], v164 offset:2048
	ds_read_b128 v[146:149], v164 offset:3072
	ds_read_b128 v[150:153], v165
	ds_read_b128 v[166:169], v165 offset:1024
	ds_read_b128 v[170:173], v165 offset:2048
	ds_read_b128 v[174:177], v165 offset:3072
	ds_read_b128 v[178:181], v163 offset:32768
	ds_read_b128 v[182:185], v163 offset:33792
	ds_read_b128 v[186:189], v163 offset:34816
	ds_read_b128 v[190:193], v163 offset:35840
	ds_read_b128 v[194:197], v163 offset:36864
	ds_read_b128 v[198:201], v163 offset:37888
	ds_read_b128 v[202:205], v163 offset:38912
	ds_read_b128 v[206:209], v163 offset:39936
	s_mov_b32 s83, m0
	s_mov_b32 m0, s34
	s_nop 0
	global_load_lds_dwordx4 v1, s[24:25]
	s_mov_b32 m0, s83
	s_nop 0
	s_mov_b32 s83, m0
	s_mov_b32 m0, s42
	s_nop 0
	global_load_lds_dwordx4 v157, s[24:25]
	s_mov_b32 m0, s83
	s_add_u32 s24, s24, 0x4000
	s_addc_u32 s25, s25, 0
	s_mov_b32 s83, m0
	s_mov_b32 m0, s43
	s_nop 0
	global_load_lds_dwordx4 v1, s[24:25]
	s_mov_b32 m0, s83
	s_nop 0
	s_mov_b32 s83, m0
	s_mov_b32 m0, s46
	s_nop 0
	global_load_lds_dwordx4 v157, s[24:25]
	s_mov_b32 m0, s83
	s_waitcnt vmcnt(8)
	s_waitcnt lgkmcnt(0)
	s_barrier
	s_setprio 1
	s_waitcnt lgkmcnt(7)
	v_mfma_f32_16x16x32_bf16 v[126:129], v[134:137], v[178:181], v[126:129]
	v_mfma_f32_16x16x32_bf16 v[122:125], v[142:145], v[178:181], v[122:125]
	s_waitcnt lgkmcnt(5)
	v_mfma_f32_16x16x32_bf16 v[114:117], v[142:145], v[186:189], v[114:117]
	v_mfma_f32_16x16x32_bf16 v[118:121], v[134:137], v[186:189], v[118:121]
	s_waitcnt lgkmcnt(3)
	v_mfma_f32_16x16x32_bf16 v[102:105], v[134:137], v[194:197], v[102:105]
	v_mfma_f32_16x16x32_bf16 v[94:97], v[142:145], v[194:197], v[94:97]
	s_waitcnt lgkmcnt(1)
	v_mfma_f32_16x16x32_bf16 v[78:81], v[142:145], v[202:205], v[78:81]
	v_mfma_f32_16x16x32_bf16 v[86:89], v[134:137], v[202:205], v[86:89]
	v_mfma_f32_16x16x32_bf16 v[126:129], v[138:141], v[182:185], v[126:129]
	v_mfma_f32_16x16x32_bf16 v[122:125], v[146:149], v[182:185], v[122:125]
	v_mfma_f32_16x16x32_bf16 v[114:117], v[146:149], v[190:193], v[114:117]
	v_mfma_f32_16x16x32_bf16 v[118:121], v[138:141], v[190:193], v[118:121]
	v_mfma_f32_16x16x32_bf16 v[102:105], v[138:141], v[198:201], v[102:105]
	v_mfma_f32_16x16x32_bf16 v[94:97], v[146:149], v[198:201], v[94:97]
	s_waitcnt lgkmcnt(0)
	v_mfma_f32_16x16x32_bf16 v[78:81], v[146:149], v[206:209], v[78:81]
	v_mfma_f32_16x16x32_bf16 v[86:89], v[138:141], v[206:209], v[86:89]
	s_setprio 0
	s_setprio 1
	v_mfma_f32_16x16x32_bf16 v[110:113], v[150:153], v[178:181], v[110:113]
	v_mfma_f32_16x16x32_bf16 v[106:109], v[170:173], v[178:181], v[106:109]
	v_mfma_f32_16x16x32_bf16 v[90:93], v[170:173], v[186:189], v[90:93]
	v_mfma_f32_16x16x32_bf16 v[98:101], v[150:153], v[186:189], v[98:101]
	v_mfma_f32_16x16x32_bf16 v[82:85], v[150:153], v[194:197], v[82:85]
	v_mfma_f32_16x16x32_bf16 v[74:77], v[170:173], v[194:197], v[74:77]
	v_mfma_f32_16x16x32_bf16 v[66:69], v[170:173], v[202:205], v[66:69]
	v_mfma_f32_16x16x32_bf16 v[70:73], v[150:153], v[202:205], v[70:73]
	v_mfma_f32_16x16x32_bf16 v[110:113], v[166:169], v[182:185], v[110:113]
	v_mfma_f32_16x16x32_bf16 v[106:109], v[174:177], v[182:185], v[106:109]
	v_mfma_f32_16x16x32_bf16 v[90:93], v[174:177], v[190:193], v[90:93]
	v_mfma_f32_16x16x32_bf16 v[98:101], v[166:169], v[190:193], v[98:101]
	v_mfma_f32_16x16x32_bf16 v[82:85], v[166:169], v[198:201], v[82:85]
	v_mfma_f32_16x16x32_bf16 v[74:77], v[174:177], v[198:201], v[74:77]
	s_setprio 2
	s_barrier
	v_mfma_f32_16x16x32_bf16 v[66:69], v[174:177], v[206:209], v[66:69]
	v_mfma_f32_16x16x32_bf16 v[70:73], v[166:169], v[206:209], v[70:73]
	s_setprio 0
	ds_read_b128 v[178:181], v163 offset:49152
	ds_read_b128 v[182:185], v163 offset:50176
	ds_read_b128 v[186:189], v163 offset:51200
	ds_read_b128 v[190:193], v163 offset:52224
	ds_read_b128 v[194:197], v163 offset:53248
	ds_read_b128 v[198:201], v163 offset:54272
	ds_read_b128 v[202:205], v163 offset:55296
	ds_read_b128 v[206:209], v163 offset:56320
	s_add_u32 s24, s22, 0x40000
	s_addc_u32 s25, s23, 0
	s_mov_b32 s83, m0
	s_mov_b32 m0, s47
	s_nop 0
	global_load_lds_dwordx4 v156, s[24:25]
	s_mov_b32 m0, s83
	s_add_u32 s22, s22, 0x44000
	s_mov_b32 s83, m0
	s_mov_b32 m0, s48
	s_nop 0
	global_load_lds_dwordx4 v158, s[24:25]
	s_mov_b32 m0, s83
	s_addc_u32 s23, s23, 0
	s_mov_b32 s24, m0
	s_mov_b32 m0, s49
	s_nop 0
	global_load_lds_dwordx4 v156, s[22:23]
	s_mov_b32 m0, s24
	s_nop 0
	s_mov_b32 s24, m0
	s_mov_b32 m0, s56
	s_nop 0
	global_load_lds_dwordx4 v158, s[22:23]
	s_mov_b32 m0, s24
	s_waitcnt vmcnt(4)
	s_waitcnt lgkmcnt(0)
	s_barrier
	s_setprio 1
	s_waitcnt lgkmcnt(7)
	v_mfma_f32_16x16x32_bf16 v[62:65], v[134:137], v[178:181], v[62:65]
	v_mfma_f32_16x16x32_bf16 v[58:61], v[142:145], v[178:181], v[58:61]
	s_waitcnt lgkmcnt(5)
	v_mfma_f32_16x16x32_bf16 v[46:49], v[142:145], v[186:189], v[46:49]
	v_mfma_f32_16x16x32_bf16 v[54:57], v[134:137], v[186:189], v[54:57]
	s_waitcnt lgkmcnt(3)
	v_mfma_f32_16x16x32_bf16 v[38:41], v[134:137], v[194:197], v[38:41]
	v_mfma_f32_16x16x32_bf16 v[30:33], v[142:145], v[194:197], v[30:33]
	s_waitcnt lgkmcnt(1)
	v_mfma_f32_16x16x32_bf16 v[14:17], v[142:145], v[202:205], v[14:17]
	v_mfma_f32_16x16x32_bf16 v[22:25], v[134:137], v[202:205], v[22:25]
	v_mfma_f32_16x16x32_bf16 v[62:65], v[138:141], v[182:185], v[62:65]
	v_mfma_f32_16x16x32_bf16 v[58:61], v[146:149], v[182:185], v[58:61]
	v_mfma_f32_16x16x32_bf16 v[46:49], v[146:149], v[190:193], v[46:49]
	v_mfma_f32_16x16x32_bf16 v[54:57], v[138:141], v[190:193], v[54:57]
	v_mfma_f32_16x16x32_bf16 v[38:41], v[138:141], v[198:201], v[38:41]
	v_mfma_f32_16x16x32_bf16 v[30:33], v[146:149], v[198:201], v[30:33]
	s_waitcnt lgkmcnt(0)
	v_mfma_f32_16x16x32_bf16 v[14:17], v[146:149], v[206:209], v[14:17]
	v_mfma_f32_16x16x32_bf16 v[22:25], v[138:141], v[206:209], v[22:25]
	s_setprio 0
	s_setprio 1
	v_mfma_f32_16x16x32_bf16 v[50:53], v[150:153], v[178:181], v[50:53]
	v_mfma_f32_16x16x32_bf16 v[42:45], v[170:173], v[178:181], v[42:45]
	v_mfma_f32_16x16x32_bf16 v[26:29], v[170:173], v[186:189], v[26:29]
	v_mfma_f32_16x16x32_bf16 v[34:37], v[150:153], v[186:189], v[34:37]
	v_mfma_f32_16x16x32_bf16 v[18:21], v[150:153], v[194:197], v[18:21]
	v_mfma_f32_16x16x32_bf16 v[10:13], v[170:173], v[194:197], v[10:13]
	v_mfma_f32_16x16x32_bf16 v[2:5], v[170:173], v[202:205], v[2:5]
	v_mfma_f32_16x16x32_bf16 v[6:9], v[150:153], v[202:205], v[6:9]
	v_mfma_f32_16x16x32_bf16 v[50:53], v[166:169], v[182:185], v[50:53]
	v_mfma_f32_16x16x32_bf16 v[42:45], v[174:177], v[182:185], v[42:45]
	v_mfma_f32_16x16x32_bf16 v[26:29], v[174:177], v[190:193], v[26:29]
	v_mfma_f32_16x16x32_bf16 v[34:37], v[166:169], v[190:193], v[34:37]
	v_mfma_f32_16x16x32_bf16 v[18:21], v[166:169], v[198:201], v[18:21]
	v_mfma_f32_16x16x32_bf16 v[10:13], v[174:177], v[198:201], v[10:13]
	s_setprio 2
	s_barrier
	v_mfma_f32_16x16x32_bf16 v[2:5], v[174:177], v[206:209], v[2:5]
	v_mfma_f32_16x16x32_bf16 v[6:9], v[166:169], v[206:209], v[6:9]
	s_setprio 0
	s_add_i32 s82, s82, 2
	s_add_u32 s78, s78, 0x80000
	s_addc_u32 s79, s79, 0
	s_add_u32 s20, s20, 0x400000
	s_addc_u32 s21, s21, 0
	s_add_u32 s80, s80, 0x400000
	s_addc_u32 s81, s81, 0
	s_cmpk_gt_u32 s82, 0x53
	.p2align 6
.LBB0_473:
	ds_read_b128 v[134:137], v161
	ds_read_b128 v[138:141], v161 offset:1024
	ds_read_b128 v[142:145], v161 offset:2048
	ds_read_b128 v[146:149], v161 offset:3072
	ds_read_b128 v[150:153], v162
	ds_read_b128 v[166:169], v162 offset:1024
	ds_read_b128 v[170:173], v162 offset:2048
	ds_read_b128 v[174:177], v162 offset:3072
	s_cmpk_eq_i32 s82, 0x52
	s_cselect_b32 s23, s11, s79
	s_cselect_b32 s22, s77, s78
	s_cselect_b32 s25, s13, s81
	s_cselect_b32 s24, s76, s80
	ds_read_b128 v[178:181], v163
	ds_read_b128 v[182:185], v163 offset:1024
	ds_read_b128 v[186:189], v163 offset:2048
	ds_read_b128 v[190:193], v163 offset:3072
	ds_read_b128 v[194:197], v163 offset:4096
	ds_read_b128 v[198:201], v163 offset:5120
	ds_read_b128 v[202:205], v163 offset:6144
	ds_read_b128 v[206:209], v163 offset:7168
	s_add_u32 s86, s20, 0xffffc000
	s_addc_u32 s87, s21, -1
	s_mov_b32 s83, m0
	s_mov_b32 m0, s65
	s_nop 0
	global_load_lds_dwordx4 v1, s[86:87]
	s_mov_b32 m0, s83
	s_nop 0
	s_mov_b32 s83, m0
	s_mov_b32 m0, s67
	s_nop 0
	global_load_lds_dwordx4 v157, s[86:87]
	s_mov_b32 m0, s83
	s_nop 0
	s_mov_b32 s83, m0
	s_mov_b32 m0, s66
	s_nop 0
	global_load_lds_dwordx4 v1, s[20:21]
	s_mov_b32 m0, s83
	s_nop 0
	s_mov_b32 s83, m0
	s_mov_b32 m0, s73
	s_nop 0
	global_load_lds_dwordx4 v157, s[20:21]
	s_mov_b32 m0, s83
	s_waitcnt vmcnt(8)
	s_waitcnt lgkmcnt(0)
	s_barrier
	s_setprio 1
	s_waitcnt lgkmcnt(7)
	v_mfma_f32_16x16x32_bf16 v[126:129], v[134:137], v[178:181], v[126:129]
	v_mfma_f32_16x16x32_bf16 v[122:125], v[142:145], v[178:181], v[122:125]
	s_waitcnt lgkmcnt(5)
	v_mfma_f32_16x16x32_bf16 v[114:117], v[142:145], v[186:189], v[114:117]
	v_mfma_f32_16x16x32_bf16 v[118:121], v[134:137], v[186:189], v[118:121]
	s_waitcnt lgkmcnt(3)
	v_mfma_f32_16x16x32_bf16 v[102:105], v[134:137], v[194:197], v[102:105]
	v_mfma_f32_16x16x32_bf16 v[94:97], v[142:145], v[194:197], v[94:97]
	s_waitcnt lgkmcnt(1)
	v_mfma_f32_16x16x32_bf16 v[78:81], v[142:145], v[202:205], v[78:81]
	v_mfma_f32_16x16x32_bf16 v[86:89], v[134:137], v[202:205], v[86:89]
	v_mfma_f32_16x16x32_bf16 v[126:129], v[138:141], v[182:185], v[126:129]
	v_mfma_f32_16x16x32_bf16 v[122:125], v[146:149], v[182:185], v[122:125]
	v_mfma_f32_16x16x32_bf16 v[114:117], v[146:149], v[190:193], v[114:117]
	v_mfma_f32_16x16x32_bf16 v[118:121], v[138:141], v[190:193], v[118:121]
	v_mfma_f32_16x16x32_bf16 v[102:105], v[138:141], v[198:201], v[102:105]
	v_mfma_f32_16x16x32_bf16 v[94:97], v[146:149], v[198:201], v[94:97]
	s_waitcnt lgkmcnt(0)
	v_mfma_f32_16x16x32_bf16 v[78:81], v[146:149], v[206:209], v[78:81]
	v_mfma_f32_16x16x32_bf16 v[86:89], v[138:141], v[206:209], v[86:89]
	s_setprio 0
	s_setprio 1
	v_mfma_f32_16x16x32_bf16 v[110:113], v[150:153], v[178:181], v[110:113]
	v_mfma_f32_16x16x32_bf16 v[106:109], v[170:173], v[178:181], v[106:109]
	v_mfma_f32_16x16x32_bf16 v[90:93], v[170:173], v[186:189], v[90:93]
	v_mfma_f32_16x16x32_bf16 v[98:101], v[150:153], v[186:189], v[98:101]
	v_mfma_f32_16x16x32_bf16 v[82:85], v[150:153], v[194:197], v[82:85]
	v_mfma_f32_16x16x32_bf16 v[74:77], v[170:173], v[194:197], v[74:77]
	v_mfma_f32_16x16x32_bf16 v[66:69], v[170:173], v[202:205], v[66:69]
	v_mfma_f32_16x16x32_bf16 v[70:73], v[150:153], v[202:205], v[70:73]
	v_mfma_f32_16x16x32_bf16 v[110:113], v[166:169], v[182:185], v[110:113]
	v_mfma_f32_16x16x32_bf16 v[106:109], v[174:177], v[182:185], v[106:109]
	v_mfma_f32_16x16x32_bf16 v[90:93], v[174:177], v[190:193], v[90:93]
	v_mfma_f32_16x16x32_bf16 v[98:101], v[166:169], v[190:193], v[98:101]
	v_mfma_f32_16x16x32_bf16 v[82:85], v[166:169], v[198:201], v[82:85]
	v_mfma_f32_16x16x32_bf16 v[74:77], v[174:177], v[198:201], v[74:77]
	s_setprio 2
	s_barrier
	v_mfma_f32_16x16x32_bf16 v[66:69], v[174:177], v[206:209], v[66:69]
	v_mfma_f32_16x16x32_bf16 v[70:73], v[166:169], v[206:209], v[70:73]
	s_setprio 0
	ds_read_b128 v[178:181], v163 offset:16384
	ds_read_b128 v[182:185], v163 offset:17408
	ds_read_b128 v[186:189], v163 offset:18432
	ds_read_b128 v[190:193], v163 offset:19456
	ds_read_b128 v[194:197], v163 offset:20480
	ds_read_b128 v[198:201], v163 offset:21504
	ds_read_b128 v[202:205], v163 offset:22528
	ds_read_b128 v[206:209], v163 offset:23552
	s_mov_b32 s83, m0
	s_mov_b32 m0, s19
	s_nop 0
	global_load_lds_dwordx4 v156, s[22:23]
	s_mov_b32 m0, s83
	s_add_u32 s86, s22, 0x4000
	s_mov_b32 s83, m0
	s_mov_b32 m0, s35
	s_nop 0
	global_load_lds_dwordx4 v158, s[22:23]
	s_mov_b32 m0, s83
	s_addc_u32 s87, s23, 0
	s_mov_b32 s83, m0
	s_mov_b32 m0, s36
	s_nop 0
	global_load_lds_dwordx4 v156, s[86:87]
	s_mov_b32 m0, s83
	s_nop 0
	s_mov_b32 s83, m0
	s_mov_b32 m0, s37
	s_nop 0
	global_load_lds_dwordx4 v158, s[86:87]
	s_mov_b32 m0, s83
	s_waitcnt vmcnt(4)
	s_waitcnt lgkmcnt(0)
	s_barrier
	s_setprio 1
	s_waitcnt lgkmcnt(7)
	v_mfma_f32_16x16x32_bf16 v[62:65], v[134:137], v[178:181], v[62:65]
	v_mfma_f32_16x16x32_bf16 v[58:61], v[142:145], v[178:181], v[58:61]
	s_waitcnt lgkmcnt(5)
	v_mfma_f32_16x16x32_bf16 v[46:49], v[142:145], v[186:189], v[46:49]
	v_mfma_f32_16x16x32_bf16 v[54:57], v[134:137], v[186:189], v[54:57]
	s_waitcnt lgkmcnt(3)
	v_mfma_f32_16x16x32_bf16 v[38:41], v[134:137], v[194:197], v[38:41]
	v_mfma_f32_16x16x32_bf16 v[30:33], v[142:145], v[194:197], v[30:33]
	s_waitcnt lgkmcnt(1)
	v_mfma_f32_16x16x32_bf16 v[14:17], v[142:145], v[202:205], v[14:17]
	v_mfma_f32_16x16x32_bf16 v[22:25], v[134:137], v[202:205], v[22:25]
	v_mfma_f32_16x16x32_bf16 v[62:65], v[138:141], v[182:185], v[62:65]
	v_mfma_f32_16x16x32_bf16 v[58:61], v[146:149], v[182:185], v[58:61]
	v_mfma_f32_16x16x32_bf16 v[46:49], v[146:149], v[190:193], v[46:49]
	v_mfma_f32_16x16x32_bf16 v[54:57], v[138:141], v[190:193], v[54:57]
	v_mfma_f32_16x16x32_bf16 v[38:41], v[138:141], v[198:201], v[38:41]
	v_mfma_f32_16x16x32_bf16 v[30:33], v[146:149], v[198:201], v[30:33]
	s_waitcnt lgkmcnt(0)
	v_mfma_f32_16x16x32_bf16 v[14:17], v[146:149], v[206:209], v[14:17]
	v_mfma_f32_16x16x32_bf16 v[22:25], v[138:141], v[206:209], v[22:25]
	s_setprio 0
	s_setprio 1
	v_mfma_f32_16x16x32_bf16 v[50:53], v[150:153], v[178:181], v[50:53]
	v_mfma_f32_16x16x32_bf16 v[42:45], v[170:173], v[178:181], v[42:45]
	v_mfma_f32_16x16x32_bf16 v[26:29], v[170:173], v[186:189], v[26:29]
	v_mfma_f32_16x16x32_bf16 v[34:37], v[150:153], v[186:189], v[34:37]
	v_mfma_f32_16x16x32_bf16 v[18:21], v[150:153], v[194:197], v[18:21]
	v_mfma_f32_16x16x32_bf16 v[10:13], v[170:173], v[194:197], v[10:13]
	v_mfma_f32_16x16x32_bf16 v[2:5], v[170:173], v[202:205], v[2:5]
	v_mfma_f32_16x16x32_bf16 v[6:9], v[150:153], v[202:205], v[6:9]
	v_mfma_f32_16x16x32_bf16 v[50:53], v[166:169], v[182:185], v[50:53]
	v_mfma_f32_16x16x32_bf16 v[42:45], v[174:177], v[182:185], v[42:45]
	v_mfma_f32_16x16x32_bf16 v[26:29], v[174:177], v[190:193], v[26:29]
	v_mfma_f32_16x16x32_bf16 v[34:37], v[166:169], v[190:193], v[34:37]
	v_mfma_f32_16x16x32_bf16 v[18:21], v[166:169], v[198:201], v[18:21]
	v_mfma_f32_16x16x32_bf16 v[10:13], v[174:177], v[198:201], v[10:13]
	s_setprio 2
	s_barrier
	v_mfma_f32_16x16x32_bf16 v[2:5], v[174:177], v[206:209], v[2:5]
	v_mfma_f32_16x16x32_bf16 v[6:9], v[166:169], v[206:209], v[6:9]
	s_setprio 0
	ds_read_b128 v[134:137], v164
	ds_read_b128 v[138:141], v164 offset:1024
	ds_read_b128 v[142:145], v164 offset:2048
	ds_read_b128 v[146:149], v164 offset:3072
	ds_read_b128 v[150:153], v165
	ds_read_b128 v[166:169], v165 offset:1024
	ds_read_b128 v[170:173], v165 offset:2048
	ds_read_b128 v[174:177], v165 offset:3072
	ds_read_b128 v[178:181], v163 offset:32768
	ds_read_b128 v[182:185], v163 offset:33792
	ds_read_b128 v[186:189], v163 offset:34816
	ds_read_b128 v[190:193], v163 offset:35840
	ds_read_b128 v[194:197], v163 offset:36864
	ds_read_b128 v[198:201], v163 offset:37888
	ds_read_b128 v[202:205], v163 offset:38912
	ds_read_b128 v[206:209], v163 offset:39936
	s_mov_b32 s83, m0
	s_mov_b32 m0, s34
	s_nop 0
	global_load_lds_dwordx4 v1, s[24:25]
	s_mov_b32 m0, s83
	s_nop 0
	s_mov_b32 s83, m0
	s_mov_b32 m0, s42
	s_nop 0
	global_load_lds_dwordx4 v157, s[24:25]
	s_mov_b32 m0, s83
	s_add_u32 s24, s24, 0x4000
	s_addc_u32 s25, s25, 0
	s_mov_b32 s83, m0
	s_mov_b32 m0, s43
	s_nop 0
	global_load_lds_dwordx4 v1, s[24:25]
	s_mov_b32 m0, s83
	s_nop 0
	s_mov_b32 s83, m0
	s_mov_b32 m0, s46
	s_nop 0
	global_load_lds_dwordx4 v157, s[24:25]
	s_mov_b32 m0, s83
	s_waitcnt vmcnt(8)
	s_waitcnt lgkmcnt(0)
	s_barrier
	s_setprio 1
	s_waitcnt lgkmcnt(7)
	v_mfma_f32_16x16x32_bf16 v[126:129], v[134:137], v[178:181], v[126:129]
	v_mfma_f32_16x16x32_bf16 v[122:125], v[142:145], v[178:181], v[122:125]
	s_waitcnt lgkmcnt(5)
	v_mfma_f32_16x16x32_bf16 v[114:117], v[142:145], v[186:189], v[114:117]
	v_mfma_f32_16x16x32_bf16 v[118:121], v[134:137], v[186:189], v[118:121]
	s_waitcnt lgkmcnt(3)
	v_mfma_f32_16x16x32_bf16 v[102:105], v[134:137], v[194:197], v[102:105]
	v_mfma_f32_16x16x32_bf16 v[94:97], v[142:145], v[194:197], v[94:97]
	s_waitcnt lgkmcnt(1)
	v_mfma_f32_16x16x32_bf16 v[78:81], v[142:145], v[202:205], v[78:81]
	v_mfma_f32_16x16x32_bf16 v[86:89], v[134:137], v[202:205], v[86:89]
	v_mfma_f32_16x16x32_bf16 v[126:129], v[138:141], v[182:185], v[126:129]
	v_mfma_f32_16x16x32_bf16 v[122:125], v[146:149], v[182:185], v[122:125]
	v_mfma_f32_16x16x32_bf16 v[114:117], v[146:149], v[190:193], v[114:117]
	v_mfma_f32_16x16x32_bf16 v[118:121], v[138:141], v[190:193], v[118:121]
	v_mfma_f32_16x16x32_bf16 v[102:105], v[138:141], v[198:201], v[102:105]
	v_mfma_f32_16x16x32_bf16 v[94:97], v[146:149], v[198:201], v[94:97]
	s_waitcnt lgkmcnt(0)
	v_mfma_f32_16x16x32_bf16 v[78:81], v[146:149], v[206:209], v[78:81]
	v_mfma_f32_16x16x32_bf16 v[86:89], v[138:141], v[206:209], v[86:89]
	s_setprio 0
	s_setprio 1
	v_mfma_f32_16x16x32_bf16 v[110:113], v[150:153], v[178:181], v[110:113]
	v_mfma_f32_16x16x32_bf16 v[106:109], v[170:173], v[178:181], v[106:109]
	v_mfma_f32_16x16x32_bf16 v[90:93], v[170:173], v[186:189], v[90:93]
	v_mfma_f32_16x16x32_bf16 v[98:101], v[150:153], v[186:189], v[98:101]
	v_mfma_f32_16x16x32_bf16 v[82:85], v[150:153], v[194:197], v[82:85]
	v_mfma_f32_16x16x32_bf16 v[74:77], v[170:173], v[194:197], v[74:77]
	v_mfma_f32_16x16x32_bf16 v[66:69], v[170:173], v[202:205], v[66:69]
	v_mfma_f32_16x16x32_bf16 v[70:73], v[150:153], v[202:205], v[70:73]
	v_mfma_f32_16x16x32_bf16 v[110:113], v[166:169], v[182:185], v[110:113]
	v_mfma_f32_16x16x32_bf16 v[106:109], v[174:177], v[182:185], v[106:109]
	v_mfma_f32_16x16x32_bf16 v[90:93], v[174:177], v[190:193], v[90:93]
	v_mfma_f32_16x16x32_bf16 v[98:101], v[166:169], v[190:193], v[98:101]
	v_mfma_f32_16x16x32_bf16 v[82:85], v[166:169], v[198:201], v[82:85]
	v_mfma_f32_16x16x32_bf16 v[74:77], v[174:177], v[198:201], v[74:77]
	s_setprio 2
	s_barrier
	v_mfma_f32_16x16x32_bf16 v[66:69], v[174:177], v[206:209], v[66:69]
	v_mfma_f32_16x16x32_bf16 v[70:73], v[166:169], v[206:209], v[70:73]
	s_setprio 0
	ds_read_b128 v[178:181], v163 offset:49152
	ds_read_b128 v[182:185], v163 offset:50176
	ds_read_b128 v[186:189], v163 offset:51200
	ds_read_b128 v[190:193], v163 offset:52224
	ds_read_b128 v[194:197], v163 offset:53248
	ds_read_b128 v[198:201], v163 offset:54272
	ds_read_b128 v[202:205], v163 offset:55296
	ds_read_b128 v[206:209], v163 offset:56320
	s_add_u32 s24, s22, 0x40000
	s_addc_u32 s25, s23, 0
	s_mov_b32 s83, m0
	s_mov_b32 m0, s47
	s_nop 0
	global_load_lds_dwordx4 v156, s[24:25]
	s_mov_b32 m0, s83
	s_add_u32 s22, s22, 0x44000
	s_mov_b32 s83, m0
	s_mov_b32 m0, s48
	s_nop 0
	global_load_lds_dwordx4 v158, s[24:25]
	s_mov_b32 m0, s83
	s_addc_u32 s23, s23, 0
	s_mov_b32 s24, m0
	s_mov_b32 m0, s49
	s_nop 0
	global_load_lds_dwordx4 v156, s[22:23]
	s_mov_b32 m0, s24
	s_nop 0
	s_mov_b32 s24, m0
	s_mov_b32 m0, s56
	s_nop 0
	global_load_lds_dwordx4 v158, s[22:23]
	s_mov_b32 m0, s24
	s_waitcnt vmcnt(4)
	s_waitcnt lgkmcnt(0)
	s_barrier
	s_setprio 1
	s_waitcnt lgkmcnt(7)
	v_mfma_f32_16x16x32_bf16 v[62:65], v[134:137], v[178:181], v[62:65]
	v_mfma_f32_16x16x32_bf16 v[58:61], v[142:145], v[178:181], v[58:61]
	s_waitcnt lgkmcnt(5)
	v_mfma_f32_16x16x32_bf16 v[46:49], v[142:145], v[186:189], v[46:49]
	v_mfma_f32_16x16x32_bf16 v[54:57], v[134:137], v[186:189], v[54:57]
	s_waitcnt lgkmcnt(3)
	v_mfma_f32_16x16x32_bf16 v[38:41], v[134:137], v[194:197], v[38:41]
	v_mfma_f32_16x16x32_bf16 v[30:33], v[142:145], v[194:197], v[30:33]
	s_waitcnt lgkmcnt(1)
	v_mfma_f32_16x16x32_bf16 v[14:17], v[142:145], v[202:205], v[14:17]
	v_mfma_f32_16x16x32_bf16 v[22:25], v[134:137], v[202:205], v[22:25]
	v_mfma_f32_16x16x32_bf16 v[62:65], v[138:141], v[182:185], v[62:65]
	v_mfma_f32_16x16x32_bf16 v[58:61], v[146:149], v[182:185], v[58:61]
	v_mfma_f32_16x16x32_bf16 v[46:49], v[146:149], v[190:193], v[46:49]
	v_mfma_f32_16x16x32_bf16 v[54:57], v[138:141], v[190:193], v[54:57]
	v_mfma_f32_16x16x32_bf16 v[38:41], v[138:141], v[198:201], v[38:41]
	v_mfma_f32_16x16x32_bf16 v[30:33], v[146:149], v[198:201], v[30:33]
	s_waitcnt lgkmcnt(0)
	v_mfma_f32_16x16x32_bf16 v[14:17], v[146:149], v[206:209], v[14:17]
	v_mfma_f32_16x16x32_bf16 v[22:25], v[138:141], v[206:209], v[22:25]
	s_setprio 0
	s_setprio 1
	v_mfma_f32_16x16x32_bf16 v[50:53], v[150:153], v[178:181], v[50:53]
	v_mfma_f32_16x16x32_bf16 v[42:45], v[170:173], v[178:181], v[42:45]
	v_mfma_f32_16x16x32_bf16 v[26:29], v[170:173], v[186:189], v[26:29]
	v_mfma_f32_16x16x32_bf16 v[34:37], v[150:153], v[186:189], v[34:37]
	v_mfma_f32_16x16x32_bf16 v[18:21], v[150:153], v[194:197], v[18:21]
	v_mfma_f32_16x16x32_bf16 v[10:13], v[170:173], v[194:197], v[10:13]
	v_mfma_f32_16x16x32_bf16 v[2:5], v[170:173], v[202:205], v[2:5]
	v_mfma_f32_16x16x32_bf16 v[6:9], v[150:153], v[202:205], v[6:9]
	v_mfma_f32_16x16x32_bf16 v[50:53], v[166:169], v[182:185], v[50:53]
	v_mfma_f32_16x16x32_bf16 v[42:45], v[174:177], v[182:185], v[42:45]
	v_mfma_f32_16x16x32_bf16 v[26:29], v[174:177], v[190:193], v[26:29]
	v_mfma_f32_16x16x32_bf16 v[34:37], v[166:169], v[190:193], v[34:37]
	v_mfma_f32_16x16x32_bf16 v[18:21], v[166:169], v[198:201], v[18:21]
	v_mfma_f32_16x16x32_bf16 v[10:13], v[174:177], v[198:201], v[10:13]
	s_setprio 2
	s_barrier
	v_mfma_f32_16x16x32_bf16 v[2:5], v[174:177], v[206:209], v[2:5]
	v_mfma_f32_16x16x32_bf16 v[6:9], v[166:169], v[206:209], v[6:9]
	s_setprio 0
	s_add_i32 s82, s82, 2
	s_add_u32 s78, s78, 0x80000
	s_addc_u32 s79, s79, 0
	s_add_u32 s20, s20, 0x400000
	s_addc_u32 s21, s21, 0
	s_add_u32 s80, s80, 0x400000
	s_addc_u32 s81, s81, 0
	s_cmpk_gt_u32 s82, 0x53
	s_cbranch_scc0 .LBB0_473
	s_and_b64 vcc, exec, s[8:9]
	s_cbranch_vccz .LBB0_476
	s_barrier

.LBB0_653:
	s_ashr_i32 s23, s22, 31
	s_lshl_b64 s[24:25], s[22:23], 20
	s_add_u32 s24, s35, s24
	s_addc_u32 s25, s36, s25
	s_and_b64 s[26:27], s[2:3], exec
	s_cselect_b32 s7, s25, s11
	s_cselect_b32 s9, s24, s10
	s_ashr_i32 s21, s20, 31
	s_lshl_b64 s[26:27], s[20:21], 20
	s_add_u32 s26, s37, s26
	s_addc_u32 s27, s40, s27
	s_and_b64 s[28:29], s[2:3], exec
	s_cselect_b32 s21, s27, s5
	s_cselect_b32 s23, s26, s4
	s_add_u32 s30, s4, 0x100
	s_addc_u32 s31, s5, 0
	s_add_u32 s4, s10, 0x80080
	s_addc_u32 s5, s11, 0
	s_add_u32 s33, s10, 0x100
	s_addc_u32 s73, s11, 0
	s_mov_b32 s74, -2
	s_waitcnt vmcnt(25)
	s_waitcnt vmcnt(24)
	s_waitcnt vmcnt(15)
	s_waitcnt vmcnt(14)
	s_waitcnt vmcnt(13)
	s_waitcnt vmcnt(12)
	s_waitcnt vmcnt(11)
	s_waitcnt vmcnt(10)
	s_waitcnt vmcnt(9)
	s_waitcnt vmcnt(8)
	s_waitcnt vmcnt(7)
	s_waitcnt vmcnt(6)
	s_waitcnt vmcnt(5)
	s_waitcnt vmcnt(4)
	s_waitcnt vmcnt(3)
	s_waitcnt vmcnt(2)
	s_waitcnt vmcnt(1)
	s_waitcnt vmcnt(0)
	ds_read_b128 v[130:133], v161
	ds_read_b128 v[138:141], v161 offset:1024
	ds_read_b128 v[142:145], v161 offset:2048
	ds_read_b128 v[146:149], v161 offset:3072
	ds_read_b128 v[150:153], v162
	ds_read_b128 v[168:171], v162 offset:1024
	ds_read_b128 v[172:175], v162 offset:2048
	ds_read_b128 v[176:179], v162 offset:3072
	s_cmp_eq_u32 s74, 28
	s_cselect_b32 s11, s21, s31
	s_cselect_b32 s10, s23, s30
	s_cselect_b32 s29, s7, s73
	s_cselect_b32 s28, s9, s33
	ds_read_b128 v[180:183], v163
	ds_read_b128 v[184:187], v163 offset:1024
	ds_read_b128 v[188:191], v163 offset:2048
	ds_read_b128 v[192:195], v163 offset:3072
	ds_read_b128 v[196:199], v163 offset:4096
	ds_read_b128 v[200:203], v163 offset:5120
	ds_read_b128 v[204:207], v163 offset:6144
	ds_read_b128 v[208:211], v163 offset:7168
	s_add_u32 s76, s4, 0xfff80000
	s_addc_u32 s77, s5, -1
	s_mov_b32 s75, m0
	s_mov_b32 m0, s80
	s_nop 0
	global_load_lds_dwordx4 v1, s[76:77]
	s_mov_b32 m0, s75
	s_nop 0
	s_mov_b32 s75, m0
	s_mov_b32 m0, s82
	s_nop 0
	global_load_lds_dwordx4 v157, s[76:77]
	s_mov_b32 m0, s75
	s_nop 0
	s_mov_b32 s75, m0
	s_mov_b32 m0, s81
	s_nop 0
	global_load_lds_dwordx4 v1, s[4:5]
	s_mov_b32 m0, s75
	s_nop 0
	s_mov_b32 s75, m0
	s_mov_b32 m0, s83
	s_nop 0
	global_load_lds_dwordx4 v157, s[4:5]
	s_mov_b32 m0, s75
	s_waitcnt vmcnt(8)
	s_waitcnt lgkmcnt(0)
	s_barrier
	s_setprio 1
	s_waitcnt lgkmcnt(7)
	v_mfma_f32_16x16x32_bf16 v[126:129], v[130:133], v[180:183], 0
	v_mfma_f32_16x16x32_bf16 v[122:125], v[142:145], v[180:183], 0
	s_waitcnt lgkmcnt(5)
	v_mfma_f32_16x16x32_bf16 v[106:109], v[142:145], v[188:191], 0
	v_mfma_f32_16x16x32_bf16 v[110:113], v[130:133], v[188:191], 0
	s_waitcnt lgkmcnt(3)
	v_mfma_f32_16x16x32_bf16 v[94:97], v[130:133], v[196:199], 0
	v_mfma_f32_16x16x32_bf16 v[90:93], v[142:145], v[196:199], 0
	s_waitcnt lgkmcnt(1)
	v_mfma_f32_16x16x32_bf16 v[74:77], v[142:145], v[204:207], 0
	v_mfma_f32_16x16x32_bf16 v[78:81], v[130:133], v[204:207], 0
	v_mfma_f32_16x16x32_bf16 v[126:129], v[138:141], v[184:187], v[126:129]
	v_mfma_f32_16x16x32_bf16 v[122:125], v[146:149], v[184:187], v[122:125]
	v_mfma_f32_16x16x32_bf16 v[106:109], v[146:149], v[192:195], v[106:109]
	v_mfma_f32_16x16x32_bf16 v[110:113], v[138:141], v[192:195], v[110:113]
	v_mfma_f32_16x16x32_bf16 v[94:97], v[138:141], v[200:203], v[94:97]
	v_mfma_f32_16x16x32_bf16 v[90:93], v[146:149], v[200:203], v[90:93]
	s_waitcnt lgkmcnt(0)
	v_mfma_f32_16x16x32_bf16 v[74:77], v[146:149], v[208:211], v[74:77]
	v_mfma_f32_16x16x32_bf16 v[78:81], v[138:141], v[208:211], v[78:81]
	s_setprio 0
	s_setprio 1
	v_mfma_f32_16x16x32_bf16 v[118:121], v[150:153], v[180:183], 0
	v_mfma_f32_16x16x32_bf16 v[114:117], v[172:175], v[180:183], 0
	v_mfma_f32_16x16x32_bf16 v[98:101], v[172:175], v[188:191], 0
	v_mfma_f32_16x16x32_bf16 v[102:105], v[150:153], v[188:191], 0
	v_mfma_f32_16x16x32_bf16 v[86:89], v[150:153], v[196:199], 0
	v_mfma_f32_16x16x32_bf16 v[82:85], v[172:175], v[196:199], 0
	v_mfma_f32_16x16x32_bf16 v[66:69], v[172:175], v[204:207], 0
	v_mfma_f32_16x16x32_bf16 v[70:73], v[150:153], v[204:207], 0
	v_mfma_f32_16x16x32_bf16 v[118:121], v[168:171], v[184:187], v[118:121]
	v_mfma_f32_16x16x32_bf16 v[114:117], v[176:179], v[184:187], v[114:117]
	v_mfma_f32_16x16x32_bf16 v[98:101], v[176:179], v[192:195], v[98:101]
	v_mfma_f32_16x16x32_bf16 v[102:105], v[168:171], v[192:195], v[102:105]
	v_mfma_f32_16x16x32_bf16 v[86:89], v[168:171], v[200:203], v[86:89]
	v_mfma_f32_16x16x32_bf16 v[82:85], v[176:179], v[200:203], v[82:85]
	s_setprio 2
	s_barrier
	v_mfma_f32_16x16x32_bf16 v[66:69], v[176:179], v[208:211], v[66:69]
	v_mfma_f32_16x16x32_bf16 v[70:73], v[168:171], v[208:211], v[70:73]
	s_setprio 0
	ds_read_b128 v[180:183], v163 offset:16384
	ds_read_b128 v[184:187], v163 offset:17408
	ds_read_b128 v[188:191], v163 offset:18432
	ds_read_b128 v[192:195], v163 offset:19456
	ds_read_b128 v[196:199], v163 offset:20480
	ds_read_b128 v[200:203], v163 offset:21504
	ds_read_b128 v[204:207], v163 offset:22528
	ds_read_b128 v[208:211], v163 offset:23552
	s_mov_b32 s75, m0
	s_mov_b32 m0, s43
	s_nop 0
	global_load_lds_dwordx4 v156, s[10:11]
	s_mov_b32 m0, s75
	s_add_u32 s76, s10, 0x80000
	s_mov_b32 s75, m0
	s_mov_b32 m0, s46
	s_nop 0
	global_load_lds_dwordx4 v158, s[10:11]
	s_mov_b32 m0, s75
	s_addc_u32 s77, s11, 0
	s_mov_b32 s75, m0
	s_mov_b32 m0, s47
	s_nop 0
	global_load_lds_dwordx4 v156, s[76:77]
	s_mov_b32 m0, s75
	s_nop 0
	s_mov_b32 s75, m0
	s_mov_b32 m0, s48
	s_nop 0
	global_load_lds_dwordx4 v158, s[76:77]
	s_mov_b32 m0, s75
	s_waitcnt vmcnt(4)
	s_waitcnt lgkmcnt(0)
	s_barrier
	s_setprio 1
	s_waitcnt lgkmcnt(7)
	v_mfma_f32_16x16x32_bf16 v[62:65], v[130:133], v[180:183], 0
	v_mfma_f32_16x16x32_bf16 v[58:61], v[142:145], v[180:183], 0
	s_waitcnt lgkmcnt(5)
	v_mfma_f32_16x16x32_bf16 v[42:45], v[142:145], v[188:191], 0
	v_mfma_f32_16x16x32_bf16 v[46:49], v[130:133], v[188:191], 0
	s_waitcnt lgkmcnt(3)
	v_mfma_f32_16x16x32_bf16 v[30:33], v[130:133], v[196:199], 0
	v_mfma_f32_16x16x32_bf16 v[26:29], v[142:145], v[196:199], 0
	s_waitcnt lgkmcnt(1)
	v_mfma_f32_16x16x32_bf16 v[10:13], v[142:145], v[204:207], 0
	v_mfma_f32_16x16x32_bf16 v[14:17], v[130:133], v[204:207], 0
	v_mfma_f32_16x16x32_bf16 v[62:65], v[138:141], v[184:187], v[62:65]
	v_mfma_f32_16x16x32_bf16 v[58:61], v[146:149], v[184:187], v[58:61]
	v_mfma_f32_16x16x32_bf16 v[42:45], v[146:149], v[192:195], v[42:45]
	v_mfma_f32_16x16x32_bf16 v[46:49], v[138:141], v[192:195], v[46:49]
	v_mfma_f32_16x16x32_bf16 v[30:33], v[138:141], v[200:203], v[30:33]
	v_mfma_f32_16x16x32_bf16 v[26:29], v[146:149], v[200:203], v[26:29]
	s_waitcnt lgkmcnt(0)
	v_mfma_f32_16x16x32_bf16 v[10:13], v[146:149], v[208:211], v[10:13]
	v_mfma_f32_16x16x32_bf16 v[14:17], v[138:141], v[208:211], v[14:17]
	s_setprio 0
	s_setprio 1
	v_mfma_f32_16x16x32_bf16 v[54:57], v[150:153], v[180:183], 0
	v_mfma_f32_16x16x32_bf16 v[50:53], v[172:175], v[180:183], 0
	v_mfma_f32_16x16x32_bf16 v[34:37], v[172:175], v[188:191], 0
	v_mfma_f32_16x16x32_bf16 v[38:41], v[150:153], v[188:191], 0
	v_mfma_f32_16x16x32_bf16 v[22:25], v[150:153], v[196:199], 0
	v_mfma_f32_16x16x32_bf16 v[18:21], v[172:175], v[196:199], 0
	v_mfma_f32_16x16x32_bf16 v[2:5], v[172:175], v[204:207], 0
	v_mfma_f32_16x16x32_bf16 v[6:9], v[150:153], v[204:207], 0
	v_mfma_f32_16x16x32_bf16 v[54:57], v[168:171], v[184:187], v[54:57]
	v_mfma_f32_16x16x32_bf16 v[50:53], v[176:179], v[184:187], v[50:53]
	v_mfma_f32_16x16x32_bf16 v[34:37], v[176:179], v[192:195], v[34:37]
	v_mfma_f32_16x16x32_bf16 v[38:41], v[168:171], v[192:195], v[38:41]
	v_mfma_f32_16x16x32_bf16 v[22:25], v[168:171], v[200:203], v[22:25]
	v_mfma_f32_16x16x32_bf16 v[18:21], v[176:179], v[200:203], v[18:21]
	s_setprio 2
	s_barrier
	v_mfma_f32_16x16x32_bf16 v[2:5], v[176:179], v[208:211], v[2:5]
	v_mfma_f32_16x16x32_bf16 v[6:9], v[168:171], v[208:211], v[6:9]
	s_setprio 0
	ds_read_b128 v[130:133], v164
	ds_read_b128 v[138:141], v164 offset:1024
	ds_read_b128 v[142:145], v164 offset:2048
	ds_read_b128 v[146:149], v164 offset:3072
	ds_read_b128 v[150:153], v165
	ds_read_b128 v[168:171], v165 offset:1024
	ds_read_b128 v[172:175], v165 offset:2048
	ds_read_b128 v[176:179], v165 offset:3072
	ds_read_b128 v[180:183], v163 offset:32768
	ds_read_b128 v[184:187], v163 offset:33792
	ds_read_b128 v[188:191], v163 offset:34816
	ds_read_b128 v[192:195], v163 offset:35840
	ds_read_b128 v[196:199], v163 offset:36864
	ds_read_b128 v[200:203], v163 offset:37888
	ds_read_b128 v[204:207], v163 offset:38912
	ds_read_b128 v[208:211], v163 offset:39936
	s_mov_b32 s75, m0
	s_mov_b32 m0, s42
	s_nop 0
	global_load_lds_dwordx4 v1, s[28:29]
	s_mov_b32 m0, s75
	s_nop 0
	s_mov_b32 s75, m0
	s_mov_b32 m0, s49
	s_nop 0
	global_load_lds_dwordx4 v157, s[28:29]
	s_mov_b32 m0, s75
	s_add_u32 s28, s28, 0x80000
	s_addc_u32 s29, s29, 0
	s_mov_b32 s75, m0
	s_mov_b32 m0, s56
	s_nop 0
	global_load_lds_dwordx4 v1, s[28:29]
	s_mov_b32 m0, s75
	s_nop 0
	s_mov_b32 s75, m0
	s_mov_b32 m0, s57
	s_nop 0
	global_load_lds_dwordx4 v157, s[28:29]
	s_mov_b32 m0, s75
	s_waitcnt vmcnt(8)
	s_waitcnt lgkmcnt(0)
	s_barrier
	s_setprio 1
	s_waitcnt lgkmcnt(7)
	v_mfma_f32_16x16x32_bf16 v[126:129], v[130:133], v[180:183], v[126:129]
	v_mfma_f32_16x16x32_bf16 v[122:125], v[142:145], v[180:183], v[122:125]
	s_waitcnt lgkmcnt(5)
	v_mfma_f32_16x16x32_bf16 v[106:109], v[142:145], v[188:191], v[106:109]
	v_mfma_f32_16x16x32_bf16 v[110:113], v[130:133], v[188:191], v[110:113]
	s_waitcnt lgkmcnt(3)
	v_mfma_f32_16x16x32_bf16 v[94:97], v[130:133], v[196:199], v[94:97]
	v_mfma_f32_16x16x32_bf16 v[90:93], v[142:145], v[196:199], v[90:93]
	s_waitcnt lgkmcnt(1)
	v_mfma_f32_16x16x32_bf16 v[74:77], v[142:145], v[204:207], v[74:77]
	v_mfma_f32_16x16x32_bf16 v[78:81], v[130:133], v[204:207], v[78:81]
	v_mfma_f32_16x16x32_bf16 v[126:129], v[138:141], v[184:187], v[126:129]
	v_mfma_f32_16x16x32_bf16 v[122:125], v[146:149], v[184:187], v[122:125]
	v_mfma_f32_16x16x32_bf16 v[106:109], v[146:149], v[192:195], v[106:109]
	v_mfma_f32_16x16x32_bf16 v[110:113], v[138:141], v[192:195], v[110:113]
	v_mfma_f32_16x16x32_bf16 v[94:97], v[138:141], v[200:203], v[94:97]
	v_mfma_f32_16x16x32_bf16 v[90:93], v[146:149], v[200:203], v[90:93]
	s_waitcnt lgkmcnt(0)
	v_mfma_f32_16x16x32_bf16 v[74:77], v[146:149], v[208:211], v[74:77]
	v_mfma_f32_16x16x32_bf16 v[78:81], v[138:141], v[208:211], v[78:81]
	s_setprio 0
	s_setprio 1
	v_mfma_f32_16x16x32_bf16 v[118:121], v[150:153], v[180:183], v[118:121]
	v_mfma_f32_16x16x32_bf16 v[114:117], v[172:175], v[180:183], v[114:117]
	v_mfma_f32_16x16x32_bf16 v[98:101], v[172:175], v[188:191], v[98:101]
	v_mfma_f32_16x16x32_bf16 v[102:105], v[150:153], v[188:191], v[102:105]
	v_mfma_f32_16x16x32_bf16 v[86:89], v[150:153], v[196:199], v[86:89]
	v_mfma_f32_16x16x32_bf16 v[82:85], v[172:175], v[196:199], v[82:85]
	v_mfma_f32_16x16x32_bf16 v[66:69], v[172:175], v[204:207], v[66:69]
	v_mfma_f32_16x16x32_bf16 v[70:73], v[150:153], v[204:207], v[70:73]
	v_mfma_f32_16x16x32_bf16 v[118:121], v[168:171], v[184:187], v[118:121]
	v_mfma_f32_16x16x32_bf16 v[114:117], v[176:179], v[184:187], v[114:117]
	v_mfma_f32_16x16x32_bf16 v[98:101], v[176:179], v[192:195], v[98:101]
	v_mfma_f32_16x16x32_bf16 v[102:105], v[168:171], v[192:195], v[102:105]
	v_mfma_f32_16x16x32_bf16 v[86:89], v[168:171], v[200:203], v[86:89]
	v_mfma_f32_16x16x32_bf16 v[82:85], v[176:179], v[200:203], v[82:85]
	s_setprio 2
	s_barrier
	v_mfma_f32_16x16x32_bf16 v[66:69], v[176:179], v[208:211], v[66:69]
	v_mfma_f32_16x16x32_bf16 v[70:73], v[168:171], v[208:211], v[70:73]
	s_setprio 0
	ds_read_b128 v[180:183], v163 offset:49152
	ds_read_b128 v[184:187], v163 offset:50176
	ds_read_b128 v[188:191], v163 offset:51200
	ds_read_b128 v[192:195], v163 offset:52224
	ds_read_b128 v[196:199], v163 offset:53248
	ds_read_b128 v[200:203], v163 offset:54272
	ds_read_b128 v[204:207], v163 offset:55296
	ds_read_b128 v[208:211], v163 offset:56320
	s_add_u32 s28, s10, 0x80
	s_addc_u32 s29, s11, 0
	s_mov_b32 s75, m0
	s_mov_b32 m0, s64
	s_nop 0
	global_load_lds_dwordx4 v156, s[28:29]
	s_mov_b32 m0, s75
	s_add_u32 s10, s10, 0x80080
	s_mov_b32 s75, m0
	s_mov_b32 m0, s65
	s_nop 0
	global_load_lds_dwordx4 v158, s[28:29]
	s_mov_b32 m0, s75
	s_addc_u32 s11, s11, 0
	s_mov_b32 s28, m0
	s_mov_b32 m0, s66
	s_nop 0
	global_load_lds_dwordx4 v156, s[10:11]
	s_mov_b32 m0, s28
	s_nop 0
	s_mov_b32 s28, m0
	s_mov_b32 m0, s67
	s_nop 0
	global_load_lds_dwordx4 v158, s[10:11]
	s_mov_b32 m0, s28
	s_waitcnt vmcnt(4)
	s_waitcnt lgkmcnt(0)
	s_barrier
	s_setprio 1
	s_waitcnt lgkmcnt(7)
	v_mfma_f32_16x16x32_bf16 v[62:65], v[130:133], v[180:183], v[62:65]
	v_mfma_f32_16x16x32_bf16 v[58:61], v[142:145], v[180:183], v[58:61]
	s_waitcnt lgkmcnt(5)
	v_mfma_f32_16x16x32_bf16 v[42:45], v[142:145], v[188:191], v[42:45]
	v_mfma_f32_16x16x32_bf16 v[46:49], v[130:133], v[188:191], v[46:49]
	s_waitcnt lgkmcnt(3)
	v_mfma_f32_16x16x32_bf16 v[30:33], v[130:133], v[196:199], v[30:33]
	v_mfma_f32_16x16x32_bf16 v[26:29], v[142:145], v[196:199], v[26:29]
	s_waitcnt lgkmcnt(1)
	v_mfma_f32_16x16x32_bf16 v[10:13], v[142:145], v[204:207], v[10:13]
	v_mfma_f32_16x16x32_bf16 v[14:17], v[130:133], v[204:207], v[14:17]
	v_mfma_f32_16x16x32_bf16 v[62:65], v[138:141], v[184:187], v[62:65]
	v_mfma_f32_16x16x32_bf16 v[58:61], v[146:149], v[184:187], v[58:61]
	v_mfma_f32_16x16x32_bf16 v[42:45], v[146:149], v[192:195], v[42:45]
	v_mfma_f32_16x16x32_bf16 v[46:49], v[138:141], v[192:195], v[46:49]
	v_mfma_f32_16x16x32_bf16 v[30:33], v[138:141], v[200:203], v[30:33]
	v_mfma_f32_16x16x32_bf16 v[26:29], v[146:149], v[200:203], v[26:29]
	s_waitcnt lgkmcnt(0)
	v_mfma_f32_16x16x32_bf16 v[10:13], v[146:149], v[208:211], v[10:13]
	v_mfma_f32_16x16x32_bf16 v[14:17], v[138:141], v[208:211], v[14:17]
	s_setprio 0
	s_setprio 1
	v_mfma_f32_16x16x32_bf16 v[54:57], v[150:153], v[180:183], v[54:57]
	v_mfma_f32_16x16x32_bf16 v[50:53], v[172:175], v[180:183], v[50:53]
	v_mfma_f32_16x16x32_bf16 v[34:37], v[172:175], v[188:191], v[34:37]
	v_mfma_f32_16x16x32_bf16 v[38:41], v[150:153], v[188:191], v[38:41]
	v_mfma_f32_16x16x32_bf16 v[22:25], v[150:153], v[196:199], v[22:25]
	v_mfma_f32_16x16x32_bf16 v[18:21], v[172:175], v[196:199], v[18:21]
	v_mfma_f32_16x16x32_bf16 v[2:5], v[172:175], v[204:207], v[2:5]
	v_mfma_f32_16x16x32_bf16 v[6:9], v[150:153], v[204:207], v[6:9]
	v_mfma_f32_16x16x32_bf16 v[54:57], v[168:171], v[184:187], v[54:57]
	v_mfma_f32_16x16x32_bf16 v[50:53], v[176:179], v[184:187], v[50:53]
	v_mfma_f32_16x16x32_bf16 v[34:37], v[176:179], v[192:195], v[34:37]
	v_mfma_f32_16x16x32_bf16 v[38:41], v[168:171], v[192:195], v[38:41]
	v_mfma_f32_16x16x32_bf16 v[22:25], v[168:171], v[200:203], v[22:25]
	v_mfma_f32_16x16x32_bf16 v[18:21], v[176:179], v[200:203], v[18:21]
	s_setprio 2
	s_barrier
	v_mfma_f32_16x16x32_bf16 v[2:5], v[176:179], v[208:211], v[2:5]
	v_mfma_f32_16x16x32_bf16 v[6:9], v[168:171], v[208:211], v[6:9]
	s_setprio 0
	s_add_i32 s74, s74, 2
	s_add_u32 s30, s30, 0x100
	s_addc_u32 s31, s31, 0
	s_add_u32 s4, s4, 0x100
	s_addc_u32 s5, s5, 0
	s_add_u32 s33, s33, 0x100
	s_addc_u32 s73, s73, 0
	s_cmp_gt_u32 s74, 29
	.p2align 6
.LBB0_654:
	ds_read_b128 v[130:133], v161
	ds_read_b128 v[138:141], v161 offset:1024
	ds_read_b128 v[142:145], v161 offset:2048
	ds_read_b128 v[146:149], v161 offset:3072
	ds_read_b128 v[150:153], v162
	ds_read_b128 v[168:171], v162 offset:1024
	ds_read_b128 v[172:175], v162 offset:2048
	ds_read_b128 v[176:179], v162 offset:3072
	s_cmp_eq_u32 s74, 28
	s_cselect_b32 s11, s21, s31
	s_cselect_b32 s10, s23, s30
	s_cselect_b32 s29, s7, s73
	s_cselect_b32 s28, s9, s33
	ds_read_b128 v[180:183], v163
	ds_read_b128 v[184:187], v163 offset:1024
	ds_read_b128 v[188:191], v163 offset:2048
	ds_read_b128 v[192:195], v163 offset:3072
	ds_read_b128 v[196:199], v163 offset:4096
	ds_read_b128 v[200:203], v163 offset:5120
	ds_read_b128 v[204:207], v163 offset:6144
	ds_read_b128 v[208:211], v163 offset:7168
	s_add_u32 s76, s4, 0xfff80000
	s_addc_u32 s77, s5, -1
	s_mov_b32 s75, m0
	s_mov_b32 m0, s80
	s_nop 0
	global_load_lds_dwordx4 v1, s[76:77]
	s_mov_b32 m0, s75
	s_nop 0
	s_mov_b32 s75, m0
	s_mov_b32 m0, s82
	s_nop 0
	global_load_lds_dwordx4 v157, s[76:77]
	s_mov_b32 m0, s75
	s_nop 0
	s_mov_b32 s75, m0
	s_mov_b32 m0, s81
	s_nop 0
	global_load_lds_dwordx4 v1, s[4:5]
	s_mov_b32 m0, s75
	s_nop 0
	s_mov_b32 s75, m0
	s_mov_b32 m0, s83
	s_nop 0
	global_load_lds_dwordx4 v157, s[4:5]
	s_mov_b32 m0, s75
	s_waitcnt vmcnt(8)
	s_waitcnt lgkmcnt(0)
	s_barrier
	s_setprio 1
	s_waitcnt lgkmcnt(7)
	v_mfma_f32_16x16x32_bf16 v[126:129], v[130:133], v[180:183], v[126:129]
	v_mfma_f32_16x16x32_bf16 v[122:125], v[142:145], v[180:183], v[122:125]
	s_waitcnt lgkmcnt(5)
	v_mfma_f32_16x16x32_bf16 v[106:109], v[142:145], v[188:191], v[106:109]
	v_mfma_f32_16x16x32_bf16 v[110:113], v[130:133], v[188:191], v[110:113]
	s_waitcnt lgkmcnt(3)
	v_mfma_f32_16x16x32_bf16 v[94:97], v[130:133], v[196:199], v[94:97]
	v_mfma_f32_16x16x32_bf16 v[90:93], v[142:145], v[196:199], v[90:93]
	s_waitcnt lgkmcnt(1)
	v_mfma_f32_16x16x32_bf16 v[74:77], v[142:145], v[204:207], v[74:77]
	v_mfma_f32_16x16x32_bf16 v[78:81], v[130:133], v[204:207], v[78:81]
	v_mfma_f32_16x16x32_bf16 v[126:129], v[138:141], v[184:187], v[126:129]
	v_mfma_f32_16x16x32_bf16 v[122:125], v[146:149], v[184:187], v[122:125]
	v_mfma_f32_16x16x32_bf16 v[106:109], v[146:149], v[192:195], v[106:109]
	v_mfma_f32_16x16x32_bf16 v[110:113], v[138:141], v[192:195], v[110:113]
	v_mfma_f32_16x16x32_bf16 v[94:97], v[138:141], v[200:203], v[94:97]
	v_mfma_f32_16x16x32_bf16 v[90:93], v[146:149], v[200:203], v[90:93]
	s_waitcnt lgkmcnt(0)
	v_mfma_f32_16x16x32_bf16 v[74:77], v[146:149], v[208:211], v[74:77]
	v_mfma_f32_16x16x32_bf16 v[78:81], v[138:141], v[208:211], v[78:81]
	s_setprio 0
	s_setprio 1
	v_mfma_f32_16x16x32_bf16 v[118:121], v[150:153], v[180:183], v[118:121]
	v_mfma_f32_16x16x32_bf16 v[114:117], v[172:175], v[180:183], v[114:117]
	v_mfma_f32_16x16x32_bf16 v[98:101], v[172:175], v[188:191], v[98:101]
	v_mfma_f32_16x16x32_bf16 v[102:105], v[150:153], v[188:191], v[102:105]
	v_mfma_f32_16x16x32_bf16 v[86:89], v[150:153], v[196:199], v[86:89]
	v_mfma_f32_16x16x32_bf16 v[82:85], v[172:175], v[196:199], v[82:85]
	v_mfma_f32_16x16x32_bf16 v[66:69], v[172:175], v[204:207], v[66:69]
	v_mfma_f32_16x16x32_bf16 v[70:73], v[150:153], v[204:207], v[70:73]
	v_mfma_f32_16x16x32_bf16 v[118:121], v[168:171], v[184:187], v[118:121]
	v_mfma_f32_16x16x32_bf16 v[114:117], v[176:179], v[184:187], v[114:117]
	v_mfma_f32_16x16x32_bf16 v[98:101], v[176:179], v[192:195], v[98:101]
	v_mfma_f32_16x16x32_bf16 v[102:105], v[168:171], v[192:195], v[102:105]
	v_mfma_f32_16x16x32_bf16 v[86:89], v[168:171], v[200:203], v[86:89]
	v_mfma_f32_16x16x32_bf16 v[82:85], v[176:179], v[200:203], v[82:85]
	s_setprio 2
	s_barrier
	v_mfma_f32_16x16x32_bf16 v[66:69], v[176:179], v[208:211], v[66:69]
	v_mfma_f32_16x16x32_bf16 v[70:73], v[168:171], v[208:211], v[70:73]
	s_setprio 0
	ds_read_b128 v[180:183], v163 offset:16384
	ds_read_b128 v[184:187], v163 offset:17408
	ds_read_b128 v[188:191], v163 offset:18432
	ds_read_b128 v[192:195], v163 offset:19456
	ds_read_b128 v[196:199], v163 offset:20480
	ds_read_b128 v[200:203], v163 offset:21504
	ds_read_b128 v[204:207], v163 offset:22528
	ds_read_b128 v[208:211], v163 offset:23552
	s_mov_b32 s75, m0
	s_mov_b32 m0, s43
	s_nop 0
	global_load_lds_dwordx4 v156, s[10:11]
	s_mov_b32 m0, s75
	s_add_u32 s76, s10, 0x80000
	s_mov_b32 s75, m0
	s_mov_b32 m0, s46
	s_nop 0
	global_load_lds_dwordx4 v158, s[10:11]
	s_mov_b32 m0, s75
	s_addc_u32 s77, s11, 0
	s_mov_b32 s75, m0
	s_mov_b32 m0, s47
	s_nop 0
	global_load_lds_dwordx4 v156, s[76:77]
	s_mov_b32 m0, s75
	s_nop 0
	s_mov_b32 s75, m0
	s_mov_b32 m0, s48
	s_nop 0
	global_load_lds_dwordx4 v158, s[76:77]
	s_mov_b32 m0, s75
	s_waitcnt vmcnt(4)
	s_waitcnt lgkmcnt(0)
	s_barrier
	s_setprio 1
	s_waitcnt lgkmcnt(7)
	v_mfma_f32_16x16x32_bf16 v[62:65], v[130:133], v[180:183], v[62:65]
	v_mfma_f32_16x16x32_bf16 v[58:61], v[142:145], v[180:183], v[58:61]
	s_waitcnt lgkmcnt(5)
	v_mfma_f32_16x16x32_bf16 v[42:45], v[142:145], v[188:191], v[42:45]
	v_mfma_f32_16x16x32_bf16 v[46:49], v[130:133], v[188:191], v[46:49]
	s_waitcnt lgkmcnt(3)
	v_mfma_f32_16x16x32_bf16 v[30:33], v[130:133], v[196:199], v[30:33]
	v_mfma_f32_16x16x32_bf16 v[26:29], v[142:145], v[196:199], v[26:29]
	s_waitcnt lgkmcnt(1)
	v_mfma_f32_16x16x32_bf16 v[10:13], v[142:145], v[204:207], v[10:13]
	v_mfma_f32_16x16x32_bf16 v[14:17], v[130:133], v[204:207], v[14:17]
	v_mfma_f32_16x16x32_bf16 v[62:65], v[138:141], v[184:187], v[62:65]
	v_mfma_f32_16x16x32_bf16 v[58:61], v[146:149], v[184:187], v[58:61]
	v_mfma_f32_16x16x32_bf16 v[42:45], v[146:149], v[192:195], v[42:45]
	v_mfma_f32_16x16x32_bf16 v[46:49], v[138:141], v[192:195], v[46:49]
	v_mfma_f32_16x16x32_bf16 v[30:33], v[138:141], v[200:203], v[30:33]
	v_mfma_f32_16x16x32_bf16 v[26:29], v[146:149], v[200:203], v[26:29]
	s_waitcnt lgkmcnt(0)
	v_mfma_f32_16x16x32_bf16 v[10:13], v[146:149], v[208:211], v[10:13]
	v_mfma_f32_16x16x32_bf16 v[14:17], v[138:141], v[208:211], v[14:17]
	s_setprio 0
	s_setprio 1
	v_mfma_f32_16x16x32_bf16 v[54:57], v[150:153], v[180:183], v[54:57]
	v_mfma_f32_16x16x32_bf16 v[50:53], v[172:175], v[180:183], v[50:53]
	v_mfma_f32_16x16x32_bf16 v[34:37], v[172:175], v[188:191], v[34:37]
	v_mfma_f32_16x16x32_bf16 v[38:41], v[150:153], v[188:191], v[38:41]
	v_mfma_f32_16x16x32_bf16 v[22:25], v[150:153], v[196:199], v[22:25]
	v_mfma_f32_16x16x32_bf16 v[18:21], v[172:175], v[196:199], v[18:21]
	v_mfma_f32_16x16x32_bf16 v[2:5], v[172:175], v[204:207], v[2:5]
	v_mfma_f32_16x16x32_bf16 v[6:9], v[150:153], v[204:207], v[6:9]
	v_mfma_f32_16x16x32_bf16 v[54:57], v[168:171], v[184:187], v[54:57]
	v_mfma_f32_16x16x32_bf16 v[50:53], v[176:179], v[184:187], v[50:53]
	v_mfma_f32_16x16x32_bf16 v[34:37], v[176:179], v[192:195], v[34:37]
	v_mfma_f32_16x16x32_bf16 v[38:41], v[168:171], v[192:195], v[38:41]
	v_mfma_f32_16x16x32_bf16 v[22:25], v[168:171], v[200:203], v[22:25]
	v_mfma_f32_16x16x32_bf16 v[18:21], v[176:179], v[200:203], v[18:21]
	s_setprio 2
	s_barrier
	v_mfma_f32_16x16x32_bf16 v[2:5], v[176:179], v[208:211], v[2:5]
	v_mfma_f32_16x16x32_bf16 v[6:9], v[168:171], v[208:211], v[6:9]
	s_setprio 0
	ds_read_b128 v[130:133], v164
	ds_read_b128 v[138:141], v164 offset:1024
	ds_read_b128 v[142:145], v164 offset:2048
	ds_read_b128 v[146:149], v164 offset:3072
	ds_read_b128 v[150:153], v165
	ds_read_b128 v[168:171], v165 offset:1024
	ds_read_b128 v[172:175], v165 offset:2048
	ds_read_b128 v[176:179], v165 offset:3072
	ds_read_b128 v[180:183], v163 offset:32768
	ds_read_b128 v[184:187], v163 offset:33792
	ds_read_b128 v[188:191], v163 offset:34816
	ds_read_b128 v[192:195], v163 offset:35840
	ds_read_b128 v[196:199], v163 offset:36864
	ds_read_b128 v[200:203], v163 offset:37888
	ds_read_b128 v[204:207], v163 offset:38912
	ds_read_b128 v[208:211], v163 offset:39936
	s_mov_b32 s75, m0
	s_mov_b32 m0, s42
	s_nop 0
	global_load_lds_dwordx4 v1, s[28:29]
	s_mov_b32 m0, s75
	s_nop 0
	s_mov_b32 s75, m0
	s_mov_b32 m0, s49
	s_nop 0
	global_load_lds_dwordx4 v157, s[28:29]
	s_mov_b32 m0, s75
	s_add_u32 s28, s28, 0x80000
	s_addc_u32 s29, s29, 0
	s_mov_b32 s75, m0
	s_mov_b32 m0, s56
	s_nop 0
	global_load_lds_dwordx4 v1, s[28:29]
	s_mov_b32 m0, s75
	s_nop 0
	s_mov_b32 s75, m0
	s_mov_b32 m0, s57
	s_nop 0
	global_load_lds_dwordx4 v157, s[28:29]
	s_mov_b32 m0, s75
	s_waitcnt vmcnt(8)
	s_waitcnt lgkmcnt(0)
	s_barrier
	s_setprio 1
	s_waitcnt lgkmcnt(7)
	v_mfma_f32_16x16x32_bf16 v[126:129], v[130:133], v[180:183], v[126:129]
	v_mfma_f32_16x16x32_bf16 v[122:125], v[142:145], v[180:183], v[122:125]
	s_waitcnt lgkmcnt(5)
	v_mfma_f32_16x16x32_bf16 v[106:109], v[142:145], v[188:191], v[106:109]
	v_mfma_f32_16x16x32_bf16 v[110:113], v[130:133], v[188:191], v[110:113]
	s_waitcnt lgkmcnt(3)
	v_mfma_f32_16x16x32_bf16 v[94:97], v[130:133], v[196:199], v[94:97]
	v_mfma_f32_16x16x32_bf16 v[90:93], v[142:145], v[196:199], v[90:93]
	s_waitcnt lgkmcnt(1)
	v_mfma_f32_16x16x32_bf16 v[74:77], v[142:145], v[204:207], v[74:77]
	v_mfma_f32_16x16x32_bf16 v[78:81], v[130:133], v[204:207], v[78:81]
	v_mfma_f32_16x16x32_bf16 v[126:129], v[138:141], v[184:187], v[126:129]
	v_mfma_f32_16x16x32_bf16 v[122:125], v[146:149], v[184:187], v[122:125]
	v_mfma_f32_16x16x32_bf16 v[106:109], v[146:149], v[192:195], v[106:109]
	v_mfma_f32_16x16x32_bf16 v[110:113], v[138:141], v[192:195], v[110:113]
	v_mfma_f32_16x16x32_bf16 v[94:97], v[138:141], v[200:203], v[94:97]
	v_mfma_f32_16x16x32_bf16 v[90:93], v[146:149], v[200:203], v[90:93]
	s_waitcnt lgkmcnt(0)
	v_mfma_f32_16x16x32_bf16 v[74:77], v[146:149], v[208:211], v[74:77]
	v_mfma_f32_16x16x32_bf16 v[78:81], v[138:141], v[208:211], v[78:81]
	s_setprio 0
	s_setprio 1
	v_mfma_f32_16x16x32_bf16 v[118:121], v[150:153], v[180:183], v[118:121]
	v_mfma_f32_16x16x32_bf16 v[114:117], v[172:175], v[180:183], v[114:117]
	v_mfma_f32_16x16x32_bf16 v[98:101], v[172:175], v[188:191], v[98:101]
	v_mfma_f32_16x16x32_bf16 v[102:105], v[150:153], v[188:191], v[102:105]
	v_mfma_f32_16x16x32_bf16 v[86:89], v[150:153], v[196:199], v[86:89]
	v_mfma_f32_16x16x32_bf16 v[82:85], v[172:175], v[196:199], v[82:85]
	v_mfma_f32_16x16x32_bf16 v[66:69], v[172:175], v[204:207], v[66:69]
	v_mfma_f32_16x16x32_bf16 v[70:73], v[150:153], v[204:207], v[70:73]
	v_mfma_f32_16x16x32_bf16 v[118:121], v[168:171], v[184:187], v[118:121]
	v_mfma_f32_16x16x32_bf16 v[114:117], v[176:179], v[184:187], v[114:117]
	v_mfma_f32_16x16x32_bf16 v[98:101], v[176:179], v[192:195], v[98:101]
	v_mfma_f32_16x16x32_bf16 v[102:105], v[168:171], v[192:195], v[102:105]
	v_mfma_f32_16x16x32_bf16 v[86:89], v[168:171], v[200:203], v[86:89]
	v_mfma_f32_16x16x32_bf16 v[82:85], v[176:179], v[200:203], v[82:85]
	s_setprio 2
	s_barrier
	v_mfma_f32_16x16x32_bf16 v[66:69], v[176:179], v[208:211], v[66:69]
	v_mfma_f32_16x16x32_bf16 v[70:73], v[168:171], v[208:211], v[70:73]
	s_setprio 0
	ds_read_b128 v[180:183], v163 offset:49152
	ds_read_b128 v[184:187], v163 offset:50176
	ds_read_b128 v[188:191], v163 offset:51200
	ds_read_b128 v[192:195], v163 offset:52224
	ds_read_b128 v[196:199], v163 offset:53248
	ds_read_b128 v[200:203], v163 offset:54272
	ds_read_b128 v[204:207], v163 offset:55296
	ds_read_b128 v[208:211], v163 offset:56320
	s_add_u32 s28, s10, 0x80
	s_addc_u32 s29, s11, 0
	s_mov_b32 s75, m0
	s_mov_b32 m0, s64
	s_nop 0
	global_load_lds_dwordx4 v156, s[28:29]
	s_mov_b32 m0, s75
	s_add_u32 s10, s10, 0x80080
	s_mov_b32 s75, m0
	s_mov_b32 m0, s65
	s_nop 0
	global_load_lds_dwordx4 v158, s[28:29]
	s_mov_b32 m0, s75
	s_addc_u32 s11, s11, 0
	s_mov_b32 s28, m0
	s_mov_b32 m0, s66
	s_nop 0
	global_load_lds_dwordx4 v156, s[10:11]
	s_mov_b32 m0, s28
	s_nop 0
	s_mov_b32 s28, m0
	s_mov_b32 m0, s67
	s_nop 0
	global_load_lds_dwordx4 v158, s[10:11]
	s_mov_b32 m0, s28
	s_waitcnt vmcnt(4)
	s_waitcnt lgkmcnt(0)
	s_barrier
	s_setprio 1
	s_waitcnt lgkmcnt(7)
	v_mfma_f32_16x16x32_bf16 v[62:65], v[130:133], v[180:183], v[62:65]
	v_mfma_f32_16x16x32_bf16 v[58:61], v[142:145], v[180:183], v[58:61]
	s_waitcnt lgkmcnt(5)
	v_mfma_f32_16x16x32_bf16 v[42:45], v[142:145], v[188:191], v[42:45]
	v_mfma_f32_16x16x32_bf16 v[46:49], v[130:133], v[188:191], v[46:49]
	s_waitcnt lgkmcnt(3)
	v_mfma_f32_16x16x32_bf16 v[30:33], v[130:133], v[196:199], v[30:33]
	v_mfma_f32_16x16x32_bf16 v[26:29], v[142:145], v[196:199], v[26:29]
	s_waitcnt lgkmcnt(1)
	v_mfma_f32_16x16x32_bf16 v[10:13], v[142:145], v[204:207], v[10:13]
	v_mfma_f32_16x16x32_bf16 v[14:17], v[130:133], v[204:207], v[14:17]
	v_mfma_f32_16x16x32_bf16 v[62:65], v[138:141], v[184:187], v[62:65]
	v_mfma_f32_16x16x32_bf16 v[58:61], v[146:149], v[184:187], v[58:61]
	v_mfma_f32_16x16x32_bf16 v[42:45], v[146:149], v[192:195], v[42:45]
	v_mfma_f32_16x16x32_bf16 v[46:49], v[138:141], v[192:195], v[46:49]
	v_mfma_f32_16x16x32_bf16 v[30:33], v[138:141], v[200:203], v[30:33]
	v_mfma_f32_16x16x32_bf16 v[26:29], v[146:149], v[200:203], v[26:29]
	s_waitcnt lgkmcnt(0)
	v_mfma_f32_16x16x32_bf16 v[10:13], v[146:149], v[208:211], v[10:13]
	v_mfma_f32_16x16x32_bf16 v[14:17], v[138:141], v[208:211], v[14:17]
	s_setprio 0
	s_setprio 1
	v_mfma_f32_16x16x32_bf16 v[54:57], v[150:153], v[180:183], v[54:57]
	v_mfma_f32_16x16x32_bf16 v[50:53], v[172:175], v[180:183], v[50:53]
	v_mfma_f32_16x16x32_bf16 v[34:37], v[172:175], v[188:191], v[34:37]
	v_mfma_f32_16x16x32_bf16 v[38:41], v[150:153], v[188:191], v[38:41]
	v_mfma_f32_16x16x32_bf16 v[22:25], v[150:153], v[196:199], v[22:25]
	v_mfma_f32_16x16x32_bf16 v[18:21], v[172:175], v[196:199], v[18:21]
	v_mfma_f32_16x16x32_bf16 v[2:5], v[172:175], v[204:207], v[2:5]
	v_mfma_f32_16x16x32_bf16 v[6:9], v[150:153], v[204:207], v[6:9]
	v_mfma_f32_16x16x32_bf16 v[54:57], v[168:171], v[184:187], v[54:57]
	v_mfma_f32_16x16x32_bf16 v[50:53], v[176:179], v[184:187], v[50:53]
	v_mfma_f32_16x16x32_bf16 v[34:37], v[176:179], v[192:195], v[34:37]
	v_mfma_f32_16x16x32_bf16 v[38:41], v[168:171], v[192:195], v[38:41]
	v_mfma_f32_16x16x32_bf16 v[22:25], v[168:171], v[200:203], v[22:25]
	v_mfma_f32_16x16x32_bf16 v[18:21], v[176:179], v[200:203], v[18:21]
	s_setprio 2
	s_barrier
	v_mfma_f32_16x16x32_bf16 v[2:5], v[176:179], v[208:211], v[2:5]
	v_mfma_f32_16x16x32_bf16 v[6:9], v[168:171], v[208:211], v[6:9]
	s_setprio 0
	s_add_i32 s74, s74, 2
	s_add_u32 s30, s30, 0x100
	s_addc_u32 s31, s31, 0
	s_add_u32 s4, s4, 0x100
	s_addc_u32 s5, s5, 0
	s_add_u32 s33, s33, 0x100
	s_addc_u32 s73, s73, 0
	s_cmp_gt_u32 s74, 29
	s_cbranch_scc0 .LBB0_654
	s_and_b64 vcc, exec, s[18:19]
	s_cbranch_vccz .LBB0_657
	s_barrier

.LBB0_1052:
	s_ashr_i32 s13, s12, 31
	s_lshl_b64 s[14:15], s[12:13], 20
	s_add_u32 s14, s28, s14
	s_addc_u32 s15, s29, s15
	s_and_b64 s[16:17], s[2:3], exec
	s_cselect_b32 s13, s15, s23
	s_cselect_b32 s67, s14, s22
	s_ashr_i32 s11, s10, 31
	s_lshl_b64 s[16:17], s[10:11], 20
	s_add_u32 s16, s30, s16
	s_addc_u32 s17, s31, s17
	s_and_b64 s[24:25], s[2:3], exec
	s_cselect_b32 s11, s17, s21
	s_cselect_b32 s73, s16, s20
	s_add_u32 s74, s20, 0x100
	s_addc_u32 s75, s21, 0
	s_add_u32 s20, s22, 0x80080
	s_addc_u32 s21, s23, 0
	s_add_u32 s76, s22, 0x100
	s_addc_u32 s77, s23, 0
	s_mov_b32 s78, -2
	s_waitcnt vmcnt(25)
	s_waitcnt vmcnt(24)
	s_waitcnt vmcnt(15)
	s_waitcnt vmcnt(14)
	s_waitcnt vmcnt(13)
	s_waitcnt vmcnt(12)
	s_waitcnt vmcnt(11)
	s_waitcnt vmcnt(10)
	s_waitcnt vmcnt(9)
	s_waitcnt vmcnt(8)
	s_waitcnt vmcnt(7)
	s_waitcnt vmcnt(6)
	s_waitcnt vmcnt(5)
	s_waitcnt vmcnt(4)
	s_waitcnt vmcnt(3)
	s_waitcnt vmcnt(2)
	s_waitcnt vmcnt(1)
	s_waitcnt vmcnt(0)
	ds_read_b128 v[130:133], v181
	ds_read_b128 v[134:137], v181 offset:1024
	ds_read_b128 v[138:141], v181 offset:2048
	ds_read_b128 v[142:145], v181 offset:3072
	ds_read_b128 v[146:149], v182
	ds_read_b128 v[150:153], v182 offset:1024
	ds_read_b128 v[154:157], v182 offset:2048
	ds_read_b128 v[158:161], v182 offset:3072
	s_cmp_eq_u32 s78, 28
	s_cselect_b32 s23, s11, s75
	s_cselect_b32 s22, s73, s74
	s_cselect_b32 s25, s13, s77
	s_cselect_b32 s24, s67, s76
	ds_read_b128 v[166:169], v183
	ds_read_b128 v[170:173], v183 offset:1024
	ds_read_b128 v[186:189], v183 offset:2048
	ds_read_b128 v[190:193], v183 offset:3072
	ds_read_b128 v[194:197], v183 offset:4096
	ds_read_b128 v[198:201], v183 offset:5120
	ds_read_b128 v[202:205], v183 offset:6144
	ds_read_b128 v[206:209], v183 offset:7168
	s_add_u32 s80, s20, 0xfff80000
	s_addc_u32 s81, s21, -1
	s_mov_b32 s79, m0
	s_mov_b32 m0, s58
	s_nop 0
	global_load_lds_dwordx4 v1, s[80:81]
	s_mov_b32 m0, s79
	s_nop 0
	s_mov_b32 s79, m0
	s_mov_b32 m0, s64
	s_nop 0
	global_load_lds_dwordx4 v177, s[80:81]
	s_mov_b32 m0, s79
	s_nop 0
	s_mov_b32 s79, m0
	s_mov_b32 m0, s59
	s_nop 0
	global_load_lds_dwordx4 v1, s[20:21]
	s_mov_b32 m0, s79
	s_nop 0
	s_mov_b32 s79, m0
	s_mov_b32 m0, s65
	s_nop 0
	global_load_lds_dwordx4 v177, s[20:21]
	s_mov_b32 m0, s79
	s_waitcnt vmcnt(8)
	s_waitcnt lgkmcnt(0)
	s_barrier
	s_setprio 1
	s_waitcnt lgkmcnt(7)
	v_mfma_f32_16x16x32_bf16 v[126:129], v[130:133], v[166:169], 0
	v_mfma_f32_16x16x32_bf16 v[122:125], v[138:141], v[166:169], 0
	s_waitcnt lgkmcnt(5)
	v_mfma_f32_16x16x32_bf16 v[114:117], v[138:141], v[186:189], 0
	v_mfma_f32_16x16x32_bf16 v[118:121], v[130:133], v[186:189], 0
	s_waitcnt lgkmcnt(3)
	v_mfma_f32_16x16x32_bf16 v[94:97], v[130:133], v[194:197], 0
	v_mfma_f32_16x16x32_bf16 v[90:93], v[138:141], v[194:197], 0
	s_waitcnt lgkmcnt(1)
	v_mfma_f32_16x16x32_bf16 v[78:81], v[138:141], v[202:205], 0
	v_mfma_f32_16x16x32_bf16 v[86:89], v[130:133], v[202:205], 0
	v_mfma_f32_16x16x32_bf16 v[126:129], v[134:137], v[170:173], v[126:129]
	v_mfma_f32_16x16x32_bf16 v[122:125], v[142:145], v[170:173], v[122:125]
	v_mfma_f32_16x16x32_bf16 v[114:117], v[142:145], v[190:193], v[114:117]
	v_mfma_f32_16x16x32_bf16 v[118:121], v[134:137], v[190:193], v[118:121]
	v_mfma_f32_16x16x32_bf16 v[94:97], v[134:137], v[198:201], v[94:97]
	v_mfma_f32_16x16x32_bf16 v[90:93], v[142:145], v[198:201], v[90:93]
	s_waitcnt lgkmcnt(0)
	v_mfma_f32_16x16x32_bf16 v[78:81], v[142:145], v[206:209], v[78:81]
	v_mfma_f32_16x16x32_bf16 v[86:89], v[134:137], v[206:209], v[86:89]
	s_setprio 0
	s_setprio 1
	v_mfma_f32_16x16x32_bf16 v[110:113], v[146:149], v[166:169], 0
	v_mfma_f32_16x16x32_bf16 v[106:109], v[154:157], v[166:169], 0
	v_mfma_f32_16x16x32_bf16 v[98:101], v[154:157], v[186:189], 0
	v_mfma_f32_16x16x32_bf16 v[102:105], v[146:149], v[186:189], 0
	v_mfma_f32_16x16x32_bf16 v[82:85], v[146:149], v[194:197], 0
	v_mfma_f32_16x16x32_bf16 v[74:77], v[154:157], v[194:197], 0
	v_mfma_f32_16x16x32_bf16 v[66:69], v[154:157], v[202:205], 0
	v_mfma_f32_16x16x32_bf16 v[70:73], v[146:149], v[202:205], 0
	v_mfma_f32_16x16x32_bf16 v[110:113], v[150:153], v[170:173], v[110:113]
	v_mfma_f32_16x16x32_bf16 v[106:109], v[158:161], v[170:173], v[106:109]
	v_mfma_f32_16x16x32_bf16 v[98:101], v[158:161], v[190:193], v[98:101]
	v_mfma_f32_16x16x32_bf16 v[102:105], v[150:153], v[190:193], v[102:105]
	v_mfma_f32_16x16x32_bf16 v[82:85], v[150:153], v[198:201], v[82:85]
	v_mfma_f32_16x16x32_bf16 v[74:77], v[158:161], v[198:201], v[74:77]
	s_setprio 2
	s_barrier
	v_mfma_f32_16x16x32_bf16 v[66:69], v[158:161], v[206:209], v[66:69]
	v_mfma_f32_16x16x32_bf16 v[70:73], v[150:153], v[206:209], v[70:73]
	s_setprio 0
	ds_read_b128 v[166:169], v183 offset:16384
	ds_read_b128 v[170:173], v183 offset:17408
	ds_read_b128 v[186:189], v183 offset:18432
	ds_read_b128 v[190:193], v183 offset:19456
	ds_read_b128 v[194:197], v183 offset:20480
	ds_read_b128 v[198:201], v183 offset:21504
	ds_read_b128 v[202:205], v183 offset:22528
	ds_read_b128 v[206:209], v183 offset:23552
	s_mov_b32 s79, m0
	s_mov_b32 m0, s35
	s_nop 0
	global_load_lds_dwordx4 v176, s[22:23]
	s_mov_b32 m0, s79
	s_add_u32 s80, s22, 0x80000
	s_mov_b32 s79, m0
	s_mov_b32 m0, s36
	s_nop 0
	global_load_lds_dwordx4 v178, s[22:23]
	s_mov_b32 m0, s79
	s_addc_u32 s81, s23, 0
	s_mov_b32 s79, m0
	s_mov_b32 m0, s37
	s_nop 0
	global_load_lds_dwordx4 v176, s[80:81]
	s_mov_b32 m0, s79
	s_nop 0
	s_mov_b32 s79, m0
	s_mov_b32 m0, s40
	s_nop 0
	global_load_lds_dwordx4 v178, s[80:81]
	s_mov_b32 m0, s79
	s_waitcnt vmcnt(4)
	s_waitcnt lgkmcnt(0)
	s_barrier
	s_setprio 1
	s_waitcnt lgkmcnt(7)
	v_mfma_f32_16x16x32_bf16 v[62:65], v[130:133], v[166:169], 0
	v_mfma_f32_16x16x32_bf16 v[58:61], v[138:141], v[166:169], 0
	s_waitcnt lgkmcnt(5)
	v_mfma_f32_16x16x32_bf16 v[42:45], v[138:141], v[186:189], 0
	v_mfma_f32_16x16x32_bf16 v[46:49], v[130:133], v[186:189], 0
	s_waitcnt lgkmcnt(3)
	v_mfma_f32_16x16x32_bf16 v[30:33], v[130:133], v[194:197], 0
	v_mfma_f32_16x16x32_bf16 v[26:29], v[138:141], v[194:197], 0
	s_waitcnt lgkmcnt(1)
	v_mfma_f32_16x16x32_bf16 v[10:13], v[138:141], v[202:205], 0
	v_mfma_f32_16x16x32_bf16 v[14:17], v[130:133], v[202:205], 0
	v_mfma_f32_16x16x32_bf16 v[62:65], v[134:137], v[170:173], v[62:65]
	v_mfma_f32_16x16x32_bf16 v[58:61], v[142:145], v[170:173], v[58:61]
	v_mfma_f32_16x16x32_bf16 v[42:45], v[142:145], v[190:193], v[42:45]
	v_mfma_f32_16x16x32_bf16 v[46:49], v[134:137], v[190:193], v[46:49]
	v_mfma_f32_16x16x32_bf16 v[30:33], v[134:137], v[198:201], v[30:33]
	v_mfma_f32_16x16x32_bf16 v[26:29], v[142:145], v[198:201], v[26:29]
	s_waitcnt lgkmcnt(0)
	v_mfma_f32_16x16x32_bf16 v[10:13], v[142:145], v[206:209], v[10:13]
	v_mfma_f32_16x16x32_bf16 v[14:17], v[134:137], v[206:209], v[14:17]
	s_setprio 0
	s_setprio 1
	v_mfma_f32_16x16x32_bf16 v[54:57], v[146:149], v[166:169], 0
	v_mfma_f32_16x16x32_bf16 v[50:53], v[154:157], v[166:169], 0
	v_mfma_f32_16x16x32_bf16 v[34:37], v[154:157], v[186:189], 0
	v_mfma_f32_16x16x32_bf16 v[38:41], v[146:149], v[186:189], 0
	v_mfma_f32_16x16x32_bf16 v[22:25], v[146:149], v[194:197], 0
	v_mfma_f32_16x16x32_bf16 v[18:21], v[154:157], v[194:197], 0
	v_mfma_f32_16x16x32_bf16 v[2:5], v[154:157], v[202:205], 0
	v_mfma_f32_16x16x32_bf16 v[6:9], v[146:149], v[202:205], 0
	v_mfma_f32_16x16x32_bf16 v[54:57], v[150:153], v[170:173], v[54:57]
	v_mfma_f32_16x16x32_bf16 v[50:53], v[158:161], v[170:173], v[50:53]
	v_mfma_f32_16x16x32_bf16 v[34:37], v[158:161], v[190:193], v[34:37]
	v_mfma_f32_16x16x32_bf16 v[38:41], v[150:153], v[190:193], v[38:41]
	v_mfma_f32_16x16x32_bf16 v[22:25], v[150:153], v[198:201], v[22:25]
	v_mfma_f32_16x16x32_bf16 v[18:21], v[158:161], v[198:201], v[18:21]
	s_setprio 2
	s_barrier
	v_mfma_f32_16x16x32_bf16 v[2:5], v[158:161], v[206:209], v[2:5]
	v_mfma_f32_16x16x32_bf16 v[6:9], v[150:153], v[206:209], v[6:9]
	s_setprio 0
	ds_read_b128 v[130:133], v184
	ds_read_b128 v[134:137], v184 offset:1024
	ds_read_b128 v[138:141], v184 offset:2048
	ds_read_b128 v[142:145], v184 offset:3072
	ds_read_b128 v[146:149], v185
	ds_read_b128 v[150:153], v185 offset:1024
	ds_read_b128 v[154:157], v185 offset:2048
	ds_read_b128 v[158:161], v185 offset:3072
	ds_read_b128 v[166:169], v183 offset:32768
	ds_read_b128 v[170:173], v183 offset:33792
	ds_read_b128 v[186:189], v183 offset:34816
	ds_read_b128 v[190:193], v183 offset:35840
	ds_read_b128 v[194:197], v183 offset:36864
	ds_read_b128 v[198:201], v183 offset:37888
	ds_read_b128 v[202:205], v183 offset:38912
	ds_read_b128 v[206:209], v183 offset:39936
	s_mov_b32 s79, m0
	s_mov_b32 m0, s34
	s_nop 0
	global_load_lds_dwordx4 v1, s[24:25]
	s_mov_b32 m0, s79
	s_nop 0
	s_mov_b32 s79, m0
	s_mov_b32 m0, s41
	s_nop 0
	global_load_lds_dwordx4 v177, s[24:25]
	s_mov_b32 m0, s79
	s_add_u32 s24, s24, 0x80000
	s_addc_u32 s25, s25, 0
	s_mov_b32 s79, m0
	s_mov_b32 m0, s42
	s_nop 0
	global_load_lds_dwordx4 v1, s[24:25]
	s_mov_b32 m0, s79
	s_nop 0
	s_mov_b32 s79, m0
	s_mov_b32 m0, s43
	s_nop 0
	global_load_lds_dwordx4 v177, s[24:25]
	s_mov_b32 m0, s79
	s_waitcnt vmcnt(8)
	s_waitcnt lgkmcnt(0)
	s_barrier
	s_setprio 1
	s_waitcnt lgkmcnt(7)
	v_mfma_f32_16x16x32_bf16 v[126:129], v[130:133], v[166:169], v[126:129]
	v_mfma_f32_16x16x32_bf16 v[122:125], v[138:141], v[166:169], v[122:125]
	s_waitcnt lgkmcnt(5)
	v_mfma_f32_16x16x32_bf16 v[114:117], v[138:141], v[186:189], v[114:117]
	v_mfma_f32_16x16x32_bf16 v[118:121], v[130:133], v[186:189], v[118:121]
	s_waitcnt lgkmcnt(3)
	v_mfma_f32_16x16x32_bf16 v[94:97], v[130:133], v[194:197], v[94:97]
	v_mfma_f32_16x16x32_bf16 v[90:93], v[138:141], v[194:197], v[90:93]
	s_waitcnt lgkmcnt(1)
	v_mfma_f32_16x16x32_bf16 v[78:81], v[138:141], v[202:205], v[78:81]
	v_mfma_f32_16x16x32_bf16 v[86:89], v[130:133], v[202:205], v[86:89]
	v_mfma_f32_16x16x32_bf16 v[126:129], v[134:137], v[170:173], v[126:129]
	v_mfma_f32_16x16x32_bf16 v[122:125], v[142:145], v[170:173], v[122:125]
	v_mfma_f32_16x16x32_bf16 v[114:117], v[142:145], v[190:193], v[114:117]
	v_mfma_f32_16x16x32_bf16 v[118:121], v[134:137], v[190:193], v[118:121]
	v_mfma_f32_16x16x32_bf16 v[94:97], v[134:137], v[198:201], v[94:97]
	v_mfma_f32_16x16x32_bf16 v[90:93], v[142:145], v[198:201], v[90:93]
	s_waitcnt lgkmcnt(0)
	v_mfma_f32_16x16x32_bf16 v[78:81], v[142:145], v[206:209], v[78:81]
	v_mfma_f32_16x16x32_bf16 v[86:89], v[134:137], v[206:209], v[86:89]
	s_setprio 0
	s_setprio 1
	v_mfma_f32_16x16x32_bf16 v[110:113], v[146:149], v[166:169], v[110:113]
	v_mfma_f32_16x16x32_bf16 v[106:109], v[154:157], v[166:169], v[106:109]
	v_mfma_f32_16x16x32_bf16 v[98:101], v[154:157], v[186:189], v[98:101]
	v_mfma_f32_16x16x32_bf16 v[102:105], v[146:149], v[186:189], v[102:105]
	v_mfma_f32_16x16x32_bf16 v[82:85], v[146:149], v[194:197], v[82:85]
	v_mfma_f32_16x16x32_bf16 v[74:77], v[154:157], v[194:197], v[74:77]
	v_mfma_f32_16x16x32_bf16 v[66:69], v[154:157], v[202:205], v[66:69]
	v_mfma_f32_16x16x32_bf16 v[70:73], v[146:149], v[202:205], v[70:73]
	v_mfma_f32_16x16x32_bf16 v[110:113], v[150:153], v[170:173], v[110:113]
	v_mfma_f32_16x16x32_bf16 v[106:109], v[158:161], v[170:173], v[106:109]
	v_mfma_f32_16x16x32_bf16 v[98:101], v[158:161], v[190:193], v[98:101]
	v_mfma_f32_16x16x32_bf16 v[102:105], v[150:153], v[190:193], v[102:105]
	v_mfma_f32_16x16x32_bf16 v[82:85], v[150:153], v[198:201], v[82:85]
	v_mfma_f32_16x16x32_bf16 v[74:77], v[158:161], v[198:201], v[74:77]
	s_setprio 2
	s_barrier
	v_mfma_f32_16x16x32_bf16 v[66:69], v[158:161], v[206:209], v[66:69]
	v_mfma_f32_16x16x32_bf16 v[70:73], v[150:153], v[206:209], v[70:73]
	s_setprio 0
	ds_read_b128 v[166:169], v183 offset:49152
	ds_read_b128 v[170:173], v183 offset:50176
	ds_read_b128 v[186:189], v183 offset:51200
	ds_read_b128 v[190:193], v183 offset:52224
	ds_read_b128 v[194:197], v183 offset:53248
	ds_read_b128 v[198:201], v183 offset:54272
	ds_read_b128 v[202:205], v183 offset:55296
	ds_read_b128 v[206:209], v183 offset:56320
	s_add_u32 s24, s22, 0x80
	s_addc_u32 s25, s23, 0
	s_mov_b32 s79, m0
	s_mov_b32 m0, s46
	s_nop 0
	global_load_lds_dwordx4 v176, s[24:25]
	s_mov_b32 m0, s79
	s_add_u32 s22, s22, 0x80080
	s_mov_b32 s79, m0
	s_mov_b32 m0, s47
	s_nop 0
	global_load_lds_dwordx4 v178, s[24:25]
	s_mov_b32 m0, s79
	s_addc_u32 s23, s23, 0
	s_mov_b32 s24, m0
	s_mov_b32 m0, s48
	s_nop 0
	global_load_lds_dwordx4 v176, s[22:23]
	s_mov_b32 m0, s24
	s_nop 0
	s_mov_b32 s24, m0
	s_mov_b32 m0, s49
	s_nop 0
	global_load_lds_dwordx4 v178, s[22:23]
	s_mov_b32 m0, s24
	s_waitcnt vmcnt(4)
	s_waitcnt lgkmcnt(0)
	s_barrier
	s_setprio 1
	s_waitcnt lgkmcnt(7)
	v_mfma_f32_16x16x32_bf16 v[62:65], v[130:133], v[166:169], v[62:65]
	v_mfma_f32_16x16x32_bf16 v[58:61], v[138:141], v[166:169], v[58:61]
	s_waitcnt lgkmcnt(5)
	v_mfma_f32_16x16x32_bf16 v[42:45], v[138:141], v[186:189], v[42:45]
	v_mfma_f32_16x16x32_bf16 v[46:49], v[130:133], v[186:189], v[46:49]
	s_waitcnt lgkmcnt(3)
	v_mfma_f32_16x16x32_bf16 v[30:33], v[130:133], v[194:197], v[30:33]
	v_mfma_f32_16x16x32_bf16 v[26:29], v[138:141], v[194:197], v[26:29]
	s_waitcnt lgkmcnt(1)
	v_mfma_f32_16x16x32_bf16 v[10:13], v[138:141], v[202:205], v[10:13]
	v_mfma_f32_16x16x32_bf16 v[14:17], v[130:133], v[202:205], v[14:17]
	v_mfma_f32_16x16x32_bf16 v[62:65], v[134:137], v[170:173], v[62:65]
	v_mfma_f32_16x16x32_bf16 v[58:61], v[142:145], v[170:173], v[58:61]
	v_mfma_f32_16x16x32_bf16 v[42:45], v[142:145], v[190:193], v[42:45]
	v_mfma_f32_16x16x32_bf16 v[46:49], v[134:137], v[190:193], v[46:49]
	v_mfma_f32_16x16x32_bf16 v[30:33], v[134:137], v[198:201], v[30:33]
	v_mfma_f32_16x16x32_bf16 v[26:29], v[142:145], v[198:201], v[26:29]
	s_waitcnt lgkmcnt(0)
	v_mfma_f32_16x16x32_bf16 v[10:13], v[142:145], v[206:209], v[10:13]
	v_mfma_f32_16x16x32_bf16 v[14:17], v[134:137], v[206:209], v[14:17]
	s_setprio 0
	s_setprio 1
	v_mfma_f32_16x16x32_bf16 v[54:57], v[146:149], v[166:169], v[54:57]
	v_mfma_f32_16x16x32_bf16 v[50:53], v[154:157], v[166:169], v[50:53]
	v_mfma_f32_16x16x32_bf16 v[34:37], v[154:157], v[186:189], v[34:37]
	v_mfma_f32_16x16x32_bf16 v[38:41], v[146:149], v[186:189], v[38:41]
	v_mfma_f32_16x16x32_bf16 v[22:25], v[146:149], v[194:197], v[22:25]
	v_mfma_f32_16x16x32_bf16 v[18:21], v[154:157], v[194:197], v[18:21]
	v_mfma_f32_16x16x32_bf16 v[2:5], v[154:157], v[202:205], v[2:5]
	v_mfma_f32_16x16x32_bf16 v[6:9], v[146:149], v[202:205], v[6:9]
	v_mfma_f32_16x16x32_bf16 v[54:57], v[150:153], v[170:173], v[54:57]
	v_mfma_f32_16x16x32_bf16 v[50:53], v[158:161], v[170:173], v[50:53]
	v_mfma_f32_16x16x32_bf16 v[34:37], v[158:161], v[190:193], v[34:37]
	v_mfma_f32_16x16x32_bf16 v[38:41], v[150:153], v[190:193], v[38:41]
	v_mfma_f32_16x16x32_bf16 v[22:25], v[150:153], v[198:201], v[22:25]
	v_mfma_f32_16x16x32_bf16 v[18:21], v[158:161], v[198:201], v[18:21]
	s_setprio 2
	s_barrier
	v_mfma_f32_16x16x32_bf16 v[2:5], v[158:161], v[206:209], v[2:5]
	v_mfma_f32_16x16x32_bf16 v[6:9], v[150:153], v[206:209], v[6:9]
	s_setprio 0
	s_add_i32 s78, s78, 2
	s_add_u32 s74, s74, 0x100
	s_addc_u32 s75, s75, 0
	s_add_u32 s20, s20, 0x100
	s_addc_u32 s21, s21, 0
	s_add_u32 s76, s76, 0x100
	s_addc_u32 s77, s77, 0
	s_cmp_gt_u32 s78, 29
	.p2align 6
.LBB0_1053:
	ds_read_b128 v[130:133], v181
	ds_read_b128 v[134:137], v181 offset:1024
	ds_read_b128 v[138:141], v181 offset:2048
	ds_read_b128 v[142:145], v181 offset:3072
	ds_read_b128 v[146:149], v182
	ds_read_b128 v[150:153], v182 offset:1024
	ds_read_b128 v[154:157], v182 offset:2048
	ds_read_b128 v[158:161], v182 offset:3072
	s_cmp_eq_u32 s78, 28
	s_cselect_b32 s23, s11, s75
	s_cselect_b32 s22, s73, s74
	s_cselect_b32 s25, s13, s77
	s_cselect_b32 s24, s67, s76
	ds_read_b128 v[166:169], v183
	ds_read_b128 v[170:173], v183 offset:1024
	ds_read_b128 v[186:189], v183 offset:2048
	ds_read_b128 v[190:193], v183 offset:3072
	ds_read_b128 v[194:197], v183 offset:4096
	ds_read_b128 v[198:201], v183 offset:5120
	ds_read_b128 v[202:205], v183 offset:6144
	ds_read_b128 v[206:209], v183 offset:7168
	s_add_u32 s80, s20, 0xfff80000
	s_addc_u32 s81, s21, -1
	s_mov_b32 s79, m0
	s_mov_b32 m0, s58
	s_nop 0
	global_load_lds_dwordx4 v1, s[80:81]
	s_mov_b32 m0, s79
	s_nop 0
	s_mov_b32 s79, m0
	s_mov_b32 m0, s64
	s_nop 0
	global_load_lds_dwordx4 v177, s[80:81]
	s_mov_b32 m0, s79
	s_nop 0
	s_mov_b32 s79, m0
	s_mov_b32 m0, s59
	s_nop 0
	global_load_lds_dwordx4 v1, s[20:21]
	s_mov_b32 m0, s79
	s_nop 0
	s_mov_b32 s79, m0
	s_mov_b32 m0, s65
	s_nop 0
	global_load_lds_dwordx4 v177, s[20:21]
	s_mov_b32 m0, s79
	s_waitcnt vmcnt(8)
	s_waitcnt lgkmcnt(0)
	s_barrier
	s_setprio 1
	s_waitcnt lgkmcnt(7)
	v_mfma_f32_16x16x32_bf16 v[126:129], v[130:133], v[166:169], v[126:129]
	v_mfma_f32_16x16x32_bf16 v[122:125], v[138:141], v[166:169], v[122:125]
	s_waitcnt lgkmcnt(5)
	v_mfma_f32_16x16x32_bf16 v[114:117], v[138:141], v[186:189], v[114:117]
	v_mfma_f32_16x16x32_bf16 v[118:121], v[130:133], v[186:189], v[118:121]
	s_waitcnt lgkmcnt(3)
	v_mfma_f32_16x16x32_bf16 v[94:97], v[130:133], v[194:197], v[94:97]
	v_mfma_f32_16x16x32_bf16 v[90:93], v[138:141], v[194:197], v[90:93]
	s_waitcnt lgkmcnt(1)
	v_mfma_f32_16x16x32_bf16 v[78:81], v[138:141], v[202:205], v[78:81]
	v_mfma_f32_16x16x32_bf16 v[86:89], v[130:133], v[202:205], v[86:89]
	v_mfma_f32_16x16x32_bf16 v[126:129], v[134:137], v[170:173], v[126:129]
	v_mfma_f32_16x16x32_bf16 v[122:125], v[142:145], v[170:173], v[122:125]
	v_mfma_f32_16x16x32_bf16 v[114:117], v[142:145], v[190:193], v[114:117]
	v_mfma_f32_16x16x32_bf16 v[118:121], v[134:137], v[190:193], v[118:121]
	v_mfma_f32_16x16x32_bf16 v[94:97], v[134:137], v[198:201], v[94:97]
	v_mfma_f32_16x16x32_bf16 v[90:93], v[142:145], v[198:201], v[90:93]
	s_waitcnt lgkmcnt(0)
	v_mfma_f32_16x16x32_bf16 v[78:81], v[142:145], v[206:209], v[78:81]
	v_mfma_f32_16x16x32_bf16 v[86:89], v[134:137], v[206:209], v[86:89]
	s_setprio 0
	s_setprio 1
	v_mfma_f32_16x16x32_bf16 v[110:113], v[146:149], v[166:169], v[110:113]
	v_mfma_f32_16x16x32_bf16 v[106:109], v[154:157], v[166:169], v[106:109]
	v_mfma_f32_16x16x32_bf16 v[98:101], v[154:157], v[186:189], v[98:101]
	v_mfma_f32_16x16x32_bf16 v[102:105], v[146:149], v[186:189], v[102:105]
	v_mfma_f32_16x16x32_bf16 v[82:85], v[146:149], v[194:197], v[82:85]
	v_mfma_f32_16x16x32_bf16 v[74:77], v[154:157], v[194:197], v[74:77]
	v_mfma_f32_16x16x32_bf16 v[66:69], v[154:157], v[202:205], v[66:69]
	v_mfma_f32_16x16x32_bf16 v[70:73], v[146:149], v[202:205], v[70:73]
	v_mfma_f32_16x16x32_bf16 v[110:113], v[150:153], v[170:173], v[110:113]
	v_mfma_f32_16x16x32_bf16 v[106:109], v[158:161], v[170:173], v[106:109]
	v_mfma_f32_16x16x32_bf16 v[98:101], v[158:161], v[190:193], v[98:101]
	v_mfma_f32_16x16x32_bf16 v[102:105], v[150:153], v[190:193], v[102:105]
	v_mfma_f32_16x16x32_bf16 v[82:85], v[150:153], v[198:201], v[82:85]
	v_mfma_f32_16x16x32_bf16 v[74:77], v[158:161], v[198:201], v[74:77]
	s_setprio 2
	s_barrier
	v_mfma_f32_16x16x32_bf16 v[66:69], v[158:161], v[206:209], v[66:69]
	v_mfma_f32_16x16x32_bf16 v[70:73], v[150:153], v[206:209], v[70:73]
	s_setprio 0
	ds_read_b128 v[166:169], v183 offset:16384
	ds_read_b128 v[170:173], v183 offset:17408
	ds_read_b128 v[186:189], v183 offset:18432
	ds_read_b128 v[190:193], v183 offset:19456
	ds_read_b128 v[194:197], v183 offset:20480
	ds_read_b128 v[198:201], v183 offset:21504
	ds_read_b128 v[202:205], v183 offset:22528
	ds_read_b128 v[206:209], v183 offset:23552
	s_mov_b32 s79, m0
	s_mov_b32 m0, s35
	s_nop 0
	global_load_lds_dwordx4 v176, s[22:23]
	s_mov_b32 m0, s79
	s_add_u32 s80, s22, 0x80000
	s_mov_b32 s79, m0
	s_mov_b32 m0, s36
	s_nop 0
	global_load_lds_dwordx4 v178, s[22:23]
	s_mov_b32 m0, s79
	s_addc_u32 s81, s23, 0
	s_mov_b32 s79, m0
	s_mov_b32 m0, s37
	s_nop 0
	global_load_lds_dwordx4 v176, s[80:81]
	s_mov_b32 m0, s79
	s_nop 0
	s_mov_b32 s79, m0
	s_mov_b32 m0, s40
	s_nop 0
	global_load_lds_dwordx4 v178, s[80:81]
	s_mov_b32 m0, s79
	s_waitcnt vmcnt(4)
	s_waitcnt lgkmcnt(0)
	s_barrier
	s_setprio 1
	s_waitcnt lgkmcnt(7)
	v_mfma_f32_16x16x32_bf16 v[62:65], v[130:133], v[166:169], v[62:65]
	v_mfma_f32_16x16x32_bf16 v[58:61], v[138:141], v[166:169], v[58:61]
	s_waitcnt lgkmcnt(5)
	v_mfma_f32_16x16x32_bf16 v[42:45], v[138:141], v[186:189], v[42:45]
	v_mfma_f32_16x16x32_bf16 v[46:49], v[130:133], v[186:189], v[46:49]
	s_waitcnt lgkmcnt(3)
	v_mfma_f32_16x16x32_bf16 v[30:33], v[130:133], v[194:197], v[30:33]
	v_mfma_f32_16x16x32_bf16 v[26:29], v[138:141], v[194:197], v[26:29]
	s_waitcnt lgkmcnt(1)
	v_mfma_f32_16x16x32_bf16 v[10:13], v[138:141], v[202:205], v[10:13]
	v_mfma_f32_16x16x32_bf16 v[14:17], v[130:133], v[202:205], v[14:17]
	v_mfma_f32_16x16x32_bf16 v[62:65], v[134:137], v[170:173], v[62:65]
	v_mfma_f32_16x16x32_bf16 v[58:61], v[142:145], v[170:173], v[58:61]
	v_mfma_f32_16x16x32_bf16 v[42:45], v[142:145], v[190:193], v[42:45]
	v_mfma_f32_16x16x32_bf16 v[46:49], v[134:137], v[190:193], v[46:49]
	v_mfma_f32_16x16x32_bf16 v[30:33], v[134:137], v[198:201], v[30:33]
	v_mfma_f32_16x16x32_bf16 v[26:29], v[142:145], v[198:201], v[26:29]
	s_waitcnt lgkmcnt(0)
	v_mfma_f32_16x16x32_bf16 v[10:13], v[142:145], v[206:209], v[10:13]
	v_mfma_f32_16x16x32_bf16 v[14:17], v[134:137], v[206:209], v[14:17]
	s_setprio 0
	s_setprio 1
	v_mfma_f32_16x16x32_bf16 v[54:57], v[146:149], v[166:169], v[54:57]
	v_mfma_f32_16x16x32_bf16 v[50:53], v[154:157], v[166:169], v[50:53]
	v_mfma_f32_16x16x32_bf16 v[34:37], v[154:157], v[186:189], v[34:37]
	v_mfma_f32_16x16x32_bf16 v[38:41], v[146:149], v[186:189], v[38:41]
	v_mfma_f32_16x16x32_bf16 v[22:25], v[146:149], v[194:197], v[22:25]
	v_mfma_f32_16x16x32_bf16 v[18:21], v[154:157], v[194:197], v[18:21]
	v_mfma_f32_16x16x32_bf16 v[2:5], v[154:157], v[202:205], v[2:5]
	v_mfma_f32_16x16x32_bf16 v[6:9], v[146:149], v[202:205], v[6:9]
	v_mfma_f32_16x16x32_bf16 v[54:57], v[150:153], v[170:173], v[54:57]
	v_mfma_f32_16x16x32_bf16 v[50:53], v[158:161], v[170:173], v[50:53]
	v_mfma_f32_16x16x32_bf16 v[34:37], v[158:161], v[190:193], v[34:37]
	v_mfma_f32_16x16x32_bf16 v[38:41], v[150:153], v[190:193], v[38:41]
	v_mfma_f32_16x16x32_bf16 v[22:25], v[150:153], v[198:201], v[22:25]
	v_mfma_f32_16x16x32_bf16 v[18:21], v[158:161], v[198:201], v[18:21]
	s_setprio 2
	s_barrier
	v_mfma_f32_16x16x32_bf16 v[2:5], v[158:161], v[206:209], v[2:5]
	v_mfma_f32_16x16x32_bf16 v[6:9], v[150:153], v[206:209], v[6:9]
	s_setprio 0
	ds_read_b128 v[130:133], v184
	ds_read_b128 v[134:137], v184 offset:1024
	ds_read_b128 v[138:141], v184 offset:2048
	ds_read_b128 v[142:145], v184 offset:3072
	ds_read_b128 v[146:149], v185
	ds_read_b128 v[150:153], v185 offset:1024
	ds_read_b128 v[154:157], v185 offset:2048
	ds_read_b128 v[158:161], v185 offset:3072
	ds_read_b128 v[166:169], v183 offset:32768
	ds_read_b128 v[170:173], v183 offset:33792
	ds_read_b128 v[186:189], v183 offset:34816
	ds_read_b128 v[190:193], v183 offset:35840
	ds_read_b128 v[194:197], v183 offset:36864
	ds_read_b128 v[198:201], v183 offset:37888
	ds_read_b128 v[202:205], v183 offset:38912
	ds_read_b128 v[206:209], v183 offset:39936
	s_mov_b32 s79, m0
	s_mov_b32 m0, s34
	s_nop 0
	global_load_lds_dwordx4 v1, s[24:25]
	s_mov_b32 m0, s79
	s_nop 0
	s_mov_b32 s79, m0
	s_mov_b32 m0, s41
	s_nop 0
	global_load_lds_dwordx4 v177, s[24:25]
	s_mov_b32 m0, s79
	s_add_u32 s24, s24, 0x80000
	s_addc_u32 s25, s25, 0
	s_mov_b32 s79, m0
	s_mov_b32 m0, s42
	s_nop 0
	global_load_lds_dwordx4 v1, s[24:25]
	s_mov_b32 m0, s79
	s_nop 0
	s_mov_b32 s79, m0
	s_mov_b32 m0, s43
	s_nop 0
	global_load_lds_dwordx4 v177, s[24:25]
	s_mov_b32 m0, s79
	s_waitcnt vmcnt(8)
	s_waitcnt lgkmcnt(0)
	s_barrier
	s_setprio 1
	s_waitcnt lgkmcnt(7)
	v_mfma_f32_16x16x32_bf16 v[126:129], v[130:133], v[166:169], v[126:129]
	v_mfma_f32_16x16x32_bf16 v[122:125], v[138:141], v[166:169], v[122:125]
	s_waitcnt lgkmcnt(5)
	v_mfma_f32_16x16x32_bf16 v[114:117], v[138:141], v[186:189], v[114:117]
	v_mfma_f32_16x16x32_bf16 v[118:121], v[130:133], v[186:189], v[118:121]
	s_waitcnt lgkmcnt(3)
	v_mfma_f32_16x16x32_bf16 v[94:97], v[130:133], v[194:197], v[94:97]
	v_mfma_f32_16x16x32_bf16 v[90:93], v[138:141], v[194:197], v[90:93]
	s_waitcnt lgkmcnt(1)
	v_mfma_f32_16x16x32_bf16 v[78:81], v[138:141], v[202:205], v[78:81]
	v_mfma_f32_16x16x32_bf16 v[86:89], v[130:133], v[202:205], v[86:89]
	v_mfma_f32_16x16x32_bf16 v[126:129], v[134:137], v[170:173], v[126:129]
	v_mfma_f32_16x16x32_bf16 v[122:125], v[142:145], v[170:173], v[122:125]
	v_mfma_f32_16x16x32_bf16 v[114:117], v[142:145], v[190:193], v[114:117]
	v_mfma_f32_16x16x32_bf16 v[118:121], v[134:137], v[190:193], v[118:121]
	v_mfma_f32_16x16x32_bf16 v[94:97], v[134:137], v[198:201], v[94:97]
	v_mfma_f32_16x16x32_bf16 v[90:93], v[142:145], v[198:201], v[90:93]
	s_waitcnt lgkmcnt(0)
	v_mfma_f32_16x16x32_bf16 v[78:81], v[142:145], v[206:209], v[78:81]
	v_mfma_f32_16x16x32_bf16 v[86:89], v[134:137], v[206:209], v[86:89]
	s_setprio 0
	s_setprio 1
	v_mfma_f32_16x16x32_bf16 v[110:113], v[146:149], v[166:169], v[110:113]
	v_mfma_f32_16x16x32_bf16 v[106:109], v[154:157], v[166:169], v[106:109]
	v_mfma_f32_16x16x32_bf16 v[98:101], v[154:157], v[186:189], v[98:101]
	v_mfma_f32_16x16x32_bf16 v[102:105], v[146:149], v[186:189], v[102:105]
	v_mfma_f32_16x16x32_bf16 v[82:85], v[146:149], v[194:197], v[82:85]
	v_mfma_f32_16x16x32_bf16 v[74:77], v[154:157], v[194:197], v[74:77]
	v_mfma_f32_16x16x32_bf16 v[66:69], v[154:157], v[202:205], v[66:69]
	v_mfma_f32_16x16x32_bf16 v[70:73], v[146:149], v[202:205], v[70:73]
	v_mfma_f32_16x16x32_bf16 v[110:113], v[150:153], v[170:173], v[110:113]
	v_mfma_f32_16x16x32_bf16 v[106:109], v[158:161], v[170:173], v[106:109]
	v_mfma_f32_16x16x32_bf16 v[98:101], v[158:161], v[190:193], v[98:101]
	v_mfma_f32_16x16x32_bf16 v[102:105], v[150:153], v[190:193], v[102:105]
	v_mfma_f32_16x16x32_bf16 v[82:85], v[150:153], v[198:201], v[82:85]
	v_mfma_f32_16x16x32_bf16 v[74:77], v[158:161], v[198:201], v[74:77]
	s_setprio 2
	s_barrier
	v_mfma_f32_16x16x32_bf16 v[66:69], v[158:161], v[206:209], v[66:69]
	v_mfma_f32_16x16x32_bf16 v[70:73], v[150:153], v[206:209], v[70:73]
	s_setprio 0
	ds_read_b128 v[166:169], v183 offset:49152
	ds_read_b128 v[170:173], v183 offset:50176
	ds_read_b128 v[186:189], v183 offset:51200
	ds_read_b128 v[190:193], v183 offset:52224
	ds_read_b128 v[194:197], v183 offset:53248
	ds_read_b128 v[198:201], v183 offset:54272
	ds_read_b128 v[202:205], v183 offset:55296
	ds_read_b128 v[206:209], v183 offset:56320
	s_add_u32 s24, s22, 0x80
	s_addc_u32 s25, s23, 0
	s_mov_b32 s79, m0
	s_mov_b32 m0, s46
	s_nop 0
	global_load_lds_dwordx4 v176, s[24:25]
	s_mov_b32 m0, s79
	s_add_u32 s22, s22, 0x80080
	s_mov_b32 s79, m0
	s_mov_b32 m0, s47
	s_nop 0
	global_load_lds_dwordx4 v178, s[24:25]
	s_mov_b32 m0, s79
	s_addc_u32 s23, s23, 0
	s_mov_b32 s24, m0
	s_mov_b32 m0, s48
	s_nop 0
	global_load_lds_dwordx4 v176, s[22:23]
	s_mov_b32 m0, s24
	s_nop 0
	s_mov_b32 s24, m0
	s_mov_b32 m0, s49
	s_nop 0
	global_load_lds_dwordx4 v178, s[22:23]
	s_mov_b32 m0, s24
	s_waitcnt vmcnt(4)
	s_waitcnt lgkmcnt(0)
	s_barrier
	s_setprio 1
	s_waitcnt lgkmcnt(7)
	v_mfma_f32_16x16x32_bf16 v[62:65], v[130:133], v[166:169], v[62:65]
	v_mfma_f32_16x16x32_bf16 v[58:61], v[138:141], v[166:169], v[58:61]
	s_waitcnt lgkmcnt(5)
	v_mfma_f32_16x16x32_bf16 v[42:45], v[138:141], v[186:189], v[42:45]
	v_mfma_f32_16x16x32_bf16 v[46:49], v[130:133], v[186:189], v[46:49]
	s_waitcnt lgkmcnt(3)
	v_mfma_f32_16x16x32_bf16 v[30:33], v[130:133], v[194:197], v[30:33]
	v_mfma_f32_16x16x32_bf16 v[26:29], v[138:141], v[194:197], v[26:29]
	s_waitcnt lgkmcnt(1)
	v_mfma_f32_16x16x32_bf16 v[10:13], v[138:141], v[202:205], v[10:13]
	v_mfma_f32_16x16x32_bf16 v[14:17], v[130:133], v[202:205], v[14:17]
	v_mfma_f32_16x16x32_bf16 v[62:65], v[134:137], v[170:173], v[62:65]
	v_mfma_f32_16x16x32_bf16 v[58:61], v[142:145], v[170:173], v[58:61]
	v_mfma_f32_16x16x32_bf16 v[42:45], v[142:145], v[190:193], v[42:45]
	v_mfma_f32_16x16x32_bf16 v[46:49], v[134:137], v[190:193], v[46:49]
	v_mfma_f32_16x16x32_bf16 v[30:33], v[134:137], v[198:201], v[30:33]
	v_mfma_f32_16x16x32_bf16 v[26:29], v[142:145], v[198:201], v[26:29]
	s_waitcnt lgkmcnt(0)
	v_mfma_f32_16x16x32_bf16 v[10:13], v[142:145], v[206:209], v[10:13]
	v_mfma_f32_16x16x32_bf16 v[14:17], v[134:137], v[206:209], v[14:17]
	s_setprio 0
	s_setprio 1
	v_mfma_f32_16x16x32_bf16 v[54:57], v[146:149], v[166:169], v[54:57]
	v_mfma_f32_16x16x32_bf16 v[50:53], v[154:157], v[166:169], v[50:53]
	v_mfma_f32_16x16x32_bf16 v[34:37], v[154:157], v[186:189], v[34:37]
	v_mfma_f32_16x16x32_bf16 v[38:41], v[146:149], v[186:189], v[38:41]
	v_mfma_f32_16x16x32_bf16 v[22:25], v[146:149], v[194:197], v[22:25]
	v_mfma_f32_16x16x32_bf16 v[18:21], v[154:157], v[194:197], v[18:21]
	v_mfma_f32_16x16x32_bf16 v[2:5], v[154:157], v[202:205], v[2:5]
	v_mfma_f32_16x16x32_bf16 v[6:9], v[146:149], v[202:205], v[6:9]
	v_mfma_f32_16x16x32_bf16 v[54:57], v[150:153], v[170:173], v[54:57]
	v_mfma_f32_16x16x32_bf16 v[50:53], v[158:161], v[170:173], v[50:53]
	v_mfma_f32_16x16x32_bf16 v[34:37], v[158:161], v[190:193], v[34:37]
	v_mfma_f32_16x16x32_bf16 v[38:41], v[150:153], v[190:193], v[38:41]
	v_mfma_f32_16x16x32_bf16 v[22:25], v[150:153], v[198:201], v[22:25]
	v_mfma_f32_16x16x32_bf16 v[18:21], v[158:161], v[198:201], v[18:21]
	s_setprio 2
	s_barrier
	v_mfma_f32_16x16x32_bf16 v[2:5], v[158:161], v[206:209], v[2:5]
	v_mfma_f32_16x16x32_bf16 v[6:9], v[150:153], v[206:209], v[6:9]
	s_setprio 0
	s_add_i32 s78, s78, 2
	s_add_u32 s74, s74, 0x100
	s_addc_u32 s75, s75, 0
	s_add_u32 s20, s20, 0x100
	s_addc_u32 s21, s21, 0
	s_add_u32 s76, s76, 0x100
	s_addc_u32 s77, s77, 0
	s_cmp_gt_u32 s78, 29
	s_cbranch_scc0 .LBB0_1053
	s_and_b64 vcc, exec, s[8:9]
	s_cbranch_vccz .LBB0_1056
	s_barrier

.LBB0_1223:
	s_ashr_i32 s11, s10, 31
	s_lshl_b64 s[12:13], s[10:11], 20
	s_add_u32 s12, s26, s12
	s_addc_u32 s13, s27, s13
	s_and_b64 s[14:15], s[2:3], exec
	s_cselect_b32 s11, s13, s21
	s_cselect_b32 s66, s12, s20
	s_ashr_i32 s9, s8, 31
	s_lshl_b64 s[14:15], s[8:9], 20
	s_add_u32 s14, s28, s14
	s_addc_u32 s15, s29, s15
	s_and_b64 s[22:23], s[2:3], exec
	s_cselect_b32 s9, s15, s19
	s_cselect_b32 s67, s14, s18
	s_add_u32 s73, s18, 0x100
	s_addc_u32 s74, s19, 0
	s_add_u32 s18, s20, 0x80080
	s_addc_u32 s19, s21, 0
	s_add_u32 s75, s20, 0x100
	s_addc_u32 s76, s21, 0
	s_mov_b32 s77, -2
	ds_read_b128 v[148:151], v143
	ds_read_b128 v[152:155], v143 offset:1024
	ds_read_b128 v[156:159], v143 offset:2048
	ds_read_b128 v[160:163], v143 offset:3072
	ds_read_b128 v[164:167], v144
	ds_read_b128 v[168:171], v144 offset:1024
	ds_read_b128 v[172:175], v144 offset:2048
	ds_read_b128 v[176:179], v144 offset:3072
	s_cmp_eq_u32 s77, 28
	s_cselect_b32 s21, s9, s74
	s_cselect_b32 s20, s67, s73
	s_cselect_b32 s23, s11, s76
	s_cselect_b32 s22, s66, s75
	ds_read_b128 v[180:183], v145
	ds_read_b128 v[184:187], v145 offset:1024
	ds_read_b128 v[188:191], v145 offset:2048
	ds_read_b128 v[192:195], v145 offset:3072
	ds_read_b128 v[196:199], v145 offset:4096
	ds_read_b128 v[200:203], v145 offset:5120
	ds_read_b128 v[204:207], v145 offset:6144
	ds_read_b128 v[208:211], v145 offset:7168
	s_add_u32 s78, s18, 0xfff80000
	s_addc_u32 s79, s19, -1
	s_mov_b32 s80, m0
	s_mov_b32 m0, s56
	s_nop 0
	global_load_lds_dwordx4 v138, s[78:79]
	s_mov_b32 m0, s80
	s_nop 0
	s_mov_b32 s80, m0
	s_mov_b32 m0, s59
	s_nop 0
	global_load_lds_dwordx4 v140, s[78:79]
	s_mov_b32 m0, s80
	s_mov_b32 s78, m0
	s_mov_b32 m0, s57
	s_nop 0
	global_load_lds_dwordx4 v138, s[18:19]
	s_mov_b32 m0, s78
	s_nop 0
	s_mov_b32 s78, m0
	s_mov_b32 m0, s64
	s_nop 0
	global_load_lds_dwordx4 v140, s[18:19]
	s_mov_b32 m0, s78
	s_waitcnt vmcnt(8)
	s_waitcnt lgkmcnt(0)
	s_barrier
	s_setprio 1
	s_waitcnt lgkmcnt(7)
	v_mfma_f32_16x16x32_bf16 v[126:129], v[148:151], v[180:183], 0
	v_mfma_f32_16x16x32_bf16 v[122:125], v[156:159], v[180:183], 0
	s_waitcnt lgkmcnt(5)
	v_mfma_f32_16x16x32_bf16 v[106:109], v[156:159], v[188:191], 0
	v_mfma_f32_16x16x32_bf16 v[110:113], v[148:151], v[188:191], 0
	s_waitcnt lgkmcnt(3)
	v_mfma_f32_16x16x32_bf16 v[94:97], v[148:151], v[196:199], 0
	v_mfma_f32_16x16x32_bf16 v[90:93], v[156:159], v[196:199], 0
	s_waitcnt lgkmcnt(1)
	v_mfma_f32_16x16x32_bf16 v[74:77], v[156:159], v[204:207], 0
	v_mfma_f32_16x16x32_bf16 v[78:81], v[148:151], v[204:207], 0
	v_mfma_f32_16x16x32_bf16 v[126:129], v[152:155], v[184:187], v[126:129]
	v_mfma_f32_16x16x32_bf16 v[122:125], v[160:163], v[184:187], v[122:125]
	v_mfma_f32_16x16x32_bf16 v[106:109], v[160:163], v[192:195], v[106:109]
	v_mfma_f32_16x16x32_bf16 v[110:113], v[152:155], v[192:195], v[110:113]
	v_mfma_f32_16x16x32_bf16 v[94:97], v[152:155], v[200:203], v[94:97]
	v_mfma_f32_16x16x32_bf16 v[90:93], v[160:163], v[200:203], v[90:93]
	s_waitcnt lgkmcnt(0)
	v_mfma_f32_16x16x32_bf16 v[74:77], v[160:163], v[208:211], v[74:77]
	v_mfma_f32_16x16x32_bf16 v[78:81], v[152:155], v[208:211], v[78:81]
	s_setprio 0
	s_setprio 1
	v_mfma_f32_16x16x32_bf16 v[118:121], v[164:167], v[180:183], 0
	v_mfma_f32_16x16x32_bf16 v[114:117], v[172:175], v[180:183], 0
	v_mfma_f32_16x16x32_bf16 v[98:101], v[172:175], v[188:191], 0
	v_mfma_f32_16x16x32_bf16 v[102:105], v[164:167], v[188:191], 0
	v_mfma_f32_16x16x32_bf16 v[86:89], v[164:167], v[196:199], 0
	v_mfma_f32_16x16x32_bf16 v[82:85], v[172:175], v[196:199], 0
	v_mfma_f32_16x16x32_bf16 v[66:69], v[172:175], v[204:207], 0
	v_mfma_f32_16x16x32_bf16 v[70:73], v[164:167], v[204:207], 0
	v_mfma_f32_16x16x32_bf16 v[118:121], v[168:171], v[184:187], v[118:121]
	v_mfma_f32_16x16x32_bf16 v[114:117], v[176:179], v[184:187], v[114:117]
	v_mfma_f32_16x16x32_bf16 v[98:101], v[176:179], v[192:195], v[98:101]
	v_mfma_f32_16x16x32_bf16 v[102:105], v[168:171], v[192:195], v[102:105]
	v_mfma_f32_16x16x32_bf16 v[86:89], v[168:171], v[200:203], v[86:89]
	v_mfma_f32_16x16x32_bf16 v[82:85], v[176:179], v[200:203], v[82:85]
	s_setprio 2
	s_barrier
	v_mfma_f32_16x16x32_bf16 v[66:69], v[176:179], v[208:211], v[66:69]
	v_mfma_f32_16x16x32_bf16 v[70:73], v[168:171], v[208:211], v[70:73]
	s_setprio 0
	ds_read_b128 v[180:183], v145 offset:16384
	ds_read_b128 v[184:187], v145 offset:17408
	ds_read_b128 v[188:191], v145 offset:18432
	ds_read_b128 v[192:195], v145 offset:19456
	ds_read_b128 v[196:199], v145 offset:20480
	ds_read_b128 v[200:203], v145 offset:21504
	ds_read_b128 v[204:207], v145 offset:22528
	ds_read_b128 v[208:211], v145 offset:23552
	s_mov_b32 s78, m0
	s_mov_b32 m0, s35
	s_nop 0
	global_load_lds_dwordx4 v139, s[20:21]
	s_mov_b32 m0, s78
	s_nop 0
	s_mov_b32 s78, m0
	s_mov_b32 m0, s36
	s_nop 0
	global_load_lds_dwordx4 v141, s[20:21]
	s_mov_b32 m0, s78
	s_add_u32 s78, s20, 0x80000
	s_addc_u32 s79, s21, 0
	s_mov_b32 s80, m0
	s_mov_b32 m0, s37
	s_nop 0
	global_load_lds_dwordx4 v139, s[78:79]
	s_mov_b32 m0, s80
	s_nop 0
	s_mov_b32 s80, m0
	s_mov_b32 m0, s40
	s_nop 0
	global_load_lds_dwordx4 v141, s[78:79]
	s_mov_b32 m0, s80
	s_waitcnt vmcnt(4)
	s_waitcnt lgkmcnt(0)
	s_barrier
	s_setprio 1
	s_waitcnt lgkmcnt(7)
	v_mfma_f32_16x16x32_bf16 v[62:65], v[148:151], v[180:183], 0
	v_mfma_f32_16x16x32_bf16 v[58:61], v[156:159], v[180:183], 0
	s_waitcnt lgkmcnt(5)
	v_mfma_f32_16x16x32_bf16 v[42:45], v[156:159], v[188:191], 0
	v_mfma_f32_16x16x32_bf16 v[46:49], v[148:151], v[188:191], 0
	s_waitcnt lgkmcnt(3)
	v_mfma_f32_16x16x32_bf16 v[30:33], v[148:151], v[196:199], 0
	v_mfma_f32_16x16x32_bf16 v[26:29], v[156:159], v[196:199], 0
	s_waitcnt lgkmcnt(1)
	v_mfma_f32_16x16x32_bf16 v[10:13], v[156:159], v[204:207], 0
	v_mfma_f32_16x16x32_bf16 v[14:17], v[148:151], v[204:207], 0
	v_mfma_f32_16x16x32_bf16 v[62:65], v[152:155], v[184:187], v[62:65]
	v_mfma_f32_16x16x32_bf16 v[58:61], v[160:163], v[184:187], v[58:61]
	v_mfma_f32_16x16x32_bf16 v[42:45], v[160:163], v[192:195], v[42:45]
	v_mfma_f32_16x16x32_bf16 v[46:49], v[152:155], v[192:195], v[46:49]
	v_mfma_f32_16x16x32_bf16 v[30:33], v[152:155], v[200:203], v[30:33]
	v_mfma_f32_16x16x32_bf16 v[26:29], v[160:163], v[200:203], v[26:29]
	s_waitcnt lgkmcnt(0)
	v_mfma_f32_16x16x32_bf16 v[10:13], v[160:163], v[208:211], v[10:13]
	v_mfma_f32_16x16x32_bf16 v[14:17], v[152:155], v[208:211], v[14:17]
	s_setprio 0
	s_setprio 1
	v_mfma_f32_16x16x32_bf16 v[54:57], v[164:167], v[180:183], 0
	v_mfma_f32_16x16x32_bf16 v[50:53], v[172:175], v[180:183], 0
	v_mfma_f32_16x16x32_bf16 v[34:37], v[172:175], v[188:191], 0
	v_mfma_f32_16x16x32_bf16 v[38:41], v[164:167], v[188:191], 0
	v_mfma_f32_16x16x32_bf16 v[22:25], v[164:167], v[196:199], 0
	v_mfma_f32_16x16x32_bf16 v[18:21], v[172:175], v[196:199], 0
	v_mfma_f32_16x16x32_bf16 v[2:5], v[172:175], v[204:207], 0
	v_mfma_f32_16x16x32_bf16 v[6:9], v[164:167], v[204:207], 0
	v_mfma_f32_16x16x32_bf16 v[54:57], v[168:171], v[184:187], v[54:57]
	v_mfma_f32_16x16x32_bf16 v[50:53], v[176:179], v[184:187], v[50:53]
	v_mfma_f32_16x16x32_bf16 v[34:37], v[176:179], v[192:195], v[34:37]
	v_mfma_f32_16x16x32_bf16 v[38:41], v[168:171], v[192:195], v[38:41]
	v_mfma_f32_16x16x32_bf16 v[22:25], v[168:171], v[200:203], v[22:25]
	v_mfma_f32_16x16x32_bf16 v[18:21], v[176:179], v[200:203], v[18:21]
	s_setprio 2
	s_barrier
	v_mfma_f32_16x16x32_bf16 v[2:5], v[176:179], v[208:211], v[2:5]
	v_mfma_f32_16x16x32_bf16 v[6:9], v[168:171], v[208:211], v[6:9]
	s_setprio 0
	ds_read_b128 v[148:151], v146
	ds_read_b128 v[152:155], v146 offset:1024
	ds_read_b128 v[156:159], v146 offset:2048
	ds_read_b128 v[160:163], v146 offset:3072
	ds_read_b128 v[164:167], v147
	ds_read_b128 v[168:171], v147 offset:1024
	ds_read_b128 v[172:175], v147 offset:2048
	ds_read_b128 v[176:179], v147 offset:3072
	ds_read_b128 v[180:183], v145 offset:32768
	ds_read_b128 v[184:187], v145 offset:33792
	ds_read_b128 v[188:191], v145 offset:34816
	ds_read_b128 v[192:195], v145 offset:35840
	ds_read_b128 v[196:199], v145 offset:36864
	ds_read_b128 v[200:203], v145 offset:37888
	ds_read_b128 v[204:207], v145 offset:38912
	ds_read_b128 v[208:211], v145 offset:39936
	s_mov_b32 s78, m0
	s_mov_b32 m0, s31
	s_nop 0
	global_load_lds_dwordx4 v138, s[22:23]
	s_mov_b32 m0, s78
	s_nop 0
	s_mov_b32 s78, m0
	s_mov_b32 m0, s41
	s_nop 0
	global_load_lds_dwordx4 v140, s[22:23]
	s_mov_b32 m0, s78
	s_add_u32 s22, s22, 0x80000
	s_addc_u32 s23, s23, 0
	s_mov_b32 s78, m0
	s_mov_b32 m0, s42
	s_nop 0
	global_load_lds_dwordx4 v138, s[22:23]
	s_mov_b32 m0, s78
	s_nop 0
	s_mov_b32 s78, m0
	s_mov_b32 m0, s43
	s_nop 0
	global_load_lds_dwordx4 v140, s[22:23]
	s_mov_b32 m0, s78
	s_waitcnt vmcnt(8)
	s_waitcnt lgkmcnt(0)
	s_barrier
	s_setprio 1
	s_waitcnt lgkmcnt(7)
	v_mfma_f32_16x16x32_bf16 v[126:129], v[148:151], v[180:183], v[126:129]
	v_mfma_f32_16x16x32_bf16 v[122:125], v[156:159], v[180:183], v[122:125]
	s_waitcnt lgkmcnt(5)
	v_mfma_f32_16x16x32_bf16 v[106:109], v[156:159], v[188:191], v[106:109]
	v_mfma_f32_16x16x32_bf16 v[110:113], v[148:151], v[188:191], v[110:113]
	s_waitcnt lgkmcnt(3)
	v_mfma_f32_16x16x32_bf16 v[94:97], v[148:151], v[196:199], v[94:97]
	v_mfma_f32_16x16x32_bf16 v[90:93], v[156:159], v[196:199], v[90:93]
	s_waitcnt lgkmcnt(1)
	v_mfma_f32_16x16x32_bf16 v[74:77], v[156:159], v[204:207], v[74:77]
	v_mfma_f32_16x16x32_bf16 v[78:81], v[148:151], v[204:207], v[78:81]
	v_mfma_f32_16x16x32_bf16 v[126:129], v[152:155], v[184:187], v[126:129]
	v_mfma_f32_16x16x32_bf16 v[122:125], v[160:163], v[184:187], v[122:125]
	v_mfma_f32_16x16x32_bf16 v[106:109], v[160:163], v[192:195], v[106:109]
	v_mfma_f32_16x16x32_bf16 v[110:113], v[152:155], v[192:195], v[110:113]
	v_mfma_f32_16x16x32_bf16 v[94:97], v[152:155], v[200:203], v[94:97]
	v_mfma_f32_16x16x32_bf16 v[90:93], v[160:163], v[200:203], v[90:93]
	s_waitcnt lgkmcnt(0)
	v_mfma_f32_16x16x32_bf16 v[74:77], v[160:163], v[208:211], v[74:77]
	v_mfma_f32_16x16x32_bf16 v[78:81], v[152:155], v[208:211], v[78:81]
	s_setprio 0
	s_setprio 1
	v_mfma_f32_16x16x32_bf16 v[118:121], v[164:167], v[180:183], v[118:121]
	v_mfma_f32_16x16x32_bf16 v[114:117], v[172:175], v[180:183], v[114:117]
	v_mfma_f32_16x16x32_bf16 v[98:101], v[172:175], v[188:191], v[98:101]
	v_mfma_f32_16x16x32_bf16 v[102:105], v[164:167], v[188:191], v[102:105]
	v_mfma_f32_16x16x32_bf16 v[86:89], v[164:167], v[196:199], v[86:89]
	v_mfma_f32_16x16x32_bf16 v[82:85], v[172:175], v[196:199], v[82:85]
	v_mfma_f32_16x16x32_bf16 v[66:69], v[172:175], v[204:207], v[66:69]
	v_mfma_f32_16x16x32_bf16 v[70:73], v[164:167], v[204:207], v[70:73]
	v_mfma_f32_16x16x32_bf16 v[118:121], v[168:171], v[184:187], v[118:121]
	v_mfma_f32_16x16x32_bf16 v[114:117], v[176:179], v[184:187], v[114:117]
	v_mfma_f32_16x16x32_bf16 v[98:101], v[176:179], v[192:195], v[98:101]
	v_mfma_f32_16x16x32_bf16 v[102:105], v[168:171], v[192:195], v[102:105]
	v_mfma_f32_16x16x32_bf16 v[86:89], v[168:171], v[200:203], v[86:89]
	v_mfma_f32_16x16x32_bf16 v[82:85], v[176:179], v[200:203], v[82:85]
	s_setprio 2
	s_barrier
	v_mfma_f32_16x16x32_bf16 v[66:69], v[176:179], v[208:211], v[66:69]
	v_mfma_f32_16x16x32_bf16 v[70:73], v[168:171], v[208:211], v[70:73]
	s_setprio 0
	ds_read_b128 v[180:183], v145 offset:49152
	ds_read_b128 v[184:187], v145 offset:50176
	ds_read_b128 v[188:191], v145 offset:51200
	ds_read_b128 v[192:195], v145 offset:52224
	ds_read_b128 v[196:199], v145 offset:53248
	ds_read_b128 v[200:203], v145 offset:54272
	ds_read_b128 v[204:207], v145 offset:55296
	ds_read_b128 v[208:211], v145 offset:56320
	s_add_u32 s22, s20, 0x80
	s_addc_u32 s23, s21, 0
	s_mov_b32 s78, m0
	s_mov_b32 m0, s46
	s_nop 0
	global_load_lds_dwordx4 v139, s[22:23]
	s_mov_b32 m0, s78
	s_add_u32 s20, s20, 0x80080
	s_mov_b32 s78, m0
	s_mov_b32 m0, s47
	s_nop 0
	global_load_lds_dwordx4 v141, s[22:23]
	s_mov_b32 m0, s78
	s_addc_u32 s21, s21, 0
	s_mov_b32 s22, m0
	s_mov_b32 m0, s48
	s_nop 0
	global_load_lds_dwordx4 v139, s[20:21]
	s_mov_b32 m0, s22
	s_nop 0
	s_mov_b32 s22, m0
	s_mov_b32 m0, s49
	s_nop 0
	global_load_lds_dwordx4 v141, s[20:21]
	s_mov_b32 m0, s22
	s_waitcnt vmcnt(4)
	s_waitcnt lgkmcnt(0)
	s_barrier
	s_setprio 1
	s_waitcnt lgkmcnt(7)
	v_mfma_f32_16x16x32_bf16 v[62:65], v[148:151], v[180:183], v[62:65]
	v_mfma_f32_16x16x32_bf16 v[58:61], v[156:159], v[180:183], v[58:61]
	s_waitcnt lgkmcnt(5)
	v_mfma_f32_16x16x32_bf16 v[42:45], v[156:159], v[188:191], v[42:45]
	v_mfma_f32_16x16x32_bf16 v[46:49], v[148:151], v[188:191], v[46:49]
	s_waitcnt lgkmcnt(3)
	v_mfma_f32_16x16x32_bf16 v[30:33], v[148:151], v[196:199], v[30:33]
	v_mfma_f32_16x16x32_bf16 v[26:29], v[156:159], v[196:199], v[26:29]
	s_waitcnt lgkmcnt(1)
	v_mfma_f32_16x16x32_bf16 v[10:13], v[156:159], v[204:207], v[10:13]
	v_mfma_f32_16x16x32_bf16 v[14:17], v[148:151], v[204:207], v[14:17]
	v_mfma_f32_16x16x32_bf16 v[62:65], v[152:155], v[184:187], v[62:65]
	v_mfma_f32_16x16x32_bf16 v[58:61], v[160:163], v[184:187], v[58:61]
	v_mfma_f32_16x16x32_bf16 v[42:45], v[160:163], v[192:195], v[42:45]
	v_mfma_f32_16x16x32_bf16 v[46:49], v[152:155], v[192:195], v[46:49]
	v_mfma_f32_16x16x32_bf16 v[30:33], v[152:155], v[200:203], v[30:33]
	v_mfma_f32_16x16x32_bf16 v[26:29], v[160:163], v[200:203], v[26:29]
	s_waitcnt lgkmcnt(0)
	v_mfma_f32_16x16x32_bf16 v[10:13], v[160:163], v[208:211], v[10:13]
	v_mfma_f32_16x16x32_bf16 v[14:17], v[152:155], v[208:211], v[14:17]
	s_setprio 0
	s_setprio 1
	v_mfma_f32_16x16x32_bf16 v[54:57], v[164:167], v[180:183], v[54:57]
	v_mfma_f32_16x16x32_bf16 v[50:53], v[172:175], v[180:183], v[50:53]
	v_mfma_f32_16x16x32_bf16 v[34:37], v[172:175], v[188:191], v[34:37]
	v_mfma_f32_16x16x32_bf16 v[38:41], v[164:167], v[188:191], v[38:41]
	v_mfma_f32_16x16x32_bf16 v[22:25], v[164:167], v[196:199], v[22:25]
	v_mfma_f32_16x16x32_bf16 v[18:21], v[172:175], v[196:199], v[18:21]
	v_mfma_f32_16x16x32_bf16 v[2:5], v[172:175], v[204:207], v[2:5]
	v_mfma_f32_16x16x32_bf16 v[6:9], v[164:167], v[204:207], v[6:9]
	v_mfma_f32_16x16x32_bf16 v[54:57], v[168:171], v[184:187], v[54:57]
	v_mfma_f32_16x16x32_bf16 v[50:53], v[176:179], v[184:187], v[50:53]
	v_mfma_f32_16x16x32_bf16 v[34:37], v[176:179], v[192:195], v[34:37]
	v_mfma_f32_16x16x32_bf16 v[38:41], v[168:171], v[192:195], v[38:41]
	v_mfma_f32_16x16x32_bf16 v[22:25], v[168:171], v[200:203], v[22:25]
	v_mfma_f32_16x16x32_bf16 v[18:21], v[176:179], v[200:203], v[18:21]
	s_setprio 2
	s_barrier
	v_mfma_f32_16x16x32_bf16 v[2:5], v[176:179], v[208:211], v[2:5]
	v_mfma_f32_16x16x32_bf16 v[6:9], v[168:171], v[208:211], v[6:9]
	s_setprio 0
	s_add_i32 s77, s77, 2
	s_add_u32 s73, s73, 0x100
	s_addc_u32 s74, s74, 0
	s_add_u32 s18, s18, 0x100
	s_addc_u32 s19, s19, 0
	s_add_u32 s75, s75, 0x100
	s_addc_u32 s76, s76, 0
	s_cmp_gt_u32 s77, 29
	.p2align 6
.LBB0_1224:
	ds_read_b128 v[148:151], v143
	ds_read_b128 v[152:155], v143 offset:1024
	ds_read_b128 v[156:159], v143 offset:2048
	ds_read_b128 v[160:163], v143 offset:3072
	ds_read_b128 v[164:167], v144
	ds_read_b128 v[168:171], v144 offset:1024
	ds_read_b128 v[172:175], v144 offset:2048
	ds_read_b128 v[176:179], v144 offset:3072
	s_cmp_eq_u32 s77, 28
	s_cselect_b32 s21, s9, s74
	s_cselect_b32 s20, s67, s73
	s_cselect_b32 s23, s11, s76
	s_cselect_b32 s22, s66, s75
	ds_read_b128 v[180:183], v145
	ds_read_b128 v[184:187], v145 offset:1024
	ds_read_b128 v[188:191], v145 offset:2048
	ds_read_b128 v[192:195], v145 offset:3072
	ds_read_b128 v[196:199], v145 offset:4096
	ds_read_b128 v[200:203], v145 offset:5120
	ds_read_b128 v[204:207], v145 offset:6144
	ds_read_b128 v[208:211], v145 offset:7168
	s_add_u32 s78, s18, 0xfff80000
	s_addc_u32 s79, s19, -1
	s_mov_b32 s80, m0
	s_mov_b32 m0, s56
	s_nop 0
	global_load_lds_dwordx4 v138, s[78:79]
	s_mov_b32 m0, s80
	s_nop 0
	s_mov_b32 s80, m0
	s_mov_b32 m0, s59
	s_nop 0
	global_load_lds_dwordx4 v140, s[78:79]
	s_mov_b32 m0, s80
	s_mov_b32 s78, m0
	s_mov_b32 m0, s57
	s_nop 0
	global_load_lds_dwordx4 v138, s[18:19]
	s_mov_b32 m0, s78
	s_nop 0
	s_mov_b32 s78, m0
	s_mov_b32 m0, s64
	s_nop 0
	global_load_lds_dwordx4 v140, s[18:19]
	s_mov_b32 m0, s78
	s_waitcnt vmcnt(8)
	s_waitcnt lgkmcnt(0)
	s_barrier
	s_setprio 1
	s_waitcnt lgkmcnt(7)
	v_mfma_f32_16x16x32_bf16 v[126:129], v[148:151], v[180:183], v[126:129]
	v_mfma_f32_16x16x32_bf16 v[122:125], v[156:159], v[180:183], v[122:125]
	s_waitcnt lgkmcnt(5)
	v_mfma_f32_16x16x32_bf16 v[106:109], v[156:159], v[188:191], v[106:109]
	v_mfma_f32_16x16x32_bf16 v[110:113], v[148:151], v[188:191], v[110:113]
	s_waitcnt lgkmcnt(3)
	v_mfma_f32_16x16x32_bf16 v[94:97], v[148:151], v[196:199], v[94:97]
	v_mfma_f32_16x16x32_bf16 v[90:93], v[156:159], v[196:199], v[90:93]
	s_waitcnt lgkmcnt(1)
	v_mfma_f32_16x16x32_bf16 v[74:77], v[156:159], v[204:207], v[74:77]
	v_mfma_f32_16x16x32_bf16 v[78:81], v[148:151], v[204:207], v[78:81]
	v_mfma_f32_16x16x32_bf16 v[126:129], v[152:155], v[184:187], v[126:129]
	v_mfma_f32_16x16x32_bf16 v[122:125], v[160:163], v[184:187], v[122:125]
	v_mfma_f32_16x16x32_bf16 v[106:109], v[160:163], v[192:195], v[106:109]
	v_mfma_f32_16x16x32_bf16 v[110:113], v[152:155], v[192:195], v[110:113]
	v_mfma_f32_16x16x32_bf16 v[94:97], v[152:155], v[200:203], v[94:97]
	v_mfma_f32_16x16x32_bf16 v[90:93], v[160:163], v[200:203], v[90:93]
	s_waitcnt lgkmcnt(0)
	v_mfma_f32_16x16x32_bf16 v[74:77], v[160:163], v[208:211], v[74:77]
	v_mfma_f32_16x16x32_bf16 v[78:81], v[152:155], v[208:211], v[78:81]
	s_setprio 0
	s_setprio 1
	v_mfma_f32_16x16x32_bf16 v[118:121], v[164:167], v[180:183], v[118:121]
	v_mfma_f32_16x16x32_bf16 v[114:117], v[172:175], v[180:183], v[114:117]
	v_mfma_f32_16x16x32_bf16 v[98:101], v[172:175], v[188:191], v[98:101]
	v_mfma_f32_16x16x32_bf16 v[102:105], v[164:167], v[188:191], v[102:105]
	v_mfma_f32_16x16x32_bf16 v[86:89], v[164:167], v[196:199], v[86:89]
	v_mfma_f32_16x16x32_bf16 v[82:85], v[172:175], v[196:199], v[82:85]
	v_mfma_f32_16x16x32_bf16 v[66:69], v[172:175], v[204:207], v[66:69]
	v_mfma_f32_16x16x32_bf16 v[70:73], v[164:167], v[204:207], v[70:73]
	v_mfma_f32_16x16x32_bf16 v[118:121], v[168:171], v[184:187], v[118:121]
	v_mfma_f32_16x16x32_bf16 v[114:117], v[176:179], v[184:187], v[114:117]
	v_mfma_f32_16x16x32_bf16 v[98:101], v[176:179], v[192:195], v[98:101]
	v_mfma_f32_16x16x32_bf16 v[102:105], v[168:171], v[192:195], v[102:105]
	v_mfma_f32_16x16x32_bf16 v[86:89], v[168:171], v[200:203], v[86:89]
	v_mfma_f32_16x16x32_bf16 v[82:85], v[176:179], v[200:203], v[82:85]
	s_setprio 2
	s_barrier
	v_mfma_f32_16x16x32_bf16 v[66:69], v[176:179], v[208:211], v[66:69]
	v_mfma_f32_16x16x32_bf16 v[70:73], v[168:171], v[208:211], v[70:73]
	s_setprio 0
	ds_read_b128 v[180:183], v145 offset:16384
	ds_read_b128 v[184:187], v145 offset:17408
	ds_read_b128 v[188:191], v145 offset:18432
	ds_read_b128 v[192:195], v145 offset:19456
	ds_read_b128 v[196:199], v145 offset:20480
	ds_read_b128 v[200:203], v145 offset:21504
	ds_read_b128 v[204:207], v145 offset:22528
	ds_read_b128 v[208:211], v145 offset:23552
	s_mov_b32 s78, m0
	s_mov_b32 m0, s35
	s_nop 0
	global_load_lds_dwordx4 v139, s[20:21]
	s_mov_b32 m0, s78
	s_nop 0
	s_mov_b32 s78, m0
	s_mov_b32 m0, s36
	s_nop 0
	global_load_lds_dwordx4 v141, s[20:21]
	s_mov_b32 m0, s78
	s_add_u32 s78, s20, 0x80000
	s_addc_u32 s79, s21, 0
	s_mov_b32 s80, m0
	s_mov_b32 m0, s37
	s_nop 0
	global_load_lds_dwordx4 v139, s[78:79]
	s_mov_b32 m0, s80
	s_nop 0
	s_mov_b32 s80, m0
	s_mov_b32 m0, s40
	s_nop 0
	global_load_lds_dwordx4 v141, s[78:79]
	s_mov_b32 m0, s80
	s_waitcnt vmcnt(4)
	s_waitcnt lgkmcnt(0)
	s_barrier
	s_setprio 1
	s_waitcnt lgkmcnt(7)
	v_mfma_f32_16x16x32_bf16 v[62:65], v[148:151], v[180:183], v[62:65]
	v_mfma_f32_16x16x32_bf16 v[58:61], v[156:159], v[180:183], v[58:61]
	s_waitcnt lgkmcnt(5)
	v_mfma_f32_16x16x32_bf16 v[42:45], v[156:159], v[188:191], v[42:45]
	v_mfma_f32_16x16x32_bf16 v[46:49], v[148:151], v[188:191], v[46:49]
	s_waitcnt lgkmcnt(3)
	v_mfma_f32_16x16x32_bf16 v[30:33], v[148:151], v[196:199], v[30:33]
	v_mfma_f32_16x16x32_bf16 v[26:29], v[156:159], v[196:199], v[26:29]
	s_waitcnt lgkmcnt(1)
	v_mfma_f32_16x16x32_bf16 v[10:13], v[156:159], v[204:207], v[10:13]
	v_mfma_f32_16x16x32_bf16 v[14:17], v[148:151], v[204:207], v[14:17]
	v_mfma_f32_16x16x32_bf16 v[62:65], v[152:155], v[184:187], v[62:65]
	v_mfma_f32_16x16x32_bf16 v[58:61], v[160:163], v[184:187], v[58:61]
	v_mfma_f32_16x16x32_bf16 v[42:45], v[160:163], v[192:195], v[42:45]
	v_mfma_f32_16x16x32_bf16 v[46:49], v[152:155], v[192:195], v[46:49]
	v_mfma_f32_16x16x32_bf16 v[30:33], v[152:155], v[200:203], v[30:33]
	v_mfma_f32_16x16x32_bf16 v[26:29], v[160:163], v[200:203], v[26:29]
	s_waitcnt lgkmcnt(0)
	v_mfma_f32_16x16x32_bf16 v[10:13], v[160:163], v[208:211], v[10:13]
	v_mfma_f32_16x16x32_bf16 v[14:17], v[152:155], v[208:211], v[14:17]
	s_setprio 0
	s_setprio 1
	v_mfma_f32_16x16x32_bf16 v[54:57], v[164:167], v[180:183], v[54:57]
	v_mfma_f32_16x16x32_bf16 v[50:53], v[172:175], v[180:183], v[50:53]
	v_mfma_f32_16x16x32_bf16 v[34:37], v[172:175], v[188:191], v[34:37]
	v_mfma_f32_16x16x32_bf16 v[38:41], v[164:167], v[188:191], v[38:41]
	v_mfma_f32_16x16x32_bf16 v[22:25], v[164:167], v[196:199], v[22:25]
	v_mfma_f32_16x16x32_bf16 v[18:21], v[172:175], v[196:199], v[18:21]
	v_mfma_f32_16x16x32_bf16 v[2:5], v[172:175], v[204:207], v[2:5]
	v_mfma_f32_16x16x32_bf16 v[6:9], v[164:167], v[204:207], v[6:9]
	v_mfma_f32_16x16x32_bf16 v[54:57], v[168:171], v[184:187], v[54:57]
	v_mfma_f32_16x16x32_bf16 v[50:53], v[176:179], v[184:187], v[50:53]
	v_mfma_f32_16x16x32_bf16 v[34:37], v[176:179], v[192:195], v[34:37]
	v_mfma_f32_16x16x32_bf16 v[38:41], v[168:171], v[192:195], v[38:41]
	v_mfma_f32_16x16x32_bf16 v[22:25], v[168:171], v[200:203], v[22:25]
	v_mfma_f32_16x16x32_bf16 v[18:21], v[176:179], v[200:203], v[18:21]
	s_setprio 2
	s_barrier
	v_mfma_f32_16x16x32_bf16 v[2:5], v[176:179], v[208:211], v[2:5]
	v_mfma_f32_16x16x32_bf16 v[6:9], v[168:171], v[208:211], v[6:9]
	s_setprio 0
	ds_read_b128 v[148:151], v146
	ds_read_b128 v[152:155], v146 offset:1024
	ds_read_b128 v[156:159], v146 offset:2048
	ds_read_b128 v[160:163], v146 offset:3072
	ds_read_b128 v[164:167], v147
	ds_read_b128 v[168:171], v147 offset:1024
	ds_read_b128 v[172:175], v147 offset:2048
	ds_read_b128 v[176:179], v147 offset:3072
	ds_read_b128 v[180:183], v145 offset:32768
	ds_read_b128 v[184:187], v145 offset:33792
	ds_read_b128 v[188:191], v145 offset:34816
	ds_read_b128 v[192:195], v145 offset:35840
	ds_read_b128 v[196:199], v145 offset:36864
	ds_read_b128 v[200:203], v145 offset:37888
	ds_read_b128 v[204:207], v145 offset:38912
	ds_read_b128 v[208:211], v145 offset:39936
	s_mov_b32 s78, m0
	s_mov_b32 m0, s31
	s_nop 0
	global_load_lds_dwordx4 v138, s[22:23]
	s_mov_b32 m0, s78
	s_nop 0
	s_mov_b32 s78, m0
	s_mov_b32 m0, s41
	s_nop 0
	global_load_lds_dwordx4 v140, s[22:23]
	s_mov_b32 m0, s78
	s_add_u32 s22, s22, 0x80000
	s_addc_u32 s23, s23, 0
	s_mov_b32 s78, m0
	s_mov_b32 m0, s42
	s_nop 0
	global_load_lds_dwordx4 v138, s[22:23]
	s_mov_b32 m0, s78
	s_nop 0
	s_mov_b32 s78, m0
	s_mov_b32 m0, s43
	s_nop 0
	global_load_lds_dwordx4 v140, s[22:23]
	s_mov_b32 m0, s78
	s_waitcnt vmcnt(8)
	s_waitcnt lgkmcnt(0)
	s_barrier
	s_setprio 1
	s_waitcnt lgkmcnt(7)
	v_mfma_f32_16x16x32_bf16 v[126:129], v[148:151], v[180:183], v[126:129]
	v_mfma_f32_16x16x32_bf16 v[122:125], v[156:159], v[180:183], v[122:125]
	s_waitcnt lgkmcnt(5)
	v_mfma_f32_16x16x32_bf16 v[106:109], v[156:159], v[188:191], v[106:109]
	v_mfma_f32_16x16x32_bf16 v[110:113], v[148:151], v[188:191], v[110:113]
	s_waitcnt lgkmcnt(3)
	v_mfma_f32_16x16x32_bf16 v[94:97], v[148:151], v[196:199], v[94:97]
	v_mfma_f32_16x16x32_bf16 v[90:93], v[156:159], v[196:199], v[90:93]
	s_waitcnt lgkmcnt(1)
	v_mfma_f32_16x16x32_bf16 v[74:77], v[156:159], v[204:207], v[74:77]
	v_mfma_f32_16x16x32_bf16 v[78:81], v[148:151], v[204:207], v[78:81]
	v_mfma_f32_16x16x32_bf16 v[126:129], v[152:155], v[184:187], v[126:129]
	v_mfma_f32_16x16x32_bf16 v[122:125], v[160:163], v[184:187], v[122:125]
	v_mfma_f32_16x16x32_bf16 v[106:109], v[160:163], v[192:195], v[106:109]
	v_mfma_f32_16x16x32_bf16 v[110:113], v[152:155], v[192:195], v[110:113]
	v_mfma_f32_16x16x32_bf16 v[94:97], v[152:155], v[200:203], v[94:97]
	v_mfma_f32_16x16x32_bf16 v[90:93], v[160:163], v[200:203], v[90:93]
	s_waitcnt lgkmcnt(0)
	v_mfma_f32_16x16x32_bf16 v[74:77], v[160:163], v[208:211], v[74:77]
	v_mfma_f32_16x16x32_bf16 v[78:81], v[152:155], v[208:211], v[78:81]
	s_setprio 0
	s_setprio 1
	v_mfma_f32_16x16x32_bf16 v[118:121], v[164:167], v[180:183], v[118:121]
	v_mfma_f32_16x16x32_bf16 v[114:117], v[172:175], v[180:183], v[114:117]
	v_mfma_f32_16x16x32_bf16 v[98:101], v[172:175], v[188:191], v[98:101]
	v_mfma_f32_16x16x32_bf16 v[102:105], v[164:167], v[188:191], v[102:105]
	v_mfma_f32_16x16x32_bf16 v[86:89], v[164:167], v[196:199], v[86:89]
	v_mfma_f32_16x16x32_bf16 v[82:85], v[172:175], v[196:199], v[82:85]
	v_mfma_f32_16x16x32_bf16 v[66:69], v[172:175], v[204:207], v[66:69]
	v_mfma_f32_16x16x32_bf16 v[70:73], v[164:167], v[204:207], v[70:73]
	v_mfma_f32_16x16x32_bf16 v[118:121], v[168:171], v[184:187], v[118:121]
	v_mfma_f32_16x16x32_bf16 v[114:117], v[176:179], v[184:187], v[114:117]
	v_mfma_f32_16x16x32_bf16 v[98:101], v[176:179], v[192:195], v[98:101]
	v_mfma_f32_16x16x32_bf16 v[102:105], v[168:171], v[192:195], v[102:105]
	v_mfma_f32_16x16x32_bf16 v[86:89], v[168:171], v[200:203], v[86:89]
	v_mfma_f32_16x16x32_bf16 v[82:85], v[176:179], v[200:203], v[82:85]
	s_setprio 2
	s_barrier
	v_mfma_f32_16x16x32_bf16 v[66:69], v[176:179], v[208:211], v[66:69]
	v_mfma_f32_16x16x32_bf16 v[70:73], v[168:171], v[208:211], v[70:73]
	s_setprio 0
	ds_read_b128 v[180:183], v145 offset:49152
	ds_read_b128 v[184:187], v145 offset:50176
	ds_read_b128 v[188:191], v145 offset:51200
	ds_read_b128 v[192:195], v145 offset:52224
	ds_read_b128 v[196:199], v145 offset:53248
	ds_read_b128 v[200:203], v145 offset:54272
	ds_read_b128 v[204:207], v145 offset:55296
	ds_read_b128 v[208:211], v145 offset:56320
	s_add_u32 s22, s20, 0x80
	s_addc_u32 s23, s21, 0
	s_mov_b32 s78, m0
	s_mov_b32 m0, s46
	s_nop 0
	global_load_lds_dwordx4 v139, s[22:23]
	s_mov_b32 m0, s78
	s_add_u32 s20, s20, 0x80080
	s_mov_b32 s78, m0
	s_mov_b32 m0, s47
	s_nop 0
	global_load_lds_dwordx4 v141, s[22:23]
	s_mov_b32 m0, s78
	s_addc_u32 s21, s21, 0
	s_mov_b32 s22, m0
	s_mov_b32 m0, s48
	s_nop 0
	global_load_lds_dwordx4 v139, s[20:21]
	s_mov_b32 m0, s22
	s_nop 0
	s_mov_b32 s22, m0
	s_mov_b32 m0, s49
	s_nop 0
	global_load_lds_dwordx4 v141, s[20:21]
	s_mov_b32 m0, s22
	s_waitcnt vmcnt(4)
	s_waitcnt lgkmcnt(0)
	s_barrier
	s_setprio 1
	s_waitcnt lgkmcnt(7)
	v_mfma_f32_16x16x32_bf16 v[62:65], v[148:151], v[180:183], v[62:65]
	v_mfma_f32_16x16x32_bf16 v[58:61], v[156:159], v[180:183], v[58:61]
	s_waitcnt lgkmcnt(5)
	v_mfma_f32_16x16x32_bf16 v[42:45], v[156:159], v[188:191], v[42:45]
	v_mfma_f32_16x16x32_bf16 v[46:49], v[148:151], v[188:191], v[46:49]
	s_waitcnt lgkmcnt(3)
	v_mfma_f32_16x16x32_bf16 v[30:33], v[148:151], v[196:199], v[30:33]
	v_mfma_f32_16x16x32_bf16 v[26:29], v[156:159], v[196:199], v[26:29]
	s_waitcnt lgkmcnt(1)
	v_mfma_f32_16x16x32_bf16 v[10:13], v[156:159], v[204:207], v[10:13]
	v_mfma_f32_16x16x32_bf16 v[14:17], v[148:151], v[204:207], v[14:17]
	v_mfma_f32_16x16x32_bf16 v[62:65], v[152:155], v[184:187], v[62:65]
	v_mfma_f32_16x16x32_bf16 v[58:61], v[160:163], v[184:187], v[58:61]
	v_mfma_f32_16x16x32_bf16 v[42:45], v[160:163], v[192:195], v[42:45]
	v_mfma_f32_16x16x32_bf16 v[46:49], v[152:155], v[192:195], v[46:49]
	v_mfma_f32_16x16x32_bf16 v[30:33], v[152:155], v[200:203], v[30:33]
	v_mfma_f32_16x16x32_bf16 v[26:29], v[160:163], v[200:203], v[26:29]
	s_waitcnt lgkmcnt(0)
	v_mfma_f32_16x16x32_bf16 v[10:13], v[160:163], v[208:211], v[10:13]
	v_mfma_f32_16x16x32_bf16 v[14:17], v[152:155], v[208:211], v[14:17]
	s_setprio 0
	s_setprio 1
	v_mfma_f32_16x16x32_bf16 v[54:57], v[164:167], v[180:183], v[54:57]
	v_mfma_f32_16x16x32_bf16 v[50:53], v[172:175], v[180:183], v[50:53]
	v_mfma_f32_16x16x32_bf16 v[34:37], v[172:175], v[188:191], v[34:37]
	v_mfma_f32_16x16x32_bf16 v[38:41], v[164:167], v[188:191], v[38:41]
	v_mfma_f32_16x16x32_bf16 v[22:25], v[164:167], v[196:199], v[22:25]
	v_mfma_f32_16x16x32_bf16 v[18:21], v[172:175], v[196:199], v[18:21]
	v_mfma_f32_16x16x32_bf16 v[2:5], v[172:175], v[204:207], v[2:5]
	v_mfma_f32_16x16x32_bf16 v[6:9], v[164:167], v[204:207], v[6:9]
	v_mfma_f32_16x16x32_bf16 v[54:57], v[168:171], v[184:187], v[54:57]
	v_mfma_f32_16x16x32_bf16 v[50:53], v[176:179], v[184:187], v[50:53]
	v_mfma_f32_16x16x32_bf16 v[34:37], v[176:179], v[192:195], v[34:37]
	v_mfma_f32_16x16x32_bf16 v[38:41], v[168:171], v[192:195], v[38:41]
	v_mfma_f32_16x16x32_bf16 v[22:25], v[168:171], v[200:203], v[22:25]
	v_mfma_f32_16x16x32_bf16 v[18:21], v[176:179], v[200:203], v[18:21]
	s_setprio 2
	s_barrier
	v_mfma_f32_16x16x32_bf16 v[2:5], v[176:179], v[208:211], v[2:5]
	v_mfma_f32_16x16x32_bf16 v[6:9], v[168:171], v[208:211], v[6:9]
	s_setprio 0
	s_add_i32 s77, s77, 2
	s_add_u32 s73, s73, 0x100
	s_addc_u32 s74, s74, 0
	s_add_u32 s18, s18, 0x100
	s_addc_u32 s19, s19, 0
	s_add_u32 s75, s75, 0x100
	s_addc_u32 s76, s76, 0
	s_cmp_gt_u32 s77, 29
	s_cbranch_scc0 .LBB0_1224
	s_and_b64 vcc, exec, s[6:7]
	s_cbranch_vccz .LBB0_1227
	s_barrier

.LBB0_1356:
	s_ashr_i32 s13, s12, 31
	s_lshl_b64 s[14:15], s[12:13], 15
	s_add_u32 s14, s28, s14
	s_addc_u32 s15, s29, s15
	s_and_b64 s[16:17], s[2:3], exec
	s_cselect_b32 s13, s15, s23
	s_cselect_b32 s67, s14, s22
	s_ashr_i32 s11, s10, 31
	s_lshl_b64 s[16:17], s[10:11], 15
	s_add_u32 s16, s30, s16
	s_addc_u32 s17, s31, s17
	s_and_b64 s[24:25], s[2:3], exec
	s_cselect_b32 s11, s17, s21
	s_cselect_b32 s73, s16, s20
	s_add_u32 s74, s20, 0x80000
	s_addc_u32 s75, s21, 0
	s_add_u32 s20, s22, 0x204000
	s_addc_u32 s21, s23, 0
	s_add_u32 s76, s22, 0x400000
	s_addc_u32 s77, s23, 0
	s_mov_b32 s78, -2
	s_waitcnt vmcnt(25)
	s_waitcnt vmcnt(24)
	s_waitcnt vmcnt(15)
	s_waitcnt vmcnt(14)
	s_waitcnt vmcnt(13)
	s_waitcnt vmcnt(12)
	s_waitcnt vmcnt(11)
	s_waitcnt vmcnt(10)
	s_waitcnt vmcnt(9)
	s_waitcnt vmcnt(8)
	s_waitcnt vmcnt(7)
	s_waitcnt vmcnt(6)
	s_waitcnt vmcnt(5)
	s_waitcnt vmcnt(4)
	s_waitcnt vmcnt(3)
	s_waitcnt vmcnt(2)
	s_waitcnt vmcnt(1)
	s_waitcnt vmcnt(0)
	ds_read_b128 v[130:133], v181
	ds_read_b128 v[134:137], v181 offset:1024
	ds_read_b128 v[138:141], v181 offset:2048
	ds_read_b128 v[142:145], v181 offset:3072
	ds_read_b128 v[150:153], v182
	ds_read_b128 v[154:157], v182 offset:1024
	ds_read_b128 v[158:161], v182 offset:2048
	ds_read_b128 v[162:165], v182 offset:3072
	s_cmpk_eq_i32 s78, 0x52
	s_cselect_b32 s23, s11, s75
	s_cselect_b32 s22, s73, s74
	s_cselect_b32 s25, s13, s77
	s_cselect_b32 s24, s67, s76
	ds_read_b128 v[166:169], v183
	ds_read_b128 v[170:173], v183 offset:1024
	ds_read_b128 v[186:189], v183 offset:2048
	ds_read_b128 v[190:193], v183 offset:3072
	ds_read_b128 v[194:197], v183 offset:4096
	ds_read_b128 v[198:201], v183 offset:5120
	ds_read_b128 v[202:205], v183 offset:6144
	ds_read_b128 v[206:209], v183 offset:7168
	s_add_u32 s80, s20, 0xffffc000
	s_addc_u32 s81, s21, -1
	s_mov_b32 s79, m0
	s_mov_b32 m0, s58
	s_nop 0
	global_load_lds_dwordx4 v1, s[80:81]
	s_mov_b32 m0, s79
	s_nop 0
	s_mov_b32 s79, m0
	s_mov_b32 m0, s64
	s_nop 0
	global_load_lds_dwordx4 v177, s[80:81]
	s_mov_b32 m0, s79
	s_nop 0
	s_mov_b32 s79, m0
	s_mov_b32 m0, s59
	s_nop 0
	global_load_lds_dwordx4 v1, s[20:21]
	s_mov_b32 m0, s79
	s_nop 0
	s_mov_b32 s79, m0
	s_mov_b32 m0, s65
	s_nop 0
	global_load_lds_dwordx4 v177, s[20:21]
	s_mov_b32 m0, s79
	s_waitcnt vmcnt(8)
	s_waitcnt lgkmcnt(0)
	s_barrier
	s_setprio 1
	s_waitcnt lgkmcnt(7)
	v_mfma_f32_16x16x32_bf16 v[126:129], v[130:133], v[166:169], 0
	v_mfma_f32_16x16x32_bf16 v[122:125], v[138:141], v[166:169], 0
	s_waitcnt lgkmcnt(5)
	v_mfma_f32_16x16x32_bf16 v[110:113], v[138:141], v[186:189], 0
	v_mfma_f32_16x16x32_bf16 v[118:121], v[130:133], v[186:189], 0
	s_waitcnt lgkmcnt(3)
	v_mfma_f32_16x16x32_bf16 v[94:97], v[130:133], v[194:197], 0
	v_mfma_f32_16x16x32_bf16 v[90:93], v[138:141], v[194:197], 0
	s_waitcnt lgkmcnt(1)
	v_mfma_f32_16x16x32_bf16 v[78:81], v[138:141], v[202:205], 0
	v_mfma_f32_16x16x32_bf16 v[86:89], v[130:133], v[202:205], 0
	v_mfma_f32_16x16x32_bf16 v[126:129], v[134:137], v[170:173], v[126:129]
	v_mfma_f32_16x16x32_bf16 v[122:125], v[142:145], v[170:173], v[122:125]
	v_mfma_f32_16x16x32_bf16 v[110:113], v[142:145], v[190:193], v[110:113]
	v_mfma_f32_16x16x32_bf16 v[118:121], v[134:137], v[190:193], v[118:121]
	v_mfma_f32_16x16x32_bf16 v[94:97], v[134:137], v[198:201], v[94:97]
	v_mfma_f32_16x16x32_bf16 v[90:93], v[142:145], v[198:201], v[90:93]
	s_waitcnt lgkmcnt(0)
	v_mfma_f32_16x16x32_bf16 v[78:81], v[142:145], v[206:209], v[78:81]
	v_mfma_f32_16x16x32_bf16 v[86:89], v[134:137], v[206:209], v[86:89]
	s_setprio 0
	s_setprio 1
	v_mfma_f32_16x16x32_bf16 v[114:117], v[150:153], v[166:169], 0
	v_mfma_f32_16x16x32_bf16 v[106:109], v[158:161], v[166:169], 0
	v_mfma_f32_16x16x32_bf16 v[98:101], v[158:161], v[186:189], 0
	v_mfma_f32_16x16x32_bf16 v[102:105], v[150:153], v[186:189], 0
	v_mfma_f32_16x16x32_bf16 v[82:85], v[150:153], v[194:197], 0
	v_mfma_f32_16x16x32_bf16 v[74:77], v[158:161], v[194:197], 0
	v_mfma_f32_16x16x32_bf16 v[66:69], v[158:161], v[202:205], 0
	v_mfma_f32_16x16x32_bf16 v[70:73], v[150:153], v[202:205], 0
	v_mfma_f32_16x16x32_bf16 v[114:117], v[154:157], v[170:173], v[114:117]
	v_mfma_f32_16x16x32_bf16 v[106:109], v[162:165], v[170:173], v[106:109]
	v_mfma_f32_16x16x32_bf16 v[98:101], v[162:165], v[190:193], v[98:101]
	v_mfma_f32_16x16x32_bf16 v[102:105], v[154:157], v[190:193], v[102:105]
	v_mfma_f32_16x16x32_bf16 v[82:85], v[154:157], v[198:201], v[82:85]
	v_mfma_f32_16x16x32_bf16 v[74:77], v[162:165], v[198:201], v[74:77]
	s_setprio 2
	s_barrier
	v_mfma_f32_16x16x32_bf16 v[66:69], v[162:165], v[206:209], v[66:69]
	v_mfma_f32_16x16x32_bf16 v[70:73], v[154:157], v[206:209], v[70:73]
	s_setprio 0
	ds_read_b128 v[166:169], v183 offset:16384
	ds_read_b128 v[170:173], v183 offset:17408
	ds_read_b128 v[186:189], v183 offset:18432
	ds_read_b128 v[190:193], v183 offset:19456
	ds_read_b128 v[194:197], v183 offset:20480
	ds_read_b128 v[198:201], v183 offset:21504
	ds_read_b128 v[202:205], v183 offset:22528
	ds_read_b128 v[206:209], v183 offset:23552
	s_mov_b32 s79, m0
	s_mov_b32 m0, s35
	s_nop 0
	global_load_lds_dwordx4 v176, s[22:23]
	s_mov_b32 m0, s79
	s_add_u32 s80, s22, 0x4000
	s_mov_b32 s79, m0
	s_mov_b32 m0, s36
	s_nop 0
	global_load_lds_dwordx4 v178, s[22:23]
	s_mov_b32 m0, s79
	s_addc_u32 s81, s23, 0
	s_mov_b32 s79, m0
	s_mov_b32 m0, s37
	s_nop 0
	global_load_lds_dwordx4 v176, s[80:81]
	s_mov_b32 m0, s79
	s_nop 0
	s_mov_b32 s79, m0
	s_mov_b32 m0, s40
	s_nop 0
	global_load_lds_dwordx4 v178, s[80:81]
	s_mov_b32 m0, s79
	s_waitcnt vmcnt(4)
	s_waitcnt lgkmcnt(0)
	s_barrier
	s_setprio 1
	s_waitcnt lgkmcnt(7)
	v_mfma_f32_16x16x32_bf16 v[62:65], v[130:133], v[166:169], 0
	v_mfma_f32_16x16x32_bf16 v[58:61], v[138:141], v[166:169], 0
	s_waitcnt lgkmcnt(5)
	v_mfma_f32_16x16x32_bf16 v[42:45], v[138:141], v[186:189], 0
	v_mfma_f32_16x16x32_bf16 v[46:49], v[130:133], v[186:189], 0
	s_waitcnt lgkmcnt(3)
	v_mfma_f32_16x16x32_bf16 v[30:33], v[130:133], v[194:197], 0
	v_mfma_f32_16x16x32_bf16 v[26:29], v[138:141], v[194:197], 0
	s_waitcnt lgkmcnt(1)
	v_mfma_f32_16x16x32_bf16 v[10:13], v[138:141], v[202:205], 0
	v_mfma_f32_16x16x32_bf16 v[14:17], v[130:133], v[202:205], 0
	v_mfma_f32_16x16x32_bf16 v[62:65], v[134:137], v[170:173], v[62:65]
	v_mfma_f32_16x16x32_bf16 v[58:61], v[142:145], v[170:173], v[58:61]
	v_mfma_f32_16x16x32_bf16 v[42:45], v[142:145], v[190:193], v[42:45]
	v_mfma_f32_16x16x32_bf16 v[46:49], v[134:137], v[190:193], v[46:49]
	v_mfma_f32_16x16x32_bf16 v[30:33], v[134:137], v[198:201], v[30:33]
	v_mfma_f32_16x16x32_bf16 v[26:29], v[142:145], v[198:201], v[26:29]
	s_waitcnt lgkmcnt(0)
	v_mfma_f32_16x16x32_bf16 v[10:13], v[142:145], v[206:209], v[10:13]
	v_mfma_f32_16x16x32_bf16 v[14:17], v[134:137], v[206:209], v[14:17]
	s_setprio 0
	s_setprio 1
	v_mfma_f32_16x16x32_bf16 v[54:57], v[150:153], v[166:169], 0
	v_mfma_f32_16x16x32_bf16 v[50:53], v[158:161], v[166:169], 0
	v_mfma_f32_16x16x32_bf16 v[34:37], v[158:161], v[186:189], 0
	v_mfma_f32_16x16x32_bf16 v[38:41], v[150:153], v[186:189], 0
	v_mfma_f32_16x16x32_bf16 v[22:25], v[150:153], v[194:197], 0
	v_mfma_f32_16x16x32_bf16 v[18:21], v[158:161], v[194:197], 0
	v_mfma_f32_16x16x32_bf16 v[2:5], v[158:161], v[202:205], 0
	v_mfma_f32_16x16x32_bf16 v[6:9], v[150:153], v[202:205], 0
	v_mfma_f32_16x16x32_bf16 v[54:57], v[154:157], v[170:173], v[54:57]
	v_mfma_f32_16x16x32_bf16 v[50:53], v[162:165], v[170:173], v[50:53]
	v_mfma_f32_16x16x32_bf16 v[34:37], v[162:165], v[190:193], v[34:37]
	v_mfma_f32_16x16x32_bf16 v[38:41], v[154:157], v[190:193], v[38:41]
	v_mfma_f32_16x16x32_bf16 v[22:25], v[154:157], v[198:201], v[22:25]
	v_mfma_f32_16x16x32_bf16 v[18:21], v[162:165], v[198:201], v[18:21]
	s_setprio 2
	s_barrier
	v_mfma_f32_16x16x32_bf16 v[2:5], v[162:165], v[206:209], v[2:5]
	v_mfma_f32_16x16x32_bf16 v[6:9], v[154:157], v[206:209], v[6:9]
	s_setprio 0
	ds_read_b128 v[130:133], v184
	ds_read_b128 v[134:137], v184 offset:1024
	ds_read_b128 v[138:141], v184 offset:2048
	ds_read_b128 v[142:145], v184 offset:3072
	ds_read_b128 v[150:153], v185
	ds_read_b128 v[154:157], v185 offset:1024
	ds_read_b128 v[158:161], v185 offset:2048
	ds_read_b128 v[162:165], v185 offset:3072
	ds_read_b128 v[166:169], v183 offset:32768
	ds_read_b128 v[170:173], v183 offset:33792
	ds_read_b128 v[186:189], v183 offset:34816
	ds_read_b128 v[190:193], v183 offset:35840
	ds_read_b128 v[194:197], v183 offset:36864
	ds_read_b128 v[198:201], v183 offset:37888
	ds_read_b128 v[202:205], v183 offset:38912
	ds_read_b128 v[206:209], v183 offset:39936
	s_mov_b32 s79, m0
	s_mov_b32 m0, s34
	s_nop 0
	global_load_lds_dwordx4 v1, s[24:25]
	s_mov_b32 m0, s79
	s_nop 0
	s_mov_b32 s79, m0
	s_mov_b32 m0, s41
	s_nop 0
	global_load_lds_dwordx4 v177, s[24:25]
	s_mov_b32 m0, s79
	s_add_u32 s24, s24, 0x4000
	s_addc_u32 s25, s25, 0
	s_mov_b32 s79, m0
	s_mov_b32 m0, s42
	s_nop 0
	global_load_lds_dwordx4 v1, s[24:25]
	s_mov_b32 m0, s79
	s_nop 0
	s_mov_b32 s79, m0
	s_mov_b32 m0, s43
	s_nop 0
	global_load_lds_dwordx4 v177, s[24:25]
	s_mov_b32 m0, s79
	s_waitcnt vmcnt(8)
	s_waitcnt lgkmcnt(0)
	s_barrier
	s_setprio 1
	s_waitcnt lgkmcnt(7)
	v_mfma_f32_16x16x32_bf16 v[126:129], v[130:133], v[166:169], v[126:129]
	v_mfma_f32_16x16x32_bf16 v[122:125], v[138:141], v[166:169], v[122:125]
	s_waitcnt lgkmcnt(5)
	v_mfma_f32_16x16x32_bf16 v[110:113], v[138:141], v[186:189], v[110:113]
	v_mfma_f32_16x16x32_bf16 v[118:121], v[130:133], v[186:189], v[118:121]
	s_waitcnt lgkmcnt(3)
	v_mfma_f32_16x16x32_bf16 v[94:97], v[130:133], v[194:197], v[94:97]
	v_mfma_f32_16x16x32_bf16 v[90:93], v[138:141], v[194:197], v[90:93]
	s_waitcnt lgkmcnt(1)
	v_mfma_f32_16x16x32_bf16 v[78:81], v[138:141], v[202:205], v[78:81]
	v_mfma_f32_16x16x32_bf16 v[86:89], v[130:133], v[202:205], v[86:89]
	v_mfma_f32_16x16x32_bf16 v[126:129], v[134:137], v[170:173], v[126:129]
	v_mfma_f32_16x16x32_bf16 v[122:125], v[142:145], v[170:173], v[122:125]
	v_mfma_f32_16x16x32_bf16 v[110:113], v[142:145], v[190:193], v[110:113]
	v_mfma_f32_16x16x32_bf16 v[118:121], v[134:137], v[190:193], v[118:121]
	v_mfma_f32_16x16x32_bf16 v[94:97], v[134:137], v[198:201], v[94:97]
	v_mfma_f32_16x16x32_bf16 v[90:93], v[142:145], v[198:201], v[90:93]
	s_waitcnt lgkmcnt(0)
	v_mfma_f32_16x16x32_bf16 v[78:81], v[142:145], v[206:209], v[78:81]
	v_mfma_f32_16x16x32_bf16 v[86:89], v[134:137], v[206:209], v[86:89]
	s_setprio 0
	s_setprio 1
	v_mfma_f32_16x16x32_bf16 v[114:117], v[150:153], v[166:169], v[114:117]
	v_mfma_f32_16x16x32_bf16 v[106:109], v[158:161], v[166:169], v[106:109]
	v_mfma_f32_16x16x32_bf16 v[98:101], v[158:161], v[186:189], v[98:101]
	v_mfma_f32_16x16x32_bf16 v[102:105], v[150:153], v[186:189], v[102:105]
	v_mfma_f32_16x16x32_bf16 v[82:85], v[150:153], v[194:197], v[82:85]
	v_mfma_f32_16x16x32_bf16 v[74:77], v[158:161], v[194:197], v[74:77]
	v_mfma_f32_16x16x32_bf16 v[66:69], v[158:161], v[202:205], v[66:69]
	v_mfma_f32_16x16x32_bf16 v[70:73], v[150:153], v[202:205], v[70:73]
	v_mfma_f32_16x16x32_bf16 v[114:117], v[154:157], v[170:173], v[114:117]
	v_mfma_f32_16x16x32_bf16 v[106:109], v[162:165], v[170:173], v[106:109]
	v_mfma_f32_16x16x32_bf16 v[98:101], v[162:165], v[190:193], v[98:101]
	v_mfma_f32_16x16x32_bf16 v[102:105], v[154:157], v[190:193], v[102:105]
	v_mfma_f32_16x16x32_bf16 v[82:85], v[154:157], v[198:201], v[82:85]
	v_mfma_f32_16x16x32_bf16 v[74:77], v[162:165], v[198:201], v[74:77]
	s_setprio 2
	s_barrier
	v_mfma_f32_16x16x32_bf16 v[66:69], v[162:165], v[206:209], v[66:69]
	v_mfma_f32_16x16x32_bf16 v[70:73], v[154:157], v[206:209], v[70:73]
	s_setprio 0
	ds_read_b128 v[166:169], v183 offset:49152
	ds_read_b128 v[170:173], v183 offset:50176
	ds_read_b128 v[186:189], v183 offset:51200
	ds_read_b128 v[190:193], v183 offset:52224
	ds_read_b128 v[194:197], v183 offset:53248
	ds_read_b128 v[198:201], v183 offset:54272
	ds_read_b128 v[202:205], v183 offset:55296
	ds_read_b128 v[206:209], v183 offset:56320
	s_add_u32 s24, s22, 0x40000
	s_addc_u32 s25, s23, 0
	s_mov_b32 s79, m0
	s_mov_b32 m0, s46
	s_nop 0
	global_load_lds_dwordx4 v176, s[24:25]
	s_mov_b32 m0, s79
	s_add_u32 s22, s22, 0x44000
	s_mov_b32 s79, m0
	s_mov_b32 m0, s47
	s_nop 0
	global_load_lds_dwordx4 v178, s[24:25]
	s_mov_b32 m0, s79
	s_addc_u32 s23, s23, 0
	s_mov_b32 s24, m0
	s_mov_b32 m0, s48
	s_nop 0
	global_load_lds_dwordx4 v176, s[22:23]
	s_mov_b32 m0, s24
	s_nop 0
	s_mov_b32 s24, m0
	s_mov_b32 m0, s49
	s_nop 0
	global_load_lds_dwordx4 v178, s[22:23]
	s_mov_b32 m0, s24
	s_waitcnt vmcnt(4)
	s_waitcnt lgkmcnt(0)
	s_barrier
	s_setprio 1
	s_waitcnt lgkmcnt(7)
	v_mfma_f32_16x16x32_bf16 v[62:65], v[130:133], v[166:169], v[62:65]
	v_mfma_f32_16x16x32_bf16 v[58:61], v[138:141], v[166:169], v[58:61]
	s_waitcnt lgkmcnt(5)
	v_mfma_f32_16x16x32_bf16 v[42:45], v[138:141], v[186:189], v[42:45]
	v_mfma_f32_16x16x32_bf16 v[46:49], v[130:133], v[186:189], v[46:49]
	s_waitcnt lgkmcnt(3)
	v_mfma_f32_16x16x32_bf16 v[30:33], v[130:133], v[194:197], v[30:33]
	v_mfma_f32_16x16x32_bf16 v[26:29], v[138:141], v[194:197], v[26:29]
	s_waitcnt lgkmcnt(1)
	v_mfma_f32_16x16x32_bf16 v[10:13], v[138:141], v[202:205], v[10:13]
	v_mfma_f32_16x16x32_bf16 v[14:17], v[130:133], v[202:205], v[14:17]
	v_mfma_f32_16x16x32_bf16 v[62:65], v[134:137], v[170:173], v[62:65]
	v_mfma_f32_16x16x32_bf16 v[58:61], v[142:145], v[170:173], v[58:61]
	v_mfma_f32_16x16x32_bf16 v[42:45], v[142:145], v[190:193], v[42:45]
	v_mfma_f32_16x16x32_bf16 v[46:49], v[134:137], v[190:193], v[46:49]
	v_mfma_f32_16x16x32_bf16 v[30:33], v[134:137], v[198:201], v[30:33]
	v_mfma_f32_16x16x32_bf16 v[26:29], v[142:145], v[198:201], v[26:29]
	s_waitcnt lgkmcnt(0)
	v_mfma_f32_16x16x32_bf16 v[10:13], v[142:145], v[206:209], v[10:13]
	v_mfma_f32_16x16x32_bf16 v[14:17], v[134:137], v[206:209], v[14:17]
	s_setprio 0
	s_setprio 1
	v_mfma_f32_16x16x32_bf16 v[54:57], v[150:153], v[166:169], v[54:57]
	v_mfma_f32_16x16x32_bf16 v[50:53], v[158:161], v[166:169], v[50:53]
	v_mfma_f32_16x16x32_bf16 v[34:37], v[158:161], v[186:189], v[34:37]
	v_mfma_f32_16x16x32_bf16 v[38:41], v[150:153], v[186:189], v[38:41]
	v_mfma_f32_16x16x32_bf16 v[22:25], v[150:153], v[194:197], v[22:25]
	v_mfma_f32_16x16x32_bf16 v[18:21], v[158:161], v[194:197], v[18:21]
	v_mfma_f32_16x16x32_bf16 v[2:5], v[158:161], v[202:205], v[2:5]
	v_mfma_f32_16x16x32_bf16 v[6:9], v[150:153], v[202:205], v[6:9]
	v_mfma_f32_16x16x32_bf16 v[54:57], v[154:157], v[170:173], v[54:57]
	v_mfma_f32_16x16x32_bf16 v[50:53], v[162:165], v[170:173], v[50:53]
	v_mfma_f32_16x16x32_bf16 v[34:37], v[162:165], v[190:193], v[34:37]
	v_mfma_f32_16x16x32_bf16 v[38:41], v[154:157], v[190:193], v[38:41]
	v_mfma_f32_16x16x32_bf16 v[22:25], v[154:157], v[198:201], v[22:25]
	v_mfma_f32_16x16x32_bf16 v[18:21], v[162:165], v[198:201], v[18:21]
	s_setprio 2
	s_barrier
	v_mfma_f32_16x16x32_bf16 v[2:5], v[162:165], v[206:209], v[2:5]
	v_mfma_f32_16x16x32_bf16 v[6:9], v[154:157], v[206:209], v[6:9]
	s_setprio 0
	s_add_i32 s78, s78, 2
	s_add_u32 s74, s74, 0x80000
	s_addc_u32 s75, s75, 0
	s_add_u32 s20, s20, 0x400000
	s_addc_u32 s21, s21, 0
	s_add_u32 s76, s76, 0x400000
	s_addc_u32 s77, s77, 0
	s_cmpk_gt_u32 s78, 0x53
	.p2align 6
.LBB0_1357:
	ds_read_b128 v[130:133], v181
	ds_read_b128 v[134:137], v181 offset:1024
	ds_read_b128 v[138:141], v181 offset:2048
	ds_read_b128 v[142:145], v181 offset:3072
	ds_read_b128 v[150:153], v182
	ds_read_b128 v[154:157], v182 offset:1024
	ds_read_b128 v[158:161], v182 offset:2048
	ds_read_b128 v[162:165], v182 offset:3072
	s_cmpk_eq_i32 s78, 0x52
	s_cselect_b32 s23, s11, s75
	s_cselect_b32 s22, s73, s74
	s_cselect_b32 s25, s13, s77
	s_cselect_b32 s24, s67, s76
	ds_read_b128 v[166:169], v183
	ds_read_b128 v[170:173], v183 offset:1024
	ds_read_b128 v[186:189], v183 offset:2048
	ds_read_b128 v[190:193], v183 offset:3072
	ds_read_b128 v[194:197], v183 offset:4096
	ds_read_b128 v[198:201], v183 offset:5120
	ds_read_b128 v[202:205], v183 offset:6144
	ds_read_b128 v[206:209], v183 offset:7168
	s_add_u32 s80, s20, 0xffffc000
	s_addc_u32 s81, s21, -1
	s_mov_b32 s79, m0
	s_mov_b32 m0, s58
	s_nop 0
	global_load_lds_dwordx4 v1, s[80:81]
	s_mov_b32 m0, s79
	s_nop 0
	s_mov_b32 s79, m0
	s_mov_b32 m0, s64
	s_nop 0
	global_load_lds_dwordx4 v177, s[80:81]
	s_mov_b32 m0, s79
	s_nop 0
	s_mov_b32 s79, m0
	s_mov_b32 m0, s59
	s_nop 0
	global_load_lds_dwordx4 v1, s[20:21]
	s_mov_b32 m0, s79
	s_nop 0
	s_mov_b32 s79, m0
	s_mov_b32 m0, s65
	s_nop 0
	global_load_lds_dwordx4 v177, s[20:21]
	s_mov_b32 m0, s79
	s_waitcnt vmcnt(8)
	s_waitcnt lgkmcnt(0)
	s_barrier
	s_setprio 1
	s_waitcnt lgkmcnt(7)
	v_mfma_f32_16x16x32_bf16 v[126:129], v[130:133], v[166:169], v[126:129]
	v_mfma_f32_16x16x32_bf16 v[122:125], v[138:141], v[166:169], v[122:125]
	s_waitcnt lgkmcnt(5)
	v_mfma_f32_16x16x32_bf16 v[110:113], v[138:141], v[186:189], v[110:113]
	v_mfma_f32_16x16x32_bf16 v[118:121], v[130:133], v[186:189], v[118:121]
	s_waitcnt lgkmcnt(3)
	v_mfma_f32_16x16x32_bf16 v[94:97], v[130:133], v[194:197], v[94:97]
	v_mfma_f32_16x16x32_bf16 v[90:93], v[138:141], v[194:197], v[90:93]
	s_waitcnt lgkmcnt(1)
	v_mfma_f32_16x16x32_bf16 v[78:81], v[138:141], v[202:205], v[78:81]
	v_mfma_f32_16x16x32_bf16 v[86:89], v[130:133], v[202:205], v[86:89]
	v_mfma_f32_16x16x32_bf16 v[126:129], v[134:137], v[170:173], v[126:129]
	v_mfma_f32_16x16x32_bf16 v[122:125], v[142:145], v[170:173], v[122:125]
	v_mfma_f32_16x16x32_bf16 v[110:113], v[142:145], v[190:193], v[110:113]
	v_mfma_f32_16x16x32_bf16 v[118:121], v[134:137], v[190:193], v[118:121]
	v_mfma_f32_16x16x32_bf16 v[94:97], v[134:137], v[198:201], v[94:97]
	v_mfma_f32_16x16x32_bf16 v[90:93], v[142:145], v[198:201], v[90:93]
	s_waitcnt lgkmcnt(0)
	v_mfma_f32_16x16x32_bf16 v[78:81], v[142:145], v[206:209], v[78:81]
	v_mfma_f32_16x16x32_bf16 v[86:89], v[134:137], v[206:209], v[86:89]
	s_setprio 0
	s_setprio 1
	v_mfma_f32_16x16x32_bf16 v[114:117], v[150:153], v[166:169], v[114:117]
	v_mfma_f32_16x16x32_bf16 v[106:109], v[158:161], v[166:169], v[106:109]
	v_mfma_f32_16x16x32_bf16 v[98:101], v[158:161], v[186:189], v[98:101]
	v_mfma_f32_16x16x32_bf16 v[102:105], v[150:153], v[186:189], v[102:105]
	v_mfma_f32_16x16x32_bf16 v[82:85], v[150:153], v[194:197], v[82:85]
	v_mfma_f32_16x16x32_bf16 v[74:77], v[158:161], v[194:197], v[74:77]
	v_mfma_f32_16x16x32_bf16 v[66:69], v[158:161], v[202:205], v[66:69]
	v_mfma_f32_16x16x32_bf16 v[70:73], v[150:153], v[202:205], v[70:73]
	v_mfma_f32_16x16x32_bf16 v[114:117], v[154:157], v[170:173], v[114:117]
	v_mfma_f32_16x16x32_bf16 v[106:109], v[162:165], v[170:173], v[106:109]
	v_mfma_f32_16x16x32_bf16 v[98:101], v[162:165], v[190:193], v[98:101]
	v_mfma_f32_16x16x32_bf16 v[102:105], v[154:157], v[190:193], v[102:105]
	v_mfma_f32_16x16x32_bf16 v[82:85], v[154:157], v[198:201], v[82:85]
	v_mfma_f32_16x16x32_bf16 v[74:77], v[162:165], v[198:201], v[74:77]
	s_setprio 2
	s_barrier
	v_mfma_f32_16x16x32_bf16 v[66:69], v[162:165], v[206:209], v[66:69]
	v_mfma_f32_16x16x32_bf16 v[70:73], v[154:157], v[206:209], v[70:73]
	s_setprio 0
	ds_read_b128 v[166:169], v183 offset:16384
	ds_read_b128 v[170:173], v183 offset:17408
	ds_read_b128 v[186:189], v183 offset:18432
	ds_read_b128 v[190:193], v183 offset:19456
	ds_read_b128 v[194:197], v183 offset:20480
	ds_read_b128 v[198:201], v183 offset:21504
	ds_read_b128 v[202:205], v183 offset:22528
	ds_read_b128 v[206:209], v183 offset:23552
	s_mov_b32 s79, m0
	s_mov_b32 m0, s35
	s_nop 0
	global_load_lds_dwordx4 v176, s[22:23]
	s_mov_b32 m0, s79
	s_add_u32 s80, s22, 0x4000
	s_mov_b32 s79, m0
	s_mov_b32 m0, s36
	s_nop 0
	global_load_lds_dwordx4 v178, s[22:23]
	s_mov_b32 m0, s79
	s_addc_u32 s81, s23, 0
	s_mov_b32 s79, m0
	s_mov_b32 m0, s37
	s_nop 0
	global_load_lds_dwordx4 v176, s[80:81]
	s_mov_b32 m0, s79
	s_nop 0
	s_mov_b32 s79, m0
	s_mov_b32 m0, s40
	s_nop 0
	global_load_lds_dwordx4 v178, s[80:81]
	s_mov_b32 m0, s79
	s_waitcnt vmcnt(4)
	s_waitcnt lgkmcnt(0)
	s_barrier
	s_setprio 1
	s_waitcnt lgkmcnt(7)
	v_mfma_f32_16x16x32_bf16 v[62:65], v[130:133], v[166:169], v[62:65]
	v_mfma_f32_16x16x32_bf16 v[58:61], v[138:141], v[166:169], v[58:61]
	s_waitcnt lgkmcnt(5)
	v_mfma_f32_16x16x32_bf16 v[42:45], v[138:141], v[186:189], v[42:45]
	v_mfma_f32_16x16x32_bf16 v[46:49], v[130:133], v[186:189], v[46:49]
	s_waitcnt lgkmcnt(3)
	v_mfma_f32_16x16x32_bf16 v[30:33], v[130:133], v[194:197], v[30:33]
	v_mfma_f32_16x16x32_bf16 v[26:29], v[138:141], v[194:197], v[26:29]
	s_waitcnt lgkmcnt(1)
	v_mfma_f32_16x16x32_bf16 v[10:13], v[138:141], v[202:205], v[10:13]
	v_mfma_f32_16x16x32_bf16 v[14:17], v[130:133], v[202:205], v[14:17]
	v_mfma_f32_16x16x32_bf16 v[62:65], v[134:137], v[170:173], v[62:65]
	v_mfma_f32_16x16x32_bf16 v[58:61], v[142:145], v[170:173], v[58:61]
	v_mfma_f32_16x16x32_bf16 v[42:45], v[142:145], v[190:193], v[42:45]
	v_mfma_f32_16x16x32_bf16 v[46:49], v[134:137], v[190:193], v[46:49]
	v_mfma_f32_16x16x32_bf16 v[30:33], v[134:137], v[198:201], v[30:33]
	v_mfma_f32_16x16x32_bf16 v[26:29], v[142:145], v[198:201], v[26:29]
	s_waitcnt lgkmcnt(0)
	v_mfma_f32_16x16x32_bf16 v[10:13], v[142:145], v[206:209], v[10:13]
	v_mfma_f32_16x16x32_bf16 v[14:17], v[134:137], v[206:209], v[14:17]
	s_setprio 0
	s_setprio 1
	v_mfma_f32_16x16x32_bf16 v[54:57], v[150:153], v[166:169], v[54:57]
	v_mfma_f32_16x16x32_bf16 v[50:53], v[158:161], v[166:169], v[50:53]
	v_mfma_f32_16x16x32_bf16 v[34:37], v[158:161], v[186:189], v[34:37]
	v_mfma_f32_16x16x32_bf16 v[38:41], v[150:153], v[186:189], v[38:41]
	v_mfma_f32_16x16x32_bf16 v[22:25], v[150:153], v[194:197], v[22:25]
	v_mfma_f32_16x16x32_bf16 v[18:21], v[158:161], v[194:197], v[18:21]
	v_mfma_f32_16x16x32_bf16 v[2:5], v[158:161], v[202:205], v[2:5]
	v_mfma_f32_16x16x32_bf16 v[6:9], v[150:153], v[202:205], v[6:9]
	v_mfma_f32_16x16x32_bf16 v[54:57], v[154:157], v[170:173], v[54:57]
	v_mfma_f32_16x16x32_bf16 v[50:53], v[162:165], v[170:173], v[50:53]
	v_mfma_f32_16x16x32_bf16 v[34:37], v[162:165], v[190:193], v[34:37]
	v_mfma_f32_16x16x32_bf16 v[38:41], v[154:157], v[190:193], v[38:41]
	v_mfma_f32_16x16x32_bf16 v[22:25], v[154:157], v[198:201], v[22:25]
	v_mfma_f32_16x16x32_bf16 v[18:21], v[162:165], v[198:201], v[18:21]
	s_setprio 2
	s_barrier
	v_mfma_f32_16x16x32_bf16 v[2:5], v[162:165], v[206:209], v[2:5]
	v_mfma_f32_16x16x32_bf16 v[6:9], v[154:157], v[206:209], v[6:9]
	s_setprio 0
	ds_read_b128 v[130:133], v184
	ds_read_b128 v[134:137], v184 offset:1024
	ds_read_b128 v[138:141], v184 offset:2048
	ds_read_b128 v[142:145], v184 offset:3072
	ds_read_b128 v[150:153], v185
	ds_read_b128 v[154:157], v185 offset:1024
	ds_read_b128 v[158:161], v185 offset:2048
	ds_read_b128 v[162:165], v185 offset:3072
	ds_read_b128 v[166:169], v183 offset:32768
	ds_read_b128 v[170:173], v183 offset:33792
	ds_read_b128 v[186:189], v183 offset:34816
	ds_read_b128 v[190:193], v183 offset:35840
	ds_read_b128 v[194:197], v183 offset:36864
	ds_read_b128 v[198:201], v183 offset:37888
	ds_read_b128 v[202:205], v183 offset:38912
	ds_read_b128 v[206:209], v183 offset:39936
	s_mov_b32 s79, m0
	s_mov_b32 m0, s34
	s_nop 0
	global_load_lds_dwordx4 v1, s[24:25]
	s_mov_b32 m0, s79
	s_nop 0
	s_mov_b32 s79, m0
	s_mov_b32 m0, s41
	s_nop 0
	global_load_lds_dwordx4 v177, s[24:25]
	s_mov_b32 m0, s79
	s_add_u32 s24, s24, 0x4000
	s_addc_u32 s25, s25, 0
	s_mov_b32 s79, m0
	s_mov_b32 m0, s42
	s_nop 0
	global_load_lds_dwordx4 v1, s[24:25]
	s_mov_b32 m0, s79
	s_nop 0
	s_mov_b32 s79, m0
	s_mov_b32 m0, s43
	s_nop 0
	global_load_lds_dwordx4 v177, s[24:25]
	s_mov_b32 m0, s79
	s_waitcnt vmcnt(8)
	s_waitcnt lgkmcnt(0)
	s_barrier
	s_setprio 1
	s_waitcnt lgkmcnt(7)
	v_mfma_f32_16x16x32_bf16 v[126:129], v[130:133], v[166:169], v[126:129]
	v_mfma_f32_16x16x32_bf16 v[122:125], v[138:141], v[166:169], v[122:125]
	s_waitcnt lgkmcnt(5)
	v_mfma_f32_16x16x32_bf16 v[110:113], v[138:141], v[186:189], v[110:113]
	v_mfma_f32_16x16x32_bf16 v[118:121], v[130:133], v[186:189], v[118:121]
	s_waitcnt lgkmcnt(3)
	v_mfma_f32_16x16x32_bf16 v[94:97], v[130:133], v[194:197], v[94:97]
	v_mfma_f32_16x16x32_bf16 v[90:93], v[138:141], v[194:197], v[90:93]
	s_waitcnt lgkmcnt(1)
	v_mfma_f32_16x16x32_bf16 v[78:81], v[138:141], v[202:205], v[78:81]
	v_mfma_f32_16x16x32_bf16 v[86:89], v[130:133], v[202:205], v[86:89]
	v_mfma_f32_16x16x32_bf16 v[126:129], v[134:137], v[170:173], v[126:129]
	v_mfma_f32_16x16x32_bf16 v[122:125], v[142:145], v[170:173], v[122:125]
	v_mfma_f32_16x16x32_bf16 v[110:113], v[142:145], v[190:193], v[110:113]
	v_mfma_f32_16x16x32_bf16 v[118:121], v[134:137], v[190:193], v[118:121]
	v_mfma_f32_16x16x32_bf16 v[94:97], v[134:137], v[198:201], v[94:97]
	v_mfma_f32_16x16x32_bf16 v[90:93], v[142:145], v[198:201], v[90:93]
	s_waitcnt lgkmcnt(0)
	v_mfma_f32_16x16x32_bf16 v[78:81], v[142:145], v[206:209], v[78:81]
	v_mfma_f32_16x16x32_bf16 v[86:89], v[134:137], v[206:209], v[86:89]
	s_setprio 0
	s_setprio 1
	v_mfma_f32_16x16x32_bf16 v[114:117], v[150:153], v[166:169], v[114:117]
	v_mfma_f32_16x16x32_bf16 v[106:109], v[158:161], v[166:169], v[106:109]
	v_mfma_f32_16x16x32_bf16 v[98:101], v[158:161], v[186:189], v[98:101]
	v_mfma_f32_16x16x32_bf16 v[102:105], v[150:153], v[186:189], v[102:105]
	v_mfma_f32_16x16x32_bf16 v[82:85], v[150:153], v[194:197], v[82:85]
	v_mfma_f32_16x16x32_bf16 v[74:77], v[158:161], v[194:197], v[74:77]
	v_mfma_f32_16x16x32_bf16 v[66:69], v[158:161], v[202:205], v[66:69]
	v_mfma_f32_16x16x32_bf16 v[70:73], v[150:153], v[202:205], v[70:73]
	v_mfma_f32_16x16x32_bf16 v[114:117], v[154:157], v[170:173], v[114:117]
	v_mfma_f32_16x16x32_bf16 v[106:109], v[162:165], v[170:173], v[106:109]
	v_mfma_f32_16x16x32_bf16 v[98:101], v[162:165], v[190:193], v[98:101]
	v_mfma_f32_16x16x32_bf16 v[102:105], v[154:157], v[190:193], v[102:105]
	v_mfma_f32_16x16x32_bf16 v[82:85], v[154:157], v[198:201], v[82:85]
	v_mfma_f32_16x16x32_bf16 v[74:77], v[162:165], v[198:201], v[74:77]
	s_setprio 2
	s_barrier
	v_mfma_f32_16x16x32_bf16 v[66:69], v[162:165], v[206:209], v[66:69]
	v_mfma_f32_16x16x32_bf16 v[70:73], v[154:157], v[206:209], v[70:73]
	s_setprio 0
	ds_read_b128 v[166:169], v183 offset:49152
	ds_read_b128 v[170:173], v183 offset:50176
	ds_read_b128 v[186:189], v183 offset:51200
	ds_read_b128 v[190:193], v183 offset:52224
	ds_read_b128 v[194:197], v183 offset:53248
	ds_read_b128 v[198:201], v183 offset:54272
	ds_read_b128 v[202:205], v183 offset:55296
	ds_read_b128 v[206:209], v183 offset:56320
	s_add_u32 s24, s22, 0x40000
	s_addc_u32 s25, s23, 0
	s_mov_b32 s79, m0
	s_mov_b32 m0, s46
	s_nop 0
	global_load_lds_dwordx4 v176, s[24:25]
	s_mov_b32 m0, s79
	s_add_u32 s22, s22, 0x44000
	s_mov_b32 s79, m0
	s_mov_b32 m0, s47
	s_nop 0
	global_load_lds_dwordx4 v178, s[24:25]
	s_mov_b32 m0, s79
	s_addc_u32 s23, s23, 0
	s_mov_b32 s24, m0
	s_mov_b32 m0, s48
	s_nop 0
	global_load_lds_dwordx4 v176, s[22:23]
	s_mov_b32 m0, s24
	s_nop 0
	s_mov_b32 s24, m0
	s_mov_b32 m0, s49
	s_nop 0
	global_load_lds_dwordx4 v178, s[22:23]
	s_mov_b32 m0, s24
	s_waitcnt vmcnt(4)
	s_waitcnt lgkmcnt(0)
	s_barrier
	s_setprio 1
	s_waitcnt lgkmcnt(7)
	v_mfma_f32_16x16x32_bf16 v[62:65], v[130:133], v[166:169], v[62:65]
	v_mfma_f32_16x16x32_bf16 v[58:61], v[138:141], v[166:169], v[58:61]
	s_waitcnt lgkmcnt(5)
	v_mfma_f32_16x16x32_bf16 v[42:45], v[138:141], v[186:189], v[42:45]
	v_mfma_f32_16x16x32_bf16 v[46:49], v[130:133], v[186:189], v[46:49]
	s_waitcnt lgkmcnt(3)
	v_mfma_f32_16x16x32_bf16 v[30:33], v[130:133], v[194:197], v[30:33]
	v_mfma_f32_16x16x32_bf16 v[26:29], v[138:141], v[194:197], v[26:29]
	s_waitcnt lgkmcnt(1)
	v_mfma_f32_16x16x32_bf16 v[10:13], v[138:141], v[202:205], v[10:13]
	v_mfma_f32_16x16x32_bf16 v[14:17], v[130:133], v[202:205], v[14:17]
	v_mfma_f32_16x16x32_bf16 v[62:65], v[134:137], v[170:173], v[62:65]
	v_mfma_f32_16x16x32_bf16 v[58:61], v[142:145], v[170:173], v[58:61]
	v_mfma_f32_16x16x32_bf16 v[42:45], v[142:145], v[190:193], v[42:45]
	v_mfma_f32_16x16x32_bf16 v[46:49], v[134:137], v[190:193], v[46:49]
	v_mfma_f32_16x16x32_bf16 v[30:33], v[134:137], v[198:201], v[30:33]
	v_mfma_f32_16x16x32_bf16 v[26:29], v[142:145], v[198:201], v[26:29]
	s_waitcnt lgkmcnt(0)
	v_mfma_f32_16x16x32_bf16 v[10:13], v[142:145], v[206:209], v[10:13]
	v_mfma_f32_16x16x32_bf16 v[14:17], v[134:137], v[206:209], v[14:17]
	s_setprio 0
	s_setprio 1
	v_mfma_f32_16x16x32_bf16 v[54:57], v[150:153], v[166:169], v[54:57]
	v_mfma_f32_16x16x32_bf16 v[50:53], v[158:161], v[166:169], v[50:53]
	v_mfma_f32_16x16x32_bf16 v[34:37], v[158:161], v[186:189], v[34:37]
	v_mfma_f32_16x16x32_bf16 v[38:41], v[150:153], v[186:189], v[38:41]
	v_mfma_f32_16x16x32_bf16 v[22:25], v[150:153], v[194:197], v[22:25]
	v_mfma_f32_16x16x32_bf16 v[18:21], v[158:161], v[194:197], v[18:21]
	v_mfma_f32_16x16x32_bf16 v[2:5], v[158:161], v[202:205], v[2:5]
	v_mfma_f32_16x16x32_bf16 v[6:9], v[150:153], v[202:205], v[6:9]
	v_mfma_f32_16x16x32_bf16 v[54:57], v[154:157], v[170:173], v[54:57]
	v_mfma_f32_16x16x32_bf16 v[50:53], v[162:165], v[170:173], v[50:53]
	v_mfma_f32_16x16x32_bf16 v[34:37], v[162:165], v[190:193], v[34:37]
	v_mfma_f32_16x16x32_bf16 v[38:41], v[154:157], v[190:193], v[38:41]
	v_mfma_f32_16x16x32_bf16 v[22:25], v[154:157], v[198:201], v[22:25]
	v_mfma_f32_16x16x32_bf16 v[18:21], v[162:165], v[198:201], v[18:21]
	s_setprio 2
	s_barrier
	v_mfma_f32_16x16x32_bf16 v[2:5], v[162:165], v[206:209], v[2:5]
	v_mfma_f32_16x16x32_bf16 v[6:9], v[154:157], v[206:209], v[6:9]
	s_setprio 0
	s_add_i32 s78, s78, 2
	s_add_u32 s74, s74, 0x80000
	s_addc_u32 s75, s75, 0
	s_add_u32 s20, s20, 0x400000
	s_addc_u32 s21, s21, 0
	s_add_u32 s76, s76, 0x400000
	s_addc_u32 s77, s77, 0
	s_cmpk_gt_u32 s78, 0x53
	s_cbranch_scc0 .LBB0_1357
	s_and_b64 vcc, exec, s[8:9]
	s_cbranch_vccz .LBB0_1360
	s_barrier

.LBB0_1784:
	s_ashr_i32 s11, s10, 31
	s_lshl_b64 s[12:13], s[10:11], 20
	s_add_u32 s12, s26, s12
	s_addc_u32 s13, s27, s13
	s_and_b64 s[14:15], s[2:3], exec
	s_cselect_b32 s11, s13, s21
	s_cselect_b32 s64, s12, s20
	s_ashr_i32 s9, s8, 31
	s_lshl_b64 s[14:15], s[8:9], 20
	s_add_u32 s14, s28, s14
	s_addc_u32 s15, s29, s15
	s_and_b64 s[22:23], s[2:3], exec
	s_cselect_b32 s9, s15, s19
	s_cselect_b32 s65, s14, s18
	s_add_u32 s66, s18, 0x100
	s_addc_u32 s67, s19, 0
	s_add_u32 s18, s20, 0x80080
	s_addc_u32 s19, s21, 0
	s_add_u32 s70, s20, 0x100
	s_addc_u32 s71, s21, 0
	s_mov_b32 s73, -2
	ds_read_b128 v[148:151], v143
	ds_read_b128 v[152:155], v143 offset:1024
	ds_read_b128 v[156:159], v143 offset:2048
	ds_read_b128 v[160:163], v143 offset:3072
	ds_read_b128 v[164:167], v144
	ds_read_b128 v[168:171], v144 offset:1024
	ds_read_b128 v[172:175], v144 offset:2048
	ds_read_b128 v[176:179], v144 offset:3072
	s_cmp_eq_u32 s73, 28
	s_cselect_b32 s21, s9, s67
	s_cselect_b32 s20, s65, s66
	s_cselect_b32 s23, s11, s71
	s_cselect_b32 s22, s64, s70
	ds_read_b128 v[180:183], v145
	ds_read_b128 v[184:187], v145 offset:1024
	ds_read_b128 v[188:191], v145 offset:2048
	ds_read_b128 v[192:195], v145 offset:3072
	ds_read_b128 v[196:199], v145 offset:4096
	ds_read_b128 v[200:203], v145 offset:5120
	ds_read_b128 v[204:207], v145 offset:6144
	ds_read_b128 v[208:211], v145 offset:7168
	s_add_u32 s74, s18, 0xfff80000
	s_addc_u32 s75, s19, -1
	s_mov_b32 s76, m0
	s_mov_b32 m0, s56
	s_nop 0
	global_load_lds_dwordx4 v138, s[74:75]
	s_mov_b32 m0, s76
	s_nop 0
	s_mov_b32 s76, m0
	s_mov_b32 m0, s59
	s_nop 0
	global_load_lds_dwordx4 v140, s[74:75]
	s_mov_b32 m0, s76
	s_mov_b32 s74, m0
	s_mov_b32 m0, s57
	s_nop 0
	global_load_lds_dwordx4 v138, s[18:19]
	s_mov_b32 m0, s74
	s_nop 0
	s_mov_b32 s74, m0
	s_mov_b32 m0, s62
	s_nop 0
	global_load_lds_dwordx4 v140, s[18:19]
	s_mov_b32 m0, s74
	s_waitcnt vmcnt(8)
	s_waitcnt lgkmcnt(0)
	s_barrier
	s_setprio 1
	s_waitcnt lgkmcnt(7)
	v_mfma_f32_16x16x32_bf16 v[126:129], v[148:151], v[180:183], 0
	v_mfma_f32_16x16x32_bf16 v[122:125], v[156:159], v[180:183], 0
	s_waitcnt lgkmcnt(5)
	v_mfma_f32_16x16x32_bf16 v[106:109], v[156:159], v[188:191], 0
	v_mfma_f32_16x16x32_bf16 v[110:113], v[148:151], v[188:191], 0
	s_waitcnt lgkmcnt(3)
	v_mfma_f32_16x16x32_bf16 v[94:97], v[148:151], v[196:199], 0
	v_mfma_f32_16x16x32_bf16 v[90:93], v[156:159], v[196:199], 0
	s_waitcnt lgkmcnt(1)
	v_mfma_f32_16x16x32_bf16 v[74:77], v[156:159], v[204:207], 0
	v_mfma_f32_16x16x32_bf16 v[78:81], v[148:151], v[204:207], 0
	v_mfma_f32_16x16x32_bf16 v[126:129], v[152:155], v[184:187], v[126:129]
	v_mfma_f32_16x16x32_bf16 v[122:125], v[160:163], v[184:187], v[122:125]
	v_mfma_f32_16x16x32_bf16 v[106:109], v[160:163], v[192:195], v[106:109]
	v_mfma_f32_16x16x32_bf16 v[110:113], v[152:155], v[192:195], v[110:113]
	v_mfma_f32_16x16x32_bf16 v[94:97], v[152:155], v[200:203], v[94:97]
	v_mfma_f32_16x16x32_bf16 v[90:93], v[160:163], v[200:203], v[90:93]
	s_waitcnt lgkmcnt(0)
	v_mfma_f32_16x16x32_bf16 v[74:77], v[160:163], v[208:211], v[74:77]
	v_mfma_f32_16x16x32_bf16 v[78:81], v[152:155], v[208:211], v[78:81]
	s_setprio 0
	s_setprio 1
	v_mfma_f32_16x16x32_bf16 v[118:121], v[164:167], v[180:183], 0
	v_mfma_f32_16x16x32_bf16 v[114:117], v[172:175], v[180:183], 0
	v_mfma_f32_16x16x32_bf16 v[98:101], v[172:175], v[188:191], 0
	v_mfma_f32_16x16x32_bf16 v[102:105], v[164:167], v[188:191], 0
	v_mfma_f32_16x16x32_bf16 v[86:89], v[164:167], v[196:199], 0
	v_mfma_f32_16x16x32_bf16 v[82:85], v[172:175], v[196:199], 0
	v_mfma_f32_16x16x32_bf16 v[66:69], v[172:175], v[204:207], 0
	v_mfma_f32_16x16x32_bf16 v[70:73], v[164:167], v[204:207], 0
	v_mfma_f32_16x16x32_bf16 v[118:121], v[168:171], v[184:187], v[118:121]
	v_mfma_f32_16x16x32_bf16 v[114:117], v[176:179], v[184:187], v[114:117]
	v_mfma_f32_16x16x32_bf16 v[98:101], v[176:179], v[192:195], v[98:101]
	v_mfma_f32_16x16x32_bf16 v[102:105], v[168:171], v[192:195], v[102:105]
	v_mfma_f32_16x16x32_bf16 v[86:89], v[168:171], v[200:203], v[86:89]
	v_mfma_f32_16x16x32_bf16 v[82:85], v[176:179], v[200:203], v[82:85]
	s_setprio 2
	s_barrier
	v_mfma_f32_16x16x32_bf16 v[66:69], v[176:179], v[208:211], v[66:69]
	v_mfma_f32_16x16x32_bf16 v[70:73], v[168:171], v[208:211], v[70:73]
	s_setprio 0
	ds_read_b128 v[180:183], v145 offset:16384
	ds_read_b128 v[184:187], v145 offset:17408
	ds_read_b128 v[188:191], v145 offset:18432
	ds_read_b128 v[192:195], v145 offset:19456
	ds_read_b128 v[196:199], v145 offset:20480
	ds_read_b128 v[200:203], v145 offset:21504
	ds_read_b128 v[204:207], v145 offset:22528
	ds_read_b128 v[208:211], v145 offset:23552
	s_mov_b32 s74, m0
	s_mov_b32 m0, s35
	s_nop 0
	global_load_lds_dwordx4 v139, s[20:21]
	s_mov_b32 m0, s74
	s_nop 0
	s_mov_b32 s74, m0
	s_mov_b32 m0, s36
	s_nop 0
	global_load_lds_dwordx4 v141, s[20:21]
	s_mov_b32 m0, s74
	s_add_u32 s74, s20, 0x80000
	s_addc_u32 s75, s21, 0
	s_mov_b32 s76, m0
	s_mov_b32 m0, s37
	s_nop 0
	global_load_lds_dwordx4 v139, s[74:75]
	s_mov_b32 m0, s76
	s_nop 0
	s_mov_b32 s76, m0
	s_mov_b32 m0, s40
	s_nop 0
	global_load_lds_dwordx4 v141, s[74:75]
	s_mov_b32 m0, s76
	s_waitcnt vmcnt(4)
	s_waitcnt lgkmcnt(0)
	s_barrier
	s_setprio 1
	s_waitcnt lgkmcnt(7)
	v_mfma_f32_16x16x32_bf16 v[62:65], v[148:151], v[180:183], 0
	v_mfma_f32_16x16x32_bf16 v[58:61], v[156:159], v[180:183], 0
	s_waitcnt lgkmcnt(5)
	v_mfma_f32_16x16x32_bf16 v[42:45], v[156:159], v[188:191], 0
	v_mfma_f32_16x16x32_bf16 v[46:49], v[148:151], v[188:191], 0
	s_waitcnt lgkmcnt(3)
	v_mfma_f32_16x16x32_bf16 v[30:33], v[148:151], v[196:199], 0
	v_mfma_f32_16x16x32_bf16 v[26:29], v[156:159], v[196:199], 0
	s_waitcnt lgkmcnt(1)
	v_mfma_f32_16x16x32_bf16 v[10:13], v[156:159], v[204:207], 0
	v_mfma_f32_16x16x32_bf16 v[14:17], v[148:151], v[204:207], 0
	v_mfma_f32_16x16x32_bf16 v[62:65], v[152:155], v[184:187], v[62:65]
	v_mfma_f32_16x16x32_bf16 v[58:61], v[160:163], v[184:187], v[58:61]
	v_mfma_f32_16x16x32_bf16 v[42:45], v[160:163], v[192:195], v[42:45]
	v_mfma_f32_16x16x32_bf16 v[46:49], v[152:155], v[192:195], v[46:49]
	v_mfma_f32_16x16x32_bf16 v[30:33], v[152:155], v[200:203], v[30:33]
	v_mfma_f32_16x16x32_bf16 v[26:29], v[160:163], v[200:203], v[26:29]
	s_waitcnt lgkmcnt(0)
	v_mfma_f32_16x16x32_bf16 v[10:13], v[160:163], v[208:211], v[10:13]
	v_mfma_f32_16x16x32_bf16 v[14:17], v[152:155], v[208:211], v[14:17]
	s_setprio 0
	s_setprio 1
	v_mfma_f32_16x16x32_bf16 v[54:57], v[164:167], v[180:183], 0
	v_mfma_f32_16x16x32_bf16 v[50:53], v[172:175], v[180:183], 0
	v_mfma_f32_16x16x32_bf16 v[34:37], v[172:175], v[188:191], 0
	v_mfma_f32_16x16x32_bf16 v[38:41], v[164:167], v[188:191], 0
	v_mfma_f32_16x16x32_bf16 v[22:25], v[164:167], v[196:199], 0
	v_mfma_f32_16x16x32_bf16 v[18:21], v[172:175], v[196:199], 0
	v_mfma_f32_16x16x32_bf16 v[2:5], v[172:175], v[204:207], 0
	v_mfma_f32_16x16x32_bf16 v[6:9], v[164:167], v[204:207], 0
	v_mfma_f32_16x16x32_bf16 v[54:57], v[168:171], v[184:187], v[54:57]
	v_mfma_f32_16x16x32_bf16 v[50:53], v[176:179], v[184:187], v[50:53]
	v_mfma_f32_16x16x32_bf16 v[34:37], v[176:179], v[192:195], v[34:37]
	v_mfma_f32_16x16x32_bf16 v[38:41], v[168:171], v[192:195], v[38:41]
	v_mfma_f32_16x16x32_bf16 v[22:25], v[168:171], v[200:203], v[22:25]
	v_mfma_f32_16x16x32_bf16 v[18:21], v[176:179], v[200:203], v[18:21]
	s_setprio 2
	s_barrier
	v_mfma_f32_16x16x32_bf16 v[2:5], v[176:179], v[208:211], v[2:5]
	v_mfma_f32_16x16x32_bf16 v[6:9], v[168:171], v[208:211], v[6:9]
	s_setprio 0
	ds_read_b128 v[148:151], v146
	ds_read_b128 v[152:155], v146 offset:1024
	ds_read_b128 v[156:159], v146 offset:2048
	ds_read_b128 v[160:163], v146 offset:3072
	ds_read_b128 v[164:167], v147
	ds_read_b128 v[168:171], v147 offset:1024
	ds_read_b128 v[172:175], v147 offset:2048
	ds_read_b128 v[176:179], v147 offset:3072
	ds_read_b128 v[180:183], v145 offset:32768
	ds_read_b128 v[184:187], v145 offset:33792
	ds_read_b128 v[188:191], v145 offset:34816
	ds_read_b128 v[192:195], v145 offset:35840
	ds_read_b128 v[196:199], v145 offset:36864
	ds_read_b128 v[200:203], v145 offset:37888
	ds_read_b128 v[204:207], v145 offset:38912
	ds_read_b128 v[208:211], v145 offset:39936
	s_mov_b32 s74, m0
	s_mov_b32 m0, s31
	s_nop 0
	global_load_lds_dwordx4 v138, s[22:23]
	s_mov_b32 m0, s74
	s_nop 0
	s_mov_b32 s74, m0
	s_mov_b32 m0, s41
	s_nop 0
	global_load_lds_dwordx4 v140, s[22:23]
	s_mov_b32 m0, s74
	s_add_u32 s22, s22, 0x80000
	s_addc_u32 s23, s23, 0
	s_mov_b32 s74, m0
	s_mov_b32 m0, s42
	s_nop 0
	global_load_lds_dwordx4 v138, s[22:23]
	s_mov_b32 m0, s74
	s_nop 0
	s_mov_b32 s74, m0
	s_mov_b32 m0, s43
	s_nop 0
	global_load_lds_dwordx4 v140, s[22:23]
	s_mov_b32 m0, s74
	s_waitcnt vmcnt(8)
	s_waitcnt lgkmcnt(0)
	s_barrier
	s_setprio 1
	s_waitcnt lgkmcnt(7)
	v_mfma_f32_16x16x32_bf16 v[126:129], v[148:151], v[180:183], v[126:129]
	v_mfma_f32_16x16x32_bf16 v[122:125], v[156:159], v[180:183], v[122:125]
	s_waitcnt lgkmcnt(5)
	v_mfma_f32_16x16x32_bf16 v[106:109], v[156:159], v[188:191], v[106:109]
	v_mfma_f32_16x16x32_bf16 v[110:113], v[148:151], v[188:191], v[110:113]
	s_waitcnt lgkmcnt(3)
	v_mfma_f32_16x16x32_bf16 v[94:97], v[148:151], v[196:199], v[94:97]
	v_mfma_f32_16x16x32_bf16 v[90:93], v[156:159], v[196:199], v[90:93]
	s_waitcnt lgkmcnt(1)
	v_mfma_f32_16x16x32_bf16 v[74:77], v[156:159], v[204:207], v[74:77]
	v_mfma_f32_16x16x32_bf16 v[78:81], v[148:151], v[204:207], v[78:81]
	v_mfma_f32_16x16x32_bf16 v[126:129], v[152:155], v[184:187], v[126:129]
	v_mfma_f32_16x16x32_bf16 v[122:125], v[160:163], v[184:187], v[122:125]
	v_mfma_f32_16x16x32_bf16 v[106:109], v[160:163], v[192:195], v[106:109]
	v_mfma_f32_16x16x32_bf16 v[110:113], v[152:155], v[192:195], v[110:113]
	v_mfma_f32_16x16x32_bf16 v[94:97], v[152:155], v[200:203], v[94:97]
	v_mfma_f32_16x16x32_bf16 v[90:93], v[160:163], v[200:203], v[90:93]
	s_waitcnt lgkmcnt(0)
	v_mfma_f32_16x16x32_bf16 v[74:77], v[160:163], v[208:211], v[74:77]
	v_mfma_f32_16x16x32_bf16 v[78:81], v[152:155], v[208:211], v[78:81]
	s_setprio 0
	s_setprio 1
	v_mfma_f32_16x16x32_bf16 v[118:121], v[164:167], v[180:183], v[118:121]
	v_mfma_f32_16x16x32_bf16 v[114:117], v[172:175], v[180:183], v[114:117]
	v_mfma_f32_16x16x32_bf16 v[98:101], v[172:175], v[188:191], v[98:101]
	v_mfma_f32_16x16x32_bf16 v[102:105], v[164:167], v[188:191], v[102:105]
	v_mfma_f32_16x16x32_bf16 v[86:89], v[164:167], v[196:199], v[86:89]
	v_mfma_f32_16x16x32_bf16 v[82:85], v[172:175], v[196:199], v[82:85]
	v_mfma_f32_16x16x32_bf16 v[66:69], v[172:175], v[204:207], v[66:69]
	v_mfma_f32_16x16x32_bf16 v[70:73], v[164:167], v[204:207], v[70:73]
	v_mfma_f32_16x16x32_bf16 v[118:121], v[168:171], v[184:187], v[118:121]
	v_mfma_f32_16x16x32_bf16 v[114:117], v[176:179], v[184:187], v[114:117]
	v_mfma_f32_16x16x32_bf16 v[98:101], v[176:179], v[192:195], v[98:101]
	v_mfma_f32_16x16x32_bf16 v[102:105], v[168:171], v[192:195], v[102:105]
	v_mfma_f32_16x16x32_bf16 v[86:89], v[168:171], v[200:203], v[86:89]
	v_mfma_f32_16x16x32_bf16 v[82:85], v[176:179], v[200:203], v[82:85]
	s_setprio 2
	s_barrier
	v_mfma_f32_16x16x32_bf16 v[66:69], v[176:179], v[208:211], v[66:69]
	v_mfma_f32_16x16x32_bf16 v[70:73], v[168:171], v[208:211], v[70:73]
	s_setprio 0
	ds_read_b128 v[180:183], v145 offset:49152
	ds_read_b128 v[184:187], v145 offset:50176
	ds_read_b128 v[188:191], v145 offset:51200
	ds_read_b128 v[192:195], v145 offset:52224
	ds_read_b128 v[196:199], v145 offset:53248
	ds_read_b128 v[200:203], v145 offset:54272
	ds_read_b128 v[204:207], v145 offset:55296
	ds_read_b128 v[208:211], v145 offset:56320
	s_add_u32 s22, s20, 0x80
	s_addc_u32 s23, s21, 0
	s_mov_b32 s74, m0
	s_mov_b32 m0, s46
	s_nop 0
	global_load_lds_dwordx4 v139, s[22:23]
	s_mov_b32 m0, s74
	s_add_u32 s20, s20, 0x80080
	s_mov_b32 s74, m0
	s_mov_b32 m0, s47
	s_nop 0
	global_load_lds_dwordx4 v141, s[22:23]
	s_mov_b32 m0, s74
	s_addc_u32 s21, s21, 0
	s_mov_b32 s22, m0
	s_mov_b32 m0, s48
	s_nop 0
	global_load_lds_dwordx4 v139, s[20:21]
	s_mov_b32 m0, s22
	s_nop 0
	s_mov_b32 s22, m0
	s_mov_b32 m0, s49
	s_nop 0
	global_load_lds_dwordx4 v141, s[20:21]
	s_mov_b32 m0, s22
	s_waitcnt vmcnt(4)
	s_waitcnt lgkmcnt(0)
	s_barrier
	s_setprio 1
	s_waitcnt lgkmcnt(7)
	v_mfma_f32_16x16x32_bf16 v[62:65], v[148:151], v[180:183], v[62:65]
	v_mfma_f32_16x16x32_bf16 v[58:61], v[156:159], v[180:183], v[58:61]
	s_waitcnt lgkmcnt(5)
	v_mfma_f32_16x16x32_bf16 v[42:45], v[156:159], v[188:191], v[42:45]
	v_mfma_f32_16x16x32_bf16 v[46:49], v[148:151], v[188:191], v[46:49]
	s_waitcnt lgkmcnt(3)
	v_mfma_f32_16x16x32_bf16 v[30:33], v[148:151], v[196:199], v[30:33]
	v_mfma_f32_16x16x32_bf16 v[26:29], v[156:159], v[196:199], v[26:29]
	s_waitcnt lgkmcnt(1)
	v_mfma_f32_16x16x32_bf16 v[10:13], v[156:159], v[204:207], v[10:13]
	v_mfma_f32_16x16x32_bf16 v[14:17], v[148:151], v[204:207], v[14:17]
	v_mfma_f32_16x16x32_bf16 v[62:65], v[152:155], v[184:187], v[62:65]
	v_mfma_f32_16x16x32_bf16 v[58:61], v[160:163], v[184:187], v[58:61]
	v_mfma_f32_16x16x32_bf16 v[42:45], v[160:163], v[192:195], v[42:45]
	v_mfma_f32_16x16x32_bf16 v[46:49], v[152:155], v[192:195], v[46:49]
	v_mfma_f32_16x16x32_bf16 v[30:33], v[152:155], v[200:203], v[30:33]
	v_mfma_f32_16x16x32_bf16 v[26:29], v[160:163], v[200:203], v[26:29]
	s_waitcnt lgkmcnt(0)
	v_mfma_f32_16x16x32_bf16 v[10:13], v[160:163], v[208:211], v[10:13]
	v_mfma_f32_16x16x32_bf16 v[14:17], v[152:155], v[208:211], v[14:17]
	s_setprio 0
	s_setprio 1
	v_mfma_f32_16x16x32_bf16 v[54:57], v[164:167], v[180:183], v[54:57]
	v_mfma_f32_16x16x32_bf16 v[50:53], v[172:175], v[180:183], v[50:53]
	v_mfma_f32_16x16x32_bf16 v[34:37], v[172:175], v[188:191], v[34:37]
	v_mfma_f32_16x16x32_bf16 v[38:41], v[164:167], v[188:191], v[38:41]
	v_mfma_f32_16x16x32_bf16 v[22:25], v[164:167], v[196:199], v[22:25]
	v_mfma_f32_16x16x32_bf16 v[18:21], v[172:175], v[196:199], v[18:21]
	v_mfma_f32_16x16x32_bf16 v[2:5], v[172:175], v[204:207], v[2:5]
	v_mfma_f32_16x16x32_bf16 v[6:9], v[164:167], v[204:207], v[6:9]
	v_mfma_f32_16x16x32_bf16 v[54:57], v[168:171], v[184:187], v[54:57]
	v_mfma_f32_16x16x32_bf16 v[50:53], v[176:179], v[184:187], v[50:53]
	v_mfma_f32_16x16x32_bf16 v[34:37], v[176:179], v[192:195], v[34:37]
	v_mfma_f32_16x16x32_bf16 v[38:41], v[168:171], v[192:195], v[38:41]
	v_mfma_f32_16x16x32_bf16 v[22:25], v[168:171], v[200:203], v[22:25]
	v_mfma_f32_16x16x32_bf16 v[18:21], v[176:179], v[200:203], v[18:21]
	s_setprio 2
	s_barrier
	v_mfma_f32_16x16x32_bf16 v[2:5], v[176:179], v[208:211], v[2:5]
	v_mfma_f32_16x16x32_bf16 v[6:9], v[168:171], v[208:211], v[6:9]
	s_setprio 0
	s_add_i32 s73, s73, 2
	s_add_u32 s66, s66, 0x100
	s_addc_u32 s67, s67, 0
	s_add_u32 s18, s18, 0x100
	s_addc_u32 s19, s19, 0
	s_add_u32 s70, s70, 0x100
	s_addc_u32 s71, s71, 0
	s_cmp_gt_u32 s73, 29
	.p2align 6
.LBB0_1785:
	ds_read_b128 v[148:151], v143
	ds_read_b128 v[152:155], v143 offset:1024
	ds_read_b128 v[156:159], v143 offset:2048
	ds_read_b128 v[160:163], v143 offset:3072
	ds_read_b128 v[164:167], v144
	ds_read_b128 v[168:171], v144 offset:1024
	ds_read_b128 v[172:175], v144 offset:2048
	ds_read_b128 v[176:179], v144 offset:3072
	s_cmp_eq_u32 s73, 28
	s_cselect_b32 s21, s9, s67
	s_cselect_b32 s20, s65, s66
	s_cselect_b32 s23, s11, s71
	s_cselect_b32 s22, s64, s70
	ds_read_b128 v[180:183], v145
	ds_read_b128 v[184:187], v145 offset:1024
	ds_read_b128 v[188:191], v145 offset:2048
	ds_read_b128 v[192:195], v145 offset:3072
	ds_read_b128 v[196:199], v145 offset:4096
	ds_read_b128 v[200:203], v145 offset:5120
	ds_read_b128 v[204:207], v145 offset:6144
	ds_read_b128 v[208:211], v145 offset:7168
	s_add_u32 s74, s18, 0xfff80000
	s_addc_u32 s75, s19, -1
	s_mov_b32 s76, m0
	s_mov_b32 m0, s56
	s_nop 0
	global_load_lds_dwordx4 v138, s[74:75]
	s_mov_b32 m0, s76
	s_nop 0
	s_mov_b32 s76, m0
	s_mov_b32 m0, s59
	s_nop 0
	global_load_lds_dwordx4 v140, s[74:75]
	s_mov_b32 m0, s76
	s_mov_b32 s74, m0
	s_mov_b32 m0, s57
	s_nop 0
	global_load_lds_dwordx4 v138, s[18:19]
	s_mov_b32 m0, s74
	s_nop 0
	s_mov_b32 s74, m0
	s_mov_b32 m0, s62
	s_nop 0
	global_load_lds_dwordx4 v140, s[18:19]
	s_mov_b32 m0, s74
	s_waitcnt vmcnt(8)
	s_waitcnt lgkmcnt(0)
	s_barrier
	s_setprio 1
	s_waitcnt lgkmcnt(7)
	v_mfma_f32_16x16x32_bf16 v[126:129], v[148:151], v[180:183], v[126:129]
	v_mfma_f32_16x16x32_bf16 v[122:125], v[156:159], v[180:183], v[122:125]
	s_waitcnt lgkmcnt(5)
	v_mfma_f32_16x16x32_bf16 v[106:109], v[156:159], v[188:191], v[106:109]
	v_mfma_f32_16x16x32_bf16 v[110:113], v[148:151], v[188:191], v[110:113]
	s_waitcnt lgkmcnt(3)
	v_mfma_f32_16x16x32_bf16 v[94:97], v[148:151], v[196:199], v[94:97]
	v_mfma_f32_16x16x32_bf16 v[90:93], v[156:159], v[196:199], v[90:93]
	s_waitcnt lgkmcnt(1)
	v_mfma_f32_16x16x32_bf16 v[74:77], v[156:159], v[204:207], v[74:77]
	v_mfma_f32_16x16x32_bf16 v[78:81], v[148:151], v[204:207], v[78:81]
	v_mfma_f32_16x16x32_bf16 v[126:129], v[152:155], v[184:187], v[126:129]
	v_mfma_f32_16x16x32_bf16 v[122:125], v[160:163], v[184:187], v[122:125]
	v_mfma_f32_16x16x32_bf16 v[106:109], v[160:163], v[192:195], v[106:109]
	v_mfma_f32_16x16x32_bf16 v[110:113], v[152:155], v[192:195], v[110:113]
	v_mfma_f32_16x16x32_bf16 v[94:97], v[152:155], v[200:203], v[94:97]
	v_mfma_f32_16x16x32_bf16 v[90:93], v[160:163], v[200:203], v[90:93]
	s_waitcnt lgkmcnt(0)
	v_mfma_f32_16x16x32_bf16 v[74:77], v[160:163], v[208:211], v[74:77]
	v_mfma_f32_16x16x32_bf16 v[78:81], v[152:155], v[208:211], v[78:81]
	s_setprio 0
	s_setprio 1
	v_mfma_f32_16x16x32_bf16 v[118:121], v[164:167], v[180:183], v[118:121]
	v_mfma_f32_16x16x32_bf16 v[114:117], v[172:175], v[180:183], v[114:117]
	v_mfma_f32_16x16x32_bf16 v[98:101], v[172:175], v[188:191], v[98:101]
	v_mfma_f32_16x16x32_bf16 v[102:105], v[164:167], v[188:191], v[102:105]
	v_mfma_f32_16x16x32_bf16 v[86:89], v[164:167], v[196:199], v[86:89]
	v_mfma_f32_16x16x32_bf16 v[82:85], v[172:175], v[196:199], v[82:85]
	v_mfma_f32_16x16x32_bf16 v[66:69], v[172:175], v[204:207], v[66:69]
	v_mfma_f32_16x16x32_bf16 v[70:73], v[164:167], v[204:207], v[70:73]
	v_mfma_f32_16x16x32_bf16 v[118:121], v[168:171], v[184:187], v[118:121]
	v_mfma_f32_16x16x32_bf16 v[114:117], v[176:179], v[184:187], v[114:117]
	v_mfma_f32_16x16x32_bf16 v[98:101], v[176:179], v[192:195], v[98:101]
	v_mfma_f32_16x16x32_bf16 v[102:105], v[168:171], v[192:195], v[102:105]
	v_mfma_f32_16x16x32_bf16 v[86:89], v[168:171], v[200:203], v[86:89]
	v_mfma_f32_16x16x32_bf16 v[82:85], v[176:179], v[200:203], v[82:85]
	s_setprio 2
	s_barrier
	v_mfma_f32_16x16x32_bf16 v[66:69], v[176:179], v[208:211], v[66:69]
	v_mfma_f32_16x16x32_bf16 v[70:73], v[168:171], v[208:211], v[70:73]
	s_setprio 0
	ds_read_b128 v[180:183], v145 offset:16384
	ds_read_b128 v[184:187], v145 offset:17408
	ds_read_b128 v[188:191], v145 offset:18432
	ds_read_b128 v[192:195], v145 offset:19456
	ds_read_b128 v[196:199], v145 offset:20480
	ds_read_b128 v[200:203], v145 offset:21504
	ds_read_b128 v[204:207], v145 offset:22528
	ds_read_b128 v[208:211], v145 offset:23552
	s_mov_b32 s74, m0
	s_mov_b32 m0, s35
	s_nop 0
	global_load_lds_dwordx4 v139, s[20:21]
	s_mov_b32 m0, s74
	s_nop 0
	s_mov_b32 s74, m0
	s_mov_b32 m0, s36
	s_nop 0
	global_load_lds_dwordx4 v141, s[20:21]
	s_mov_b32 m0, s74
	s_add_u32 s74, s20, 0x80000
	s_addc_u32 s75, s21, 0
	s_mov_b32 s76, m0
	s_mov_b32 m0, s37
	s_nop 0
	global_load_lds_dwordx4 v139, s[74:75]
	s_mov_b32 m0, s76
	s_nop 0
	s_mov_b32 s76, m0
	s_mov_b32 m0, s40
	s_nop 0
	global_load_lds_dwordx4 v141, s[74:75]
	s_mov_b32 m0, s76
	s_waitcnt vmcnt(4)
	s_waitcnt lgkmcnt(0)
	s_barrier
	s_setprio 1
	s_waitcnt lgkmcnt(7)
	v_mfma_f32_16x16x32_bf16 v[62:65], v[148:151], v[180:183], v[62:65]
	v_mfma_f32_16x16x32_bf16 v[58:61], v[156:159], v[180:183], v[58:61]
	s_waitcnt lgkmcnt(5)
	v_mfma_f32_16x16x32_bf16 v[42:45], v[156:159], v[188:191], v[42:45]
	v_mfma_f32_16x16x32_bf16 v[46:49], v[148:151], v[188:191], v[46:49]
	s_waitcnt lgkmcnt(3)
	v_mfma_f32_16x16x32_bf16 v[30:33], v[148:151], v[196:199], v[30:33]
	v_mfma_f32_16x16x32_bf16 v[26:29], v[156:159], v[196:199], v[26:29]
	s_waitcnt lgkmcnt(1)
	v_mfma_f32_16x16x32_bf16 v[10:13], v[156:159], v[204:207], v[10:13]
	v_mfma_f32_16x16x32_bf16 v[14:17], v[148:151], v[204:207], v[14:17]
	v_mfma_f32_16x16x32_bf16 v[62:65], v[152:155], v[184:187], v[62:65]
	v_mfma_f32_16x16x32_bf16 v[58:61], v[160:163], v[184:187], v[58:61]
	v_mfma_f32_16x16x32_bf16 v[42:45], v[160:163], v[192:195], v[42:45]
	v_mfma_f32_16x16x32_bf16 v[46:49], v[152:155], v[192:195], v[46:49]
	v_mfma_f32_16x16x32_bf16 v[30:33], v[152:155], v[200:203], v[30:33]
	v_mfma_f32_16x16x32_bf16 v[26:29], v[160:163], v[200:203], v[26:29]
	s_waitcnt lgkmcnt(0)
	v_mfma_f32_16x16x32_bf16 v[10:13], v[160:163], v[208:211], v[10:13]
	v_mfma_f32_16x16x32_bf16 v[14:17], v[152:155], v[208:211], v[14:17]
	s_setprio 0
	s_setprio 1
	v_mfma_f32_16x16x32_bf16 v[54:57], v[164:167], v[180:183], v[54:57]
	v_mfma_f32_16x16x32_bf16 v[50:53], v[172:175], v[180:183], v[50:53]
	v_mfma_f32_16x16x32_bf16 v[34:37], v[172:175], v[188:191], v[34:37]
	v_mfma_f32_16x16x32_bf16 v[38:41], v[164:167], v[188:191], v[38:41]
	v_mfma_f32_16x16x32_bf16 v[22:25], v[164:167], v[196:199], v[22:25]
	v_mfma_f32_16x16x32_bf16 v[18:21], v[172:175], v[196:199], v[18:21]
	v_mfma_f32_16x16x32_bf16 v[2:5], v[172:175], v[204:207], v[2:5]
	v_mfma_f32_16x16x32_bf16 v[6:9], v[164:167], v[204:207], v[6:9]
	v_mfma_f32_16x16x32_bf16 v[54:57], v[168:171], v[184:187], v[54:57]
	v_mfma_f32_16x16x32_bf16 v[50:53], v[176:179], v[184:187], v[50:53]
	v_mfma_f32_16x16x32_bf16 v[34:37], v[176:179], v[192:195], v[34:37]
	v_mfma_f32_16x16x32_bf16 v[38:41], v[168:171], v[192:195], v[38:41]
	v_mfma_f32_16x16x32_bf16 v[22:25], v[168:171], v[200:203], v[22:25]
	v_mfma_f32_16x16x32_bf16 v[18:21], v[176:179], v[200:203], v[18:21]
	s_setprio 2
	s_barrier
	v_mfma_f32_16x16x32_bf16 v[2:5], v[176:179], v[208:211], v[2:5]
	v_mfma_f32_16x16x32_bf16 v[6:9], v[168:171], v[208:211], v[6:9]
	s_setprio 0
	ds_read_b128 v[148:151], v146
	ds_read_b128 v[152:155], v146 offset:1024
	ds_read_b128 v[156:159], v146 offset:2048
	ds_read_b128 v[160:163], v146 offset:3072
	ds_read_b128 v[164:167], v147
	ds_read_b128 v[168:171], v147 offset:1024
	ds_read_b128 v[172:175], v147 offset:2048
	ds_read_b128 v[176:179], v147 offset:3072
	ds_read_b128 v[180:183], v145 offset:32768
	ds_read_b128 v[184:187], v145 offset:33792
	ds_read_b128 v[188:191], v145 offset:34816
	ds_read_b128 v[192:195], v145 offset:35840
	ds_read_b128 v[196:199], v145 offset:36864
	ds_read_b128 v[200:203], v145 offset:37888
	ds_read_b128 v[204:207], v145 offset:38912
	ds_read_b128 v[208:211], v145 offset:39936
	s_mov_b32 s74, m0
	s_mov_b32 m0, s31
	s_nop 0
	global_load_lds_dwordx4 v138, s[22:23]
	s_mov_b32 m0, s74
	s_nop 0
	s_mov_b32 s74, m0
	s_mov_b32 m0, s41
	s_nop 0
	global_load_lds_dwordx4 v140, s[22:23]
	s_mov_b32 m0, s74
	s_add_u32 s22, s22, 0x80000
	s_addc_u32 s23, s23, 0
	s_mov_b32 s74, m0
	s_mov_b32 m0, s42
	s_nop 0
	global_load_lds_dwordx4 v138, s[22:23]
	s_mov_b32 m0, s74
	s_nop 0
	s_mov_b32 s74, m0
	s_mov_b32 m0, s43
	s_nop 0
	global_load_lds_dwordx4 v140, s[22:23]
	s_mov_b32 m0, s74
	s_waitcnt vmcnt(8)
	s_waitcnt lgkmcnt(0)
	s_barrier
	s_setprio 1
	s_waitcnt lgkmcnt(7)
	v_mfma_f32_16x16x32_bf16 v[126:129], v[148:151], v[180:183], v[126:129]
	v_mfma_f32_16x16x32_bf16 v[122:125], v[156:159], v[180:183], v[122:125]
	s_waitcnt lgkmcnt(5)
	v_mfma_f32_16x16x32_bf16 v[106:109], v[156:159], v[188:191], v[106:109]
	v_mfma_f32_16x16x32_bf16 v[110:113], v[148:151], v[188:191], v[110:113]
	s_waitcnt lgkmcnt(3)
	v_mfma_f32_16x16x32_bf16 v[94:97], v[148:151], v[196:199], v[94:97]
	v_mfma_f32_16x16x32_bf16 v[90:93], v[156:159], v[196:199], v[90:93]
	s_waitcnt lgkmcnt(1)
	v_mfma_f32_16x16x32_bf16 v[74:77], v[156:159], v[204:207], v[74:77]
	v_mfma_f32_16x16x32_bf16 v[78:81], v[148:151], v[204:207], v[78:81]
	v_mfma_f32_16x16x32_bf16 v[126:129], v[152:155], v[184:187], v[126:129]
	v_mfma_f32_16x16x32_bf16 v[122:125], v[160:163], v[184:187], v[122:125]
	v_mfma_f32_16x16x32_bf16 v[106:109], v[160:163], v[192:195], v[106:109]
	v_mfma_f32_16x16x32_bf16 v[110:113], v[152:155], v[192:195], v[110:113]
	v_mfma_f32_16x16x32_bf16 v[94:97], v[152:155], v[200:203], v[94:97]
	v_mfma_f32_16x16x32_bf16 v[90:93], v[160:163], v[200:203], v[90:93]
	s_waitcnt lgkmcnt(0)
	v_mfma_f32_16x16x32_bf16 v[74:77], v[160:163], v[208:211], v[74:77]
	v_mfma_f32_16x16x32_bf16 v[78:81], v[152:155], v[208:211], v[78:81]
	s_setprio 0
	s_setprio 1
	v_mfma_f32_16x16x32_bf16 v[118:121], v[164:167], v[180:183], v[118:121]
	v_mfma_f32_16x16x32_bf16 v[114:117], v[172:175], v[180:183], v[114:117]
	v_mfma_f32_16x16x32_bf16 v[98:101], v[172:175], v[188:191], v[98:101]
	v_mfma_f32_16x16x32_bf16 v[102:105], v[164:167], v[188:191], v[102:105]
	v_mfma_f32_16x16x32_bf16 v[86:89], v[164:167], v[196:199], v[86:89]
	v_mfma_f32_16x16x32_bf16 v[82:85], v[172:175], v[196:199], v[82:85]
	v_mfma_f32_16x16x32_bf16 v[66:69], v[172:175], v[204:207], v[66:69]
	v_mfma_f32_16x16x32_bf16 v[70:73], v[164:167], v[204:207], v[70:73]
	v_mfma_f32_16x16x32_bf16 v[118:121], v[168:171], v[184:187], v[118:121]
	v_mfma_f32_16x16x32_bf16 v[114:117], v[176:179], v[184:187], v[114:117]
	v_mfma_f32_16x16x32_bf16 v[98:101], v[176:179], v[192:195], v[98:101]
	v_mfma_f32_16x16x32_bf16 v[102:105], v[168:171], v[192:195], v[102:105]
	v_mfma_f32_16x16x32_bf16 v[86:89], v[168:171], v[200:203], v[86:89]
	v_mfma_f32_16x16x32_bf16 v[82:85], v[176:179], v[200:203], v[82:85]
	s_setprio 2
	s_barrier
	v_mfma_f32_16x16x32_bf16 v[66:69], v[176:179], v[208:211], v[66:69]
	v_mfma_f32_16x16x32_bf16 v[70:73], v[168:171], v[208:211], v[70:73]
	s_setprio 0
	ds_read_b128 v[180:183], v145 offset:49152
	ds_read_b128 v[184:187], v145 offset:50176
	ds_read_b128 v[188:191], v145 offset:51200
	ds_read_b128 v[192:195], v145 offset:52224
	ds_read_b128 v[196:199], v145 offset:53248
	ds_read_b128 v[200:203], v145 offset:54272
	ds_read_b128 v[204:207], v145 offset:55296
	ds_read_b128 v[208:211], v145 offset:56320
	s_add_u32 s22, s20, 0x80
	s_addc_u32 s23, s21, 0
	s_mov_b32 s74, m0
	s_mov_b32 m0, s46
	s_nop 0
	global_load_lds_dwordx4 v139, s[22:23]
	s_mov_b32 m0, s74
	s_add_u32 s20, s20, 0x80080
	s_mov_b32 s74, m0
	s_mov_b32 m0, s47
	s_nop 0
	global_load_lds_dwordx4 v141, s[22:23]
	s_mov_b32 m0, s74
	s_addc_u32 s21, s21, 0
	s_mov_b32 s22, m0
	s_mov_b32 m0, s48
	s_nop 0
	global_load_lds_dwordx4 v139, s[20:21]
	s_mov_b32 m0, s22
	s_nop 0
	s_mov_b32 s22, m0
	s_mov_b32 m0, s49
	s_nop 0
	global_load_lds_dwordx4 v141, s[20:21]
	s_mov_b32 m0, s22
	s_waitcnt vmcnt(4)
	s_waitcnt lgkmcnt(0)
	s_barrier
	s_setprio 1
	s_waitcnt lgkmcnt(7)
	v_mfma_f32_16x16x32_bf16 v[62:65], v[148:151], v[180:183], v[62:65]
	v_mfma_f32_16x16x32_bf16 v[58:61], v[156:159], v[180:183], v[58:61]
	s_waitcnt lgkmcnt(5)
	v_mfma_f32_16x16x32_bf16 v[42:45], v[156:159], v[188:191], v[42:45]
	v_mfma_f32_16x16x32_bf16 v[46:49], v[148:151], v[188:191], v[46:49]
	s_waitcnt lgkmcnt(3)
	v_mfma_f32_16x16x32_bf16 v[30:33], v[148:151], v[196:199], v[30:33]
	v_mfma_f32_16x16x32_bf16 v[26:29], v[156:159], v[196:199], v[26:29]
	s_waitcnt lgkmcnt(1)
	v_mfma_f32_16x16x32_bf16 v[10:13], v[156:159], v[204:207], v[10:13]
	v_mfma_f32_16x16x32_bf16 v[14:17], v[148:151], v[204:207], v[14:17]
	v_mfma_f32_16x16x32_bf16 v[62:65], v[152:155], v[184:187], v[62:65]
	v_mfma_f32_16x16x32_bf16 v[58:61], v[160:163], v[184:187], v[58:61]
	v_mfma_f32_16x16x32_bf16 v[42:45], v[160:163], v[192:195], v[42:45]
	v_mfma_f32_16x16x32_bf16 v[46:49], v[152:155], v[192:195], v[46:49]
	v_mfma_f32_16x16x32_bf16 v[30:33], v[152:155], v[200:203], v[30:33]
	v_mfma_f32_16x16x32_bf16 v[26:29], v[160:163], v[200:203], v[26:29]
	s_waitcnt lgkmcnt(0)
	v_mfma_f32_16x16x32_bf16 v[10:13], v[160:163], v[208:211], v[10:13]
	v_mfma_f32_16x16x32_bf16 v[14:17], v[152:155], v[208:211], v[14:17]
	s_setprio 0
	s_setprio 1
	v_mfma_f32_16x16x32_bf16 v[54:57], v[164:167], v[180:183], v[54:57]
	v_mfma_f32_16x16x32_bf16 v[50:53], v[172:175], v[180:183], v[50:53]
	v_mfma_f32_16x16x32_bf16 v[34:37], v[172:175], v[188:191], v[34:37]
	v_mfma_f32_16x16x32_bf16 v[38:41], v[164:167], v[188:191], v[38:41]
	v_mfma_f32_16x16x32_bf16 v[22:25], v[164:167], v[196:199], v[22:25]
	v_mfma_f32_16x16x32_bf16 v[18:21], v[172:175], v[196:199], v[18:21]
	v_mfma_f32_16x16x32_bf16 v[2:5], v[172:175], v[204:207], v[2:5]
	v_mfma_f32_16x16x32_bf16 v[6:9], v[164:167], v[204:207], v[6:9]
	v_mfma_f32_16x16x32_bf16 v[54:57], v[168:171], v[184:187], v[54:57]
	v_mfma_f32_16x16x32_bf16 v[50:53], v[176:179], v[184:187], v[50:53]
	v_mfma_f32_16x16x32_bf16 v[34:37], v[176:179], v[192:195], v[34:37]
	v_mfma_f32_16x16x32_bf16 v[38:41], v[168:171], v[192:195], v[38:41]
	v_mfma_f32_16x16x32_bf16 v[22:25], v[168:171], v[200:203], v[22:25]
	v_mfma_f32_16x16x32_bf16 v[18:21], v[176:179], v[200:203], v[18:21]
	s_setprio 2
	s_barrier
	v_mfma_f32_16x16x32_bf16 v[2:5], v[176:179], v[208:211], v[2:5]
	v_mfma_f32_16x16x32_bf16 v[6:9], v[168:171], v[208:211], v[6:9]
	s_setprio 0
	s_add_i32 s73, s73, 2
	s_add_u32 s66, s66, 0x100
	s_addc_u32 s67, s67, 0
	s_add_u32 s18, s18, 0x100
	s_addc_u32 s19, s19, 0
	s_add_u32 s70, s70, 0x100
	s_addc_u32 s71, s71, 0
	s_cmp_gt_u32 s73, 29
	s_cbranch_scc0 .LBB0_1785
	s_and_b64 vcc, exec, s[6:7]
	s_cbranch_vccz .LBB0_1788
	s_barrier

.LBB0_1951:
	s_ashr_i32 s13, s12, 31
	s_lshl_b64 s[14:15], s[12:13], 15
	s_add_u32 s14, s28, s14
	s_addc_u32 s15, s29, s15
	s_and_b64 s[16:17], s[2:3], exec
	s_cselect_b32 s13, s15, s23
	s_cselect_b32 s65, s14, s22
	s_ashr_i32 s11, s10, 31
	s_lshl_b64 s[16:17], s[10:11], 15
	s_add_u32 s16, s30, s16
	s_addc_u32 s17, s31, s17
	s_and_b64 s[24:25], s[2:3], exec
	s_cselect_b32 s11, s17, s21
	s_cselect_b32 s66, s16, s20
	s_add_u32 s67, s20, 0x80000
	s_addc_u32 s70, s21, 0
	s_add_u32 s20, s22, 0x204000
	s_addc_u32 s21, s23, 0
	s_add_u32 s71, s22, 0x400000
	s_addc_u32 s73, s23, 0
	s_mov_b32 s74, -2
	s_waitcnt vmcnt(25)
	s_waitcnt vmcnt(24)
	s_waitcnt vmcnt(4)
	s_waitcnt vmcnt(2)
	s_waitcnt vmcnt(1)
	s_waitcnt vmcnt(0)
	ds_read_b128 v[130:133], v181
	ds_read_b128 v[134:137], v181 offset:1024
	ds_read_b128 v[138:141], v181 offset:2048
	ds_read_b128 v[142:145], v181 offset:3072
	ds_read_b128 v[150:153], v182
	ds_read_b128 v[154:157], v182 offset:1024
	ds_read_b128 v[158:161], v182 offset:2048
	ds_read_b128 v[162:165], v182 offset:3072
	s_cmpk_eq_i32 s74, 0x52
	s_cselect_b32 s23, s11, s70
	s_cselect_b32 s22, s66, s67
	s_cselect_b32 s25, s13, s73
	s_cselect_b32 s24, s65, s71
	ds_read_b128 v[166:169], v183
	ds_read_b128 v[170:173], v183 offset:1024
	ds_read_b128 v[186:189], v183 offset:2048
	ds_read_b128 v[190:193], v183 offset:3072
	ds_read_b128 v[194:197], v183 offset:4096
	ds_read_b128 v[198:201], v183 offset:5120
	ds_read_b128 v[202:205], v183 offset:6144
	ds_read_b128 v[206:209], v183 offset:7168
	s_add_u32 s76, s20, 0xffffc000
	s_addc_u32 s77, s21, -1
	s_mov_b32 s75, m0
	s_mov_b32 m0, s58
	s_nop 0
	global_load_lds_dwordx4 v1, s[76:77]
	s_mov_b32 m0, s75
	s_nop 0
	s_mov_b32 s75, m0
	s_mov_b32 m0, s62
	s_nop 0
	global_load_lds_dwordx4 v177, s[76:77]
	s_mov_b32 m0, s75
	s_nop 0
	s_mov_b32 s75, m0
	s_mov_b32 m0, s59
	s_nop 0
	global_load_lds_dwordx4 v1, s[20:21]
	s_mov_b32 m0, s75
	s_nop 0
	s_mov_b32 s75, m0
	s_mov_b32 m0, s63
	s_nop 0
	global_load_lds_dwordx4 v177, s[20:21]
	s_mov_b32 m0, s75
	s_waitcnt vmcnt(8)
	s_waitcnt lgkmcnt(0)
	s_barrier
	s_setprio 1
	s_waitcnt lgkmcnt(7)
	v_mfma_f32_16x16x32_bf16 v[126:129], v[130:133], v[166:169], 0
	v_mfma_f32_16x16x32_bf16 v[122:125], v[138:141], v[166:169], 0
	s_waitcnt lgkmcnt(5)
	v_mfma_f32_16x16x32_bf16 v[110:113], v[138:141], v[186:189], 0
	v_mfma_f32_16x16x32_bf16 v[118:121], v[130:133], v[186:189], 0
	s_waitcnt lgkmcnt(3)
	v_mfma_f32_16x16x32_bf16 v[94:97], v[130:133], v[194:197], 0
	v_mfma_f32_16x16x32_bf16 v[90:93], v[138:141], v[194:197], 0
	s_waitcnt lgkmcnt(1)
	v_mfma_f32_16x16x32_bf16 v[78:81], v[138:141], v[202:205], 0
	v_mfma_f32_16x16x32_bf16 v[86:89], v[130:133], v[202:205], 0
	v_mfma_f32_16x16x32_bf16 v[126:129], v[134:137], v[170:173], v[126:129]
	v_mfma_f32_16x16x32_bf16 v[122:125], v[142:145], v[170:173], v[122:125]
	v_mfma_f32_16x16x32_bf16 v[110:113], v[142:145], v[190:193], v[110:113]
	v_mfma_f32_16x16x32_bf16 v[118:121], v[134:137], v[190:193], v[118:121]
	v_mfma_f32_16x16x32_bf16 v[94:97], v[134:137], v[198:201], v[94:97]
	v_mfma_f32_16x16x32_bf16 v[90:93], v[142:145], v[198:201], v[90:93]
	s_waitcnt lgkmcnt(0)
	v_mfma_f32_16x16x32_bf16 v[78:81], v[142:145], v[206:209], v[78:81]
	v_mfma_f32_16x16x32_bf16 v[86:89], v[134:137], v[206:209], v[86:89]
	s_setprio 0
	s_setprio 1
	v_mfma_f32_16x16x32_bf16 v[114:117], v[150:153], v[166:169], 0
	v_mfma_f32_16x16x32_bf16 v[106:109], v[158:161], v[166:169], 0
	v_mfma_f32_16x16x32_bf16 v[98:101], v[158:161], v[186:189], 0
	v_mfma_f32_16x16x32_bf16 v[102:105], v[150:153], v[186:189], 0
	v_mfma_f32_16x16x32_bf16 v[82:85], v[150:153], v[194:197], 0
	v_mfma_f32_16x16x32_bf16 v[74:77], v[158:161], v[194:197], 0
	v_mfma_f32_16x16x32_bf16 v[66:69], v[158:161], v[202:205], 0
	v_mfma_f32_16x16x32_bf16 v[70:73], v[150:153], v[202:205], 0
	v_mfma_f32_16x16x32_bf16 v[114:117], v[154:157], v[170:173], v[114:117]
	v_mfma_f32_16x16x32_bf16 v[106:109], v[162:165], v[170:173], v[106:109]
	v_mfma_f32_16x16x32_bf16 v[98:101], v[162:165], v[190:193], v[98:101]
	v_mfma_f32_16x16x32_bf16 v[102:105], v[154:157], v[190:193], v[102:105]
	v_mfma_f32_16x16x32_bf16 v[82:85], v[154:157], v[198:201], v[82:85]
	v_mfma_f32_16x16x32_bf16 v[74:77], v[162:165], v[198:201], v[74:77]
	s_setprio 2
	s_barrier
	v_mfma_f32_16x16x32_bf16 v[66:69], v[162:165], v[206:209], v[66:69]
	v_mfma_f32_16x16x32_bf16 v[70:73], v[154:157], v[206:209], v[70:73]
	s_setprio 0
	ds_read_b128 v[166:169], v183 offset:16384
	ds_read_b128 v[170:173], v183 offset:17408
	ds_read_b128 v[186:189], v183 offset:18432
	ds_read_b128 v[190:193], v183 offset:19456
	ds_read_b128 v[194:197], v183 offset:20480
	ds_read_b128 v[198:201], v183 offset:21504
	ds_read_b128 v[202:205], v183 offset:22528
	ds_read_b128 v[206:209], v183 offset:23552
	s_mov_b32 s75, m0
	s_mov_b32 m0, s35
	s_nop 0
	global_load_lds_dwordx4 v176, s[22:23]
	s_mov_b32 m0, s75
	s_add_u32 s76, s22, 0x4000
	s_mov_b32 s75, m0
	s_mov_b32 m0, s36
	s_nop 0
	global_load_lds_dwordx4 v178, s[22:23]
	s_mov_b32 m0, s75
	s_addc_u32 s77, s23, 0
	s_mov_b32 s75, m0
	s_mov_b32 m0, s37
	s_nop 0
	global_load_lds_dwordx4 v176, s[76:77]
	s_mov_b32 m0, s75
	s_nop 0
	s_mov_b32 s75, m0
	s_mov_b32 m0, s40
	s_nop 0
	global_load_lds_dwordx4 v178, s[76:77]
	s_mov_b32 m0, s75
	s_waitcnt vmcnt(4)
	s_waitcnt lgkmcnt(0)
	s_barrier
	s_setprio 1
	s_waitcnt lgkmcnt(7)
	v_mfma_f32_16x16x32_bf16 v[62:65], v[130:133], v[166:169], 0
	v_mfma_f32_16x16x32_bf16 v[58:61], v[138:141], v[166:169], 0
	s_waitcnt lgkmcnt(5)
	v_mfma_f32_16x16x32_bf16 v[42:45], v[138:141], v[186:189], 0
	v_mfma_f32_16x16x32_bf16 v[46:49], v[130:133], v[186:189], 0
	s_waitcnt lgkmcnt(3)
	v_mfma_f32_16x16x32_bf16 v[30:33], v[130:133], v[194:197], 0
	v_mfma_f32_16x16x32_bf16 v[26:29], v[138:141], v[194:197], 0
	s_waitcnt lgkmcnt(1)
	v_mfma_f32_16x16x32_bf16 v[10:13], v[138:141], v[202:205], 0
	v_mfma_f32_16x16x32_bf16 v[14:17], v[130:133], v[202:205], 0
	v_mfma_f32_16x16x32_bf16 v[62:65], v[134:137], v[170:173], v[62:65]
	v_mfma_f32_16x16x32_bf16 v[58:61], v[142:145], v[170:173], v[58:61]
	v_mfma_f32_16x16x32_bf16 v[42:45], v[142:145], v[190:193], v[42:45]
	v_mfma_f32_16x16x32_bf16 v[46:49], v[134:137], v[190:193], v[46:49]
	v_mfma_f32_16x16x32_bf16 v[30:33], v[134:137], v[198:201], v[30:33]
	v_mfma_f32_16x16x32_bf16 v[26:29], v[142:145], v[198:201], v[26:29]
	s_waitcnt lgkmcnt(0)
	v_mfma_f32_16x16x32_bf16 v[10:13], v[142:145], v[206:209], v[10:13]
	v_mfma_f32_16x16x32_bf16 v[14:17], v[134:137], v[206:209], v[14:17]
	s_setprio 0
	s_setprio 1
	v_mfma_f32_16x16x32_bf16 v[54:57], v[150:153], v[166:169], 0
	v_mfma_f32_16x16x32_bf16 v[50:53], v[158:161], v[166:169], 0
	v_mfma_f32_16x16x32_bf16 v[34:37], v[158:161], v[186:189], 0
	v_mfma_f32_16x16x32_bf16 v[38:41], v[150:153], v[186:189], 0
	v_mfma_f32_16x16x32_bf16 v[22:25], v[150:153], v[194:197], 0
	v_mfma_f32_16x16x32_bf16 v[18:21], v[158:161], v[194:197], 0
	v_mfma_f32_16x16x32_bf16 v[2:5], v[158:161], v[202:205], 0
	v_mfma_f32_16x16x32_bf16 v[6:9], v[150:153], v[202:205], 0
	v_mfma_f32_16x16x32_bf16 v[54:57], v[154:157], v[170:173], v[54:57]
	v_mfma_f32_16x16x32_bf16 v[50:53], v[162:165], v[170:173], v[50:53]
	v_mfma_f32_16x16x32_bf16 v[34:37], v[162:165], v[190:193], v[34:37]
	v_mfma_f32_16x16x32_bf16 v[38:41], v[154:157], v[190:193], v[38:41]
	v_mfma_f32_16x16x32_bf16 v[22:25], v[154:157], v[198:201], v[22:25]
	v_mfma_f32_16x16x32_bf16 v[18:21], v[162:165], v[198:201], v[18:21]
	s_setprio 2
	s_barrier
	v_mfma_f32_16x16x32_bf16 v[2:5], v[162:165], v[206:209], v[2:5]
	v_mfma_f32_16x16x32_bf16 v[6:9], v[154:157], v[206:209], v[6:9]
	s_setprio 0
	ds_read_b128 v[130:133], v184
	ds_read_b128 v[134:137], v184 offset:1024
	ds_read_b128 v[138:141], v184 offset:2048
	ds_read_b128 v[142:145], v184 offset:3072
	ds_read_b128 v[150:153], v185
	ds_read_b128 v[154:157], v185 offset:1024
	ds_read_b128 v[158:161], v185 offset:2048
	ds_read_b128 v[162:165], v185 offset:3072
	ds_read_b128 v[166:169], v183 offset:32768
	ds_read_b128 v[170:173], v183 offset:33792
	ds_read_b128 v[186:189], v183 offset:34816
	ds_read_b128 v[190:193], v183 offset:35840
	ds_read_b128 v[194:197], v183 offset:36864
	ds_read_b128 v[198:201], v183 offset:37888
	ds_read_b128 v[202:205], v183 offset:38912
	ds_read_b128 v[206:209], v183 offset:39936
	s_mov_b32 s75, m0
	s_mov_b32 m0, s34
	s_nop 0
	global_load_lds_dwordx4 v1, s[24:25]
	s_mov_b32 m0, s75
	s_nop 0
	s_mov_b32 s75, m0
	s_mov_b32 m0, s41
	s_nop 0
	global_load_lds_dwordx4 v177, s[24:25]
	s_mov_b32 m0, s75
	s_add_u32 s24, s24, 0x4000
	s_addc_u32 s25, s25, 0
	s_mov_b32 s75, m0
	s_mov_b32 m0, s42
	s_nop 0
	global_load_lds_dwordx4 v1, s[24:25]
	s_mov_b32 m0, s75
	s_nop 0
	s_mov_b32 s75, m0
	s_mov_b32 m0, s43
	s_nop 0
	global_load_lds_dwordx4 v177, s[24:25]
	s_mov_b32 m0, s75
	s_waitcnt vmcnt(8)
	s_waitcnt lgkmcnt(0)
	s_barrier
	s_setprio 1
	s_waitcnt lgkmcnt(7)
	v_mfma_f32_16x16x32_bf16 v[126:129], v[130:133], v[166:169], v[126:129]
	v_mfma_f32_16x16x32_bf16 v[122:125], v[138:141], v[166:169], v[122:125]
	s_waitcnt lgkmcnt(5)
	v_mfma_f32_16x16x32_bf16 v[110:113], v[138:141], v[186:189], v[110:113]
	v_mfma_f32_16x16x32_bf16 v[118:121], v[130:133], v[186:189], v[118:121]
	s_waitcnt lgkmcnt(3)
	v_mfma_f32_16x16x32_bf16 v[94:97], v[130:133], v[194:197], v[94:97]
	v_mfma_f32_16x16x32_bf16 v[90:93], v[138:141], v[194:197], v[90:93]
	s_waitcnt lgkmcnt(1)
	v_mfma_f32_16x16x32_bf16 v[78:81], v[138:141], v[202:205], v[78:81]
	v_mfma_f32_16x16x32_bf16 v[86:89], v[130:133], v[202:205], v[86:89]
	v_mfma_f32_16x16x32_bf16 v[126:129], v[134:137], v[170:173], v[126:129]
	v_mfma_f32_16x16x32_bf16 v[122:125], v[142:145], v[170:173], v[122:125]
	v_mfma_f32_16x16x32_bf16 v[110:113], v[142:145], v[190:193], v[110:113]
	v_mfma_f32_16x16x32_bf16 v[118:121], v[134:137], v[190:193], v[118:121]
	v_mfma_f32_16x16x32_bf16 v[94:97], v[134:137], v[198:201], v[94:97]
	v_mfma_f32_16x16x32_bf16 v[90:93], v[142:145], v[198:201], v[90:93]
	s_waitcnt lgkmcnt(0)
	v_mfma_f32_16x16x32_bf16 v[78:81], v[142:145], v[206:209], v[78:81]
	v_mfma_f32_16x16x32_bf16 v[86:89], v[134:137], v[206:209], v[86:89]
	s_setprio 0
	s_setprio 1
	v_mfma_f32_16x16x32_bf16 v[114:117], v[150:153], v[166:169], v[114:117]
	v_mfma_f32_16x16x32_bf16 v[106:109], v[158:161], v[166:169], v[106:109]
	v_mfma_f32_16x16x32_bf16 v[98:101], v[158:161], v[186:189], v[98:101]
	v_mfma_f32_16x16x32_bf16 v[102:105], v[150:153], v[186:189], v[102:105]
	v_mfma_f32_16x16x32_bf16 v[82:85], v[150:153], v[194:197], v[82:85]
	v_mfma_f32_16x16x32_bf16 v[74:77], v[158:161], v[194:197], v[74:77]
	v_mfma_f32_16x16x32_bf16 v[66:69], v[158:161], v[202:205], v[66:69]
	v_mfma_f32_16x16x32_bf16 v[70:73], v[150:153], v[202:205], v[70:73]
	v_mfma_f32_16x16x32_bf16 v[114:117], v[154:157], v[170:173], v[114:117]
	v_mfma_f32_16x16x32_bf16 v[106:109], v[162:165], v[170:173], v[106:109]
	v_mfma_f32_16x16x32_bf16 v[98:101], v[162:165], v[190:193], v[98:101]
	v_mfma_f32_16x16x32_bf16 v[102:105], v[154:157], v[190:193], v[102:105]
	v_mfma_f32_16x16x32_bf16 v[82:85], v[154:157], v[198:201], v[82:85]
	v_mfma_f32_16x16x32_bf16 v[74:77], v[162:165], v[198:201], v[74:77]
	s_setprio 2
	s_barrier
	v_mfma_f32_16x16x32_bf16 v[66:69], v[162:165], v[206:209], v[66:69]
	v_mfma_f32_16x16x32_bf16 v[70:73], v[154:157], v[206:209], v[70:73]
	s_setprio 0
	ds_read_b128 v[166:169], v183 offset:49152
	ds_read_b128 v[170:173], v183 offset:50176
	ds_read_b128 v[186:189], v183 offset:51200
	ds_read_b128 v[190:193], v183 offset:52224
	ds_read_b128 v[194:197], v183 offset:53248
	ds_read_b128 v[198:201], v183 offset:54272
	ds_read_b128 v[202:205], v183 offset:55296
	ds_read_b128 v[206:209], v183 offset:56320
	s_add_u32 s24, s22, 0x40000
	s_addc_u32 s25, s23, 0
	s_mov_b32 s75, m0
	s_mov_b32 m0, s46
	s_nop 0
	global_load_lds_dwordx4 v176, s[24:25]
	s_mov_b32 m0, s75
	s_add_u32 s22, s22, 0x44000
	s_mov_b32 s75, m0
	s_mov_b32 m0, s47
	s_nop 0
	global_load_lds_dwordx4 v178, s[24:25]
	s_mov_b32 m0, s75
	s_addc_u32 s23, s23, 0
	s_mov_b32 s24, m0
	s_mov_b32 m0, s48
	s_nop 0
	global_load_lds_dwordx4 v176, s[22:23]
	s_mov_b32 m0, s24
	s_nop 0
	s_mov_b32 s24, m0
	s_mov_b32 m0, s49
	s_nop 0
	global_load_lds_dwordx4 v178, s[22:23]
	s_mov_b32 m0, s24
	s_waitcnt vmcnt(4)
	s_waitcnt lgkmcnt(0)
	s_barrier
	s_setprio 1
	s_waitcnt lgkmcnt(7)
	v_mfma_f32_16x16x32_bf16 v[62:65], v[130:133], v[166:169], v[62:65]
	v_mfma_f32_16x16x32_bf16 v[58:61], v[138:141], v[166:169], v[58:61]
	s_waitcnt lgkmcnt(5)
	v_mfma_f32_16x16x32_bf16 v[42:45], v[138:141], v[186:189], v[42:45]
	v_mfma_f32_16x16x32_bf16 v[46:49], v[130:133], v[186:189], v[46:49]
	s_waitcnt lgkmcnt(3)
	v_mfma_f32_16x16x32_bf16 v[30:33], v[130:133], v[194:197], v[30:33]
	v_mfma_f32_16x16x32_bf16 v[26:29], v[138:141], v[194:197], v[26:29]
	s_waitcnt lgkmcnt(1)
	v_mfma_f32_16x16x32_bf16 v[10:13], v[138:141], v[202:205], v[10:13]
	v_mfma_f32_16x16x32_bf16 v[14:17], v[130:133], v[202:205], v[14:17]
	v_mfma_f32_16x16x32_bf16 v[62:65], v[134:137], v[170:173], v[62:65]
	v_mfma_f32_16x16x32_bf16 v[58:61], v[142:145], v[170:173], v[58:61]
	v_mfma_f32_16x16x32_bf16 v[42:45], v[142:145], v[190:193], v[42:45]
	v_mfma_f32_16x16x32_bf16 v[46:49], v[134:137], v[190:193], v[46:49]
	v_mfma_f32_16x16x32_bf16 v[30:33], v[134:137], v[198:201], v[30:33]
	v_mfma_f32_16x16x32_bf16 v[26:29], v[142:145], v[198:201], v[26:29]
	s_waitcnt lgkmcnt(0)
	v_mfma_f32_16x16x32_bf16 v[10:13], v[142:145], v[206:209], v[10:13]
	v_mfma_f32_16x16x32_bf16 v[14:17], v[134:137], v[206:209], v[14:17]
	s_setprio 0
	s_setprio 1
	v_mfma_f32_16x16x32_bf16 v[54:57], v[150:153], v[166:169], v[54:57]
	v_mfma_f32_16x16x32_bf16 v[50:53], v[158:161], v[166:169], v[50:53]
	v_mfma_f32_16x16x32_bf16 v[34:37], v[158:161], v[186:189], v[34:37]
	v_mfma_f32_16x16x32_bf16 v[38:41], v[150:153], v[186:189], v[38:41]
	v_mfma_f32_16x16x32_bf16 v[22:25], v[150:153], v[194:197], v[22:25]
	v_mfma_f32_16x16x32_bf16 v[18:21], v[158:161], v[194:197], v[18:21]
	v_mfma_f32_16x16x32_bf16 v[2:5], v[158:161], v[202:205], v[2:5]
	v_mfma_f32_16x16x32_bf16 v[6:9], v[150:153], v[202:205], v[6:9]
	v_mfma_f32_16x16x32_bf16 v[54:57], v[154:157], v[170:173], v[54:57]
	v_mfma_f32_16x16x32_bf16 v[50:53], v[162:165], v[170:173], v[50:53]
	v_mfma_f32_16x16x32_bf16 v[34:37], v[162:165], v[190:193], v[34:37]
	v_mfma_f32_16x16x32_bf16 v[38:41], v[154:157], v[190:193], v[38:41]
	v_mfma_f32_16x16x32_bf16 v[22:25], v[154:157], v[198:201], v[22:25]
	v_mfma_f32_16x16x32_bf16 v[18:21], v[162:165], v[198:201], v[18:21]
	s_setprio 2
	s_barrier
	v_mfma_f32_16x16x32_bf16 v[2:5], v[162:165], v[206:209], v[2:5]
	v_mfma_f32_16x16x32_bf16 v[6:9], v[154:157], v[206:209], v[6:9]
	s_setprio 0
	s_add_i32 s74, s74, 2
	s_add_u32 s67, s67, 0x80000
	s_addc_u32 s70, s70, 0
	s_add_u32 s20, s20, 0x400000
	s_addc_u32 s21, s21, 0
	s_add_u32 s71, s71, 0x400000
	s_addc_u32 s73, s73, 0
	s_cmpk_gt_u32 s74, 0x53
	.p2align 6
.LBB0_1952:
	ds_read_b128 v[130:133], v181
	ds_read_b128 v[134:137], v181 offset:1024
	ds_read_b128 v[138:141], v181 offset:2048
	ds_read_b128 v[142:145], v181 offset:3072
	ds_read_b128 v[150:153], v182
	ds_read_b128 v[154:157], v182 offset:1024
	ds_read_b128 v[158:161], v182 offset:2048
	ds_read_b128 v[162:165], v182 offset:3072
	s_cmpk_eq_i32 s74, 0x52
	s_cselect_b32 s23, s11, s70
	s_cselect_b32 s22, s66, s67
	s_cselect_b32 s25, s13, s73
	s_cselect_b32 s24, s65, s71
	ds_read_b128 v[166:169], v183
	ds_read_b128 v[170:173], v183 offset:1024
	ds_read_b128 v[186:189], v183 offset:2048
	ds_read_b128 v[190:193], v183 offset:3072
	ds_read_b128 v[194:197], v183 offset:4096
	ds_read_b128 v[198:201], v183 offset:5120
	ds_read_b128 v[202:205], v183 offset:6144
	ds_read_b128 v[206:209], v183 offset:7168
	s_add_u32 s76, s20, 0xffffc000
	s_addc_u32 s77, s21, -1
	s_mov_b32 s75, m0
	s_mov_b32 m0, s58
	s_nop 0
	global_load_lds_dwordx4 v1, s[76:77]
	s_mov_b32 m0, s75
	s_nop 0
	s_mov_b32 s75, m0
	s_mov_b32 m0, s62
	s_nop 0
	global_load_lds_dwordx4 v177, s[76:77]
	s_mov_b32 m0, s75
	s_nop 0
	s_mov_b32 s75, m0
	s_mov_b32 m0, s59
	s_nop 0
	global_load_lds_dwordx4 v1, s[20:21]
	s_mov_b32 m0, s75
	s_nop 0
	s_mov_b32 s75, m0
	s_mov_b32 m0, s63
	s_nop 0
	global_load_lds_dwordx4 v177, s[20:21]
	s_mov_b32 m0, s75
	s_waitcnt vmcnt(8)
	s_waitcnt lgkmcnt(0)
	s_barrier
	s_setprio 1
	s_waitcnt lgkmcnt(7)
	v_mfma_f32_16x16x32_bf16 v[126:129], v[130:133], v[166:169], v[126:129]
	v_mfma_f32_16x16x32_bf16 v[122:125], v[138:141], v[166:169], v[122:125]
	s_waitcnt lgkmcnt(5)
	v_mfma_f32_16x16x32_bf16 v[110:113], v[138:141], v[186:189], v[110:113]
	v_mfma_f32_16x16x32_bf16 v[118:121], v[130:133], v[186:189], v[118:121]
	s_waitcnt lgkmcnt(3)
	v_mfma_f32_16x16x32_bf16 v[94:97], v[130:133], v[194:197], v[94:97]
	v_mfma_f32_16x16x32_bf16 v[90:93], v[138:141], v[194:197], v[90:93]
	s_waitcnt lgkmcnt(1)
	v_mfma_f32_16x16x32_bf16 v[78:81], v[138:141], v[202:205], v[78:81]
	v_mfma_f32_16x16x32_bf16 v[86:89], v[130:133], v[202:205], v[86:89]
	v_mfma_f32_16x16x32_bf16 v[126:129], v[134:137], v[170:173], v[126:129]
	v_mfma_f32_16x16x32_bf16 v[122:125], v[142:145], v[170:173], v[122:125]
	v_mfma_f32_16x16x32_bf16 v[110:113], v[142:145], v[190:193], v[110:113]
	v_mfma_f32_16x16x32_bf16 v[118:121], v[134:137], v[190:193], v[118:121]
	v_mfma_f32_16x16x32_bf16 v[94:97], v[134:137], v[198:201], v[94:97]
	v_mfma_f32_16x16x32_bf16 v[90:93], v[142:145], v[198:201], v[90:93]
	s_waitcnt lgkmcnt(0)
	v_mfma_f32_16x16x32_bf16 v[78:81], v[142:145], v[206:209], v[78:81]
	v_mfma_f32_16x16x32_bf16 v[86:89], v[134:137], v[206:209], v[86:89]
	s_setprio 0
	s_setprio 1
	v_mfma_f32_16x16x32_bf16 v[114:117], v[150:153], v[166:169], v[114:117]
	v_mfma_f32_16x16x32_bf16 v[106:109], v[158:161], v[166:169], v[106:109]
	v_mfma_f32_16x16x32_bf16 v[98:101], v[158:161], v[186:189], v[98:101]
	v_mfma_f32_16x16x32_bf16 v[102:105], v[150:153], v[186:189], v[102:105]
	v_mfma_f32_16x16x32_bf16 v[82:85], v[150:153], v[194:197], v[82:85]
	v_mfma_f32_16x16x32_bf16 v[74:77], v[158:161], v[194:197], v[74:77]
	v_mfma_f32_16x16x32_bf16 v[66:69], v[158:161], v[202:205], v[66:69]
	v_mfma_f32_16x16x32_bf16 v[70:73], v[150:153], v[202:205], v[70:73]
	v_mfma_f32_16x16x32_bf16 v[114:117], v[154:157], v[170:173], v[114:117]
	v_mfma_f32_16x16x32_bf16 v[106:109], v[162:165], v[170:173], v[106:109]
	v_mfma_f32_16x16x32_bf16 v[98:101], v[162:165], v[190:193], v[98:101]
	v_mfma_f32_16x16x32_bf16 v[102:105], v[154:157], v[190:193], v[102:105]
	v_mfma_f32_16x16x32_bf16 v[82:85], v[154:157], v[198:201], v[82:85]
	v_mfma_f32_16x16x32_bf16 v[74:77], v[162:165], v[198:201], v[74:77]
	s_setprio 2
	s_barrier
	v_mfma_f32_16x16x32_bf16 v[66:69], v[162:165], v[206:209], v[66:69]
	v_mfma_f32_16x16x32_bf16 v[70:73], v[154:157], v[206:209], v[70:73]
	s_setprio 0
	ds_read_b128 v[166:169], v183 offset:16384
	ds_read_b128 v[170:173], v183 offset:17408
	ds_read_b128 v[186:189], v183 offset:18432
	ds_read_b128 v[190:193], v183 offset:19456
	ds_read_b128 v[194:197], v183 offset:20480
	ds_read_b128 v[198:201], v183 offset:21504
	ds_read_b128 v[202:205], v183 offset:22528
	ds_read_b128 v[206:209], v183 offset:23552
	s_mov_b32 s75, m0
	s_mov_b32 m0, s35
	s_nop 0
	global_load_lds_dwordx4 v176, s[22:23]
	s_mov_b32 m0, s75
	s_add_u32 s76, s22, 0x4000
	s_mov_b32 s75, m0
	s_mov_b32 m0, s36
	s_nop 0
	global_load_lds_dwordx4 v178, s[22:23]
	s_mov_b32 m0, s75
	s_addc_u32 s77, s23, 0
	s_mov_b32 s75, m0
	s_mov_b32 m0, s37
	s_nop 0
	global_load_lds_dwordx4 v176, s[76:77]
	s_mov_b32 m0, s75
	s_nop 0
	s_mov_b32 s75, m0
	s_mov_b32 m0, s40
	s_nop 0
	global_load_lds_dwordx4 v178, s[76:77]
	s_mov_b32 m0, s75
	s_waitcnt vmcnt(4)
	s_waitcnt lgkmcnt(0)
	s_barrier
	s_setprio 1
	s_waitcnt lgkmcnt(7)
	v_mfma_f32_16x16x32_bf16 v[62:65], v[130:133], v[166:169], v[62:65]
	v_mfma_f32_16x16x32_bf16 v[58:61], v[138:141], v[166:169], v[58:61]
	s_waitcnt lgkmcnt(5)
	v_mfma_f32_16x16x32_bf16 v[42:45], v[138:141], v[186:189], v[42:45]
	v_mfma_f32_16x16x32_bf16 v[46:49], v[130:133], v[186:189], v[46:49]
	s_waitcnt lgkmcnt(3)
	v_mfma_f32_16x16x32_bf16 v[30:33], v[130:133], v[194:197], v[30:33]
	v_mfma_f32_16x16x32_bf16 v[26:29], v[138:141], v[194:197], v[26:29]
	s_waitcnt lgkmcnt(1)
	v_mfma_f32_16x16x32_bf16 v[10:13], v[138:141], v[202:205], v[10:13]
	v_mfma_f32_16x16x32_bf16 v[14:17], v[130:133], v[202:205], v[14:17]
	v_mfma_f32_16x16x32_bf16 v[62:65], v[134:137], v[170:173], v[62:65]
	v_mfma_f32_16x16x32_bf16 v[58:61], v[142:145], v[170:173], v[58:61]
	v_mfma_f32_16x16x32_bf16 v[42:45], v[142:145], v[190:193], v[42:45]
	v_mfma_f32_16x16x32_bf16 v[46:49], v[134:137], v[190:193], v[46:49]
	v_mfma_f32_16x16x32_bf16 v[30:33], v[134:137], v[198:201], v[30:33]
	v_mfma_f32_16x16x32_bf16 v[26:29], v[142:145], v[198:201], v[26:29]
	s_waitcnt lgkmcnt(0)
	v_mfma_f32_16x16x32_bf16 v[10:13], v[142:145], v[206:209], v[10:13]
	v_mfma_f32_16x16x32_bf16 v[14:17], v[134:137], v[206:209], v[14:17]
	s_setprio 0
	s_setprio 1
	v_mfma_f32_16x16x32_bf16 v[54:57], v[150:153], v[166:169], v[54:57]
	v_mfma_f32_16x16x32_bf16 v[50:53], v[158:161], v[166:169], v[50:53]
	v_mfma_f32_16x16x32_bf16 v[34:37], v[158:161], v[186:189], v[34:37]
	v_mfma_f32_16x16x32_bf16 v[38:41], v[150:153], v[186:189], v[38:41]
	v_mfma_f32_16x16x32_bf16 v[22:25], v[150:153], v[194:197], v[22:25]
	v_mfma_f32_16x16x32_bf16 v[18:21], v[158:161], v[194:197], v[18:21]
	v_mfma_f32_16x16x32_bf16 v[2:5], v[158:161], v[202:205], v[2:5]
	v_mfma_f32_16x16x32_bf16 v[6:9], v[150:153], v[202:205], v[6:9]
	v_mfma_f32_16x16x32_bf16 v[54:57], v[154:157], v[170:173], v[54:57]
	v_mfma_f32_16x16x32_bf16 v[50:53], v[162:165], v[170:173], v[50:53]
	v_mfma_f32_16x16x32_bf16 v[34:37], v[162:165], v[190:193], v[34:37]
	v_mfma_f32_16x16x32_bf16 v[38:41], v[154:157], v[190:193], v[38:41]
	v_mfma_f32_16x16x32_bf16 v[22:25], v[154:157], v[198:201], v[22:25]
	v_mfma_f32_16x16x32_bf16 v[18:21], v[162:165], v[198:201], v[18:21]
	s_setprio 2
	s_barrier
	v_mfma_f32_16x16x32_bf16 v[2:5], v[162:165], v[206:209], v[2:5]
	v_mfma_f32_16x16x32_bf16 v[6:9], v[154:157], v[206:209], v[6:9]
	s_setprio 0
	ds_read_b128 v[130:133], v184
	ds_read_b128 v[134:137], v184 offset:1024
	ds_read_b128 v[138:141], v184 offset:2048
	ds_read_b128 v[142:145], v184 offset:3072
	ds_read_b128 v[150:153], v185
	ds_read_b128 v[154:157], v185 offset:1024
	ds_read_b128 v[158:161], v185 offset:2048
	ds_read_b128 v[162:165], v185 offset:3072
	ds_read_b128 v[166:169], v183 offset:32768
	ds_read_b128 v[170:173], v183 offset:33792
	ds_read_b128 v[186:189], v183 offset:34816
	ds_read_b128 v[190:193], v183 offset:35840
	ds_read_b128 v[194:197], v183 offset:36864
	ds_read_b128 v[198:201], v183 offset:37888
	ds_read_b128 v[202:205], v183 offset:38912
	ds_read_b128 v[206:209], v183 offset:39936
	s_mov_b32 s75, m0
	s_mov_b32 m0, s34
	s_nop 0
	global_load_lds_dwordx4 v1, s[24:25]
	s_mov_b32 m0, s75
	s_nop 0
	s_mov_b32 s75, m0
	s_mov_b32 m0, s41
	s_nop 0
	global_load_lds_dwordx4 v177, s[24:25]
	s_mov_b32 m0, s75
	s_add_u32 s24, s24, 0x4000
	s_addc_u32 s25, s25, 0
	s_mov_b32 s75, m0
	s_mov_b32 m0, s42
	s_nop 0
	global_load_lds_dwordx4 v1, s[24:25]
	s_mov_b32 m0, s75
	s_nop 0
	s_mov_b32 s75, m0
	s_mov_b32 m0, s43
	s_nop 0
	global_load_lds_dwordx4 v177, s[24:25]
	s_mov_b32 m0, s75
	s_waitcnt vmcnt(8)
	s_waitcnt lgkmcnt(0)
	s_barrier
	s_setprio 1
	s_waitcnt lgkmcnt(7)
	v_mfma_f32_16x16x32_bf16 v[126:129], v[130:133], v[166:169], v[126:129]
	v_mfma_f32_16x16x32_bf16 v[122:125], v[138:141], v[166:169], v[122:125]
	s_waitcnt lgkmcnt(5)
	v_mfma_f32_16x16x32_bf16 v[110:113], v[138:141], v[186:189], v[110:113]
	v_mfma_f32_16x16x32_bf16 v[118:121], v[130:133], v[186:189], v[118:121]
	s_waitcnt lgkmcnt(3)
	v_mfma_f32_16x16x32_bf16 v[94:97], v[130:133], v[194:197], v[94:97]
	v_mfma_f32_16x16x32_bf16 v[90:93], v[138:141], v[194:197], v[90:93]
	s_waitcnt lgkmcnt(1)
	v_mfma_f32_16x16x32_bf16 v[78:81], v[138:141], v[202:205], v[78:81]
	v_mfma_f32_16x16x32_bf16 v[86:89], v[130:133], v[202:205], v[86:89]
	v_mfma_f32_16x16x32_bf16 v[126:129], v[134:137], v[170:173], v[126:129]
	v_mfma_f32_16x16x32_bf16 v[122:125], v[142:145], v[170:173], v[122:125]
	v_mfma_f32_16x16x32_bf16 v[110:113], v[142:145], v[190:193], v[110:113]
	v_mfma_f32_16x16x32_bf16 v[118:121], v[134:137], v[190:193], v[118:121]
	v_mfma_f32_16x16x32_bf16 v[94:97], v[134:137], v[198:201], v[94:97]
	v_mfma_f32_16x16x32_bf16 v[90:93], v[142:145], v[198:201], v[90:93]
	s_waitcnt lgkmcnt(0)
	v_mfma_f32_16x16x32_bf16 v[78:81], v[142:145], v[206:209], v[78:81]
	v_mfma_f32_16x16x32_bf16 v[86:89], v[134:137], v[206:209], v[86:89]
	s_setprio 0
	s_setprio 1
	v_mfma_f32_16x16x32_bf16 v[114:117], v[150:153], v[166:169], v[114:117]
	v_mfma_f32_16x16x32_bf16 v[106:109], v[158:161], v[166:169], v[106:109]
	v_mfma_f32_16x16x32_bf16 v[98:101], v[158:161], v[186:189], v[98:101]
	v_mfma_f32_16x16x32_bf16 v[102:105], v[150:153], v[186:189], v[102:105]
	v_mfma_f32_16x16x32_bf16 v[82:85], v[150:153], v[194:197], v[82:85]
	v_mfma_f32_16x16x32_bf16 v[74:77], v[158:161], v[194:197], v[74:77]
	v_mfma_f32_16x16x32_bf16 v[66:69], v[158:161], v[202:205], v[66:69]
	v_mfma_f32_16x16x32_bf16 v[70:73], v[150:153], v[202:205], v[70:73]
	v_mfma_f32_16x16x32_bf16 v[114:117], v[154:157], v[170:173], v[114:117]
	v_mfma_f32_16x16x32_bf16 v[106:109], v[162:165], v[170:173], v[106:109]
	v_mfma_f32_16x16x32_bf16 v[98:101], v[162:165], v[190:193], v[98:101]
	v_mfma_f32_16x16x32_bf16 v[102:105], v[154:157], v[190:193], v[102:105]
	v_mfma_f32_16x16x32_bf16 v[82:85], v[154:157], v[198:201], v[82:85]
	v_mfma_f32_16x16x32_bf16 v[74:77], v[162:165], v[198:201], v[74:77]
	s_setprio 2
	s_barrier
	v_mfma_f32_16x16x32_bf16 v[66:69], v[162:165], v[206:209], v[66:69]
	v_mfma_f32_16x16x32_bf16 v[70:73], v[154:157], v[206:209], v[70:73]
	s_setprio 0
	ds_read_b128 v[166:169], v183 offset:49152
	ds_read_b128 v[170:173], v183 offset:50176
	ds_read_b128 v[186:189], v183 offset:51200
	ds_read_b128 v[190:193], v183 offset:52224
	ds_read_b128 v[194:197], v183 offset:53248
	ds_read_b128 v[198:201], v183 offset:54272
	ds_read_b128 v[202:205], v183 offset:55296
	ds_read_b128 v[206:209], v183 offset:56320
	s_add_u32 s24, s22, 0x40000
	s_addc_u32 s25, s23, 0
	s_mov_b32 s75, m0
	s_mov_b32 m0, s46
	s_nop 0
	global_load_lds_dwordx4 v176, s[24:25]
	s_mov_b32 m0, s75
	s_add_u32 s22, s22, 0x44000
	s_mov_b32 s75, m0
	s_mov_b32 m0, s47
	s_nop 0
	global_load_lds_dwordx4 v178, s[24:25]
	s_mov_b32 m0, s75
	s_addc_u32 s23, s23, 0
	s_mov_b32 s24, m0
	s_mov_b32 m0, s48
	s_nop 0
	global_load_lds_dwordx4 v176, s[22:23]
	s_mov_b32 m0, s24
	s_nop 0
	s_mov_b32 s24, m0
	s_mov_b32 m0, s49
	s_nop 0
	global_load_lds_dwordx4 v178, s[22:23]
	s_mov_b32 m0, s24
	s_waitcnt vmcnt(4)
	s_waitcnt lgkmcnt(0)
	s_barrier
	s_setprio 1
	s_waitcnt lgkmcnt(7)
	v_mfma_f32_16x16x32_bf16 v[62:65], v[130:133], v[166:169], v[62:65]
	v_mfma_f32_16x16x32_bf16 v[58:61], v[138:141], v[166:169], v[58:61]
	s_waitcnt lgkmcnt(5)
	v_mfma_f32_16x16x32_bf16 v[42:45], v[138:141], v[186:189], v[42:45]
	v_mfma_f32_16x16x32_bf16 v[46:49], v[130:133], v[186:189], v[46:49]
	s_waitcnt lgkmcnt(3)
	v_mfma_f32_16x16x32_bf16 v[30:33], v[130:133], v[194:197], v[30:33]
	v_mfma_f32_16x16x32_bf16 v[26:29], v[138:141], v[194:197], v[26:29]
	s_waitcnt lgkmcnt(1)
	v_mfma_f32_16x16x32_bf16 v[10:13], v[138:141], v[202:205], v[10:13]
	v_mfma_f32_16x16x32_bf16 v[14:17], v[130:133], v[202:205], v[14:17]
	v_mfma_f32_16x16x32_bf16 v[62:65], v[134:137], v[170:173], v[62:65]
	v_mfma_f32_16x16x32_bf16 v[58:61], v[142:145], v[170:173], v[58:61]
	v_mfma_f32_16x16x32_bf16 v[42:45], v[142:145], v[190:193], v[42:45]
	v_mfma_f32_16x16x32_bf16 v[46:49], v[134:137], v[190:193], v[46:49]
	v_mfma_f32_16x16x32_bf16 v[30:33], v[134:137], v[198:201], v[30:33]
	v_mfma_f32_16x16x32_bf16 v[26:29], v[142:145], v[198:201], v[26:29]
	s_waitcnt lgkmcnt(0)
	v_mfma_f32_16x16x32_bf16 v[10:13], v[142:145], v[206:209], v[10:13]
	v_mfma_f32_16x16x32_bf16 v[14:17], v[134:137], v[206:209], v[14:17]
	s_setprio 0
	s_setprio 1
	v_mfma_f32_16x16x32_bf16 v[54:57], v[150:153], v[166:169], v[54:57]
	v_mfma_f32_16x16x32_bf16 v[50:53], v[158:161], v[166:169], v[50:53]
	v_mfma_f32_16x16x32_bf16 v[34:37], v[158:161], v[186:189], v[34:37]
	v_mfma_f32_16x16x32_bf16 v[38:41], v[150:153], v[186:189], v[38:41]
	v_mfma_f32_16x16x32_bf16 v[22:25], v[150:153], v[194:197], v[22:25]
	v_mfma_f32_16x16x32_bf16 v[18:21], v[158:161], v[194:197], v[18:21]
	v_mfma_f32_16x16x32_bf16 v[2:5], v[158:161], v[202:205], v[2:5]
	v_mfma_f32_16x16x32_bf16 v[6:9], v[150:153], v[202:205], v[6:9]
	v_mfma_f32_16x16x32_bf16 v[54:57], v[154:157], v[170:173], v[54:57]
	v_mfma_f32_16x16x32_bf16 v[50:53], v[162:165], v[170:173], v[50:53]
	v_mfma_f32_16x16x32_bf16 v[34:37], v[162:165], v[190:193], v[34:37]
	v_mfma_f32_16x16x32_bf16 v[38:41], v[154:157], v[190:193], v[38:41]
	v_mfma_f32_16x16x32_bf16 v[22:25], v[154:157], v[198:201], v[22:25]
	v_mfma_f32_16x16x32_bf16 v[18:21], v[162:165], v[198:201], v[18:21]
	s_setprio 2
	s_barrier
	v_mfma_f32_16x16x32_bf16 v[2:5], v[162:165], v[206:209], v[2:5]
	v_mfma_f32_16x16x32_bf16 v[6:9], v[154:157], v[206:209], v[6:9]
	s_setprio 0
	s_add_i32 s74, s74, 2
	s_add_u32 s67, s67, 0x80000
	s_addc_u32 s70, s70, 0
	s_add_u32 s20, s20, 0x400000
	s_addc_u32 s21, s21, 0
	s_add_u32 s71, s71, 0x400000
	s_addc_u32 s73, s73, 0
	s_cmpk_gt_u32 s74, 0x53
	s_cbranch_scc0 .LBB0_1952
	s_and_b64 vcc, exec, s[8:9]
	s_cbranch_vccz .LBB0_1955
	s_barrier

.LBB0_2409:
	s_ashr_i32 s17, s16, 31
	s_lshl_b64 s[18:19], s[16:17], 20
	s_add_u32 s18, s33, s18
	s_addc_u32 s19, s34, s19
	s_and_b64 s[20:21], s[2:3], exec
	s_cselect_b32 s17, s19, s27
	s_cselect_b32 s71, s18, s26
	s_ashr_i32 s15, s14, 31
	s_lshl_b64 s[20:21], s[14:15], 20
	s_add_u32 s20, s35, s20
	s_addc_u32 s21, s36, s21
	s_and_b64 s[28:29], s[2:3], exec
	s_cselect_b32 s15, s21, s25
	s_cselect_b32 s73, s20, s24
	s_add_u32 s74, s24, 0x100
	s_addc_u32 s75, s25, 0
	s_add_u32 s24, s26, 0x80080
	s_addc_u32 s25, s27, 0
	s_add_u32 s76, s26, 0x100
	s_addc_u32 s77, s27, 0
	s_mov_b32 s78, -2
	s_waitcnt vmcnt(25)
	s_waitcnt vmcnt(24)
	s_waitcnt vmcnt(4)
	s_waitcnt vmcnt(2)
	s_waitcnt vmcnt(1)
	s_waitcnt vmcnt(0)
	ds_read_b128 v[130:133], v181
	ds_read_b128 v[134:137], v181 offset:1024
	ds_read_b128 v[138:141], v181 offset:2048
	ds_read_b128 v[142:145], v181 offset:3072
	ds_read_b128 v[146:149], v182
	ds_read_b128 v[150:153], v182 offset:1024
	ds_read_b128 v[154:157], v182 offset:2048
	ds_read_b128 v[158:161], v182 offset:3072
	s_cmp_eq_u32 s78, 28
	s_cselect_b32 s27, s15, s75
	s_cselect_b32 s26, s73, s74
	s_cselect_b32 s29, s17, s77
	s_cselect_b32 s28, s71, s76
	ds_read_b128 v[166:169], v183
	ds_read_b128 v[170:173], v183 offset:1024
	ds_read_b128 v[186:189], v183 offset:2048
	ds_read_b128 v[190:193], v183 offset:3072
	ds_read_b128 v[194:197], v183 offset:4096
	ds_read_b128 v[198:201], v183 offset:5120
	ds_read_b128 v[202:205], v183 offset:6144
	ds_read_b128 v[206:209], v183 offset:7168
	s_add_u32 s80, s24, 0xfff80000
	s_addc_u32 s81, s25, -1
	s_mov_b32 s79, m0
	s_mov_b32 m0, s64
	s_nop 0
	global_load_lds_dwordx4 v1, s[80:81]
	s_mov_b32 m0, s79
	s_nop 0
	s_mov_b32 s79, m0
	s_mov_b32 m0, s66
	s_nop 0
	global_load_lds_dwordx4 v177, s[80:81]
	s_mov_b32 m0, s79
	s_nop 0
	s_mov_b32 s79, m0
	s_mov_b32 m0, s65
	s_nop 0
	global_load_lds_dwordx4 v1, s[24:25]
	s_mov_b32 m0, s79
	s_nop 0
	s_mov_b32 s79, m0
	s_mov_b32 m0, s67
	s_nop 0
	global_load_lds_dwordx4 v177, s[24:25]
	s_mov_b32 m0, s79
	s_waitcnt vmcnt(8)
	s_waitcnt lgkmcnt(0)
	s_barrier
	s_setprio 1
	s_waitcnt lgkmcnt(7)
	v_mfma_f32_16x16x32_bf16 v[126:129], v[130:133], v[166:169], 0
	v_mfma_f32_16x16x32_bf16 v[122:125], v[138:141], v[166:169], 0
	s_waitcnt lgkmcnt(5)
	v_mfma_f32_16x16x32_bf16 v[114:117], v[138:141], v[186:189], 0
	v_mfma_f32_16x16x32_bf16 v[118:121], v[130:133], v[186:189], 0
	s_waitcnt lgkmcnt(3)
	v_mfma_f32_16x16x32_bf16 v[94:97], v[130:133], v[194:197], 0
	v_mfma_f32_16x16x32_bf16 v[90:93], v[138:141], v[194:197], 0
	s_waitcnt lgkmcnt(1)
	v_mfma_f32_16x16x32_bf16 v[78:81], v[138:141], v[202:205], 0
	v_mfma_f32_16x16x32_bf16 v[86:89], v[130:133], v[202:205], 0
	v_mfma_f32_16x16x32_bf16 v[126:129], v[134:137], v[170:173], v[126:129]
	v_mfma_f32_16x16x32_bf16 v[122:125], v[142:145], v[170:173], v[122:125]
	v_mfma_f32_16x16x32_bf16 v[114:117], v[142:145], v[190:193], v[114:117]
	v_mfma_f32_16x16x32_bf16 v[118:121], v[134:137], v[190:193], v[118:121]
	v_mfma_f32_16x16x32_bf16 v[94:97], v[134:137], v[198:201], v[94:97]
	v_mfma_f32_16x16x32_bf16 v[90:93], v[142:145], v[198:201], v[90:93]
	s_waitcnt lgkmcnt(0)
	v_mfma_f32_16x16x32_bf16 v[78:81], v[142:145], v[206:209], v[78:81]
	v_mfma_f32_16x16x32_bf16 v[86:89], v[134:137], v[206:209], v[86:89]
	s_setprio 0
	s_setprio 1
	v_mfma_f32_16x16x32_bf16 v[110:113], v[146:149], v[166:169], 0
	v_mfma_f32_16x16x32_bf16 v[106:109], v[154:157], v[166:169], 0
	v_mfma_f32_16x16x32_bf16 v[98:101], v[154:157], v[186:189], 0
	v_mfma_f32_16x16x32_bf16 v[102:105], v[146:149], v[186:189], 0
	v_mfma_f32_16x16x32_bf16 v[82:85], v[146:149], v[194:197], 0
	v_mfma_f32_16x16x32_bf16 v[74:77], v[154:157], v[194:197], 0
	v_mfma_f32_16x16x32_bf16 v[66:69], v[154:157], v[202:205], 0
	v_mfma_f32_16x16x32_bf16 v[70:73], v[146:149], v[202:205], 0
	v_mfma_f32_16x16x32_bf16 v[110:113], v[150:153], v[170:173], v[110:113]
	v_mfma_f32_16x16x32_bf16 v[106:109], v[158:161], v[170:173], v[106:109]
	v_mfma_f32_16x16x32_bf16 v[98:101], v[158:161], v[190:193], v[98:101]
	v_mfma_f32_16x16x32_bf16 v[102:105], v[150:153], v[190:193], v[102:105]
	v_mfma_f32_16x16x32_bf16 v[82:85], v[150:153], v[198:201], v[82:85]
	v_mfma_f32_16x16x32_bf16 v[74:77], v[158:161], v[198:201], v[74:77]
	s_setprio 2
	s_barrier
	v_mfma_f32_16x16x32_bf16 v[66:69], v[158:161], v[206:209], v[66:69]
	v_mfma_f32_16x16x32_bf16 v[70:73], v[150:153], v[206:209], v[70:73]
	s_setprio 0
	ds_read_b128 v[166:169], v183 offset:16384
	ds_read_b128 v[170:173], v183 offset:17408
	ds_read_b128 v[186:189], v183 offset:18432
	ds_read_b128 v[190:193], v183 offset:19456
	ds_read_b128 v[194:197], v183 offset:20480
	ds_read_b128 v[198:201], v183 offset:21504
	ds_read_b128 v[202:205], v183 offset:22528
	ds_read_b128 v[206:209], v183 offset:23552
	s_mov_b32 s79, m0
	s_mov_b32 m0, s41
	s_nop 0
	global_load_lds_dwordx4 v176, s[26:27]
	s_mov_b32 m0, s79
	s_add_u32 s80, s26, 0x80000
	s_mov_b32 s79, m0
	s_mov_b32 m0, s42
	s_nop 0
	global_load_lds_dwordx4 v178, s[26:27]
	s_mov_b32 m0, s79
	s_addc_u32 s81, s27, 0
	s_mov_b32 s79, m0
	s_mov_b32 m0, s43
	s_nop 0
	global_load_lds_dwordx4 v176, s[80:81]
	s_mov_b32 m0, s79
	s_nop 0
	s_mov_b32 s79, m0
	s_mov_b32 m0, s46
	s_nop 0
	global_load_lds_dwordx4 v178, s[80:81]
	s_mov_b32 m0, s79
	s_waitcnt vmcnt(4)
	s_waitcnt lgkmcnt(0)
	s_barrier
	s_setprio 1
	s_waitcnt lgkmcnt(7)
	v_mfma_f32_16x16x32_bf16 v[62:65], v[130:133], v[166:169], 0
	v_mfma_f32_16x16x32_bf16 v[58:61], v[138:141], v[166:169], 0
	s_waitcnt lgkmcnt(5)
	v_mfma_f32_16x16x32_bf16 v[42:45], v[138:141], v[186:189], 0
	v_mfma_f32_16x16x32_bf16 v[46:49], v[130:133], v[186:189], 0
	s_waitcnt lgkmcnt(3)
	v_mfma_f32_16x16x32_bf16 v[30:33], v[130:133], v[194:197], 0
	v_mfma_f32_16x16x32_bf16 v[26:29], v[138:141], v[194:197], 0
	s_waitcnt lgkmcnt(1)
	v_mfma_f32_16x16x32_bf16 v[10:13], v[138:141], v[202:205], 0
	v_mfma_f32_16x16x32_bf16 v[14:17], v[130:133], v[202:205], 0
	v_mfma_f32_16x16x32_bf16 v[62:65], v[134:137], v[170:173], v[62:65]
	v_mfma_f32_16x16x32_bf16 v[58:61], v[142:145], v[170:173], v[58:61]
	v_mfma_f32_16x16x32_bf16 v[42:45], v[142:145], v[190:193], v[42:45]
	v_mfma_f32_16x16x32_bf16 v[46:49], v[134:137], v[190:193], v[46:49]
	v_mfma_f32_16x16x32_bf16 v[30:33], v[134:137], v[198:201], v[30:33]
	v_mfma_f32_16x16x32_bf16 v[26:29], v[142:145], v[198:201], v[26:29]
	s_waitcnt lgkmcnt(0)
	v_mfma_f32_16x16x32_bf16 v[10:13], v[142:145], v[206:209], v[10:13]
	v_mfma_f32_16x16x32_bf16 v[14:17], v[134:137], v[206:209], v[14:17]
	s_setprio 0
	s_setprio 1
	v_mfma_f32_16x16x32_bf16 v[54:57], v[146:149], v[166:169], 0
	v_mfma_f32_16x16x32_bf16 v[50:53], v[154:157], v[166:169], 0
	v_mfma_f32_16x16x32_bf16 v[34:37], v[154:157], v[186:189], 0
	v_mfma_f32_16x16x32_bf16 v[38:41], v[146:149], v[186:189], 0
	v_mfma_f32_16x16x32_bf16 v[22:25], v[146:149], v[194:197], 0
	v_mfma_f32_16x16x32_bf16 v[18:21], v[154:157], v[194:197], 0
	v_mfma_f32_16x16x32_bf16 v[2:5], v[154:157], v[202:205], 0
	v_mfma_f32_16x16x32_bf16 v[6:9], v[146:149], v[202:205], 0
	v_mfma_f32_16x16x32_bf16 v[54:57], v[150:153], v[170:173], v[54:57]
	v_mfma_f32_16x16x32_bf16 v[50:53], v[158:161], v[170:173], v[50:53]
	v_mfma_f32_16x16x32_bf16 v[34:37], v[158:161], v[190:193], v[34:37]
	v_mfma_f32_16x16x32_bf16 v[38:41], v[150:153], v[190:193], v[38:41]
	v_mfma_f32_16x16x32_bf16 v[22:25], v[150:153], v[198:201], v[22:25]
	v_mfma_f32_16x16x32_bf16 v[18:21], v[158:161], v[198:201], v[18:21]
	s_setprio 2
	s_barrier
	v_mfma_f32_16x16x32_bf16 v[2:5], v[158:161], v[206:209], v[2:5]
	v_mfma_f32_16x16x32_bf16 v[6:9], v[150:153], v[206:209], v[6:9]
	s_setprio 0
	ds_read_b128 v[130:133], v184
	ds_read_b128 v[134:137], v184 offset:1024
	ds_read_b128 v[138:141], v184 offset:2048
	ds_read_b128 v[142:145], v184 offset:3072
	ds_read_b128 v[146:149], v185
	ds_read_b128 v[150:153], v185 offset:1024
	ds_read_b128 v[154:157], v185 offset:2048
	ds_read_b128 v[158:161], v185 offset:3072
	ds_read_b128 v[166:169], v183 offset:32768
	ds_read_b128 v[170:173], v183 offset:33792
	ds_read_b128 v[186:189], v183 offset:34816
	ds_read_b128 v[190:193], v183 offset:35840
	ds_read_b128 v[194:197], v183 offset:36864
	ds_read_b128 v[198:201], v183 offset:37888
	ds_read_b128 v[202:205], v183 offset:38912
	ds_read_b128 v[206:209], v183 offset:39936
	s_mov_b32 s79, m0
	s_mov_b32 m0, s40
	s_nop 0
	global_load_lds_dwordx4 v1, s[28:29]
	s_mov_b32 m0, s79
	s_nop 0
	s_mov_b32 s79, m0
	s_mov_b32 m0, s47
	s_nop 0
	global_load_lds_dwordx4 v177, s[28:29]
	s_mov_b32 m0, s79
	s_add_u32 s28, s28, 0x80000
	s_addc_u32 s29, s29, 0
	s_mov_b32 s79, m0
	s_mov_b32 m0, s48
	s_nop 0
	global_load_lds_dwordx4 v1, s[28:29]
	s_mov_b32 m0, s79
	s_nop 0
	s_mov_b32 s79, m0
	s_mov_b32 m0, s49
	s_nop 0
	global_load_lds_dwordx4 v177, s[28:29]
	s_mov_b32 m0, s79
	s_waitcnt vmcnt(8)
	s_waitcnt lgkmcnt(0)
	s_barrier
	s_setprio 1
	s_waitcnt lgkmcnt(7)
	v_mfma_f32_16x16x32_bf16 v[126:129], v[130:133], v[166:169], v[126:129]
	v_mfma_f32_16x16x32_bf16 v[122:125], v[138:141], v[166:169], v[122:125]
	s_waitcnt lgkmcnt(5)
	v_mfma_f32_16x16x32_bf16 v[114:117], v[138:141], v[186:189], v[114:117]
	v_mfma_f32_16x16x32_bf16 v[118:121], v[130:133], v[186:189], v[118:121]
	s_waitcnt lgkmcnt(3)
	v_mfma_f32_16x16x32_bf16 v[94:97], v[130:133], v[194:197], v[94:97]
	v_mfma_f32_16x16x32_bf16 v[90:93], v[138:141], v[194:197], v[90:93]
	s_waitcnt lgkmcnt(1)
	v_mfma_f32_16x16x32_bf16 v[78:81], v[138:141], v[202:205], v[78:81]
	v_mfma_f32_16x16x32_bf16 v[86:89], v[130:133], v[202:205], v[86:89]
	v_mfma_f32_16x16x32_bf16 v[126:129], v[134:137], v[170:173], v[126:129]
	v_mfma_f32_16x16x32_bf16 v[122:125], v[142:145], v[170:173], v[122:125]
	v_mfma_f32_16x16x32_bf16 v[114:117], v[142:145], v[190:193], v[114:117]
	v_mfma_f32_16x16x32_bf16 v[118:121], v[134:137], v[190:193], v[118:121]
	v_mfma_f32_16x16x32_bf16 v[94:97], v[134:137], v[198:201], v[94:97]
	v_mfma_f32_16x16x32_bf16 v[90:93], v[142:145], v[198:201], v[90:93]
	s_waitcnt lgkmcnt(0)
	v_mfma_f32_16x16x32_bf16 v[78:81], v[142:145], v[206:209], v[78:81]
	v_mfma_f32_16x16x32_bf16 v[86:89], v[134:137], v[206:209], v[86:89]
	s_setprio 0
	s_setprio 1
	v_mfma_f32_16x16x32_bf16 v[110:113], v[146:149], v[166:169], v[110:113]
	v_mfma_f32_16x16x32_bf16 v[106:109], v[154:157], v[166:169], v[106:109]
	v_mfma_f32_16x16x32_bf16 v[98:101], v[154:157], v[186:189], v[98:101]
	v_mfma_f32_16x16x32_bf16 v[102:105], v[146:149], v[186:189], v[102:105]
	v_mfma_f32_16x16x32_bf16 v[82:85], v[146:149], v[194:197], v[82:85]
	v_mfma_f32_16x16x32_bf16 v[74:77], v[154:157], v[194:197], v[74:77]
	v_mfma_f32_16x16x32_bf16 v[66:69], v[154:157], v[202:205], v[66:69]
	v_mfma_f32_16x16x32_bf16 v[70:73], v[146:149], v[202:205], v[70:73]
	v_mfma_f32_16x16x32_bf16 v[110:113], v[150:153], v[170:173], v[110:113]
	v_mfma_f32_16x16x32_bf16 v[106:109], v[158:161], v[170:173], v[106:109]
	v_mfma_f32_16x16x32_bf16 v[98:101], v[158:161], v[190:193], v[98:101]
	v_mfma_f32_16x16x32_bf16 v[102:105], v[150:153], v[190:193], v[102:105]
	v_mfma_f32_16x16x32_bf16 v[82:85], v[150:153], v[198:201], v[82:85]
	v_mfma_f32_16x16x32_bf16 v[74:77], v[158:161], v[198:201], v[74:77]
	s_setprio 2
	s_barrier
	v_mfma_f32_16x16x32_bf16 v[66:69], v[158:161], v[206:209], v[66:69]
	v_mfma_f32_16x16x32_bf16 v[70:73], v[150:153], v[206:209], v[70:73]
	s_setprio 0
	ds_read_b128 v[166:169], v183 offset:49152
	ds_read_b128 v[170:173], v183 offset:50176
	ds_read_b128 v[186:189], v183 offset:51200
	ds_read_b128 v[190:193], v183 offset:52224
	ds_read_b128 v[194:197], v183 offset:53248
	ds_read_b128 v[198:201], v183 offset:54272
	ds_read_b128 v[202:205], v183 offset:55296
	ds_read_b128 v[206:209], v183 offset:56320
	s_add_u32 s28, s26, 0x80
	s_addc_u32 s29, s27, 0
	s_mov_b32 s79, m0
	s_mov_b32 m0, s56
	s_nop 0
	global_load_lds_dwordx4 v176, s[28:29]
	s_mov_b32 m0, s79
	s_add_u32 s26, s26, 0x80080
	s_mov_b32 s79, m0
	s_mov_b32 m0, s57
	s_nop 0
	global_load_lds_dwordx4 v178, s[28:29]
	s_mov_b32 m0, s79
	s_addc_u32 s27, s27, 0
	s_mov_b32 s28, m0
	s_mov_b32 m0, s58
	s_nop 0
	global_load_lds_dwordx4 v176, s[26:27]
	s_mov_b32 m0, s28
	s_nop 0
	s_mov_b32 s28, m0
	s_mov_b32 m0, s59
	s_nop 0
	global_load_lds_dwordx4 v178, s[26:27]
	s_mov_b32 m0, s28
	s_waitcnt vmcnt(4)
	s_waitcnt lgkmcnt(0)
	s_barrier
	s_setprio 1
	s_waitcnt lgkmcnt(7)
	v_mfma_f32_16x16x32_bf16 v[62:65], v[130:133], v[166:169], v[62:65]
	v_mfma_f32_16x16x32_bf16 v[58:61], v[138:141], v[166:169], v[58:61]
	s_waitcnt lgkmcnt(5)
	v_mfma_f32_16x16x32_bf16 v[42:45], v[138:141], v[186:189], v[42:45]
	v_mfma_f32_16x16x32_bf16 v[46:49], v[130:133], v[186:189], v[46:49]
	s_waitcnt lgkmcnt(3)
	v_mfma_f32_16x16x32_bf16 v[30:33], v[130:133], v[194:197], v[30:33]
	v_mfma_f32_16x16x32_bf16 v[26:29], v[138:141], v[194:197], v[26:29]
	s_waitcnt lgkmcnt(1)
	v_mfma_f32_16x16x32_bf16 v[10:13], v[138:141], v[202:205], v[10:13]
	v_mfma_f32_16x16x32_bf16 v[14:17], v[130:133], v[202:205], v[14:17]
	v_mfma_f32_16x16x32_bf16 v[62:65], v[134:137], v[170:173], v[62:65]
	v_mfma_f32_16x16x32_bf16 v[58:61], v[142:145], v[170:173], v[58:61]
	v_mfma_f32_16x16x32_bf16 v[42:45], v[142:145], v[190:193], v[42:45]
	v_mfma_f32_16x16x32_bf16 v[46:49], v[134:137], v[190:193], v[46:49]
	v_mfma_f32_16x16x32_bf16 v[30:33], v[134:137], v[198:201], v[30:33]
	v_mfma_f32_16x16x32_bf16 v[26:29], v[142:145], v[198:201], v[26:29]
	s_waitcnt lgkmcnt(0)
	v_mfma_f32_16x16x32_bf16 v[10:13], v[142:145], v[206:209], v[10:13]
	v_mfma_f32_16x16x32_bf16 v[14:17], v[134:137], v[206:209], v[14:17]
	s_setprio 0
	s_setprio 1
	v_mfma_f32_16x16x32_bf16 v[54:57], v[146:149], v[166:169], v[54:57]
	v_mfma_f32_16x16x32_bf16 v[50:53], v[154:157], v[166:169], v[50:53]
	v_mfma_f32_16x16x32_bf16 v[34:37], v[154:157], v[186:189], v[34:37]
	v_mfma_f32_16x16x32_bf16 v[38:41], v[146:149], v[186:189], v[38:41]
	v_mfma_f32_16x16x32_bf16 v[22:25], v[146:149], v[194:197], v[22:25]
	v_mfma_f32_16x16x32_bf16 v[18:21], v[154:157], v[194:197], v[18:21]
	v_mfma_f32_16x16x32_bf16 v[2:5], v[154:157], v[202:205], v[2:5]
	v_mfma_f32_16x16x32_bf16 v[6:9], v[146:149], v[202:205], v[6:9]
	v_mfma_f32_16x16x32_bf16 v[54:57], v[150:153], v[170:173], v[54:57]
	v_mfma_f32_16x16x32_bf16 v[50:53], v[158:161], v[170:173], v[50:53]
	v_mfma_f32_16x16x32_bf16 v[34:37], v[158:161], v[190:193], v[34:37]
	v_mfma_f32_16x16x32_bf16 v[38:41], v[150:153], v[190:193], v[38:41]
	v_mfma_f32_16x16x32_bf16 v[22:25], v[150:153], v[198:201], v[22:25]
	v_mfma_f32_16x16x32_bf16 v[18:21], v[158:161], v[198:201], v[18:21]
	s_setprio 2
	s_barrier
	v_mfma_f32_16x16x32_bf16 v[2:5], v[158:161], v[206:209], v[2:5]
	v_mfma_f32_16x16x32_bf16 v[6:9], v[150:153], v[206:209], v[6:9]
	s_setprio 0
	s_add_i32 s78, s78, 2
	s_add_u32 s74, s74, 0x100
	s_addc_u32 s75, s75, 0
	s_add_u32 s24, s24, 0x100
	s_addc_u32 s25, s25, 0
	s_add_u32 s76, s76, 0x100
	s_addc_u32 s77, s77, 0
	s_cmp_gt_u32 s78, 29
	.p2align 6
.LBB0_2410:
	ds_read_b128 v[130:133], v181
	ds_read_b128 v[134:137], v181 offset:1024
	ds_read_b128 v[138:141], v181 offset:2048
	ds_read_b128 v[142:145], v181 offset:3072
	ds_read_b128 v[146:149], v182
	ds_read_b128 v[150:153], v182 offset:1024
	ds_read_b128 v[154:157], v182 offset:2048
	ds_read_b128 v[158:161], v182 offset:3072
	s_cmp_eq_u32 s78, 28
	s_cselect_b32 s27, s15, s75
	s_cselect_b32 s26, s73, s74
	s_cselect_b32 s29, s17, s77
	s_cselect_b32 s28, s71, s76
	ds_read_b128 v[166:169], v183
	ds_read_b128 v[170:173], v183 offset:1024
	ds_read_b128 v[186:189], v183 offset:2048
	ds_read_b128 v[190:193], v183 offset:3072
	ds_read_b128 v[194:197], v183 offset:4096
	ds_read_b128 v[198:201], v183 offset:5120
	ds_read_b128 v[202:205], v183 offset:6144
	ds_read_b128 v[206:209], v183 offset:7168
	s_add_u32 s80, s24, 0xfff80000
	s_addc_u32 s81, s25, -1
	s_mov_b32 s79, m0
	s_mov_b32 m0, s64
	s_nop 0
	global_load_lds_dwordx4 v1, s[80:81]
	s_mov_b32 m0, s79
	s_nop 0
	s_mov_b32 s79, m0
	s_mov_b32 m0, s66
	s_nop 0
	global_load_lds_dwordx4 v177, s[80:81]
	s_mov_b32 m0, s79
	s_nop 0
	s_mov_b32 s79, m0
	s_mov_b32 m0, s65
	s_nop 0
	global_load_lds_dwordx4 v1, s[24:25]
	s_mov_b32 m0, s79
	s_nop 0
	s_mov_b32 s79, m0
	s_mov_b32 m0, s67
	s_nop 0
	global_load_lds_dwordx4 v177, s[24:25]
	s_mov_b32 m0, s79
	s_waitcnt vmcnt(8)
	s_waitcnt lgkmcnt(0)
	s_barrier
	s_setprio 1
	s_waitcnt lgkmcnt(7)
	v_mfma_f32_16x16x32_bf16 v[126:129], v[130:133], v[166:169], v[126:129]
	v_mfma_f32_16x16x32_bf16 v[122:125], v[138:141], v[166:169], v[122:125]
	s_waitcnt lgkmcnt(5)
	v_mfma_f32_16x16x32_bf16 v[114:117], v[138:141], v[186:189], v[114:117]
	v_mfma_f32_16x16x32_bf16 v[118:121], v[130:133], v[186:189], v[118:121]
	s_waitcnt lgkmcnt(3)
	v_mfma_f32_16x16x32_bf16 v[94:97], v[130:133], v[194:197], v[94:97]
	v_mfma_f32_16x16x32_bf16 v[90:93], v[138:141], v[194:197], v[90:93]
	s_waitcnt lgkmcnt(1)
	v_mfma_f32_16x16x32_bf16 v[78:81], v[138:141], v[202:205], v[78:81]
	v_mfma_f32_16x16x32_bf16 v[86:89], v[130:133], v[202:205], v[86:89]
	v_mfma_f32_16x16x32_bf16 v[126:129], v[134:137], v[170:173], v[126:129]
	v_mfma_f32_16x16x32_bf16 v[122:125], v[142:145], v[170:173], v[122:125]
	v_mfma_f32_16x16x32_bf16 v[114:117], v[142:145], v[190:193], v[114:117]
	v_mfma_f32_16x16x32_bf16 v[118:121], v[134:137], v[190:193], v[118:121]
	v_mfma_f32_16x16x32_bf16 v[94:97], v[134:137], v[198:201], v[94:97]
	v_mfma_f32_16x16x32_bf16 v[90:93], v[142:145], v[198:201], v[90:93]
	s_waitcnt lgkmcnt(0)
	v_mfma_f32_16x16x32_bf16 v[78:81], v[142:145], v[206:209], v[78:81]
	v_mfma_f32_16x16x32_bf16 v[86:89], v[134:137], v[206:209], v[86:89]
	s_setprio 0
	s_setprio 1
	v_mfma_f32_16x16x32_bf16 v[110:113], v[146:149], v[166:169], v[110:113]
	v_mfma_f32_16x16x32_bf16 v[106:109], v[154:157], v[166:169], v[106:109]
	v_mfma_f32_16x16x32_bf16 v[98:101], v[154:157], v[186:189], v[98:101]
	v_mfma_f32_16x16x32_bf16 v[102:105], v[146:149], v[186:189], v[102:105]
	v_mfma_f32_16x16x32_bf16 v[82:85], v[146:149], v[194:197], v[82:85]
	v_mfma_f32_16x16x32_bf16 v[74:77], v[154:157], v[194:197], v[74:77]
	v_mfma_f32_16x16x32_bf16 v[66:69], v[154:157], v[202:205], v[66:69]
	v_mfma_f32_16x16x32_bf16 v[70:73], v[146:149], v[202:205], v[70:73]
	v_mfma_f32_16x16x32_bf16 v[110:113], v[150:153], v[170:173], v[110:113]
	v_mfma_f32_16x16x32_bf16 v[106:109], v[158:161], v[170:173], v[106:109]
	v_mfma_f32_16x16x32_bf16 v[98:101], v[158:161], v[190:193], v[98:101]
	v_mfma_f32_16x16x32_bf16 v[102:105], v[150:153], v[190:193], v[102:105]
	v_mfma_f32_16x16x32_bf16 v[82:85], v[150:153], v[198:201], v[82:85]
	v_mfma_f32_16x16x32_bf16 v[74:77], v[158:161], v[198:201], v[74:77]
	s_setprio 2
	s_barrier
	v_mfma_f32_16x16x32_bf16 v[66:69], v[158:161], v[206:209], v[66:69]
	v_mfma_f32_16x16x32_bf16 v[70:73], v[150:153], v[206:209], v[70:73]
	s_setprio 0
	ds_read_b128 v[166:169], v183 offset:16384
	ds_read_b128 v[170:173], v183 offset:17408
	ds_read_b128 v[186:189], v183 offset:18432
	ds_read_b128 v[190:193], v183 offset:19456
	ds_read_b128 v[194:197], v183 offset:20480
	ds_read_b128 v[198:201], v183 offset:21504
	ds_read_b128 v[202:205], v183 offset:22528
	ds_read_b128 v[206:209], v183 offset:23552
	s_mov_b32 s79, m0
	s_mov_b32 m0, s41
	s_nop 0
	global_load_lds_dwordx4 v176, s[26:27]
	s_mov_b32 m0, s79
	s_add_u32 s80, s26, 0x80000
	s_mov_b32 s79, m0
	s_mov_b32 m0, s42
	s_nop 0
	global_load_lds_dwordx4 v178, s[26:27]
	s_mov_b32 m0, s79
	s_addc_u32 s81, s27, 0
	s_mov_b32 s79, m0
	s_mov_b32 m0, s43
	s_nop 0
	global_load_lds_dwordx4 v176, s[80:81]
	s_mov_b32 m0, s79
	s_nop 0
	s_mov_b32 s79, m0
	s_mov_b32 m0, s46
	s_nop 0
	global_load_lds_dwordx4 v178, s[80:81]
	s_mov_b32 m0, s79
	s_waitcnt vmcnt(4)
	s_waitcnt lgkmcnt(0)
	s_barrier
	s_setprio 1
	s_waitcnt lgkmcnt(7)
	v_mfma_f32_16x16x32_bf16 v[62:65], v[130:133], v[166:169], v[62:65]
	v_mfma_f32_16x16x32_bf16 v[58:61], v[138:141], v[166:169], v[58:61]
	s_waitcnt lgkmcnt(5)
	v_mfma_f32_16x16x32_bf16 v[42:45], v[138:141], v[186:189], v[42:45]
	v_mfma_f32_16x16x32_bf16 v[46:49], v[130:133], v[186:189], v[46:49]
	s_waitcnt lgkmcnt(3)
	v_mfma_f32_16x16x32_bf16 v[30:33], v[130:133], v[194:197], v[30:33]
	v_mfma_f32_16x16x32_bf16 v[26:29], v[138:141], v[194:197], v[26:29]
	s_waitcnt lgkmcnt(1)
	v_mfma_f32_16x16x32_bf16 v[10:13], v[138:141], v[202:205], v[10:13]
	v_mfma_f32_16x16x32_bf16 v[14:17], v[130:133], v[202:205], v[14:17]
	v_mfma_f32_16x16x32_bf16 v[62:65], v[134:137], v[170:173], v[62:65]
	v_mfma_f32_16x16x32_bf16 v[58:61], v[142:145], v[170:173], v[58:61]
	v_mfma_f32_16x16x32_bf16 v[42:45], v[142:145], v[190:193], v[42:45]
	v_mfma_f32_16x16x32_bf16 v[46:49], v[134:137], v[190:193], v[46:49]
	v_mfma_f32_16x16x32_bf16 v[30:33], v[134:137], v[198:201], v[30:33]
	v_mfma_f32_16x16x32_bf16 v[26:29], v[142:145], v[198:201], v[26:29]
	s_waitcnt lgkmcnt(0)
	v_mfma_f32_16x16x32_bf16 v[10:13], v[142:145], v[206:209], v[10:13]
	v_mfma_f32_16x16x32_bf16 v[14:17], v[134:137], v[206:209], v[14:17]
	s_setprio 0
	s_setprio 1
	v_mfma_f32_16x16x32_bf16 v[54:57], v[146:149], v[166:169], v[54:57]
	v_mfma_f32_16x16x32_bf16 v[50:53], v[154:157], v[166:169], v[50:53]
	v_mfma_f32_16x16x32_bf16 v[34:37], v[154:157], v[186:189], v[34:37]
	v_mfma_f32_16x16x32_bf16 v[38:41], v[146:149], v[186:189], v[38:41]
	v_mfma_f32_16x16x32_bf16 v[22:25], v[146:149], v[194:197], v[22:25]
	v_mfma_f32_16x16x32_bf16 v[18:21], v[154:157], v[194:197], v[18:21]
	v_mfma_f32_16x16x32_bf16 v[2:5], v[154:157], v[202:205], v[2:5]
	v_mfma_f32_16x16x32_bf16 v[6:9], v[146:149], v[202:205], v[6:9]
	v_mfma_f32_16x16x32_bf16 v[54:57], v[150:153], v[170:173], v[54:57]
	v_mfma_f32_16x16x32_bf16 v[50:53], v[158:161], v[170:173], v[50:53]
	v_mfma_f32_16x16x32_bf16 v[34:37], v[158:161], v[190:193], v[34:37]
	v_mfma_f32_16x16x32_bf16 v[38:41], v[150:153], v[190:193], v[38:41]
	v_mfma_f32_16x16x32_bf16 v[22:25], v[150:153], v[198:201], v[22:25]
	v_mfma_f32_16x16x32_bf16 v[18:21], v[158:161], v[198:201], v[18:21]
	s_setprio 2
	s_barrier
	v_mfma_f32_16x16x32_bf16 v[2:5], v[158:161], v[206:209], v[2:5]
	v_mfma_f32_16x16x32_bf16 v[6:9], v[150:153], v[206:209], v[6:9]
	s_setprio 0
	ds_read_b128 v[130:133], v184
	ds_read_b128 v[134:137], v184 offset:1024
	ds_read_b128 v[138:141], v184 offset:2048
	ds_read_b128 v[142:145], v184 offset:3072
	ds_read_b128 v[146:149], v185
	ds_read_b128 v[150:153], v185 offset:1024
	ds_read_b128 v[154:157], v185 offset:2048
	ds_read_b128 v[158:161], v185 offset:3072
	ds_read_b128 v[166:169], v183 offset:32768
	ds_read_b128 v[170:173], v183 offset:33792
	ds_read_b128 v[186:189], v183 offset:34816
	ds_read_b128 v[190:193], v183 offset:35840
	ds_read_b128 v[194:197], v183 offset:36864
	ds_read_b128 v[198:201], v183 offset:37888
	ds_read_b128 v[202:205], v183 offset:38912
	ds_read_b128 v[206:209], v183 offset:39936
	s_mov_b32 s79, m0
	s_mov_b32 m0, s40
	s_nop 0
	global_load_lds_dwordx4 v1, s[28:29]
	s_mov_b32 m0, s79
	s_nop 0
	s_mov_b32 s79, m0
	s_mov_b32 m0, s47
	s_nop 0
	global_load_lds_dwordx4 v177, s[28:29]
	s_mov_b32 m0, s79
	s_add_u32 s28, s28, 0x80000
	s_addc_u32 s29, s29, 0
	s_mov_b32 s79, m0
	s_mov_b32 m0, s48
	s_nop 0
	global_load_lds_dwordx4 v1, s[28:29]
	s_mov_b32 m0, s79
	s_nop 0
	s_mov_b32 s79, m0
	s_mov_b32 m0, s49
	s_nop 0
	global_load_lds_dwordx4 v177, s[28:29]
	s_mov_b32 m0, s79
	s_waitcnt vmcnt(8)
	s_waitcnt lgkmcnt(0)
	s_barrier
	s_setprio 1
	s_waitcnt lgkmcnt(7)
	v_mfma_f32_16x16x32_bf16 v[126:129], v[130:133], v[166:169], v[126:129]
	v_mfma_f32_16x16x32_bf16 v[122:125], v[138:141], v[166:169], v[122:125]
	s_waitcnt lgkmcnt(5)
	v_mfma_f32_16x16x32_bf16 v[114:117], v[138:141], v[186:189], v[114:117]
	v_mfma_f32_16x16x32_bf16 v[118:121], v[130:133], v[186:189], v[118:121]
	s_waitcnt lgkmcnt(3)
	v_mfma_f32_16x16x32_bf16 v[94:97], v[130:133], v[194:197], v[94:97]
	v_mfma_f32_16x16x32_bf16 v[90:93], v[138:141], v[194:197], v[90:93]
	s_waitcnt lgkmcnt(1)
	v_mfma_f32_16x16x32_bf16 v[78:81], v[138:141], v[202:205], v[78:81]
	v_mfma_f32_16x16x32_bf16 v[86:89], v[130:133], v[202:205], v[86:89]
	v_mfma_f32_16x16x32_bf16 v[126:129], v[134:137], v[170:173], v[126:129]
	v_mfma_f32_16x16x32_bf16 v[122:125], v[142:145], v[170:173], v[122:125]
	v_mfma_f32_16x16x32_bf16 v[114:117], v[142:145], v[190:193], v[114:117]
	v_mfma_f32_16x16x32_bf16 v[118:121], v[134:137], v[190:193], v[118:121]
	v_mfma_f32_16x16x32_bf16 v[94:97], v[134:137], v[198:201], v[94:97]
	v_mfma_f32_16x16x32_bf16 v[90:93], v[142:145], v[198:201], v[90:93]
	s_waitcnt lgkmcnt(0)
	v_mfma_f32_16x16x32_bf16 v[78:81], v[142:145], v[206:209], v[78:81]
	v_mfma_f32_16x16x32_bf16 v[86:89], v[134:137], v[206:209], v[86:89]
	s_setprio 0
	s_setprio 1
	v_mfma_f32_16x16x32_bf16 v[110:113], v[146:149], v[166:169], v[110:113]
	v_mfma_f32_16x16x32_bf16 v[106:109], v[154:157], v[166:169], v[106:109]
	v_mfma_f32_16x16x32_bf16 v[98:101], v[154:157], v[186:189], v[98:101]
	v_mfma_f32_16x16x32_bf16 v[102:105], v[146:149], v[186:189], v[102:105]
	v_mfma_f32_16x16x32_bf16 v[82:85], v[146:149], v[194:197], v[82:85]
	v_mfma_f32_16x16x32_bf16 v[74:77], v[154:157], v[194:197], v[74:77]
	v_mfma_f32_16x16x32_bf16 v[66:69], v[154:157], v[202:205], v[66:69]
	v_mfma_f32_16x16x32_bf16 v[70:73], v[146:149], v[202:205], v[70:73]
	v_mfma_f32_16x16x32_bf16 v[110:113], v[150:153], v[170:173], v[110:113]
	v_mfma_f32_16x16x32_bf16 v[106:109], v[158:161], v[170:173], v[106:109]
	v_mfma_f32_16x16x32_bf16 v[98:101], v[158:161], v[190:193], v[98:101]
	v_mfma_f32_16x16x32_bf16 v[102:105], v[150:153], v[190:193], v[102:105]
	v_mfma_f32_16x16x32_bf16 v[82:85], v[150:153], v[198:201], v[82:85]
	v_mfma_f32_16x16x32_bf16 v[74:77], v[158:161], v[198:201], v[74:77]
	s_setprio 2
	s_barrier
	v_mfma_f32_16x16x32_bf16 v[66:69], v[158:161], v[206:209], v[66:69]
	v_mfma_f32_16x16x32_bf16 v[70:73], v[150:153], v[206:209], v[70:73]
	s_setprio 0
	ds_read_b128 v[166:169], v183 offset:49152
	ds_read_b128 v[170:173], v183 offset:50176
	ds_read_b128 v[186:189], v183 offset:51200
	ds_read_b128 v[190:193], v183 offset:52224
	ds_read_b128 v[194:197], v183 offset:53248
	ds_read_b128 v[198:201], v183 offset:54272
	ds_read_b128 v[202:205], v183 offset:55296
	ds_read_b128 v[206:209], v183 offset:56320
	s_add_u32 s28, s26, 0x80
	s_addc_u32 s29, s27, 0
	s_mov_b32 s79, m0
	s_mov_b32 m0, s56
	s_nop 0
	global_load_lds_dwordx4 v176, s[28:29]
	s_mov_b32 m0, s79
	s_add_u32 s26, s26, 0x80080
	s_mov_b32 s79, m0
	s_mov_b32 m0, s57
	s_nop 0
	global_load_lds_dwordx4 v178, s[28:29]
	s_mov_b32 m0, s79
	s_addc_u32 s27, s27, 0
	s_mov_b32 s28, m0
	s_mov_b32 m0, s58
	s_nop 0
	global_load_lds_dwordx4 v176, s[26:27]
	s_mov_b32 m0, s28
	s_nop 0
	s_mov_b32 s28, m0
	s_mov_b32 m0, s59
	s_nop 0
	global_load_lds_dwordx4 v178, s[26:27]
	s_mov_b32 m0, s28
	s_waitcnt vmcnt(4)
	s_waitcnt lgkmcnt(0)
	s_barrier
	s_setprio 1
	s_waitcnt lgkmcnt(7)
	v_mfma_f32_16x16x32_bf16 v[62:65], v[130:133], v[166:169], v[62:65]
	v_mfma_f32_16x16x32_bf16 v[58:61], v[138:141], v[166:169], v[58:61]
	s_waitcnt lgkmcnt(5)
	v_mfma_f32_16x16x32_bf16 v[42:45], v[138:141], v[186:189], v[42:45]
	v_mfma_f32_16x16x32_bf16 v[46:49], v[130:133], v[186:189], v[46:49]
	s_waitcnt lgkmcnt(3)
	v_mfma_f32_16x16x32_bf16 v[30:33], v[130:133], v[194:197], v[30:33]
	v_mfma_f32_16x16x32_bf16 v[26:29], v[138:141], v[194:197], v[26:29]
	s_waitcnt lgkmcnt(1)
	v_mfma_f32_16x16x32_bf16 v[10:13], v[138:141], v[202:205], v[10:13]
	v_mfma_f32_16x16x32_bf16 v[14:17], v[130:133], v[202:205], v[14:17]
	v_mfma_f32_16x16x32_bf16 v[62:65], v[134:137], v[170:173], v[62:65]
	v_mfma_f32_16x16x32_bf16 v[58:61], v[142:145], v[170:173], v[58:61]
	v_mfma_f32_16x16x32_bf16 v[42:45], v[142:145], v[190:193], v[42:45]
	v_mfma_f32_16x16x32_bf16 v[46:49], v[134:137], v[190:193], v[46:49]
	v_mfma_f32_16x16x32_bf16 v[30:33], v[134:137], v[198:201], v[30:33]
	v_mfma_f32_16x16x32_bf16 v[26:29], v[142:145], v[198:201], v[26:29]
	s_waitcnt lgkmcnt(0)
	v_mfma_f32_16x16x32_bf16 v[10:13], v[142:145], v[206:209], v[10:13]
	v_mfma_f32_16x16x32_bf16 v[14:17], v[134:137], v[206:209], v[14:17]
	s_setprio 0
	s_setprio 1
	v_mfma_f32_16x16x32_bf16 v[54:57], v[146:149], v[166:169], v[54:57]
	v_mfma_f32_16x16x32_bf16 v[50:53], v[154:157], v[166:169], v[50:53]
	v_mfma_f32_16x16x32_bf16 v[34:37], v[154:157], v[186:189], v[34:37]
	v_mfma_f32_16x16x32_bf16 v[38:41], v[146:149], v[186:189], v[38:41]
	v_mfma_f32_16x16x32_bf16 v[22:25], v[146:149], v[194:197], v[22:25]
	v_mfma_f32_16x16x32_bf16 v[18:21], v[154:157], v[194:197], v[18:21]
	v_mfma_f32_16x16x32_bf16 v[2:5], v[154:157], v[202:205], v[2:5]
	v_mfma_f32_16x16x32_bf16 v[6:9], v[146:149], v[202:205], v[6:9]
	v_mfma_f32_16x16x32_bf16 v[54:57], v[150:153], v[170:173], v[54:57]
	v_mfma_f32_16x16x32_bf16 v[50:53], v[158:161], v[170:173], v[50:53]
	v_mfma_f32_16x16x32_bf16 v[34:37], v[158:161], v[190:193], v[34:37]
	v_mfma_f32_16x16x32_bf16 v[38:41], v[150:153], v[190:193], v[38:41]
	v_mfma_f32_16x16x32_bf16 v[22:25], v[150:153], v[198:201], v[22:25]
	v_mfma_f32_16x16x32_bf16 v[18:21], v[158:161], v[198:201], v[18:21]
	s_setprio 2
	s_barrier
	v_mfma_f32_16x16x32_bf16 v[2:5], v[158:161], v[206:209], v[2:5]
	v_mfma_f32_16x16x32_bf16 v[6:9], v[150:153], v[206:209], v[6:9]
	s_setprio 0
	s_add_i32 s78, s78, 2
	s_add_u32 s74, s74, 0x100
	s_addc_u32 s75, s75, 0
	s_add_u32 s24, s24, 0x100
	s_addc_u32 s25, s25, 0
	s_add_u32 s76, s76, 0x100
	s_addc_u32 s77, s77, 0
	s_cmp_gt_u32 s78, 29
	s_cbranch_scc0 .LBB0_2410
	s_and_b64 vcc, exec, s[8:9]
	s_cbranch_vccz .LBB0_2413
	s_barrier

.LBB0_2593:
	s_ashr_i32 s11, s10, 31
	s_lshl_b64 s[12:13], s[10:11], 20
	s_add_u32 s12, s26, s12
	s_addc_u32 s13, s27, s13
	s_and_b64 s[14:15], s[2:3], exec
	s_cselect_b32 s11, s13, s21
	s_cselect_b32 s62, s12, s20
	s_ashr_i32 s9, s8, 31
	s_lshl_b64 s[14:15], s[8:9], 20
	s_add_u32 s14, s28, s14
	s_addc_u32 s15, s29, s15
	s_and_b64 s[22:23], s[2:3], exec
	s_cselect_b32 s9, s15, s19
	s_cselect_b32 s63, s14, s18
	s_add_u32 s64, s18, 0x100
	s_addc_u32 s65, s19, 0
	s_add_u32 s18, s20, 0x80080
	s_addc_u32 s19, s21, 0
	s_add_u32 s66, s20, 0x100
	s_addc_u32 s67, s21, 0
	s_mov_b32 s70, -2
	ds_read_b128 v[148:151], v143
	ds_read_b128 v[152:155], v143 offset:1024
	ds_read_b128 v[156:159], v143 offset:2048
	ds_read_b128 v[160:163], v143 offset:3072
	ds_read_b128 v[164:167], v144
	ds_read_b128 v[168:171], v144 offset:1024
	ds_read_b128 v[172:175], v144 offset:2048
	ds_read_b128 v[176:179], v144 offset:3072
	s_cmp_eq_u32 s70, 28
	s_cselect_b32 s21, s9, s65
	s_cselect_b32 s20, s63, s64
	s_cselect_b32 s23, s11, s67
	s_cselect_b32 s22, s62, s66
	ds_read_b128 v[180:183], v145
	ds_read_b128 v[184:187], v145 offset:1024
	ds_read_b128 v[188:191], v145 offset:2048
	ds_read_b128 v[192:195], v145 offset:3072
	ds_read_b128 v[196:199], v145 offset:4096
	ds_read_b128 v[200:203], v145 offset:5120
	ds_read_b128 v[204:207], v145 offset:6144
	ds_read_b128 v[208:211], v145 offset:7168
	s_add_u32 s74, s18, 0xfff80000
	s_addc_u32 s75, s19, -1
	s_mov_b32 s71, m0
	s_mov_b32 m0, s48
	s_nop 0
	global_load_lds_dwordx4 v138, s[74:75]
	s_mov_b32 m0, s71
	s_nop 0
	s_mov_b32 s71, m0
	s_mov_b32 m0, s57
	s_nop 0
	global_load_lds_dwordx4 v140, s[74:75]
	s_mov_b32 m0, s71
	s_nop 0
	s_mov_b32 s71, m0
	s_mov_b32 m0, s49
	s_nop 0
	global_load_lds_dwordx4 v138, s[18:19]
	s_mov_b32 m0, s71
	s_nop 0
	s_mov_b32 s71, m0
	s_mov_b32 m0, s58
	s_nop 0
	global_load_lds_dwordx4 v140, s[18:19]
	s_mov_b32 m0, s71
	s_waitcnt vmcnt(8)
	s_waitcnt lgkmcnt(0)
	s_barrier
	s_setprio 1
	s_waitcnt lgkmcnt(7)
	v_mfma_f32_16x16x32_bf16 v[126:129], v[148:151], v[180:183], 0
	v_mfma_f32_16x16x32_bf16 v[122:125], v[156:159], v[180:183], 0
	s_waitcnt lgkmcnt(5)
	v_mfma_f32_16x16x32_bf16 v[106:109], v[156:159], v[188:191], 0
	v_mfma_f32_16x16x32_bf16 v[110:113], v[148:151], v[188:191], 0
	s_waitcnt lgkmcnt(3)
	v_mfma_f32_16x16x32_bf16 v[94:97], v[148:151], v[196:199], 0
	v_mfma_f32_16x16x32_bf16 v[90:93], v[156:159], v[196:199], 0
	s_waitcnt lgkmcnt(1)
	v_mfma_f32_16x16x32_bf16 v[74:77], v[156:159], v[204:207], 0
	v_mfma_f32_16x16x32_bf16 v[78:81], v[148:151], v[204:207], 0
	v_mfma_f32_16x16x32_bf16 v[126:129], v[152:155], v[184:187], v[126:129]
	v_mfma_f32_16x16x32_bf16 v[122:125], v[160:163], v[184:187], v[122:125]
	v_mfma_f32_16x16x32_bf16 v[106:109], v[160:163], v[192:195], v[106:109]
	v_mfma_f32_16x16x32_bf16 v[110:113], v[152:155], v[192:195], v[110:113]
	v_mfma_f32_16x16x32_bf16 v[94:97], v[152:155], v[200:203], v[94:97]
	v_mfma_f32_16x16x32_bf16 v[90:93], v[160:163], v[200:203], v[90:93]
	s_waitcnt lgkmcnt(0)
	v_mfma_f32_16x16x32_bf16 v[74:77], v[160:163], v[208:211], v[74:77]
	v_mfma_f32_16x16x32_bf16 v[78:81], v[152:155], v[208:211], v[78:81]
	s_setprio 0
	s_setprio 1
	v_mfma_f32_16x16x32_bf16 v[118:121], v[164:167], v[180:183], 0
	v_mfma_f32_16x16x32_bf16 v[114:117], v[172:175], v[180:183], 0
	v_mfma_f32_16x16x32_bf16 v[98:101], v[172:175], v[188:191], 0
	v_mfma_f32_16x16x32_bf16 v[102:105], v[164:167], v[188:191], 0
	v_mfma_f32_16x16x32_bf16 v[86:89], v[164:167], v[196:199], 0
	v_mfma_f32_16x16x32_bf16 v[82:85], v[172:175], v[196:199], 0
	v_mfma_f32_16x16x32_bf16 v[66:69], v[172:175], v[204:207], 0
	v_mfma_f32_16x16x32_bf16 v[70:73], v[164:167], v[204:207], 0
	v_mfma_f32_16x16x32_bf16 v[118:121], v[168:171], v[184:187], v[118:121]
	v_mfma_f32_16x16x32_bf16 v[114:117], v[176:179], v[184:187], v[114:117]
	v_mfma_f32_16x16x32_bf16 v[98:101], v[176:179], v[192:195], v[98:101]
	v_mfma_f32_16x16x32_bf16 v[102:105], v[168:171], v[192:195], v[102:105]
	v_mfma_f32_16x16x32_bf16 v[86:89], v[168:171], v[200:203], v[86:89]
	v_mfma_f32_16x16x32_bf16 v[82:85], v[176:179], v[200:203], v[82:85]
	s_setprio 2
	s_barrier
	v_mfma_f32_16x16x32_bf16 v[66:69], v[176:179], v[208:211], v[66:69]
	v_mfma_f32_16x16x32_bf16 v[70:73], v[168:171], v[208:211], v[70:73]
	s_setprio 0
	ds_read_b128 v[180:183], v145 offset:16384
	ds_read_b128 v[184:187], v145 offset:17408
	ds_read_b128 v[188:191], v145 offset:18432
	ds_read_b128 v[192:195], v145 offset:19456
	ds_read_b128 v[196:199], v145 offset:20480
	ds_read_b128 v[200:203], v145 offset:21504
	ds_read_b128 v[204:207], v145 offset:22528
	ds_read_b128 v[208:211], v145 offset:23552
	s_mov_b32 s71, m0
	s_mov_b32 m0, s35
	s_nop 0
	global_load_lds_dwordx4 v139, s[20:21]
	s_mov_b32 m0, s71
	s_add_u32 s74, s20, 0x80000
	s_mov_b32 s71, m0
	s_mov_b32 m0, s36
	s_nop 0
	global_load_lds_dwordx4 v141, s[20:21]
	s_mov_b32 m0, s71
	s_addc_u32 s75, s21, 0
	s_mov_b32 s71, m0
	s_mov_b32 m0, s37
	s_nop 0
	global_load_lds_dwordx4 v139, s[74:75]
	s_mov_b32 m0, s71
	s_nop 0
	s_mov_b32 s71, m0
	s_mov_b32 m0, s40
	s_nop 0
	global_load_lds_dwordx4 v141, s[74:75]
	s_mov_b32 m0, s71
	s_waitcnt vmcnt(4)
	s_waitcnt lgkmcnt(0)
	s_barrier
	s_setprio 1
	s_waitcnt lgkmcnt(7)
	v_mfma_f32_16x16x32_bf16 v[62:65], v[148:151], v[180:183], 0
	v_mfma_f32_16x16x32_bf16 v[58:61], v[156:159], v[180:183], 0
	s_waitcnt lgkmcnt(5)
	v_mfma_f32_16x16x32_bf16 v[42:45], v[156:159], v[188:191], 0
	v_mfma_f32_16x16x32_bf16 v[46:49], v[148:151], v[188:191], 0
	s_waitcnt lgkmcnt(3)
	v_mfma_f32_16x16x32_bf16 v[30:33], v[148:151], v[196:199], 0
	v_mfma_f32_16x16x32_bf16 v[26:29], v[156:159], v[196:199], 0
	s_waitcnt lgkmcnt(1)
	v_mfma_f32_16x16x32_bf16 v[10:13], v[156:159], v[204:207], 0
	v_mfma_f32_16x16x32_bf16 v[14:17], v[148:151], v[204:207], 0
	v_mfma_f32_16x16x32_bf16 v[62:65], v[152:155], v[184:187], v[62:65]
	v_mfma_f32_16x16x32_bf16 v[58:61], v[160:163], v[184:187], v[58:61]
	v_mfma_f32_16x16x32_bf16 v[42:45], v[160:163], v[192:195], v[42:45]
	v_mfma_f32_16x16x32_bf16 v[46:49], v[152:155], v[192:195], v[46:49]
	v_mfma_f32_16x16x32_bf16 v[30:33], v[152:155], v[200:203], v[30:33]
	v_mfma_f32_16x16x32_bf16 v[26:29], v[160:163], v[200:203], v[26:29]
	s_waitcnt lgkmcnt(0)
	v_mfma_f32_16x16x32_bf16 v[10:13], v[160:163], v[208:211], v[10:13]
	v_mfma_f32_16x16x32_bf16 v[14:17], v[152:155], v[208:211], v[14:17]
	s_setprio 0
	s_setprio 1
	v_mfma_f32_16x16x32_bf16 v[54:57], v[164:167], v[180:183], 0
	v_mfma_f32_16x16x32_bf16 v[50:53], v[172:175], v[180:183], 0
	v_mfma_f32_16x16x32_bf16 v[34:37], v[172:175], v[188:191], 0
	v_mfma_f32_16x16x32_bf16 v[38:41], v[164:167], v[188:191], 0
	v_mfma_f32_16x16x32_bf16 v[22:25], v[164:167], v[196:199], 0
	v_mfma_f32_16x16x32_bf16 v[18:21], v[172:175], v[196:199], 0
	v_mfma_f32_16x16x32_bf16 v[2:5], v[172:175], v[204:207], 0
	v_mfma_f32_16x16x32_bf16 v[6:9], v[164:167], v[204:207], 0
	v_mfma_f32_16x16x32_bf16 v[54:57], v[168:171], v[184:187], v[54:57]
	v_mfma_f32_16x16x32_bf16 v[50:53], v[176:179], v[184:187], v[50:53]
	v_mfma_f32_16x16x32_bf16 v[34:37], v[176:179], v[192:195], v[34:37]
	v_mfma_f32_16x16x32_bf16 v[38:41], v[168:171], v[192:195], v[38:41]
	v_mfma_f32_16x16x32_bf16 v[22:25], v[168:171], v[200:203], v[22:25]
	v_mfma_f32_16x16x32_bf16 v[18:21], v[176:179], v[200:203], v[18:21]
	s_setprio 2
	s_barrier
	v_mfma_f32_16x16x32_bf16 v[2:5], v[176:179], v[208:211], v[2:5]
	v_mfma_f32_16x16x32_bf16 v[6:9], v[168:171], v[208:211], v[6:9]
	s_setprio 0
	ds_read_b128 v[148:151], v146
	ds_read_b128 v[152:155], v146 offset:1024
	ds_read_b128 v[156:159], v146 offset:2048
	ds_read_b128 v[160:163], v146 offset:3072
	ds_read_b128 v[164:167], v147
	ds_read_b128 v[168:171], v147 offset:1024
	ds_read_b128 v[172:175], v147 offset:2048
	ds_read_b128 v[176:179], v147 offset:3072
	ds_read_b128 v[180:183], v145 offset:32768
	ds_read_b128 v[184:187], v145 offset:33792
	ds_read_b128 v[188:191], v145 offset:34816
	ds_read_b128 v[192:195], v145 offset:35840
	ds_read_b128 v[196:199], v145 offset:36864
	ds_read_b128 v[200:203], v145 offset:37888
	ds_read_b128 v[204:207], v145 offset:38912
	ds_read_b128 v[208:211], v145 offset:39936
	s_mov_b32 s71, m0
	s_mov_b32 m0, s31
	s_nop 0
	global_load_lds_dwordx4 v138, s[22:23]
	s_mov_b32 m0, s71
	s_nop 0
	s_mov_b32 s71, m0
	s_mov_b32 m0, s41
	s_nop 0
	global_load_lds_dwordx4 v140, s[22:23]
	s_mov_b32 m0, s71
	s_add_u32 s22, s22, 0x80000
	s_addc_u32 s23, s23, 0
	s_mov_b32 s71, m0
	s_mov_b32 m0, s42
	s_nop 0
	global_load_lds_dwordx4 v138, s[22:23]
	s_mov_b32 m0, s71
	s_nop 0
	s_mov_b32 s71, m0
	s_mov_b32 m0, s43
	s_nop 0
	global_load_lds_dwordx4 v140, s[22:23]
	s_mov_b32 m0, s71
	s_waitcnt vmcnt(8)
	s_waitcnt lgkmcnt(0)
	s_barrier
	s_setprio 1
	s_waitcnt lgkmcnt(7)
	v_mfma_f32_16x16x32_bf16 v[126:129], v[148:151], v[180:183], v[126:129]
	v_mfma_f32_16x16x32_bf16 v[122:125], v[156:159], v[180:183], v[122:125]
	s_waitcnt lgkmcnt(5)
	v_mfma_f32_16x16x32_bf16 v[106:109], v[156:159], v[188:191], v[106:109]
	v_mfma_f32_16x16x32_bf16 v[110:113], v[148:151], v[188:191], v[110:113]
	s_waitcnt lgkmcnt(3)
	v_mfma_f32_16x16x32_bf16 v[94:97], v[148:151], v[196:199], v[94:97]
	v_mfma_f32_16x16x32_bf16 v[90:93], v[156:159], v[196:199], v[90:93]
	s_waitcnt lgkmcnt(1)
	v_mfma_f32_16x16x32_bf16 v[74:77], v[156:159], v[204:207], v[74:77]
	v_mfma_f32_16x16x32_bf16 v[78:81], v[148:151], v[204:207], v[78:81]
	v_mfma_f32_16x16x32_bf16 v[126:129], v[152:155], v[184:187], v[126:129]
	v_mfma_f32_16x16x32_bf16 v[122:125], v[160:163], v[184:187], v[122:125]
	v_mfma_f32_16x16x32_bf16 v[106:109], v[160:163], v[192:195], v[106:109]
	v_mfma_f32_16x16x32_bf16 v[110:113], v[152:155], v[192:195], v[110:113]
	v_mfma_f32_16x16x32_bf16 v[94:97], v[152:155], v[200:203], v[94:97]
	v_mfma_f32_16x16x32_bf16 v[90:93], v[160:163], v[200:203], v[90:93]
	s_waitcnt lgkmcnt(0)
	v_mfma_f32_16x16x32_bf16 v[74:77], v[160:163], v[208:211], v[74:77]
	v_mfma_f32_16x16x32_bf16 v[78:81], v[152:155], v[208:211], v[78:81]
	s_setprio 0
	s_setprio 1
	v_mfma_f32_16x16x32_bf16 v[118:121], v[164:167], v[180:183], v[118:121]
	v_mfma_f32_16x16x32_bf16 v[114:117], v[172:175], v[180:183], v[114:117]
	v_mfma_f32_16x16x32_bf16 v[98:101], v[172:175], v[188:191], v[98:101]
	v_mfma_f32_16x16x32_bf16 v[102:105], v[164:167], v[188:191], v[102:105]
	v_mfma_f32_16x16x32_bf16 v[86:89], v[164:167], v[196:199], v[86:89]
	v_mfma_f32_16x16x32_bf16 v[82:85], v[172:175], v[196:199], v[82:85]
	v_mfma_f32_16x16x32_bf16 v[66:69], v[172:175], v[204:207], v[66:69]
	v_mfma_f32_16x16x32_bf16 v[70:73], v[164:167], v[204:207], v[70:73]
	v_mfma_f32_16x16x32_bf16 v[118:121], v[168:171], v[184:187], v[118:121]
	v_mfma_f32_16x16x32_bf16 v[114:117], v[176:179], v[184:187], v[114:117]
	v_mfma_f32_16x16x32_bf16 v[98:101], v[176:179], v[192:195], v[98:101]
	v_mfma_f32_16x16x32_bf16 v[102:105], v[168:171], v[192:195], v[102:105]
	v_mfma_f32_16x16x32_bf16 v[86:89], v[168:171], v[200:203], v[86:89]
	v_mfma_f32_16x16x32_bf16 v[82:85], v[176:179], v[200:203], v[82:85]
	s_setprio 2
	s_barrier
	v_mfma_f32_16x16x32_bf16 v[66:69], v[176:179], v[208:211], v[66:69]
	v_mfma_f32_16x16x32_bf16 v[70:73], v[168:171], v[208:211], v[70:73]
	s_setprio 0
	ds_read_b128 v[180:183], v145 offset:49152
	ds_read_b128 v[184:187], v145 offset:50176
	ds_read_b128 v[188:191], v145 offset:51200
	ds_read_b128 v[192:195], v145 offset:52224
	ds_read_b128 v[196:199], v145 offset:53248
	ds_read_b128 v[200:203], v145 offset:54272
	ds_read_b128 v[204:207], v145 offset:55296
	ds_read_b128 v[208:211], v145 offset:56320
	s_add_u32 s22, s20, 0x80
	s_addc_u32 s23, s21, 0
	s_mov_b32 s71, m0
	s_mov_b32 m0, s44
	s_nop 0
	global_load_lds_dwordx4 v139, s[22:23]
	s_mov_b32 m0, s71
	s_add_u32 s20, s20, 0x80080
	s_mov_b32 s71, m0
	s_mov_b32 m0, s45
	s_nop 0
	global_load_lds_dwordx4 v141, s[22:23]
	s_mov_b32 m0, s71
	s_addc_u32 s21, s21, 0
	s_mov_b32 s22, m0
	s_mov_b32 m0, s46
	s_nop 0
	global_load_lds_dwordx4 v139, s[20:21]
	s_mov_b32 m0, s22
	s_nop 0
	s_mov_b32 s22, m0
	s_mov_b32 m0, s47
	s_nop 0
	global_load_lds_dwordx4 v141, s[20:21]
	s_mov_b32 m0, s22
	s_waitcnt vmcnt(4)
	s_waitcnt lgkmcnt(0)
	s_barrier
	s_setprio 1
	s_waitcnt lgkmcnt(7)
	v_mfma_f32_16x16x32_bf16 v[62:65], v[148:151], v[180:183], v[62:65]
	v_mfma_f32_16x16x32_bf16 v[58:61], v[156:159], v[180:183], v[58:61]
	s_waitcnt lgkmcnt(5)
	v_mfma_f32_16x16x32_bf16 v[42:45], v[156:159], v[188:191], v[42:45]
	v_mfma_f32_16x16x32_bf16 v[46:49], v[148:151], v[188:191], v[46:49]
	s_waitcnt lgkmcnt(3)
	v_mfma_f32_16x16x32_bf16 v[30:33], v[148:151], v[196:199], v[30:33]
	v_mfma_f32_16x16x32_bf16 v[26:29], v[156:159], v[196:199], v[26:29]
	s_waitcnt lgkmcnt(1)
	v_mfma_f32_16x16x32_bf16 v[10:13], v[156:159], v[204:207], v[10:13]
	v_mfma_f32_16x16x32_bf16 v[14:17], v[148:151], v[204:207], v[14:17]
	v_mfma_f32_16x16x32_bf16 v[62:65], v[152:155], v[184:187], v[62:65]
	v_mfma_f32_16x16x32_bf16 v[58:61], v[160:163], v[184:187], v[58:61]
	v_mfma_f32_16x16x32_bf16 v[42:45], v[160:163], v[192:195], v[42:45]
	v_mfma_f32_16x16x32_bf16 v[46:49], v[152:155], v[192:195], v[46:49]
	v_mfma_f32_16x16x32_bf16 v[30:33], v[152:155], v[200:203], v[30:33]
	v_mfma_f32_16x16x32_bf16 v[26:29], v[160:163], v[200:203], v[26:29]
	s_waitcnt lgkmcnt(0)
	v_mfma_f32_16x16x32_bf16 v[10:13], v[160:163], v[208:211], v[10:13]
	v_mfma_f32_16x16x32_bf16 v[14:17], v[152:155], v[208:211], v[14:17]
	s_setprio 0
	s_setprio 1
	v_mfma_f32_16x16x32_bf16 v[54:57], v[164:167], v[180:183], v[54:57]
	v_mfma_f32_16x16x32_bf16 v[50:53], v[172:175], v[180:183], v[50:53]
	v_mfma_f32_16x16x32_bf16 v[34:37], v[172:175], v[188:191], v[34:37]
	v_mfma_f32_16x16x32_bf16 v[38:41], v[164:167], v[188:191], v[38:41]
	v_mfma_f32_16x16x32_bf16 v[22:25], v[164:167], v[196:199], v[22:25]
	v_mfma_f32_16x16x32_bf16 v[18:21], v[172:175], v[196:199], v[18:21]
	v_mfma_f32_16x16x32_bf16 v[2:5], v[172:175], v[204:207], v[2:5]
	v_mfma_f32_16x16x32_bf16 v[6:9], v[164:167], v[204:207], v[6:9]
	v_mfma_f32_16x16x32_bf16 v[54:57], v[168:171], v[184:187], v[54:57]
	v_mfma_f32_16x16x32_bf16 v[50:53], v[176:179], v[184:187], v[50:53]
	v_mfma_f32_16x16x32_bf16 v[34:37], v[176:179], v[192:195], v[34:37]
	v_mfma_f32_16x16x32_bf16 v[38:41], v[168:171], v[192:195], v[38:41]
	v_mfma_f32_16x16x32_bf16 v[22:25], v[168:171], v[200:203], v[22:25]
	v_mfma_f32_16x16x32_bf16 v[18:21], v[176:179], v[200:203], v[18:21]
	s_setprio 2
	s_barrier
	v_mfma_f32_16x16x32_bf16 v[2:5], v[176:179], v[208:211], v[2:5]
	v_mfma_f32_16x16x32_bf16 v[6:9], v[168:171], v[208:211], v[6:9]
	s_setprio 0
	s_add_i32 s70, s70, 2
	s_add_u32 s64, s64, 0x100
	s_addc_u32 s65, s65, 0
	s_add_u32 s18, s18, 0x100
	s_addc_u32 s19, s19, 0
	s_add_u32 s66, s66, 0x100
	s_addc_u32 s67, s67, 0
	s_cmp_gt_u32 s70, 29
	.p2align 6
.LBB0_2594:
	ds_read_b128 v[148:151], v143
	ds_read_b128 v[152:155], v143 offset:1024
	ds_read_b128 v[156:159], v143 offset:2048
	ds_read_b128 v[160:163], v143 offset:3072
	ds_read_b128 v[164:167], v144
	ds_read_b128 v[168:171], v144 offset:1024
	ds_read_b128 v[172:175], v144 offset:2048
	ds_read_b128 v[176:179], v144 offset:3072
	s_cmp_eq_u32 s70, 28
	s_cselect_b32 s21, s9, s65
	s_cselect_b32 s20, s63, s64
	s_cselect_b32 s23, s11, s67
	s_cselect_b32 s22, s62, s66
	ds_read_b128 v[180:183], v145
	ds_read_b128 v[184:187], v145 offset:1024
	ds_read_b128 v[188:191], v145 offset:2048
	ds_read_b128 v[192:195], v145 offset:3072
	ds_read_b128 v[196:199], v145 offset:4096
	ds_read_b128 v[200:203], v145 offset:5120
	ds_read_b128 v[204:207], v145 offset:6144
	ds_read_b128 v[208:211], v145 offset:7168
	s_add_u32 s74, s18, 0xfff80000
	s_addc_u32 s75, s19, -1
	s_mov_b32 s71, m0
	s_mov_b32 m0, s48
	s_nop 0
	global_load_lds_dwordx4 v138, s[74:75]
	s_mov_b32 m0, s71
	s_nop 0
	s_mov_b32 s71, m0
	s_mov_b32 m0, s57
	s_nop 0
	global_load_lds_dwordx4 v140, s[74:75]
	s_mov_b32 m0, s71
	s_nop 0
	s_mov_b32 s71, m0
	s_mov_b32 m0, s49
	s_nop 0
	global_load_lds_dwordx4 v138, s[18:19]
	s_mov_b32 m0, s71
	s_nop 0
	s_mov_b32 s71, m0
	s_mov_b32 m0, s58
	s_nop 0
	global_load_lds_dwordx4 v140, s[18:19]
	s_mov_b32 m0, s71
	s_waitcnt vmcnt(8)
	s_waitcnt lgkmcnt(0)
	s_barrier
	s_setprio 1
	s_waitcnt lgkmcnt(7)
	v_mfma_f32_16x16x32_bf16 v[126:129], v[148:151], v[180:183], v[126:129]
	v_mfma_f32_16x16x32_bf16 v[122:125], v[156:159], v[180:183], v[122:125]
	s_waitcnt lgkmcnt(5)
	v_mfma_f32_16x16x32_bf16 v[106:109], v[156:159], v[188:191], v[106:109]
	v_mfma_f32_16x16x32_bf16 v[110:113], v[148:151], v[188:191], v[110:113]
	s_waitcnt lgkmcnt(3)
	v_mfma_f32_16x16x32_bf16 v[94:97], v[148:151], v[196:199], v[94:97]
	v_mfma_f32_16x16x32_bf16 v[90:93], v[156:159], v[196:199], v[90:93]
	s_waitcnt lgkmcnt(1)
	v_mfma_f32_16x16x32_bf16 v[74:77], v[156:159], v[204:207], v[74:77]
	v_mfma_f32_16x16x32_bf16 v[78:81], v[148:151], v[204:207], v[78:81]
	v_mfma_f32_16x16x32_bf16 v[126:129], v[152:155], v[184:187], v[126:129]
	v_mfma_f32_16x16x32_bf16 v[122:125], v[160:163], v[184:187], v[122:125]
	v_mfma_f32_16x16x32_bf16 v[106:109], v[160:163], v[192:195], v[106:109]
	v_mfma_f32_16x16x32_bf16 v[110:113], v[152:155], v[192:195], v[110:113]
	v_mfma_f32_16x16x32_bf16 v[94:97], v[152:155], v[200:203], v[94:97]
	v_mfma_f32_16x16x32_bf16 v[90:93], v[160:163], v[200:203], v[90:93]
	s_waitcnt lgkmcnt(0)
	v_mfma_f32_16x16x32_bf16 v[74:77], v[160:163], v[208:211], v[74:77]
	v_mfma_f32_16x16x32_bf16 v[78:81], v[152:155], v[208:211], v[78:81]
	s_setprio 0
	s_setprio 1
	v_mfma_f32_16x16x32_bf16 v[118:121], v[164:167], v[180:183], v[118:121]
	v_mfma_f32_16x16x32_bf16 v[114:117], v[172:175], v[180:183], v[114:117]
	v_mfma_f32_16x16x32_bf16 v[98:101], v[172:175], v[188:191], v[98:101]
	v_mfma_f32_16x16x32_bf16 v[102:105], v[164:167], v[188:191], v[102:105]
	v_mfma_f32_16x16x32_bf16 v[86:89], v[164:167], v[196:199], v[86:89]
	v_mfma_f32_16x16x32_bf16 v[82:85], v[172:175], v[196:199], v[82:85]
	v_mfma_f32_16x16x32_bf16 v[66:69], v[172:175], v[204:207], v[66:69]
	v_mfma_f32_16x16x32_bf16 v[70:73], v[164:167], v[204:207], v[70:73]
	v_mfma_f32_16x16x32_bf16 v[118:121], v[168:171], v[184:187], v[118:121]
	v_mfma_f32_16x16x32_bf16 v[114:117], v[176:179], v[184:187], v[114:117]
	v_mfma_f32_16x16x32_bf16 v[98:101], v[176:179], v[192:195], v[98:101]
	v_mfma_f32_16x16x32_bf16 v[102:105], v[168:171], v[192:195], v[102:105]
	v_mfma_f32_16x16x32_bf16 v[86:89], v[168:171], v[200:203], v[86:89]
	v_mfma_f32_16x16x32_bf16 v[82:85], v[176:179], v[200:203], v[82:85]
	s_setprio 2
	s_barrier
	v_mfma_f32_16x16x32_bf16 v[66:69], v[176:179], v[208:211], v[66:69]
	v_mfma_f32_16x16x32_bf16 v[70:73], v[168:171], v[208:211], v[70:73]
	s_setprio 0
	ds_read_b128 v[180:183], v145 offset:16384
	ds_read_b128 v[184:187], v145 offset:17408
	ds_read_b128 v[188:191], v145 offset:18432
	ds_read_b128 v[192:195], v145 offset:19456
	ds_read_b128 v[196:199], v145 offset:20480
	ds_read_b128 v[200:203], v145 offset:21504
	ds_read_b128 v[204:207], v145 offset:22528
	ds_read_b128 v[208:211], v145 offset:23552
	s_mov_b32 s71, m0
	s_mov_b32 m0, s35
	s_nop 0
	global_load_lds_dwordx4 v139, s[20:21]
	s_mov_b32 m0, s71
	s_add_u32 s74, s20, 0x80000
	s_mov_b32 s71, m0
	s_mov_b32 m0, s36
	s_nop 0
	global_load_lds_dwordx4 v141, s[20:21]
	s_mov_b32 m0, s71
	s_addc_u32 s75, s21, 0
	s_mov_b32 s71, m0
	s_mov_b32 m0, s37
	s_nop 0
	global_load_lds_dwordx4 v139, s[74:75]
	s_mov_b32 m0, s71
	s_nop 0
	s_mov_b32 s71, m0
	s_mov_b32 m0, s40
	s_nop 0
	global_load_lds_dwordx4 v141, s[74:75]
	s_mov_b32 m0, s71
	s_waitcnt vmcnt(4)
	s_waitcnt lgkmcnt(0)
	s_barrier
	s_setprio 1
	s_waitcnt lgkmcnt(7)
	v_mfma_f32_16x16x32_bf16 v[62:65], v[148:151], v[180:183], v[62:65]
	v_mfma_f32_16x16x32_bf16 v[58:61], v[156:159], v[180:183], v[58:61]
	s_waitcnt lgkmcnt(5)
	v_mfma_f32_16x16x32_bf16 v[42:45], v[156:159], v[188:191], v[42:45]
	v_mfma_f32_16x16x32_bf16 v[46:49], v[148:151], v[188:191], v[46:49]
	s_waitcnt lgkmcnt(3)
	v_mfma_f32_16x16x32_bf16 v[30:33], v[148:151], v[196:199], v[30:33]
	v_mfma_f32_16x16x32_bf16 v[26:29], v[156:159], v[196:199], v[26:29]
	s_waitcnt lgkmcnt(1)
	v_mfma_f32_16x16x32_bf16 v[10:13], v[156:159], v[204:207], v[10:13]
	v_mfma_f32_16x16x32_bf16 v[14:17], v[148:151], v[204:207], v[14:17]
	v_mfma_f32_16x16x32_bf16 v[62:65], v[152:155], v[184:187], v[62:65]
	v_mfma_f32_16x16x32_bf16 v[58:61], v[160:163], v[184:187], v[58:61]
	v_mfma_f32_16x16x32_bf16 v[42:45], v[160:163], v[192:195], v[42:45]
	v_mfma_f32_16x16x32_bf16 v[46:49], v[152:155], v[192:195], v[46:49]
	v_mfma_f32_16x16x32_bf16 v[30:33], v[152:155], v[200:203], v[30:33]
	v_mfma_f32_16x16x32_bf16 v[26:29], v[160:163], v[200:203], v[26:29]
	s_waitcnt lgkmcnt(0)
	v_mfma_f32_16x16x32_bf16 v[10:13], v[160:163], v[208:211], v[10:13]
	v_mfma_f32_16x16x32_bf16 v[14:17], v[152:155], v[208:211], v[14:17]
	s_setprio 0
	s_setprio 1
	v_mfma_f32_16x16x32_bf16 v[54:57], v[164:167], v[180:183], v[54:57]
	v_mfma_f32_16x16x32_bf16 v[50:53], v[172:175], v[180:183], v[50:53]
	v_mfma_f32_16x16x32_bf16 v[34:37], v[172:175], v[188:191], v[34:37]
	v_mfma_f32_16x16x32_bf16 v[38:41], v[164:167], v[188:191], v[38:41]
	v_mfma_f32_16x16x32_bf16 v[22:25], v[164:167], v[196:199], v[22:25]
	v_mfma_f32_16x16x32_bf16 v[18:21], v[172:175], v[196:199], v[18:21]
	v_mfma_f32_16x16x32_bf16 v[2:5], v[172:175], v[204:207], v[2:5]
	v_mfma_f32_16x16x32_bf16 v[6:9], v[164:167], v[204:207], v[6:9]
	v_mfma_f32_16x16x32_bf16 v[54:57], v[168:171], v[184:187], v[54:57]
	v_mfma_f32_16x16x32_bf16 v[50:53], v[176:179], v[184:187], v[50:53]
	v_mfma_f32_16x16x32_bf16 v[34:37], v[176:179], v[192:195], v[34:37]
	v_mfma_f32_16x16x32_bf16 v[38:41], v[168:171], v[192:195], v[38:41]
	v_mfma_f32_16x16x32_bf16 v[22:25], v[168:171], v[200:203], v[22:25]
	v_mfma_f32_16x16x32_bf16 v[18:21], v[176:179], v[200:203], v[18:21]
	s_setprio 2
	s_barrier
	v_mfma_f32_16x16x32_bf16 v[2:5], v[176:179], v[208:211], v[2:5]
	v_mfma_f32_16x16x32_bf16 v[6:9], v[168:171], v[208:211], v[6:9]
	s_setprio 0
	ds_read_b128 v[148:151], v146
	ds_read_b128 v[152:155], v146 offset:1024
	ds_read_b128 v[156:159], v146 offset:2048
	ds_read_b128 v[160:163], v146 offset:3072
	ds_read_b128 v[164:167], v147
	ds_read_b128 v[168:171], v147 offset:1024
	ds_read_b128 v[172:175], v147 offset:2048
	ds_read_b128 v[176:179], v147 offset:3072
	ds_read_b128 v[180:183], v145 offset:32768
	ds_read_b128 v[184:187], v145 offset:33792
	ds_read_b128 v[188:191], v145 offset:34816
	ds_read_b128 v[192:195], v145 offset:35840
	ds_read_b128 v[196:199], v145 offset:36864
	ds_read_b128 v[200:203], v145 offset:37888
	ds_read_b128 v[204:207], v145 offset:38912
	ds_read_b128 v[208:211], v145 offset:39936
	s_mov_b32 s71, m0
	s_mov_b32 m0, s31
	s_nop 0
	global_load_lds_dwordx4 v138, s[22:23]
	s_mov_b32 m0, s71
	s_nop 0
	s_mov_b32 s71, m0
	s_mov_b32 m0, s41
	s_nop 0
	global_load_lds_dwordx4 v140, s[22:23]
	s_mov_b32 m0, s71
	s_add_u32 s22, s22, 0x80000
	s_addc_u32 s23, s23, 0
	s_mov_b32 s71, m0
	s_mov_b32 m0, s42
	s_nop 0
	global_load_lds_dwordx4 v138, s[22:23]
	s_mov_b32 m0, s71
	s_nop 0
	s_mov_b32 s71, m0
	s_mov_b32 m0, s43
	s_nop 0
	global_load_lds_dwordx4 v140, s[22:23]
	s_mov_b32 m0, s71
	s_waitcnt vmcnt(8)
	s_waitcnt lgkmcnt(0)
	s_barrier
	s_setprio 1
	s_waitcnt lgkmcnt(7)
	v_mfma_f32_16x16x32_bf16 v[126:129], v[148:151], v[180:183], v[126:129]
	v_mfma_f32_16x16x32_bf16 v[122:125], v[156:159], v[180:183], v[122:125]
	s_waitcnt lgkmcnt(5)
	v_mfma_f32_16x16x32_bf16 v[106:109], v[156:159], v[188:191], v[106:109]
	v_mfma_f32_16x16x32_bf16 v[110:113], v[148:151], v[188:191], v[110:113]
	s_waitcnt lgkmcnt(3)
	v_mfma_f32_16x16x32_bf16 v[94:97], v[148:151], v[196:199], v[94:97]
	v_mfma_f32_16x16x32_bf16 v[90:93], v[156:159], v[196:199], v[90:93]
	s_waitcnt lgkmcnt(1)
	v_mfma_f32_16x16x32_bf16 v[74:77], v[156:159], v[204:207], v[74:77]
	v_mfma_f32_16x16x32_bf16 v[78:81], v[148:151], v[204:207], v[78:81]
	v_mfma_f32_16x16x32_bf16 v[126:129], v[152:155], v[184:187], v[126:129]
	v_mfma_f32_16x16x32_bf16 v[122:125], v[160:163], v[184:187], v[122:125]
	v_mfma_f32_16x16x32_bf16 v[106:109], v[160:163], v[192:195], v[106:109]
	v_mfma_f32_16x16x32_bf16 v[110:113], v[152:155], v[192:195], v[110:113]
	v_mfma_f32_16x16x32_bf16 v[94:97], v[152:155], v[200:203], v[94:97]
	v_mfma_f32_16x16x32_bf16 v[90:93], v[160:163], v[200:203], v[90:93]
	s_waitcnt lgkmcnt(0)
	v_mfma_f32_16x16x32_bf16 v[74:77], v[160:163], v[208:211], v[74:77]
	v_mfma_f32_16x16x32_bf16 v[78:81], v[152:155], v[208:211], v[78:81]
	s_setprio 0
	s_setprio 1
	v_mfma_f32_16x16x32_bf16 v[118:121], v[164:167], v[180:183], v[118:121]
	v_mfma_f32_16x16x32_bf16 v[114:117], v[172:175], v[180:183], v[114:117]
	v_mfma_f32_16x16x32_bf16 v[98:101], v[172:175], v[188:191], v[98:101]
	v_mfma_f32_16x16x32_bf16 v[102:105], v[164:167], v[188:191], v[102:105]
	v_mfma_f32_16x16x32_bf16 v[86:89], v[164:167], v[196:199], v[86:89]
	v_mfma_f32_16x16x32_bf16 v[82:85], v[172:175], v[196:199], v[82:85]
	v_mfma_f32_16x16x32_bf16 v[66:69], v[172:175], v[204:207], v[66:69]
	v_mfma_f32_16x16x32_bf16 v[70:73], v[164:167], v[204:207], v[70:73]
	v_mfma_f32_16x16x32_bf16 v[118:121], v[168:171], v[184:187], v[118:121]
	v_mfma_f32_16x16x32_bf16 v[114:117], v[176:179], v[184:187], v[114:117]
	v_mfma_f32_16x16x32_bf16 v[98:101], v[176:179], v[192:195], v[98:101]
	v_mfma_f32_16x16x32_bf16 v[102:105], v[168:171], v[192:195], v[102:105]
	v_mfma_f32_16x16x32_bf16 v[86:89], v[168:171], v[200:203], v[86:89]
	v_mfma_f32_16x16x32_bf16 v[82:85], v[176:179], v[200:203], v[82:85]
	s_setprio 2
	s_barrier
	v_mfma_f32_16x16x32_bf16 v[66:69], v[176:179], v[208:211], v[66:69]
	v_mfma_f32_16x16x32_bf16 v[70:73], v[168:171], v[208:211], v[70:73]
	s_setprio 0
	ds_read_b128 v[180:183], v145 offset:49152
	ds_read_b128 v[184:187], v145 offset:50176
	ds_read_b128 v[188:191], v145 offset:51200
	ds_read_b128 v[192:195], v145 offset:52224
	ds_read_b128 v[196:199], v145 offset:53248
	ds_read_b128 v[200:203], v145 offset:54272
	ds_read_b128 v[204:207], v145 offset:55296
	ds_read_b128 v[208:211], v145 offset:56320
	s_add_u32 s22, s20, 0x80
	s_addc_u32 s23, s21, 0
	s_mov_b32 s71, m0
	s_mov_b32 m0, s44
	s_nop 0
	global_load_lds_dwordx4 v139, s[22:23]
	s_mov_b32 m0, s71
	s_add_u32 s20, s20, 0x80080
	s_mov_b32 s71, m0
	s_mov_b32 m0, s45
	s_nop 0
	global_load_lds_dwordx4 v141, s[22:23]
	s_mov_b32 m0, s71
	s_addc_u32 s21, s21, 0
	s_mov_b32 s22, m0
	s_mov_b32 m0, s46
	s_nop 0
	global_load_lds_dwordx4 v139, s[20:21]
	s_mov_b32 m0, s22
	s_nop 0
	s_mov_b32 s22, m0
	s_mov_b32 m0, s47
	s_nop 0
	global_load_lds_dwordx4 v141, s[20:21]
	s_mov_b32 m0, s22
	s_waitcnt vmcnt(4)
	s_waitcnt lgkmcnt(0)
	s_barrier
	s_setprio 1
	s_waitcnt lgkmcnt(7)
	v_mfma_f32_16x16x32_bf16 v[62:65], v[148:151], v[180:183], v[62:65]
	v_mfma_f32_16x16x32_bf16 v[58:61], v[156:159], v[180:183], v[58:61]
	s_waitcnt lgkmcnt(5)
	v_mfma_f32_16x16x32_bf16 v[42:45], v[156:159], v[188:191], v[42:45]
	v_mfma_f32_16x16x32_bf16 v[46:49], v[148:151], v[188:191], v[46:49]
	s_waitcnt lgkmcnt(3)
	v_mfma_f32_16x16x32_bf16 v[30:33], v[148:151], v[196:199], v[30:33]
	v_mfma_f32_16x16x32_bf16 v[26:29], v[156:159], v[196:199], v[26:29]
	s_waitcnt lgkmcnt(1)
	v_mfma_f32_16x16x32_bf16 v[10:13], v[156:159], v[204:207], v[10:13]
	v_mfma_f32_16x16x32_bf16 v[14:17], v[148:151], v[204:207], v[14:17]
	v_mfma_f32_16x16x32_bf16 v[62:65], v[152:155], v[184:187], v[62:65]
	v_mfma_f32_16x16x32_bf16 v[58:61], v[160:163], v[184:187], v[58:61]
	v_mfma_f32_16x16x32_bf16 v[42:45], v[160:163], v[192:195], v[42:45]
	v_mfma_f32_16x16x32_bf16 v[46:49], v[152:155], v[192:195], v[46:49]
	v_mfma_f32_16x16x32_bf16 v[30:33], v[152:155], v[200:203], v[30:33]
	v_mfma_f32_16x16x32_bf16 v[26:29], v[160:163], v[200:203], v[26:29]
	s_waitcnt lgkmcnt(0)
	v_mfma_f32_16x16x32_bf16 v[10:13], v[160:163], v[208:211], v[10:13]
	v_mfma_f32_16x16x32_bf16 v[14:17], v[152:155], v[208:211], v[14:17]
	s_setprio 0
	s_setprio 1
	v_mfma_f32_16x16x32_bf16 v[54:57], v[164:167], v[180:183], v[54:57]
	v_mfma_f32_16x16x32_bf16 v[50:53], v[172:175], v[180:183], v[50:53]
	v_mfma_f32_16x16x32_bf16 v[34:37], v[172:175], v[188:191], v[34:37]
	v_mfma_f32_16x16x32_bf16 v[38:41], v[164:167], v[188:191], v[38:41]
	v_mfma_f32_16x16x32_bf16 v[22:25], v[164:167], v[196:199], v[22:25]
	v_mfma_f32_16x16x32_bf16 v[18:21], v[172:175], v[196:199], v[18:21]
	v_mfma_f32_16x16x32_bf16 v[2:5], v[172:175], v[204:207], v[2:5]
	v_mfma_f32_16x16x32_bf16 v[6:9], v[164:167], v[204:207], v[6:9]
	v_mfma_f32_16x16x32_bf16 v[54:57], v[168:171], v[184:187], v[54:57]
	v_mfma_f32_16x16x32_bf16 v[50:53], v[176:179], v[184:187], v[50:53]
	v_mfma_f32_16x16x32_bf16 v[34:37], v[176:179], v[192:195], v[34:37]
	v_mfma_f32_16x16x32_bf16 v[38:41], v[168:171], v[192:195], v[38:41]
	v_mfma_f32_16x16x32_bf16 v[22:25], v[168:171], v[200:203], v[22:25]
	v_mfma_f32_16x16x32_bf16 v[18:21], v[176:179], v[200:203], v[18:21]
	s_setprio 2
	s_barrier
	v_mfma_f32_16x16x32_bf16 v[2:5], v[176:179], v[208:211], v[2:5]
	v_mfma_f32_16x16x32_bf16 v[6:9], v[168:171], v[208:211], v[6:9]
	s_setprio 0
	s_add_i32 s70, s70, 2
	s_add_u32 s64, s64, 0x100
	s_addc_u32 s65, s65, 0
	s_add_u32 s18, s18, 0x100
	s_addc_u32 s19, s19, 0
	s_add_u32 s66, s66, 0x100
	s_addc_u32 s67, s67, 0
	s_cmp_gt_u32 s70, 29
	s_cbranch_scc0 .LBB0_2594
	s_and_b64 vcc, exec, s[6:7]
	s_cbranch_vccz .LBB0_2597
	s_barrier

.LBB0_2791:
	s_ashr_i32 s21, s20, 31
	s_lshl_b64 s[22:23], s[20:21], 15
	s_add_u32 s22, s37, s22
	s_addc_u32 s23, s40, s23
	s_and_b64 s[24:25], s[2:3], exec
	s_cselect_b32 s21, s23, s31
	s_cselect_b32 s63, s22, s30
	s_ashr_i32 s19, s18, 31
	s_lshl_b64 s[24:25], s[18:19], 15
	s_add_u32 s24, s41, s24
	s_addc_u32 s25, s42, s25
	s_and_b64 s[34:35], s[2:3], exec
	s_cselect_b32 s19, s25, s29
	s_cselect_b32 s64, s24, s28
	s_add_u32 s65, s28, 0x80000
	s_addc_u32 s66, s29, 0
	s_add_u32 s28, s30, 0x204000
	s_addc_u32 s29, s31, 0
	s_add_u32 s67, s30, 0x400000
	s_addc_u32 s68, s31, 0
	s_mov_b32 s69, -2
	s_waitcnt vmcnt(25)
	s_waitcnt vmcnt(24)
	s_waitcnt vmcnt(4)
	s_waitcnt vmcnt(2)
	s_waitcnt vmcnt(1)
	s_waitcnt vmcnt(0)
	ds_read_b128 v[130:133], v181
	ds_read_b128 v[134:137], v181 offset:1024
	ds_read_b128 v[138:141], v181 offset:2048
	ds_read_b128 v[142:145], v181 offset:3072
	ds_read_b128 v[150:153], v182
	ds_read_b128 v[154:157], v182 offset:1024
	ds_read_b128 v[158:161], v182 offset:2048
	ds_read_b128 v[162:165], v182 offset:3072
	s_cmpk_eq_i32 s69, 0x52
	s_cselect_b32 s31, s19, s66
	s_cselect_b32 s30, s64, s65
	s_cselect_b32 s35, s21, s68
	s_cselect_b32 s34, s63, s67
	ds_read_b128 v[166:169], v183
	ds_read_b128 v[170:173], v183 offset:1024
	ds_read_b128 v[186:189], v183 offset:2048
	ds_read_b128 v[190:193], v183 offset:3072
	ds_read_b128 v[194:197], v183 offset:4096
	ds_read_b128 v[198:201], v183 offset:5120
	ds_read_b128 v[202:205], v183 offset:6144
	ds_read_b128 v[206:209], v183 offset:7168
	s_add_u32 s70, s28, 0xffffc000
	s_addc_u32 s71, s29, -1
	s_mov_b32 s73, m0
	s_mov_b32 m0, s57
	s_nop 0
	global_load_lds_dwordx4 v1, s[70:71]
	s_mov_b32 m0, s73
	s_nop 0
	s_mov_b32 s73, m0
	s_mov_b32 m0, s59
	s_nop 0
	global_load_lds_dwordx4 v177, s[70:71]
	s_mov_b32 m0, s73
	s_mov_b32 s70, m0
	s_mov_b32 m0, s58
	s_nop 0
	global_load_lds_dwordx4 v1, s[28:29]
	s_mov_b32 m0, s70
	s_nop 0
	s_mov_b32 s70, m0
	s_mov_b32 m0, s60
	s_nop 0
	global_load_lds_dwordx4 v177, s[28:29]
	s_mov_b32 m0, s70
	s_waitcnt vmcnt(8)
	s_waitcnt lgkmcnt(0)
	s_barrier
	s_setprio 1
	s_waitcnt lgkmcnt(7)
	v_mfma_f32_16x16x32_bf16 v[126:129], v[130:133], v[166:169], 0
	v_mfma_f32_16x16x32_bf16 v[122:125], v[138:141], v[166:169], 0
	s_waitcnt lgkmcnt(5)
	v_mfma_f32_16x16x32_bf16 v[110:113], v[138:141], v[186:189], 0
	v_mfma_f32_16x16x32_bf16 v[118:121], v[130:133], v[186:189], 0
	s_waitcnt lgkmcnt(3)
	v_mfma_f32_16x16x32_bf16 v[94:97], v[130:133], v[194:197], 0
	v_mfma_f32_16x16x32_bf16 v[90:93], v[138:141], v[194:197], 0
	s_waitcnt lgkmcnt(1)
	v_mfma_f32_16x16x32_bf16 v[78:81], v[138:141], v[202:205], 0
	v_mfma_f32_16x16x32_bf16 v[86:89], v[130:133], v[202:205], 0
	v_mfma_f32_16x16x32_bf16 v[126:129], v[134:137], v[170:173], v[126:129]
	v_mfma_f32_16x16x32_bf16 v[122:125], v[142:145], v[170:173], v[122:125]
	v_mfma_f32_16x16x32_bf16 v[110:113], v[142:145], v[190:193], v[110:113]
	v_mfma_f32_16x16x32_bf16 v[118:121], v[134:137], v[190:193], v[118:121]
	v_mfma_f32_16x16x32_bf16 v[94:97], v[134:137], v[198:201], v[94:97]
	v_mfma_f32_16x16x32_bf16 v[90:93], v[142:145], v[198:201], v[90:93]
	s_waitcnt lgkmcnt(0)
	v_mfma_f32_16x16x32_bf16 v[78:81], v[142:145], v[206:209], v[78:81]
	v_mfma_f32_16x16x32_bf16 v[86:89], v[134:137], v[206:209], v[86:89]
	s_setprio 0
	s_setprio 1
	v_mfma_f32_16x16x32_bf16 v[114:117], v[150:153], v[166:169], 0
	v_mfma_f32_16x16x32_bf16 v[106:109], v[158:161], v[166:169], 0
	v_mfma_f32_16x16x32_bf16 v[98:101], v[158:161], v[186:189], 0
	v_mfma_f32_16x16x32_bf16 v[102:105], v[150:153], v[186:189], 0
	v_mfma_f32_16x16x32_bf16 v[82:85], v[150:153], v[194:197], 0
	v_mfma_f32_16x16x32_bf16 v[74:77], v[158:161], v[194:197], 0
	v_mfma_f32_16x16x32_bf16 v[66:69], v[158:161], v[202:205], 0
	v_mfma_f32_16x16x32_bf16 v[70:73], v[150:153], v[202:205], 0
	v_mfma_f32_16x16x32_bf16 v[114:117], v[154:157], v[170:173], v[114:117]
	v_mfma_f32_16x16x32_bf16 v[106:109], v[162:165], v[170:173], v[106:109]
	v_mfma_f32_16x16x32_bf16 v[98:101], v[162:165], v[190:193], v[98:101]
	v_mfma_f32_16x16x32_bf16 v[102:105], v[154:157], v[190:193], v[102:105]
	v_mfma_f32_16x16x32_bf16 v[82:85], v[154:157], v[198:201], v[82:85]
	v_mfma_f32_16x16x32_bf16 v[74:77], v[162:165], v[198:201], v[74:77]
	s_setprio 2
	s_barrier
	v_mfma_f32_16x16x32_bf16 v[66:69], v[162:165], v[206:209], v[66:69]
	v_mfma_f32_16x16x32_bf16 v[70:73], v[154:157], v[206:209], v[70:73]
	s_setprio 0
	ds_read_b128 v[166:169], v183 offset:16384
	ds_read_b128 v[170:173], v183 offset:17408
	ds_read_b128 v[186:189], v183 offset:18432
	ds_read_b128 v[190:193], v183 offset:19456
	ds_read_b128 v[194:197], v183 offset:20480
	ds_read_b128 v[198:201], v183 offset:21504
	ds_read_b128 v[202:205], v183 offset:22528
	ds_read_b128 v[206:209], v183 offset:23552
	s_mov_b32 s70, m0
	s_mov_b32 m0, s27
	s_nop 0
	global_load_lds_dwordx4 v176, s[30:31]
	s_mov_b32 m0, s70
	s_nop 0
	s_mov_b32 s70, m0
	s_mov_b32 m0, s45
	s_nop 0
	global_load_lds_dwordx4 v178, s[30:31]
	s_mov_b32 m0, s70
	s_add_u32 s70, s30, 0x4000
	s_addc_u32 s71, s31, 0
	s_mov_b32 s73, m0
	s_mov_b32 m0, s46
	s_nop 0
	global_load_lds_dwordx4 v176, s[70:71]
	s_mov_b32 m0, s73
	s_nop 0
	s_mov_b32 s73, m0
	s_mov_b32 m0, s47
	s_nop 0
	global_load_lds_dwordx4 v178, s[70:71]
	s_mov_b32 m0, s73
	s_waitcnt vmcnt(4)
	s_waitcnt lgkmcnt(0)
	s_barrier
	s_setprio 1
	s_waitcnt lgkmcnt(7)
	v_mfma_f32_16x16x32_bf16 v[62:65], v[130:133], v[166:169], 0
	v_mfma_f32_16x16x32_bf16 v[58:61], v[138:141], v[166:169], 0
	s_waitcnt lgkmcnt(5)
	v_mfma_f32_16x16x32_bf16 v[42:45], v[138:141], v[186:189], 0
	v_mfma_f32_16x16x32_bf16 v[46:49], v[130:133], v[186:189], 0
	s_waitcnt lgkmcnt(3)
	v_mfma_f32_16x16x32_bf16 v[30:33], v[130:133], v[194:197], 0
	v_mfma_f32_16x16x32_bf16 v[26:29], v[138:141], v[194:197], 0
	s_waitcnt lgkmcnt(1)
	v_mfma_f32_16x16x32_bf16 v[10:13], v[138:141], v[202:205], 0
	v_mfma_f32_16x16x32_bf16 v[14:17], v[130:133], v[202:205], 0
	v_mfma_f32_16x16x32_bf16 v[62:65], v[134:137], v[170:173], v[62:65]
	v_mfma_f32_16x16x32_bf16 v[58:61], v[142:145], v[170:173], v[58:61]
	v_mfma_f32_16x16x32_bf16 v[42:45], v[142:145], v[190:193], v[42:45]
	v_mfma_f32_16x16x32_bf16 v[46:49], v[134:137], v[190:193], v[46:49]
	v_mfma_f32_16x16x32_bf16 v[30:33], v[134:137], v[198:201], v[30:33]
	v_mfma_f32_16x16x32_bf16 v[26:29], v[142:145], v[198:201], v[26:29]
	s_waitcnt lgkmcnt(0)
	v_mfma_f32_16x16x32_bf16 v[10:13], v[142:145], v[206:209], v[10:13]
	v_mfma_f32_16x16x32_bf16 v[14:17], v[134:137], v[206:209], v[14:17]
	s_setprio 0
	s_setprio 1
	v_mfma_f32_16x16x32_bf16 v[54:57], v[150:153], v[166:169], 0
	v_mfma_f32_16x16x32_bf16 v[50:53], v[158:161], v[166:169], 0
	v_mfma_f32_16x16x32_bf16 v[34:37], v[158:161], v[186:189], 0
	v_mfma_f32_16x16x32_bf16 v[38:41], v[150:153], v[186:189], 0
	v_mfma_f32_16x16x32_bf16 v[22:25], v[150:153], v[194:197], 0
	v_mfma_f32_16x16x32_bf16 v[18:21], v[158:161], v[194:197], 0
	v_mfma_f32_16x16x32_bf16 v[2:5], v[158:161], v[202:205], 0
	v_mfma_f32_16x16x32_bf16 v[6:9], v[150:153], v[202:205], 0
	v_mfma_f32_16x16x32_bf16 v[54:57], v[154:157], v[170:173], v[54:57]
	v_mfma_f32_16x16x32_bf16 v[50:53], v[162:165], v[170:173], v[50:53]
	v_mfma_f32_16x16x32_bf16 v[34:37], v[162:165], v[190:193], v[34:37]
	v_mfma_f32_16x16x32_bf16 v[38:41], v[154:157], v[190:193], v[38:41]
	v_mfma_f32_16x16x32_bf16 v[22:25], v[154:157], v[198:201], v[22:25]
	v_mfma_f32_16x16x32_bf16 v[18:21], v[162:165], v[198:201], v[18:21]
	s_setprio 2
	s_barrier
	v_mfma_f32_16x16x32_bf16 v[2:5], v[162:165], v[206:209], v[2:5]
	v_mfma_f32_16x16x32_bf16 v[6:9], v[154:157], v[206:209], v[6:9]
	s_setprio 0
	ds_read_b128 v[130:133], v184
	ds_read_b128 v[134:137], v184 offset:1024
	ds_read_b128 v[138:141], v184 offset:2048
	ds_read_b128 v[142:145], v184 offset:3072
	ds_read_b128 v[150:153], v185
	ds_read_b128 v[154:157], v185 offset:1024
	ds_read_b128 v[158:161], v185 offset:2048
	ds_read_b128 v[162:165], v185 offset:3072
	ds_read_b128 v[166:169], v183 offset:32768
	ds_read_b128 v[170:173], v183 offset:33792
	ds_read_b128 v[186:189], v183 offset:34816
	ds_read_b128 v[190:193], v183 offset:35840
	ds_read_b128 v[194:197], v183 offset:36864
	ds_read_b128 v[198:201], v183 offset:37888
	ds_read_b128 v[202:205], v183 offset:38912
	ds_read_b128 v[206:209], v183 offset:39936
	s_mov_b32 s70, m0
	s_mov_b32 m0, s44
	s_nop 0
	global_load_lds_dwordx4 v1, s[34:35]
	s_mov_b32 m0, s70
	s_nop 0
	s_mov_b32 s70, m0
	s_mov_b32 m0, s48
	s_nop 0
	global_load_lds_dwordx4 v177, s[34:35]
	s_mov_b32 m0, s70
	s_add_u32 s34, s34, 0x4000
	s_addc_u32 s35, s35, 0
	s_mov_b32 s70, m0
	s_mov_b32 m0, s49
	s_nop 0
	global_load_lds_dwordx4 v1, s[34:35]
	s_mov_b32 m0, s70
	s_nop 0
	s_mov_b32 s70, m0
	s_mov_b32 m0, s50
	s_nop 0
	global_load_lds_dwordx4 v177, s[34:35]
	s_mov_b32 m0, s70
	s_waitcnt vmcnt(8)
	s_waitcnt lgkmcnt(0)
	s_barrier
	s_setprio 1
	s_waitcnt lgkmcnt(7)
	v_mfma_f32_16x16x32_bf16 v[126:129], v[130:133], v[166:169], v[126:129]
	v_mfma_f32_16x16x32_bf16 v[122:125], v[138:141], v[166:169], v[122:125]
	s_waitcnt lgkmcnt(5)
	v_mfma_f32_16x16x32_bf16 v[110:113], v[138:141], v[186:189], v[110:113]
	v_mfma_f32_16x16x32_bf16 v[118:121], v[130:133], v[186:189], v[118:121]
	s_waitcnt lgkmcnt(3)
	v_mfma_f32_16x16x32_bf16 v[94:97], v[130:133], v[194:197], v[94:97]
	v_mfma_f32_16x16x32_bf16 v[90:93], v[138:141], v[194:197], v[90:93]
	s_waitcnt lgkmcnt(1)
	v_mfma_f32_16x16x32_bf16 v[78:81], v[138:141], v[202:205], v[78:81]
	v_mfma_f32_16x16x32_bf16 v[86:89], v[130:133], v[202:205], v[86:89]
	v_mfma_f32_16x16x32_bf16 v[126:129], v[134:137], v[170:173], v[126:129]
	v_mfma_f32_16x16x32_bf16 v[122:125], v[142:145], v[170:173], v[122:125]
	v_mfma_f32_16x16x32_bf16 v[110:113], v[142:145], v[190:193], v[110:113]
	v_mfma_f32_16x16x32_bf16 v[118:121], v[134:137], v[190:193], v[118:121]
	v_mfma_f32_16x16x32_bf16 v[94:97], v[134:137], v[198:201], v[94:97]
	v_mfma_f32_16x16x32_bf16 v[90:93], v[142:145], v[198:201], v[90:93]
	s_waitcnt lgkmcnt(0)
	v_mfma_f32_16x16x32_bf16 v[78:81], v[142:145], v[206:209], v[78:81]
	v_mfma_f32_16x16x32_bf16 v[86:89], v[134:137], v[206:209], v[86:89]
	s_setprio 0
	s_setprio 1
	v_mfma_f32_16x16x32_bf16 v[114:117], v[150:153], v[166:169], v[114:117]
	v_mfma_f32_16x16x32_bf16 v[106:109], v[158:161], v[166:169], v[106:109]
	v_mfma_f32_16x16x32_bf16 v[98:101], v[158:161], v[186:189], v[98:101]
	v_mfma_f32_16x16x32_bf16 v[102:105], v[150:153], v[186:189], v[102:105]
	v_mfma_f32_16x16x32_bf16 v[82:85], v[150:153], v[194:197], v[82:85]
	v_mfma_f32_16x16x32_bf16 v[74:77], v[158:161], v[194:197], v[74:77]
	v_mfma_f32_16x16x32_bf16 v[66:69], v[158:161], v[202:205], v[66:69]
	v_mfma_f32_16x16x32_bf16 v[70:73], v[150:153], v[202:205], v[70:73]
	v_mfma_f32_16x16x32_bf16 v[114:117], v[154:157], v[170:173], v[114:117]
	v_mfma_f32_16x16x32_bf16 v[106:109], v[162:165], v[170:173], v[106:109]
	v_mfma_f32_16x16x32_bf16 v[98:101], v[162:165], v[190:193], v[98:101]
	v_mfma_f32_16x16x32_bf16 v[102:105], v[154:157], v[190:193], v[102:105]
	v_mfma_f32_16x16x32_bf16 v[82:85], v[154:157], v[198:201], v[82:85]
	v_mfma_f32_16x16x32_bf16 v[74:77], v[162:165], v[198:201], v[74:77]
	s_setprio 2
	s_barrier
	v_mfma_f32_16x16x32_bf16 v[66:69], v[162:165], v[206:209], v[66:69]
	v_mfma_f32_16x16x32_bf16 v[70:73], v[154:157], v[206:209], v[70:73]
	s_setprio 0
	ds_read_b128 v[166:169], v183 offset:49152
	ds_read_b128 v[170:173], v183 offset:50176
	ds_read_b128 v[186:189], v183 offset:51200
	ds_read_b128 v[190:193], v183 offset:52224
	ds_read_b128 v[194:197], v183 offset:53248
	ds_read_b128 v[198:201], v183 offset:54272
	ds_read_b128 v[202:205], v183 offset:55296
	ds_read_b128 v[206:209], v183 offset:56320
	s_add_u32 s34, s30, 0x40000
	s_addc_u32 s35, s31, 0
	s_mov_b32 s70, m0
	s_mov_b32 m0, s51
	s_nop 0
	global_load_lds_dwordx4 v176, s[34:35]
	s_mov_b32 m0, s70
	s_add_u32 s30, s30, 0x44000
	s_mov_b32 s70, m0
	s_mov_b32 m0, s52
	s_nop 0
	global_load_lds_dwordx4 v178, s[34:35]
	s_mov_b32 m0, s70
	s_addc_u32 s31, s31, 0
	s_mov_b32 s34, m0
	s_mov_b32 m0, s53
	s_nop 0
	global_load_lds_dwordx4 v176, s[30:31]
	s_mov_b32 m0, s34
	s_nop 0
	s_mov_b32 s34, m0
	s_mov_b32 m0, s54
	s_nop 0
	global_load_lds_dwordx4 v178, s[30:31]
	s_mov_b32 m0, s34
	s_waitcnt vmcnt(4)
	s_waitcnt lgkmcnt(0)
	s_barrier
	s_setprio 1
	s_waitcnt lgkmcnt(7)
	v_mfma_f32_16x16x32_bf16 v[62:65], v[130:133], v[166:169], v[62:65]
	v_mfma_f32_16x16x32_bf16 v[58:61], v[138:141], v[166:169], v[58:61]
	s_waitcnt lgkmcnt(5)
	v_mfma_f32_16x16x32_bf16 v[42:45], v[138:141], v[186:189], v[42:45]
	v_mfma_f32_16x16x32_bf16 v[46:49], v[130:133], v[186:189], v[46:49]
	s_waitcnt lgkmcnt(3)
	v_mfma_f32_16x16x32_bf16 v[30:33], v[130:133], v[194:197], v[30:33]
	v_mfma_f32_16x16x32_bf16 v[26:29], v[138:141], v[194:197], v[26:29]
	s_waitcnt lgkmcnt(1)
	v_mfma_f32_16x16x32_bf16 v[10:13], v[138:141], v[202:205], v[10:13]
	v_mfma_f32_16x16x32_bf16 v[14:17], v[130:133], v[202:205], v[14:17]
	v_mfma_f32_16x16x32_bf16 v[62:65], v[134:137], v[170:173], v[62:65]
	v_mfma_f32_16x16x32_bf16 v[58:61], v[142:145], v[170:173], v[58:61]
	v_mfma_f32_16x16x32_bf16 v[42:45], v[142:145], v[190:193], v[42:45]
	v_mfma_f32_16x16x32_bf16 v[46:49], v[134:137], v[190:193], v[46:49]
	v_mfma_f32_16x16x32_bf16 v[30:33], v[134:137], v[198:201], v[30:33]
	v_mfma_f32_16x16x32_bf16 v[26:29], v[142:145], v[198:201], v[26:29]
	s_waitcnt lgkmcnt(0)
	v_mfma_f32_16x16x32_bf16 v[10:13], v[142:145], v[206:209], v[10:13]
	v_mfma_f32_16x16x32_bf16 v[14:17], v[134:137], v[206:209], v[14:17]
	s_setprio 0
	s_setprio 1
	v_mfma_f32_16x16x32_bf16 v[54:57], v[150:153], v[166:169], v[54:57]
	v_mfma_f32_16x16x32_bf16 v[50:53], v[158:161], v[166:169], v[50:53]
	v_mfma_f32_16x16x32_bf16 v[34:37], v[158:161], v[186:189], v[34:37]
	v_mfma_f32_16x16x32_bf16 v[38:41], v[150:153], v[186:189], v[38:41]
	v_mfma_f32_16x16x32_bf16 v[22:25], v[150:153], v[194:197], v[22:25]
	v_mfma_f32_16x16x32_bf16 v[18:21], v[158:161], v[194:197], v[18:21]
	v_mfma_f32_16x16x32_bf16 v[2:5], v[158:161], v[202:205], v[2:5]
	v_mfma_f32_16x16x32_bf16 v[6:9], v[150:153], v[202:205], v[6:9]
	v_mfma_f32_16x16x32_bf16 v[54:57], v[154:157], v[170:173], v[54:57]
	v_mfma_f32_16x16x32_bf16 v[50:53], v[162:165], v[170:173], v[50:53]
	v_mfma_f32_16x16x32_bf16 v[34:37], v[162:165], v[190:193], v[34:37]
	v_mfma_f32_16x16x32_bf16 v[38:41], v[154:157], v[190:193], v[38:41]
	v_mfma_f32_16x16x32_bf16 v[22:25], v[154:157], v[198:201], v[22:25]
	v_mfma_f32_16x16x32_bf16 v[18:21], v[162:165], v[198:201], v[18:21]
	s_setprio 2
	s_barrier
	v_mfma_f32_16x16x32_bf16 v[2:5], v[162:165], v[206:209], v[2:5]
	v_mfma_f32_16x16x32_bf16 v[6:9], v[154:157], v[206:209], v[6:9]
	s_setprio 0
	s_add_i32 s69, s69, 2
	s_add_u32 s65, s65, 0x80000
	s_addc_u32 s66, s66, 0
	s_add_u32 s28, s28, 0x400000
	s_addc_u32 s29, s29, 0
	s_add_u32 s67, s67, 0x400000
	s_addc_u32 s68, s68, 0
	s_cmpk_gt_u32 s69, 0x53
	.p2align 6
.LBB0_2792:
	ds_read_b128 v[130:133], v181
	ds_read_b128 v[134:137], v181 offset:1024
	ds_read_b128 v[138:141], v181 offset:2048
	ds_read_b128 v[142:145], v181 offset:3072
	ds_read_b128 v[150:153], v182
	ds_read_b128 v[154:157], v182 offset:1024
	ds_read_b128 v[158:161], v182 offset:2048
	ds_read_b128 v[162:165], v182 offset:3072
	s_cmpk_eq_i32 s69, 0x52
	s_cselect_b32 s31, s19, s66
	s_cselect_b32 s30, s64, s65
	s_cselect_b32 s35, s21, s68
	s_cselect_b32 s34, s63, s67
	ds_read_b128 v[166:169], v183
	ds_read_b128 v[170:173], v183 offset:1024
	ds_read_b128 v[186:189], v183 offset:2048
	ds_read_b128 v[190:193], v183 offset:3072
	ds_read_b128 v[194:197], v183 offset:4096
	ds_read_b128 v[198:201], v183 offset:5120
	ds_read_b128 v[202:205], v183 offset:6144
	ds_read_b128 v[206:209], v183 offset:7168
	s_add_u32 s70, s28, 0xffffc000
	s_addc_u32 s71, s29, -1
	s_mov_b32 s73, m0
	s_mov_b32 m0, s57
	s_nop 0
	global_load_lds_dwordx4 v1, s[70:71]
	s_mov_b32 m0, s73
	s_nop 0
	s_mov_b32 s73, m0
	s_mov_b32 m0, s59
	s_nop 0
	global_load_lds_dwordx4 v177, s[70:71]
	s_mov_b32 m0, s73
	s_mov_b32 s70, m0
	s_mov_b32 m0, s58
	s_nop 0
	global_load_lds_dwordx4 v1, s[28:29]
	s_mov_b32 m0, s70
	s_nop 0
	s_mov_b32 s70, m0
	s_mov_b32 m0, s60
	s_nop 0
	global_load_lds_dwordx4 v177, s[28:29]
	s_mov_b32 m0, s70
	s_waitcnt vmcnt(8)
	s_waitcnt lgkmcnt(0)
	s_barrier
	s_setprio 1
	s_waitcnt lgkmcnt(7)
	v_mfma_f32_16x16x32_bf16 v[126:129], v[130:133], v[166:169], v[126:129]
	v_mfma_f32_16x16x32_bf16 v[122:125], v[138:141], v[166:169], v[122:125]
	s_waitcnt lgkmcnt(5)
	v_mfma_f32_16x16x32_bf16 v[110:113], v[138:141], v[186:189], v[110:113]
	v_mfma_f32_16x16x32_bf16 v[118:121], v[130:133], v[186:189], v[118:121]
	s_waitcnt lgkmcnt(3)
	v_mfma_f32_16x16x32_bf16 v[94:97], v[130:133], v[194:197], v[94:97]
	v_mfma_f32_16x16x32_bf16 v[90:93], v[138:141], v[194:197], v[90:93]
	s_waitcnt lgkmcnt(1)
	v_mfma_f32_16x16x32_bf16 v[78:81], v[138:141], v[202:205], v[78:81]
	v_mfma_f32_16x16x32_bf16 v[86:89], v[130:133], v[202:205], v[86:89]
	v_mfma_f32_16x16x32_bf16 v[126:129], v[134:137], v[170:173], v[126:129]
	v_mfma_f32_16x16x32_bf16 v[122:125], v[142:145], v[170:173], v[122:125]
	v_mfma_f32_16x16x32_bf16 v[110:113], v[142:145], v[190:193], v[110:113]
	v_mfma_f32_16x16x32_bf16 v[118:121], v[134:137], v[190:193], v[118:121]
	v_mfma_f32_16x16x32_bf16 v[94:97], v[134:137], v[198:201], v[94:97]
	v_mfma_f32_16x16x32_bf16 v[90:93], v[142:145], v[198:201], v[90:93]
	s_waitcnt lgkmcnt(0)
	v_mfma_f32_16x16x32_bf16 v[78:81], v[142:145], v[206:209], v[78:81]
	v_mfma_f32_16x16x32_bf16 v[86:89], v[134:137], v[206:209], v[86:89]
	s_setprio 0
	s_setprio 1
	v_mfma_f32_16x16x32_bf16 v[114:117], v[150:153], v[166:169], v[114:117]
	v_mfma_f32_16x16x32_bf16 v[106:109], v[158:161], v[166:169], v[106:109]
	v_mfma_f32_16x16x32_bf16 v[98:101], v[158:161], v[186:189], v[98:101]
	v_mfma_f32_16x16x32_bf16 v[102:105], v[150:153], v[186:189], v[102:105]
	v_mfma_f32_16x16x32_bf16 v[82:85], v[150:153], v[194:197], v[82:85]
	v_mfma_f32_16x16x32_bf16 v[74:77], v[158:161], v[194:197], v[74:77]
	v_mfma_f32_16x16x32_bf16 v[66:69], v[158:161], v[202:205], v[66:69]
	v_mfma_f32_16x16x32_bf16 v[70:73], v[150:153], v[202:205], v[70:73]
	v_mfma_f32_16x16x32_bf16 v[114:117], v[154:157], v[170:173], v[114:117]
	v_mfma_f32_16x16x32_bf16 v[106:109], v[162:165], v[170:173], v[106:109]
	v_mfma_f32_16x16x32_bf16 v[98:101], v[162:165], v[190:193], v[98:101]
	v_mfma_f32_16x16x32_bf16 v[102:105], v[154:157], v[190:193], v[102:105]
	v_mfma_f32_16x16x32_bf16 v[82:85], v[154:157], v[198:201], v[82:85]
	v_mfma_f32_16x16x32_bf16 v[74:77], v[162:165], v[198:201], v[74:77]
	s_setprio 2
	s_barrier
	v_mfma_f32_16x16x32_bf16 v[66:69], v[162:165], v[206:209], v[66:69]
	v_mfma_f32_16x16x32_bf16 v[70:73], v[154:157], v[206:209], v[70:73]
	s_setprio 0
	ds_read_b128 v[166:169], v183 offset:16384
	ds_read_b128 v[170:173], v183 offset:17408
	ds_read_b128 v[186:189], v183 offset:18432
	ds_read_b128 v[190:193], v183 offset:19456
	ds_read_b128 v[194:197], v183 offset:20480
	ds_read_b128 v[198:201], v183 offset:21504
	ds_read_b128 v[202:205], v183 offset:22528
	ds_read_b128 v[206:209], v183 offset:23552
	s_mov_b32 s70, m0
	s_mov_b32 m0, s27
	s_nop 0
	global_load_lds_dwordx4 v176, s[30:31]
	s_mov_b32 m0, s70
	s_nop 0
	s_mov_b32 s70, m0
	s_mov_b32 m0, s45
	s_nop 0
	global_load_lds_dwordx4 v178, s[30:31]
	s_mov_b32 m0, s70
	s_add_u32 s70, s30, 0x4000
	s_addc_u32 s71, s31, 0
	s_mov_b32 s73, m0
	s_mov_b32 m0, s46
	s_nop 0
	global_load_lds_dwordx4 v176, s[70:71]
	s_mov_b32 m0, s73
	s_nop 0
	s_mov_b32 s73, m0
	s_mov_b32 m0, s47
	s_nop 0
	global_load_lds_dwordx4 v178, s[70:71]
	s_mov_b32 m0, s73
	s_waitcnt vmcnt(4)
	s_waitcnt lgkmcnt(0)
	s_barrier
	s_setprio 1
	s_waitcnt lgkmcnt(7)
	v_mfma_f32_16x16x32_bf16 v[62:65], v[130:133], v[166:169], v[62:65]
	v_mfma_f32_16x16x32_bf16 v[58:61], v[138:141], v[166:169], v[58:61]
	s_waitcnt lgkmcnt(5)
	v_mfma_f32_16x16x32_bf16 v[42:45], v[138:141], v[186:189], v[42:45]
	v_mfma_f32_16x16x32_bf16 v[46:49], v[130:133], v[186:189], v[46:49]
	s_waitcnt lgkmcnt(3)
	v_mfma_f32_16x16x32_bf16 v[30:33], v[130:133], v[194:197], v[30:33]
	v_mfma_f32_16x16x32_bf16 v[26:29], v[138:141], v[194:197], v[26:29]
	s_waitcnt lgkmcnt(1)
	v_mfma_f32_16x16x32_bf16 v[10:13], v[138:141], v[202:205], v[10:13]
	v_mfma_f32_16x16x32_bf16 v[14:17], v[130:133], v[202:205], v[14:17]
	v_mfma_f32_16x16x32_bf16 v[62:65], v[134:137], v[170:173], v[62:65]
	v_mfma_f32_16x16x32_bf16 v[58:61], v[142:145], v[170:173], v[58:61]
	v_mfma_f32_16x16x32_bf16 v[42:45], v[142:145], v[190:193], v[42:45]
	v_mfma_f32_16x16x32_bf16 v[46:49], v[134:137], v[190:193], v[46:49]
	v_mfma_f32_16x16x32_bf16 v[30:33], v[134:137], v[198:201], v[30:33]
	v_mfma_f32_16x16x32_bf16 v[26:29], v[142:145], v[198:201], v[26:29]
	s_waitcnt lgkmcnt(0)
	v_mfma_f32_16x16x32_bf16 v[10:13], v[142:145], v[206:209], v[10:13]
	v_mfma_f32_16x16x32_bf16 v[14:17], v[134:137], v[206:209], v[14:17]
	s_setprio 0
	s_setprio 1
	v_mfma_f32_16x16x32_bf16 v[54:57], v[150:153], v[166:169], v[54:57]
	v_mfma_f32_16x16x32_bf16 v[50:53], v[158:161], v[166:169], v[50:53]
	v_mfma_f32_16x16x32_bf16 v[34:37], v[158:161], v[186:189], v[34:37]
	v_mfma_f32_16x16x32_bf16 v[38:41], v[150:153], v[186:189], v[38:41]
	v_mfma_f32_16x16x32_bf16 v[22:25], v[150:153], v[194:197], v[22:25]
	v_mfma_f32_16x16x32_bf16 v[18:21], v[158:161], v[194:197], v[18:21]
	v_mfma_f32_16x16x32_bf16 v[2:5], v[158:161], v[202:205], v[2:5]
	v_mfma_f32_16x16x32_bf16 v[6:9], v[150:153], v[202:205], v[6:9]
	v_mfma_f32_16x16x32_bf16 v[54:57], v[154:157], v[170:173], v[54:57]
	v_mfma_f32_16x16x32_bf16 v[50:53], v[162:165], v[170:173], v[50:53]
	v_mfma_f32_16x16x32_bf16 v[34:37], v[162:165], v[190:193], v[34:37]
	v_mfma_f32_16x16x32_bf16 v[38:41], v[154:157], v[190:193], v[38:41]
	v_mfma_f32_16x16x32_bf16 v[22:25], v[154:157], v[198:201], v[22:25]
	v_mfma_f32_16x16x32_bf16 v[18:21], v[162:165], v[198:201], v[18:21]
	s_setprio 2
	s_barrier
	v_mfma_f32_16x16x32_bf16 v[2:5], v[162:165], v[206:209], v[2:5]
	v_mfma_f32_16x16x32_bf16 v[6:9], v[154:157], v[206:209], v[6:9]
	s_setprio 0
	ds_read_b128 v[130:133], v184
	ds_read_b128 v[134:137], v184 offset:1024
	ds_read_b128 v[138:141], v184 offset:2048
	ds_read_b128 v[142:145], v184 offset:3072
	ds_read_b128 v[150:153], v185
	ds_read_b128 v[154:157], v185 offset:1024
	ds_read_b128 v[158:161], v185 offset:2048
	ds_read_b128 v[162:165], v185 offset:3072
	ds_read_b128 v[166:169], v183 offset:32768
	ds_read_b128 v[170:173], v183 offset:33792
	ds_read_b128 v[186:189], v183 offset:34816
	ds_read_b128 v[190:193], v183 offset:35840
	ds_read_b128 v[194:197], v183 offset:36864
	ds_read_b128 v[198:201], v183 offset:37888
	ds_read_b128 v[202:205], v183 offset:38912
	ds_read_b128 v[206:209], v183 offset:39936
	s_mov_b32 s70, m0
	s_mov_b32 m0, s44
	s_nop 0
	global_load_lds_dwordx4 v1, s[34:35]
	s_mov_b32 m0, s70
	s_nop 0
	s_mov_b32 s70, m0
	s_mov_b32 m0, s48
	s_nop 0
	global_load_lds_dwordx4 v177, s[34:35]
	s_mov_b32 m0, s70
	s_add_u32 s34, s34, 0x4000
	s_addc_u32 s35, s35, 0
	s_mov_b32 s70, m0
	s_mov_b32 m0, s49
	s_nop 0
	global_load_lds_dwordx4 v1, s[34:35]
	s_mov_b32 m0, s70
	s_nop 0
	s_mov_b32 s70, m0
	s_mov_b32 m0, s50
	s_nop 0
	global_load_lds_dwordx4 v177, s[34:35]
	s_mov_b32 m0, s70
	s_waitcnt vmcnt(8)
	s_waitcnt lgkmcnt(0)
	s_barrier
	s_setprio 1
	s_waitcnt lgkmcnt(7)
	v_mfma_f32_16x16x32_bf16 v[126:129], v[130:133], v[166:169], v[126:129]
	v_mfma_f32_16x16x32_bf16 v[122:125], v[138:141], v[166:169], v[122:125]
	s_waitcnt lgkmcnt(5)
	v_mfma_f32_16x16x32_bf16 v[110:113], v[138:141], v[186:189], v[110:113]
	v_mfma_f32_16x16x32_bf16 v[118:121], v[130:133], v[186:189], v[118:121]
	s_waitcnt lgkmcnt(3)
	v_mfma_f32_16x16x32_bf16 v[94:97], v[130:133], v[194:197], v[94:97]
	v_mfma_f32_16x16x32_bf16 v[90:93], v[138:141], v[194:197], v[90:93]
	s_waitcnt lgkmcnt(1)
	v_mfma_f32_16x16x32_bf16 v[78:81], v[138:141], v[202:205], v[78:81]
	v_mfma_f32_16x16x32_bf16 v[86:89], v[130:133], v[202:205], v[86:89]
	v_mfma_f32_16x16x32_bf16 v[126:129], v[134:137], v[170:173], v[126:129]
	v_mfma_f32_16x16x32_bf16 v[122:125], v[142:145], v[170:173], v[122:125]
	v_mfma_f32_16x16x32_bf16 v[110:113], v[142:145], v[190:193], v[110:113]
	v_mfma_f32_16x16x32_bf16 v[118:121], v[134:137], v[190:193], v[118:121]
	v_mfma_f32_16x16x32_bf16 v[94:97], v[134:137], v[198:201], v[94:97]
	v_mfma_f32_16x16x32_bf16 v[90:93], v[142:145], v[198:201], v[90:93]
	s_waitcnt lgkmcnt(0)
	v_mfma_f32_16x16x32_bf16 v[78:81], v[142:145], v[206:209], v[78:81]
	v_mfma_f32_16x16x32_bf16 v[86:89], v[134:137], v[206:209], v[86:89]
	s_setprio 0
	s_setprio 1
	v_mfma_f32_16x16x32_bf16 v[114:117], v[150:153], v[166:169], v[114:117]
	v_mfma_f32_16x16x32_bf16 v[106:109], v[158:161], v[166:169], v[106:109]
	v_mfma_f32_16x16x32_bf16 v[98:101], v[158:161], v[186:189], v[98:101]
	v_mfma_f32_16x16x32_bf16 v[102:105], v[150:153], v[186:189], v[102:105]
	v_mfma_f32_16x16x32_bf16 v[82:85], v[150:153], v[194:197], v[82:85]
	v_mfma_f32_16x16x32_bf16 v[74:77], v[158:161], v[194:197], v[74:77]
	v_mfma_f32_16x16x32_bf16 v[66:69], v[158:161], v[202:205], v[66:69]
	v_mfma_f32_16x16x32_bf16 v[70:73], v[150:153], v[202:205], v[70:73]
	v_mfma_f32_16x16x32_bf16 v[114:117], v[154:157], v[170:173], v[114:117]
	v_mfma_f32_16x16x32_bf16 v[106:109], v[162:165], v[170:173], v[106:109]
	v_mfma_f32_16x16x32_bf16 v[98:101], v[162:165], v[190:193], v[98:101]
	v_mfma_f32_16x16x32_bf16 v[102:105], v[154:157], v[190:193], v[102:105]
	v_mfma_f32_16x16x32_bf16 v[82:85], v[154:157], v[198:201], v[82:85]
	v_mfma_f32_16x16x32_bf16 v[74:77], v[162:165], v[198:201], v[74:77]
	s_setprio 2
	s_barrier
	v_mfma_f32_16x16x32_bf16 v[66:69], v[162:165], v[206:209], v[66:69]
	v_mfma_f32_16x16x32_bf16 v[70:73], v[154:157], v[206:209], v[70:73]
	s_setprio 0
	ds_read_b128 v[166:169], v183 offset:49152
	ds_read_b128 v[170:173], v183 offset:50176
	ds_read_b128 v[186:189], v183 offset:51200
	ds_read_b128 v[190:193], v183 offset:52224
	ds_read_b128 v[194:197], v183 offset:53248
	ds_read_b128 v[198:201], v183 offset:54272
	ds_read_b128 v[202:205], v183 offset:55296
	ds_read_b128 v[206:209], v183 offset:56320
	s_add_u32 s34, s30, 0x40000
	s_addc_u32 s35, s31, 0
	s_mov_b32 s70, m0
	s_mov_b32 m0, s51
	s_nop 0
	global_load_lds_dwordx4 v176, s[34:35]
	s_mov_b32 m0, s70
	s_add_u32 s30, s30, 0x44000
	s_mov_b32 s70, m0
	s_mov_b32 m0, s52
	s_nop 0
	global_load_lds_dwordx4 v178, s[34:35]
	s_mov_b32 m0, s70
	s_addc_u32 s31, s31, 0
	s_mov_b32 s34, m0
	s_mov_b32 m0, s53
	s_nop 0
	global_load_lds_dwordx4 v176, s[30:31]
	s_mov_b32 m0, s34
	s_nop 0
	s_mov_b32 s34, m0
	s_mov_b32 m0, s54
	s_nop 0
	global_load_lds_dwordx4 v178, s[30:31]
	s_mov_b32 m0, s34
	s_waitcnt vmcnt(4)
	s_waitcnt lgkmcnt(0)
	s_barrier
	s_setprio 1
	s_waitcnt lgkmcnt(7)
	v_mfma_f32_16x16x32_bf16 v[62:65], v[130:133], v[166:169], v[62:65]
	v_mfma_f32_16x16x32_bf16 v[58:61], v[138:141], v[166:169], v[58:61]
	s_waitcnt lgkmcnt(5)
	v_mfma_f32_16x16x32_bf16 v[42:45], v[138:141], v[186:189], v[42:45]
	v_mfma_f32_16x16x32_bf16 v[46:49], v[130:133], v[186:189], v[46:49]
	s_waitcnt lgkmcnt(3)
	v_mfma_f32_16x16x32_bf16 v[30:33], v[130:133], v[194:197], v[30:33]
	v_mfma_f32_16x16x32_bf16 v[26:29], v[138:141], v[194:197], v[26:29]
	s_waitcnt lgkmcnt(1)
	v_mfma_f32_16x16x32_bf16 v[10:13], v[138:141], v[202:205], v[10:13]
	v_mfma_f32_16x16x32_bf16 v[14:17], v[130:133], v[202:205], v[14:17]
	v_mfma_f32_16x16x32_bf16 v[62:65], v[134:137], v[170:173], v[62:65]
	v_mfma_f32_16x16x32_bf16 v[58:61], v[142:145], v[170:173], v[58:61]
	v_mfma_f32_16x16x32_bf16 v[42:45], v[142:145], v[190:193], v[42:45]
	v_mfma_f32_16x16x32_bf16 v[46:49], v[134:137], v[190:193], v[46:49]
	v_mfma_f32_16x16x32_bf16 v[30:33], v[134:137], v[198:201], v[30:33]
	v_mfma_f32_16x16x32_bf16 v[26:29], v[142:145], v[198:201], v[26:29]
	s_waitcnt lgkmcnt(0)
	v_mfma_f32_16x16x32_bf16 v[10:13], v[142:145], v[206:209], v[10:13]
	v_mfma_f32_16x16x32_bf16 v[14:17], v[134:137], v[206:209], v[14:17]
	s_setprio 0
	s_setprio 1
	v_mfma_f32_16x16x32_bf16 v[54:57], v[150:153], v[166:169], v[54:57]
	v_mfma_f32_16x16x32_bf16 v[50:53], v[158:161], v[166:169], v[50:53]
	v_mfma_f32_16x16x32_bf16 v[34:37], v[158:161], v[186:189], v[34:37]
	v_mfma_f32_16x16x32_bf16 v[38:41], v[150:153], v[186:189], v[38:41]
	v_mfma_f32_16x16x32_bf16 v[22:25], v[150:153], v[194:197], v[22:25]
	v_mfma_f32_16x16x32_bf16 v[18:21], v[158:161], v[194:197], v[18:21]
	v_mfma_f32_16x16x32_bf16 v[2:5], v[158:161], v[202:205], v[2:5]
	v_mfma_f32_16x16x32_bf16 v[6:9], v[150:153], v[202:205], v[6:9]
	v_mfma_f32_16x16x32_bf16 v[54:57], v[154:157], v[170:173], v[54:57]
	v_mfma_f32_16x16x32_bf16 v[50:53], v[162:165], v[170:173], v[50:53]
	v_mfma_f32_16x16x32_bf16 v[34:37], v[162:165], v[190:193], v[34:37]
	v_mfma_f32_16x16x32_bf16 v[38:41], v[154:157], v[190:193], v[38:41]
	v_mfma_f32_16x16x32_bf16 v[22:25], v[154:157], v[198:201], v[22:25]
	v_mfma_f32_16x16x32_bf16 v[18:21], v[162:165], v[198:201], v[18:21]
	s_setprio 2
	s_barrier
	v_mfma_f32_16x16x32_bf16 v[2:5], v[162:165], v[206:209], v[2:5]
	v_mfma_f32_16x16x32_bf16 v[6:9], v[154:157], v[206:209], v[6:9]
	s_setprio 0
	s_add_i32 s69, s69, 2
	s_add_u32 s65, s65, 0x80000
	s_addc_u32 s66, s66, 0
	s_add_u32 s28, s28, 0x400000
	s_addc_u32 s29, s29, 0
	s_add_u32 s67, s67, 0x400000
	s_addc_u32 s68, s68, 0
	s_cmpk_gt_u32 s69, 0x53
	s_cbranch_scc0 .LBB0_2792
	s_and_b64 vcc, exec, s[8:9]
	s_cbranch_vccz .LBB0_2795
	s_barrier
